# v58 + post-barrier fragment ds_reads issued before the next-k-tile global loads in the win k-loop
# speedup vs baseline: 1.0010x; 1.0010x over previous
.LBB0_257:
	v_ashrrev_i32_e32 v3, 31, v2
	v_lshlrev_b64 v[2:3], 11, v[2:3]
	v_lshl_add_u64 v[70:71], v[86:87], 0, v[2:3]
	v_or_b32_e32 v2, s56, v154
	v_ashrrev_i32_e32 v3, 31, v2
	v_lshlrev_b64 v[2:3], 11, v[2:3]
	v_lshl_add_u64 v[72:73], v[84:85], 0, v[2:3]
	v_add_u32_e32 v2, s56, v155
	v_ashrrev_i32_e32 v3, 31, v2
	v_lshlrev_b64 v[2:3], 11, v[2:3]
	v_lshl_add_u64 v[74:75], v[84:85], 0, v[2:3]
	v_add_u32_e32 v2, s56, v156
	v_ashrrev_i32_e32 v3, 31, v2
	v_lshlrev_b64 v[2:3], 11, v[2:3]
	v_lshl_add_u64 v[76:77], v[84:85], 0, v[2:3]
	v_add_u32_e32 v2, s56, v157
	v_ashrrev_i32_e32 v3, 31, v2
	v_ashrrev_i32_e32 v9, 31, v8
	v_ashrrev_i32_e32 v5, 31, v4
	v_lshlrev_b64 v[2:3], 11, v[2:3]
	v_ashrrev_i32_e32 v7, 31, v6
	v_lshlrev_b64 v[8:9], 11, v[8:9]
	v_lshlrev_b64 v[4:5], 11, v[4:5]
	v_lshl_add_u64 v[78:79], v[84:85], 0, v[2:3]
	v_lshlrev_b64 v[2:3], 11, v[6:7]
	v_lshl_add_u64 v[66:67], v[86:87], 0, v[8:9]
	v_lshl_add_u64 v[68:69], v[86:87], 0, v[4:5]
	v_lshl_add_u64 v[80:81], v[86:87], 0, v[2:3]
	global_load_dwordx4 v[2:5], v[70:71], off
	global_load_dwordx4 v[6:9], v[68:69], off
	global_load_dwordx4 v[10:13], v[66:67], off
	global_load_dwordx4 v[14:17], v[80:81], off
	global_load_dwordx4 v[18:21], v[72:73], off
	global_load_dwordx4 v[22:25], v[74:75], off
	global_load_dwordx4 v[26:29], v[76:77], off
	global_load_dwordx4 v[30:33], v[78:79], off
	global_load_dwordx4 v[122:125], v[70:71], off offset:128
	global_load_dwordx4 v[126:129], v[68:69], off offset:128
	global_load_dwordx4 v[136:139], v[66:67], off offset:128
	global_load_dwordx4 v[140:143], v[80:81], off offset:128
	global_load_dwordx4 v[144:147], v[72:73], off offset:128
	global_load_dwordx4 v[148:151], v[74:75], off offset:128
	global_load_dwordx4 v[172:175], v[76:77], off offset:128
	global_load_dwordx4 v[176:179], v[78:79], off offset:128
	s_waitcnt vmcnt(15)
	ds_write_b128 v165, v[2:5] offset:36864
	s_waitcnt vmcnt(14)
	ds_write_b128 v165, v[6:9] offset:41472
	s_waitcnt vmcnt(13)
	ds_write_b128 v165, v[10:13] offset:46080
	s_waitcnt vmcnt(12)
	ds_write_b128 v165, v[14:17] offset:50688
	s_waitcnt vmcnt(11)
	ds_write_b128 v165, v[18:21]
	s_waitcnt vmcnt(10)
	ds_write_b128 v165, v[22:25] offset:4608
	s_waitcnt vmcnt(9)
	ds_write_b128 v165, v[26:29] offset:9216
	s_waitcnt vmcnt(8)
	ds_write_b128 v165, v[30:33] offset:13824
	s_waitcnt lgkmcnt(0)
	s_barrier
	global_load_dwordx4 v[180:183], v[74:75], off offset:256
	global_load_dwordx4 v[184:187], v[76:77], off offset:256
	global_load_dwordx4 v[188:191], v[72:73], off offset:256
	global_load_dwordx4 v[192:195], v[70:71], off offset:256
	global_load_dwordx4 v[196:199], v[68:69], off offset:256
	global_load_dwordx4 v[200:203], v[66:67], off offset:256
	global_load_dwordx4 v[204:207], v[78:79], off offset:256
	global_load_dwordx4 v[208:211], v[80:81], off offset:256
	v_and_b32_e32 v246, 15, v1
	v_add_u32_e32 v246, 4, v246
	v_bfe_u32 v246, v246, 3, 1
	v_bfe_u32 v249, v1, 4, 2
	v_xor_b32_e32 v246, v246, v249
	v_bfe_u32 v249, v1, 5, 1
	v_sub_u32_e32 v246, v246, v249
	v_lshlrev_b32_e32 v246, 4, v246
	v_bfe_u32 v249, v1, 4, 1
	v_mul_u32_u24_e32 v249, 0x900, v249
	v_sub_u32_e32 v246, v246, v249
	v_add_u32_e32 v244, v246, v162
	v_add_u32_e32 v245, v246, v164
	ds_read_b128 v[228:231], v245 offset:36864
	ds_read_b128 v[212:215], v244
	ds_read_b128 v[236:239], v245 offset:39168
	ds_read_b128 v[240:243], v245 offset:41472
	ds_read_b128 v[252:255], v245 offset:43776
	ds_read_b128 v[216:219], v244 offset:2304
	ds_read_b128 v[220:223], v244 offset:4608
	ds_read_b128 v[224:227], v244 offset:6912
	s_waitcnt lgkmcnt(6)
	v_mfma_f32_16x16x32_bf16 v[50:53], v[212:215], v[228:231], 0
	s_waitcnt lgkmcnt(5)
	v_mfma_f32_16x16x32_bf16 v[54:57], v[212:215], v[236:239], 0
	s_waitcnt lgkmcnt(4)
	v_mfma_f32_16x16x32_bf16 v[34:37], v[212:215], v[240:243], 0
	s_waitcnt lgkmcnt(3)
	v_mfma_f32_16x16x32_bf16 v[38:41], v[212:215], v[252:255], 0
	ds_read_b128 v[212:215], v244 offset:64
	s_waitcnt lgkmcnt(3)
	v_mfma_f32_16x16x32_bf16 v[58:61], v[216:219], v[228:231], 0
	v_mfma_f32_16x16x32_bf16 v[62:65], v[216:219], v[236:239], 0
	v_mfma_f32_16x16x32_bf16 v[42:45], v[216:219], v[240:243], 0
	v_mfma_f32_16x16x32_bf16 v[46:49], v[216:219], v[252:255], 0
	ds_read_b128 v[216:219], v244 offset:2368
	s_setprio 1
	s_waitcnt vmcnt(11)
	ds_write_b128 v165, v[144:147] offset:18432
	s_waitcnt vmcnt(10)
	ds_write_b128 v165, v[148:151] offset:23040
	s_waitcnt lgkmcnt(5)
	v_mfma_f32_16x16x32_bf16 v[18:21], v[220:223], v[228:231], 0
	v_mfma_f32_16x16x32_bf16 v[22:25], v[220:223], v[236:239], 0
	v_mfma_f32_16x16x32_bf16 v[2:5], v[220:223], v[240:243], 0
	v_mfma_f32_16x16x32_bf16 v[6:9], v[220:223], v[252:255], 0
	ds_read_b128 v[220:223], v244 offset:4672
	s_waitcnt vmcnt(9)
	ds_write_b128 v165, v[172:175] offset:27648
	s_waitcnt vmcnt(8)
	ds_write_b128 v165, v[176:179] offset:32256
	s_waitcnt lgkmcnt(7)
	v_mfma_f32_16x16x32_bf16 v[26:29], v[224:227], v[228:231], 0
	ds_read_b128 v[228:231], v245 offset:36928
	v_mfma_f32_16x16x32_bf16 v[30:33], v[224:227], v[236:239], 0
	ds_read_b128 v[236:239], v245 offset:39232
	v_mfma_f32_16x16x32_bf16 v[10:13], v[224:227], v[240:243], 0
	ds_read_b128 v[240:243], v245 offset:41536
	v_mfma_f32_16x16x32_bf16 v[14:17], v[224:227], v[252:255], 0
	ds_read_b128 v[252:255], v245 offset:43840
	ds_read_b128 v[224:227], v244 offset:6976
	s_waitcnt lgkmcnt(4)
	v_mfma_f32_16x16x32_bf16 v[50:53], v[212:215], v[228:231], v[50:53]
	s_waitcnt lgkmcnt(3)
	v_mfma_f32_16x16x32_bf16 v[54:57], v[212:215], v[236:239], v[54:57]
	s_waitcnt lgkmcnt(2)
	v_mfma_f32_16x16x32_bf16 v[34:37], v[212:215], v[240:243], v[34:37]
	s_waitcnt lgkmcnt(1)
	v_mfma_f32_16x16x32_bf16 v[38:41], v[212:215], v[252:255], v[38:41]
	ds_write_b128 v165, v[122:125] offset:55296
	ds_write_b128 v165, v[126:129] offset:59904
	v_mfma_f32_16x16x32_bf16 v[58:61], v[216:219], v[228:231], v[58:61]
	v_mfma_f32_16x16x32_bf16 v[62:65], v[216:219], v[236:239], v[62:65]
	v_mfma_f32_16x16x32_bf16 v[42:45], v[216:219], v[240:243], v[42:45]
	v_mfma_f32_16x16x32_bf16 v[46:49], v[216:219], v[252:255], v[46:49]
	ds_write_b128 v165, v[136:139] offset:64512
	ds_write_b128 v166, v[140:143] offset:32256
	v_mfma_f32_16x16x32_bf16 v[18:21], v[220:223], v[228:231], v[18:21]
	v_mfma_f32_16x16x32_bf16 v[22:25], v[220:223], v[236:239], v[22:25]
	v_mfma_f32_16x16x32_bf16 v[2:5], v[220:223], v[240:243], v[2:5]
	v_mfma_f32_16x16x32_bf16 v[6:9], v[220:223], v[252:255], v[6:9]
	s_waitcnt lgkmcnt(4)
	v_mfma_f32_16x16x32_bf16 v[26:29], v[224:227], v[228:231], v[26:29]
	v_mfma_f32_16x16x32_bf16 v[30:33], v[224:227], v[236:239], v[30:33]
	v_mfma_f32_16x16x32_bf16 v[10:13], v[224:227], v[240:243], v[10:13]
	v_mfma_f32_16x16x32_bf16 v[14:17], v[224:227], v[252:255], v[14:17]
	s_waitcnt lgkmcnt(0)
	s_barrier
	s_setprio 0
	ds_read_b128 v[228:231], v245 offset:55296
	ds_read_b128 v[212:215], v244 offset:18432
	ds_read_b128 v[236:239], v245 offset:57600
	ds_read_b128 v[240:243], v245 offset:59904
	ds_read_b128 v[252:255], v245 offset:62208
	ds_read_b128 v[216:219], v244 offset:20736
	ds_read_b128 v[220:223], v244 offset:23040
	ds_read_b128 v[224:227], v244 offset:25344
	global_load_dwordx4 v[122:125], v[72:73], off offset:384
	global_load_dwordx4 v[126:129], v[74:75], off offset:384
	global_load_dwordx4 v[136:139], v[76:77], off offset:384
	global_load_dwordx4 v[140:143], v[78:79], off offset:384
	global_load_dwordx4 v[144:147], v[70:71], off offset:384
	global_load_dwordx4 v[148:151], v[68:69], off offset:384
	global_load_dwordx4 v[172:175], v[66:67], off offset:384
	global_load_dwordx4 v[176:179], v[80:81], off offset:384
	s_waitcnt lgkmcnt(6)
	v_mfma_f32_16x16x32_bf16 v[50:53], v[212:215], v[228:231], v[50:53]
	s_waitcnt lgkmcnt(5)
	v_mfma_f32_16x16x32_bf16 v[54:57], v[212:215], v[236:239], v[54:57]
	s_waitcnt lgkmcnt(4)
	v_mfma_f32_16x16x32_bf16 v[34:37], v[212:215], v[240:243], v[34:37]
	s_waitcnt lgkmcnt(3)
	v_mfma_f32_16x16x32_bf16 v[38:41], v[212:215], v[252:255], v[38:41]
	ds_read_b128 v[212:215], v244 offset:18496
	s_waitcnt lgkmcnt(3)
	v_mfma_f32_16x16x32_bf16 v[58:61], v[216:219], v[228:231], v[58:61]
	v_mfma_f32_16x16x32_bf16 v[62:65], v[216:219], v[236:239], v[62:65]
	v_mfma_f32_16x16x32_bf16 v[42:45], v[216:219], v[240:243], v[42:45]
	v_mfma_f32_16x16x32_bf16 v[46:49], v[216:219], v[252:255], v[46:49]
	ds_read_b128 v[216:219], v244 offset:20800
	s_setprio 1
	s_waitcnt vmcnt(13)
	ds_write_b128 v165, v[188:191]
	ds_write_b128 v165, v[180:183] offset:4608
	s_waitcnt lgkmcnt(5)
	v_mfma_f32_16x16x32_bf16 v[18:21], v[220:223], v[228:231], v[18:21]
	v_mfma_f32_16x16x32_bf16 v[22:25], v[220:223], v[236:239], v[22:25]
	v_mfma_f32_16x16x32_bf16 v[2:5], v[220:223], v[240:243], v[2:5]
	v_mfma_f32_16x16x32_bf16 v[6:9], v[220:223], v[252:255], v[6:9]
	ds_read_b128 v[220:223], v244 offset:23104
	ds_write_b128 v165, v[184:187] offset:9216
	s_waitcnt vmcnt(9)
	ds_write_b128 v165, v[204:207] offset:13824
	s_waitcnt lgkmcnt(7)
	v_mfma_f32_16x16x32_bf16 v[26:29], v[224:227], v[228:231], v[26:29]
	ds_read_b128 v[228:231], v245 offset:55360
	v_mfma_f32_16x16x32_bf16 v[30:33], v[224:227], v[236:239], v[30:33]
	ds_read_b128 v[236:239], v245 offset:57664
	v_mfma_f32_16x16x32_bf16 v[10:13], v[224:227], v[240:243], v[10:13]
	ds_read_b128 v[240:243], v245 offset:59968
	v_mfma_f32_16x16x32_bf16 v[14:17], v[224:227], v[252:255], v[14:17]
	ds_read_b128 v[252:255], v245 offset:62272
	ds_read_b128 v[224:227], v244 offset:25408
	s_waitcnt lgkmcnt(4)
	v_mfma_f32_16x16x32_bf16 v[50:53], v[212:215], v[228:231], v[50:53]
	s_waitcnt lgkmcnt(3)
	v_mfma_f32_16x16x32_bf16 v[54:57], v[212:215], v[236:239], v[54:57]
	s_waitcnt lgkmcnt(2)
	v_mfma_f32_16x16x32_bf16 v[34:37], v[212:215], v[240:243], v[34:37]
	s_waitcnt lgkmcnt(1)
	v_mfma_f32_16x16x32_bf16 v[38:41], v[212:215], v[252:255], v[38:41]
	ds_write_b128 v165, v[192:195] offset:36864
	ds_write_b128 v165, v[196:199] offset:41472
	v_mfma_f32_16x16x32_bf16 v[58:61], v[216:219], v[228:231], v[58:61]
	v_mfma_f32_16x16x32_bf16 v[62:65], v[216:219], v[236:239], v[62:65]
	v_mfma_f32_16x16x32_bf16 v[42:45], v[216:219], v[240:243], v[42:45]
	v_mfma_f32_16x16x32_bf16 v[46:49], v[216:219], v[252:255], v[46:49]
	ds_write_b128 v165, v[200:203] offset:46080
	s_waitcnt vmcnt(8)
	ds_write_b128 v165, v[208:211] offset:50688
	v_mfma_f32_16x16x32_bf16 v[18:21], v[220:223], v[228:231], v[18:21]
	v_mfma_f32_16x16x32_bf16 v[22:25], v[220:223], v[236:239], v[22:25]
	v_mfma_f32_16x16x32_bf16 v[2:5], v[220:223], v[240:243], v[2:5]
	v_mfma_f32_16x16x32_bf16 v[6:9], v[220:223], v[252:255], v[6:9]
	s_waitcnt lgkmcnt(4)
	v_mfma_f32_16x16x32_bf16 v[26:29], v[224:227], v[228:231], v[26:29]
	v_mfma_f32_16x16x32_bf16 v[30:33], v[224:227], v[236:239], v[30:33]
	v_mfma_f32_16x16x32_bf16 v[10:13], v[224:227], v[240:243], v[10:13]
	v_mfma_f32_16x16x32_bf16 v[14:17], v[224:227], v[252:255], v[14:17]
	s_waitcnt lgkmcnt(0)
	s_barrier
	s_setprio 0
	ds_read_b128 v[228:231], v245 offset:36864
	ds_read_b128 v[212:215], v244
	ds_read_b128 v[236:239], v245 offset:39168
	ds_read_b128 v[240:243], v245 offset:41472
	ds_read_b128 v[252:255], v245 offset:43776
	ds_read_b128 v[216:219], v244 offset:2304
	ds_read_b128 v[220:223], v244 offset:4608
	ds_read_b128 v[224:227], v244 offset:6912
	global_load_dwordx4 v[180:183], v[72:73], off offset:512
	global_load_dwordx4 v[184:187], v[74:75], off offset:512
	global_load_dwordx4 v[188:191], v[76:77], off offset:512
	global_load_dwordx4 v[192:195], v[78:79], off offset:512
	global_load_dwordx4 v[196:199], v[70:71], off offset:512
	global_load_dwordx4 v[200:203], v[68:69], off offset:512
	global_load_dwordx4 v[204:207], v[66:67], off offset:512
	global_load_dwordx4 v[208:211], v[80:81], off offset:512
	s_waitcnt lgkmcnt(6)
	v_mfma_f32_16x16x32_bf16 v[50:53], v[212:215], v[228:231], v[50:53]
	s_waitcnt lgkmcnt(5)
	v_mfma_f32_16x16x32_bf16 v[54:57], v[212:215], v[236:239], v[54:57]
	s_waitcnt lgkmcnt(4)
	v_mfma_f32_16x16x32_bf16 v[34:37], v[212:215], v[240:243], v[34:37]
	s_waitcnt lgkmcnt(3)
	v_mfma_f32_16x16x32_bf16 v[38:41], v[212:215], v[252:255], v[38:41]
	ds_read_b128 v[212:215], v244 offset:64
	s_waitcnt lgkmcnt(3)
	v_mfma_f32_16x16x32_bf16 v[58:61], v[216:219], v[228:231], v[58:61]
	v_mfma_f32_16x16x32_bf16 v[62:65], v[216:219], v[236:239], v[62:65]
	v_mfma_f32_16x16x32_bf16 v[42:45], v[216:219], v[240:243], v[42:45]
	v_mfma_f32_16x16x32_bf16 v[46:49], v[216:219], v[252:255], v[46:49]
	ds_read_b128 v[216:219], v244 offset:2368
	s_setprio 1
	s_waitcnt vmcnt(15)
	ds_write_b128 v165, v[122:125] offset:18432
	s_waitcnt vmcnt(14)
	ds_write_b128 v165, v[126:129] offset:23040
	s_waitcnt lgkmcnt(5)
	v_mfma_f32_16x16x32_bf16 v[18:21], v[220:223], v[228:231], v[18:21]
	v_mfma_f32_16x16x32_bf16 v[22:25], v[220:223], v[236:239], v[22:25]
	v_mfma_f32_16x16x32_bf16 v[2:5], v[220:223], v[240:243], v[2:5]
	v_mfma_f32_16x16x32_bf16 v[6:9], v[220:223], v[252:255], v[6:9]
	ds_read_b128 v[220:223], v244 offset:4672
	s_waitcnt vmcnt(13)
	ds_write_b128 v165, v[136:139] offset:27648
	s_waitcnt vmcnt(12)
	ds_write_b128 v165, v[140:143] offset:32256
	s_waitcnt lgkmcnt(7)
	v_mfma_f32_16x16x32_bf16 v[26:29], v[224:227], v[228:231], v[26:29]
	ds_read_b128 v[228:231], v245 offset:36928
	v_mfma_f32_16x16x32_bf16 v[30:33], v[224:227], v[236:239], v[30:33]
	ds_read_b128 v[236:239], v245 offset:39232
	v_mfma_f32_16x16x32_bf16 v[10:13], v[224:227], v[240:243], v[10:13]
	ds_read_b128 v[240:243], v245 offset:41536
	v_mfma_f32_16x16x32_bf16 v[14:17], v[224:227], v[252:255], v[14:17]
	ds_read_b128 v[252:255], v245 offset:43840
	ds_read_b128 v[224:227], v244 offset:6976
	s_waitcnt lgkmcnt(4)
	v_mfma_f32_16x16x32_bf16 v[50:53], v[212:215], v[228:231], v[50:53]
	s_waitcnt lgkmcnt(3)
	v_mfma_f32_16x16x32_bf16 v[54:57], v[212:215], v[236:239], v[54:57]
	s_waitcnt lgkmcnt(2)
	v_mfma_f32_16x16x32_bf16 v[34:37], v[212:215], v[240:243], v[34:37]
	s_waitcnt lgkmcnt(1)
	v_mfma_f32_16x16x32_bf16 v[38:41], v[212:215], v[252:255], v[38:41]
	s_waitcnt vmcnt(11)
	ds_write_b128 v165, v[144:147] offset:55296
	s_waitcnt vmcnt(10)
	ds_write_b128 v165, v[148:151] offset:59904
	v_mfma_f32_16x16x32_bf16 v[58:61], v[216:219], v[228:231], v[58:61]
	v_mfma_f32_16x16x32_bf16 v[62:65], v[216:219], v[236:239], v[62:65]
	v_mfma_f32_16x16x32_bf16 v[42:45], v[216:219], v[240:243], v[42:45]
	v_mfma_f32_16x16x32_bf16 v[46:49], v[216:219], v[252:255], v[46:49]
	s_waitcnt vmcnt(9)
	ds_write_b128 v165, v[172:175] offset:64512
	s_waitcnt vmcnt(8)
	ds_write_b128 v166, v[176:179] offset:32256
	v_mfma_f32_16x16x32_bf16 v[18:21], v[220:223], v[228:231], v[18:21]
	v_mfma_f32_16x16x32_bf16 v[22:25], v[220:223], v[236:239], v[22:25]
	v_mfma_f32_16x16x32_bf16 v[2:5], v[220:223], v[240:243], v[2:5]
	v_mfma_f32_16x16x32_bf16 v[6:9], v[220:223], v[252:255], v[6:9]
	s_waitcnt lgkmcnt(4)
	v_mfma_f32_16x16x32_bf16 v[26:29], v[224:227], v[228:231], v[26:29]
	v_mfma_f32_16x16x32_bf16 v[30:33], v[224:227], v[236:239], v[30:33]
	v_mfma_f32_16x16x32_bf16 v[10:13], v[224:227], v[240:243], v[10:13]
	v_mfma_f32_16x16x32_bf16 v[14:17], v[224:227], v[252:255], v[14:17]
	s_waitcnt lgkmcnt(0)
	s_barrier
	s_setprio 0
	ds_read_b128 v[228:231], v245 offset:55296
	ds_read_b128 v[212:215], v244 offset:18432
	ds_read_b128 v[236:239], v245 offset:57600
	ds_read_b128 v[240:243], v245 offset:59904
	ds_read_b128 v[252:255], v245 offset:62208
	ds_read_b128 v[216:219], v244 offset:20736
	ds_read_b128 v[220:223], v244 offset:23040
	ds_read_b128 v[224:227], v244 offset:25344
	global_load_dwordx4 v[122:125], v[72:73], off offset:640
	global_load_dwordx4 v[126:129], v[74:75], off offset:640
	global_load_dwordx4 v[136:139], v[76:77], off offset:640
	global_load_dwordx4 v[140:143], v[78:79], off offset:640
	global_load_dwordx4 v[144:147], v[70:71], off offset:640
	global_load_dwordx4 v[148:151], v[68:69], off offset:640
	global_load_dwordx4 v[172:175], v[66:67], off offset:640
	global_load_dwordx4 v[176:179], v[80:81], off offset:640
	s_waitcnt lgkmcnt(6)
	v_mfma_f32_16x16x32_bf16 v[50:53], v[212:215], v[228:231], v[50:53]
	s_waitcnt lgkmcnt(5)
	v_mfma_f32_16x16x32_bf16 v[54:57], v[212:215], v[236:239], v[54:57]
	s_waitcnt lgkmcnt(4)
	v_mfma_f32_16x16x32_bf16 v[34:37], v[212:215], v[240:243], v[34:37]
	s_waitcnt lgkmcnt(3)
	v_mfma_f32_16x16x32_bf16 v[38:41], v[212:215], v[252:255], v[38:41]
	ds_read_b128 v[212:215], v244 offset:18496
	s_waitcnt lgkmcnt(3)
	v_mfma_f32_16x16x32_bf16 v[58:61], v[216:219], v[228:231], v[58:61]
	v_mfma_f32_16x16x32_bf16 v[62:65], v[216:219], v[236:239], v[62:65]
	v_mfma_f32_16x16x32_bf16 v[42:45], v[216:219], v[240:243], v[42:45]
	v_mfma_f32_16x16x32_bf16 v[46:49], v[216:219], v[252:255], v[46:49]
	ds_read_b128 v[216:219], v244 offset:20800
	s_setprio 1
	s_waitcnt vmcnt(15)
	ds_write_b128 v165, v[180:183]
	s_waitcnt vmcnt(14)
	ds_write_b128 v165, v[184:187] offset:4608
	s_waitcnt lgkmcnt(5)
	v_mfma_f32_16x16x32_bf16 v[18:21], v[220:223], v[228:231], v[18:21]
	v_mfma_f32_16x16x32_bf16 v[22:25], v[220:223], v[236:239], v[22:25]
	v_mfma_f32_16x16x32_bf16 v[2:5], v[220:223], v[240:243], v[2:5]
	v_mfma_f32_16x16x32_bf16 v[6:9], v[220:223], v[252:255], v[6:9]
	ds_read_b128 v[220:223], v244 offset:23104
	s_waitcnt vmcnt(13)
	ds_write_b128 v165, v[188:191] offset:9216
	s_waitcnt vmcnt(12)
	ds_write_b128 v165, v[192:195] offset:13824
	s_waitcnt lgkmcnt(7)
	v_mfma_f32_16x16x32_bf16 v[26:29], v[224:227], v[228:231], v[26:29]
	ds_read_b128 v[228:231], v245 offset:55360
	v_mfma_f32_16x16x32_bf16 v[30:33], v[224:227], v[236:239], v[30:33]
	ds_read_b128 v[236:239], v245 offset:57664
	v_mfma_f32_16x16x32_bf16 v[10:13], v[224:227], v[240:243], v[10:13]
	ds_read_b128 v[240:243], v245 offset:59968
	v_mfma_f32_16x16x32_bf16 v[14:17], v[224:227], v[252:255], v[14:17]
	ds_read_b128 v[252:255], v245 offset:62272
	ds_read_b128 v[224:227], v244 offset:25408
	s_waitcnt lgkmcnt(4)
	v_mfma_f32_16x16x32_bf16 v[50:53], v[212:215], v[228:231], v[50:53]
	s_waitcnt lgkmcnt(3)
	v_mfma_f32_16x16x32_bf16 v[54:57], v[212:215], v[236:239], v[54:57]
	s_waitcnt lgkmcnt(2)
	v_mfma_f32_16x16x32_bf16 v[34:37], v[212:215], v[240:243], v[34:37]
	s_waitcnt lgkmcnt(1)
	v_mfma_f32_16x16x32_bf16 v[38:41], v[212:215], v[252:255], v[38:41]
	s_waitcnt vmcnt(11)
	ds_write_b128 v165, v[196:199] offset:36864
	s_waitcnt vmcnt(10)
	ds_write_b128 v165, v[200:203] offset:41472
	v_mfma_f32_16x16x32_bf16 v[58:61], v[216:219], v[228:231], v[58:61]
	v_mfma_f32_16x16x32_bf16 v[62:65], v[216:219], v[236:239], v[62:65]
	v_mfma_f32_16x16x32_bf16 v[42:45], v[216:219], v[240:243], v[42:45]
	v_mfma_f32_16x16x32_bf16 v[46:49], v[216:219], v[252:255], v[46:49]
	s_waitcnt vmcnt(9)
	ds_write_b128 v165, v[204:207] offset:46080
	s_waitcnt vmcnt(8)
	ds_write_b128 v165, v[208:211] offset:50688
	v_mfma_f32_16x16x32_bf16 v[18:21], v[220:223], v[228:231], v[18:21]
	v_mfma_f32_16x16x32_bf16 v[22:25], v[220:223], v[236:239], v[22:25]
	v_mfma_f32_16x16x32_bf16 v[2:5], v[220:223], v[240:243], v[2:5]
	v_mfma_f32_16x16x32_bf16 v[6:9], v[220:223], v[252:255], v[6:9]
	s_waitcnt lgkmcnt(4)
	v_mfma_f32_16x16x32_bf16 v[26:29], v[224:227], v[228:231], v[26:29]
	v_mfma_f32_16x16x32_bf16 v[30:33], v[224:227], v[236:239], v[30:33]
	v_mfma_f32_16x16x32_bf16 v[10:13], v[224:227], v[240:243], v[10:13]
	v_mfma_f32_16x16x32_bf16 v[14:17], v[224:227], v[252:255], v[14:17]
	s_waitcnt lgkmcnt(0)
	s_barrier
	s_setprio 0
	ds_read_b128 v[228:231], v245 offset:36864
	ds_read_b128 v[212:215], v244
	ds_read_b128 v[236:239], v245 offset:39168
	ds_read_b128 v[240:243], v245 offset:41472
	ds_read_b128 v[252:255], v245 offset:43776
	ds_read_b128 v[216:219], v244 offset:2304
	ds_read_b128 v[220:223], v244 offset:4608
	ds_read_b128 v[224:227], v244 offset:6912
	global_load_dwordx4 v[180:183], v[72:73], off offset:768
	global_load_dwordx4 v[184:187], v[74:75], off offset:768
	global_load_dwordx4 v[188:191], v[76:77], off offset:768
	global_load_dwordx4 v[192:195], v[78:79], off offset:768
	global_load_dwordx4 v[196:199], v[70:71], off offset:768
	global_load_dwordx4 v[200:203], v[68:69], off offset:768
	global_load_dwordx4 v[204:207], v[66:67], off offset:768
	global_load_dwordx4 v[208:211], v[80:81], off offset:768
	s_waitcnt lgkmcnt(6)
	v_mfma_f32_16x16x32_bf16 v[50:53], v[212:215], v[228:231], v[50:53]
	s_waitcnt lgkmcnt(5)
	v_mfma_f32_16x16x32_bf16 v[54:57], v[212:215], v[236:239], v[54:57]
	s_waitcnt lgkmcnt(4)
	v_mfma_f32_16x16x32_bf16 v[34:37], v[212:215], v[240:243], v[34:37]
	s_waitcnt lgkmcnt(3)
	v_mfma_f32_16x16x32_bf16 v[38:41], v[212:215], v[252:255], v[38:41]
	ds_read_b128 v[212:215], v244 offset:64
	s_waitcnt lgkmcnt(3)
	v_mfma_f32_16x16x32_bf16 v[58:61], v[216:219], v[228:231], v[58:61]
	v_mfma_f32_16x16x32_bf16 v[62:65], v[216:219], v[236:239], v[62:65]
	v_mfma_f32_16x16x32_bf16 v[42:45], v[216:219], v[240:243], v[42:45]
	v_mfma_f32_16x16x32_bf16 v[46:49], v[216:219], v[252:255], v[46:49]
	ds_read_b128 v[216:219], v244 offset:2368
	s_setprio 1
	s_waitcnt vmcnt(15)
	ds_write_b128 v165, v[122:125] offset:18432
	s_waitcnt vmcnt(14)
	ds_write_b128 v165, v[126:129] offset:23040
	s_waitcnt lgkmcnt(5)
	v_mfma_f32_16x16x32_bf16 v[18:21], v[220:223], v[228:231], v[18:21]
	v_mfma_f32_16x16x32_bf16 v[22:25], v[220:223], v[236:239], v[22:25]
	v_mfma_f32_16x16x32_bf16 v[2:5], v[220:223], v[240:243], v[2:5]
	v_mfma_f32_16x16x32_bf16 v[6:9], v[220:223], v[252:255], v[6:9]
	ds_read_b128 v[220:223], v244 offset:4672
	s_waitcnt vmcnt(13)
	ds_write_b128 v165, v[136:139] offset:27648
	s_waitcnt vmcnt(12)
	ds_write_b128 v165, v[140:143] offset:32256
	s_waitcnt lgkmcnt(7)
	v_mfma_f32_16x16x32_bf16 v[26:29], v[224:227], v[228:231], v[26:29]
	ds_read_b128 v[228:231], v245 offset:36928
	v_mfma_f32_16x16x32_bf16 v[30:33], v[224:227], v[236:239], v[30:33]
	ds_read_b128 v[236:239], v245 offset:39232
	v_mfma_f32_16x16x32_bf16 v[10:13], v[224:227], v[240:243], v[10:13]
	ds_read_b128 v[240:243], v245 offset:41536
	v_mfma_f32_16x16x32_bf16 v[14:17], v[224:227], v[252:255], v[14:17]
	ds_read_b128 v[252:255], v245 offset:43840
	ds_read_b128 v[224:227], v244 offset:6976
	s_waitcnt lgkmcnt(4)
	v_mfma_f32_16x16x32_bf16 v[50:53], v[212:215], v[228:231], v[50:53]
	s_waitcnt lgkmcnt(3)
	v_mfma_f32_16x16x32_bf16 v[54:57], v[212:215], v[236:239], v[54:57]
	s_waitcnt lgkmcnt(2)
	v_mfma_f32_16x16x32_bf16 v[34:37], v[212:215], v[240:243], v[34:37]
	s_waitcnt lgkmcnt(1)
	v_mfma_f32_16x16x32_bf16 v[38:41], v[212:215], v[252:255], v[38:41]
	s_waitcnt vmcnt(11)
	ds_write_b128 v165, v[144:147] offset:55296
	s_waitcnt vmcnt(10)
	ds_write_b128 v165, v[148:151] offset:59904
	v_mfma_f32_16x16x32_bf16 v[58:61], v[216:219], v[228:231], v[58:61]
	v_mfma_f32_16x16x32_bf16 v[62:65], v[216:219], v[236:239], v[62:65]
	v_mfma_f32_16x16x32_bf16 v[42:45], v[216:219], v[240:243], v[42:45]
	v_mfma_f32_16x16x32_bf16 v[46:49], v[216:219], v[252:255], v[46:49]
	s_waitcnt vmcnt(9)
	ds_write_b128 v165, v[172:175] offset:64512
	s_waitcnt vmcnt(8)
	ds_write_b128 v166, v[176:179] offset:32256
	v_mfma_f32_16x16x32_bf16 v[18:21], v[220:223], v[228:231], v[18:21]
	v_mfma_f32_16x16x32_bf16 v[22:25], v[220:223], v[236:239], v[22:25]
	v_mfma_f32_16x16x32_bf16 v[2:5], v[220:223], v[240:243], v[2:5]
	v_mfma_f32_16x16x32_bf16 v[6:9], v[220:223], v[252:255], v[6:9]
	s_waitcnt lgkmcnt(4)
	v_mfma_f32_16x16x32_bf16 v[26:29], v[224:227], v[228:231], v[26:29]
	v_mfma_f32_16x16x32_bf16 v[30:33], v[224:227], v[236:239], v[30:33]
	v_mfma_f32_16x16x32_bf16 v[10:13], v[224:227], v[240:243], v[10:13]
	v_mfma_f32_16x16x32_bf16 v[14:17], v[224:227], v[252:255], v[14:17]
	s_waitcnt lgkmcnt(0)
	s_barrier
	s_setprio 0
	ds_read_b128 v[228:231], v245 offset:55296
	ds_read_b128 v[212:215], v244 offset:18432
	ds_read_b128 v[236:239], v245 offset:57600
	ds_read_b128 v[240:243], v245 offset:59904
	ds_read_b128 v[252:255], v245 offset:62208
	ds_read_b128 v[216:219], v244 offset:20736
	ds_read_b128 v[220:223], v244 offset:23040
	ds_read_b128 v[224:227], v244 offset:25344
	global_load_dwordx4 v[122:125], v[72:73], off offset:896
	global_load_dwordx4 v[126:129], v[74:75], off offset:896
	global_load_dwordx4 v[136:139], v[76:77], off offset:896
	global_load_dwordx4 v[140:143], v[78:79], off offset:896
	global_load_dwordx4 v[144:147], v[70:71], off offset:896
	global_load_dwordx4 v[148:151], v[68:69], off offset:896
	global_load_dwordx4 v[172:175], v[66:67], off offset:896
	global_load_dwordx4 v[176:179], v[80:81], off offset:896
	s_waitcnt lgkmcnt(6)
	v_mfma_f32_16x16x32_bf16 v[50:53], v[212:215], v[228:231], v[50:53]
	s_waitcnt lgkmcnt(5)
	v_mfma_f32_16x16x32_bf16 v[54:57], v[212:215], v[236:239], v[54:57]
	s_waitcnt lgkmcnt(4)
	v_mfma_f32_16x16x32_bf16 v[34:37], v[212:215], v[240:243], v[34:37]
	s_waitcnt lgkmcnt(3)
	v_mfma_f32_16x16x32_bf16 v[38:41], v[212:215], v[252:255], v[38:41]
	ds_read_b128 v[212:215], v244 offset:18496
	s_waitcnt lgkmcnt(3)
	v_mfma_f32_16x16x32_bf16 v[58:61], v[216:219], v[228:231], v[58:61]
	v_mfma_f32_16x16x32_bf16 v[62:65], v[216:219], v[236:239], v[62:65]
	v_mfma_f32_16x16x32_bf16 v[42:45], v[216:219], v[240:243], v[42:45]
	v_mfma_f32_16x16x32_bf16 v[46:49], v[216:219], v[252:255], v[46:49]
	ds_read_b128 v[216:219], v244 offset:20800
	s_setprio 1
	s_waitcnt vmcnt(15)
	ds_write_b128 v165, v[180:183]
	s_waitcnt vmcnt(14)
	ds_write_b128 v165, v[184:187] offset:4608
	s_waitcnt lgkmcnt(5)
	v_mfma_f32_16x16x32_bf16 v[18:21], v[220:223], v[228:231], v[18:21]
	v_mfma_f32_16x16x32_bf16 v[22:25], v[220:223], v[236:239], v[22:25]
	v_mfma_f32_16x16x32_bf16 v[2:5], v[220:223], v[240:243], v[2:5]
	v_mfma_f32_16x16x32_bf16 v[6:9], v[220:223], v[252:255], v[6:9]
	ds_read_b128 v[220:223], v244 offset:23104
	s_waitcnt vmcnt(13)
	ds_write_b128 v165, v[188:191] offset:9216
	s_waitcnt vmcnt(12)
	ds_write_b128 v165, v[192:195] offset:13824
	s_waitcnt lgkmcnt(7)
	v_mfma_f32_16x16x32_bf16 v[26:29], v[224:227], v[228:231], v[26:29]
	ds_read_b128 v[228:231], v245 offset:55360
	v_mfma_f32_16x16x32_bf16 v[30:33], v[224:227], v[236:239], v[30:33]
	ds_read_b128 v[236:239], v245 offset:57664
	v_mfma_f32_16x16x32_bf16 v[10:13], v[224:227], v[240:243], v[10:13]
	ds_read_b128 v[240:243], v245 offset:59968
	v_mfma_f32_16x16x32_bf16 v[14:17], v[224:227], v[252:255], v[14:17]
	ds_read_b128 v[252:255], v245 offset:62272
	ds_read_b128 v[224:227], v244 offset:25408
	s_waitcnt lgkmcnt(4)
	v_mfma_f32_16x16x32_bf16 v[50:53], v[212:215], v[228:231], v[50:53]
	s_waitcnt lgkmcnt(3)
	v_mfma_f32_16x16x32_bf16 v[54:57], v[212:215], v[236:239], v[54:57]
	s_waitcnt lgkmcnt(2)
	v_mfma_f32_16x16x32_bf16 v[34:37], v[212:215], v[240:243], v[34:37]
	s_waitcnt lgkmcnt(1)
	v_mfma_f32_16x16x32_bf16 v[38:41], v[212:215], v[252:255], v[38:41]
	s_waitcnt vmcnt(11)
	ds_write_b128 v165, v[196:199] offset:36864
	s_waitcnt vmcnt(10)
	ds_write_b128 v165, v[200:203] offset:41472
	v_mfma_f32_16x16x32_bf16 v[58:61], v[216:219], v[228:231], v[58:61]
	v_mfma_f32_16x16x32_bf16 v[62:65], v[216:219], v[236:239], v[62:65]
	v_mfma_f32_16x16x32_bf16 v[42:45], v[216:219], v[240:243], v[42:45]
	v_mfma_f32_16x16x32_bf16 v[46:49], v[216:219], v[252:255], v[46:49]
	s_waitcnt vmcnt(9)
	ds_write_b128 v165, v[204:207] offset:46080
	s_waitcnt vmcnt(8)
	ds_write_b128 v165, v[208:211] offset:50688
	v_mfma_f32_16x16x32_bf16 v[18:21], v[220:223], v[228:231], v[18:21]
	v_mfma_f32_16x16x32_bf16 v[22:25], v[220:223], v[236:239], v[22:25]
	v_mfma_f32_16x16x32_bf16 v[2:5], v[220:223], v[240:243], v[2:5]
	v_mfma_f32_16x16x32_bf16 v[6:9], v[220:223], v[252:255], v[6:9]
	s_waitcnt lgkmcnt(4)
	v_mfma_f32_16x16x32_bf16 v[26:29], v[224:227], v[228:231], v[26:29]
	v_mfma_f32_16x16x32_bf16 v[30:33], v[224:227], v[236:239], v[30:33]
	v_mfma_f32_16x16x32_bf16 v[10:13], v[224:227], v[240:243], v[10:13]
	v_mfma_f32_16x16x32_bf16 v[14:17], v[224:227], v[252:255], v[14:17]
	s_waitcnt lgkmcnt(0)
	s_barrier
	s_setprio 0
	ds_read_b128 v[228:231], v245 offset:36864
	ds_read_b128 v[212:215], v244
	ds_read_b128 v[236:239], v245 offset:39168
	ds_read_b128 v[240:243], v245 offset:41472
	ds_read_b128 v[252:255], v245 offset:43776
	ds_read_b128 v[216:219], v244 offset:2304
	ds_read_b128 v[220:223], v244 offset:4608
	ds_read_b128 v[224:227], v244 offset:6912
	global_load_dwordx4 v[180:183], v[72:73], off offset:1024
	global_load_dwordx4 v[184:187], v[74:75], off offset:1024
	global_load_dwordx4 v[188:191], v[76:77], off offset:1024
	global_load_dwordx4 v[192:195], v[78:79], off offset:1024
	global_load_dwordx4 v[196:199], v[70:71], off offset:1024
	global_load_dwordx4 v[200:203], v[68:69], off offset:1024
	global_load_dwordx4 v[204:207], v[66:67], off offset:1024
	global_load_dwordx4 v[208:211], v[80:81], off offset:1024
	s_waitcnt lgkmcnt(6)
	v_mfma_f32_16x16x32_bf16 v[50:53], v[212:215], v[228:231], v[50:53]
	s_waitcnt lgkmcnt(5)
	v_mfma_f32_16x16x32_bf16 v[54:57], v[212:215], v[236:239], v[54:57]
	s_waitcnt lgkmcnt(4)
	v_mfma_f32_16x16x32_bf16 v[34:37], v[212:215], v[240:243], v[34:37]
	s_waitcnt lgkmcnt(3)
	v_mfma_f32_16x16x32_bf16 v[38:41], v[212:215], v[252:255], v[38:41]
	ds_read_b128 v[212:215], v244 offset:64
	s_waitcnt lgkmcnt(3)
	v_mfma_f32_16x16x32_bf16 v[58:61], v[216:219], v[228:231], v[58:61]
	v_mfma_f32_16x16x32_bf16 v[62:65], v[216:219], v[236:239], v[62:65]
	v_mfma_f32_16x16x32_bf16 v[42:45], v[216:219], v[240:243], v[42:45]
	v_mfma_f32_16x16x32_bf16 v[46:49], v[216:219], v[252:255], v[46:49]
	ds_read_b128 v[216:219], v244 offset:2368
	s_setprio 1
	s_waitcnt vmcnt(15)
	ds_write_b128 v165, v[122:125] offset:18432
	s_waitcnt vmcnt(14)
	ds_write_b128 v165, v[126:129] offset:23040
	s_waitcnt lgkmcnt(5)
	v_mfma_f32_16x16x32_bf16 v[18:21], v[220:223], v[228:231], v[18:21]
	v_mfma_f32_16x16x32_bf16 v[22:25], v[220:223], v[236:239], v[22:25]
	v_mfma_f32_16x16x32_bf16 v[2:5], v[220:223], v[240:243], v[2:5]
	v_mfma_f32_16x16x32_bf16 v[6:9], v[220:223], v[252:255], v[6:9]
	ds_read_b128 v[220:223], v244 offset:4672
	s_waitcnt vmcnt(13)
	ds_write_b128 v165, v[136:139] offset:27648
	s_waitcnt vmcnt(12)
	ds_write_b128 v165, v[140:143] offset:32256
	s_waitcnt lgkmcnt(7)
	v_mfma_f32_16x16x32_bf16 v[26:29], v[224:227], v[228:231], v[26:29]
	ds_read_b128 v[228:231], v245 offset:36928
	v_mfma_f32_16x16x32_bf16 v[30:33], v[224:227], v[236:239], v[30:33]
	ds_read_b128 v[236:239], v245 offset:39232
	v_mfma_f32_16x16x32_bf16 v[10:13], v[224:227], v[240:243], v[10:13]
	ds_read_b128 v[240:243], v245 offset:41536
	v_mfma_f32_16x16x32_bf16 v[14:17], v[224:227], v[252:255], v[14:17]
	ds_read_b128 v[252:255], v245 offset:43840
	ds_read_b128 v[224:227], v244 offset:6976
	s_waitcnt lgkmcnt(4)
	v_mfma_f32_16x16x32_bf16 v[50:53], v[212:215], v[228:231], v[50:53]
	s_waitcnt lgkmcnt(3)
	v_mfma_f32_16x16x32_bf16 v[54:57], v[212:215], v[236:239], v[54:57]
	s_waitcnt lgkmcnt(2)
	v_mfma_f32_16x16x32_bf16 v[34:37], v[212:215], v[240:243], v[34:37]
	s_waitcnt lgkmcnt(1)
	v_mfma_f32_16x16x32_bf16 v[38:41], v[212:215], v[252:255], v[38:41]
	s_waitcnt vmcnt(11)
	ds_write_b128 v165, v[144:147] offset:55296
	s_waitcnt vmcnt(10)
	ds_write_b128 v165, v[148:151] offset:59904
	v_mfma_f32_16x16x32_bf16 v[58:61], v[216:219], v[228:231], v[58:61]
	v_mfma_f32_16x16x32_bf16 v[62:65], v[216:219], v[236:239], v[62:65]
	v_mfma_f32_16x16x32_bf16 v[42:45], v[216:219], v[240:243], v[42:45]
	v_mfma_f32_16x16x32_bf16 v[46:49], v[216:219], v[252:255], v[46:49]
	s_waitcnt vmcnt(9)
	ds_write_b128 v165, v[172:175] offset:64512
	s_waitcnt vmcnt(8)
	ds_write_b128 v166, v[176:179] offset:32256
	v_mfma_f32_16x16x32_bf16 v[18:21], v[220:223], v[228:231], v[18:21]
	v_mfma_f32_16x16x32_bf16 v[22:25], v[220:223], v[236:239], v[22:25]
	v_mfma_f32_16x16x32_bf16 v[2:5], v[220:223], v[240:243], v[2:5]
	v_mfma_f32_16x16x32_bf16 v[6:9], v[220:223], v[252:255], v[6:9]
	s_waitcnt lgkmcnt(4)
	v_mfma_f32_16x16x32_bf16 v[26:29], v[224:227], v[228:231], v[26:29]
	v_mfma_f32_16x16x32_bf16 v[30:33], v[224:227], v[236:239], v[30:33]
	v_mfma_f32_16x16x32_bf16 v[10:13], v[224:227], v[240:243], v[10:13]
	v_mfma_f32_16x16x32_bf16 v[14:17], v[224:227], v[252:255], v[14:17]
	s_waitcnt lgkmcnt(0)
	s_barrier
	s_setprio 0
	ds_read_b128 v[228:231], v245 offset:55296
	ds_read_b128 v[212:215], v244 offset:18432
	ds_read_b128 v[236:239], v245 offset:57600
	ds_read_b128 v[240:243], v245 offset:59904
	ds_read_b128 v[252:255], v245 offset:62208
	ds_read_b128 v[216:219], v244 offset:20736
	ds_read_b128 v[220:223], v244 offset:23040
	ds_read_b128 v[224:227], v244 offset:25344
	global_load_dwordx4 v[122:125], v[72:73], off offset:1152
	global_load_dwordx4 v[126:129], v[74:75], off offset:1152
	global_load_dwordx4 v[136:139], v[76:77], off offset:1152
	global_load_dwordx4 v[140:143], v[78:79], off offset:1152
	global_load_dwordx4 v[144:147], v[70:71], off offset:1152
	global_load_dwordx4 v[148:151], v[68:69], off offset:1152
	global_load_dwordx4 v[172:175], v[66:67], off offset:1152
	global_load_dwordx4 v[176:179], v[80:81], off offset:1152
	s_waitcnt lgkmcnt(6)
	v_mfma_f32_16x16x32_bf16 v[50:53], v[212:215], v[228:231], v[50:53]
	s_waitcnt lgkmcnt(5)
	v_mfma_f32_16x16x32_bf16 v[54:57], v[212:215], v[236:239], v[54:57]
	s_waitcnt lgkmcnt(4)
	v_mfma_f32_16x16x32_bf16 v[34:37], v[212:215], v[240:243], v[34:37]
	s_waitcnt lgkmcnt(3)
	v_mfma_f32_16x16x32_bf16 v[38:41], v[212:215], v[252:255], v[38:41]
	ds_read_b128 v[212:215], v244 offset:18496
	s_waitcnt lgkmcnt(3)
	v_mfma_f32_16x16x32_bf16 v[58:61], v[216:219], v[228:231], v[58:61]
	v_mfma_f32_16x16x32_bf16 v[62:65], v[216:219], v[236:239], v[62:65]
	v_mfma_f32_16x16x32_bf16 v[42:45], v[216:219], v[240:243], v[42:45]
	v_mfma_f32_16x16x32_bf16 v[46:49], v[216:219], v[252:255], v[46:49]
	ds_read_b128 v[216:219], v244 offset:20800
	s_setprio 1
	s_waitcnt vmcnt(15)
	ds_write_b128 v165, v[180:183]
	s_waitcnt vmcnt(14)
	ds_write_b128 v165, v[184:187] offset:4608
	s_waitcnt lgkmcnt(5)
	v_mfma_f32_16x16x32_bf16 v[18:21], v[220:223], v[228:231], v[18:21]
	v_mfma_f32_16x16x32_bf16 v[22:25], v[220:223], v[236:239], v[22:25]
	v_mfma_f32_16x16x32_bf16 v[2:5], v[220:223], v[240:243], v[2:5]
	v_mfma_f32_16x16x32_bf16 v[6:9], v[220:223], v[252:255], v[6:9]
	ds_read_b128 v[220:223], v244 offset:23104
	s_waitcnt vmcnt(13)
	ds_write_b128 v165, v[188:191] offset:9216
	s_waitcnt vmcnt(12)
	ds_write_b128 v165, v[192:195] offset:13824
	s_waitcnt lgkmcnt(7)
	v_mfma_f32_16x16x32_bf16 v[26:29], v[224:227], v[228:231], v[26:29]
	ds_read_b128 v[228:231], v245 offset:55360
	v_mfma_f32_16x16x32_bf16 v[30:33], v[224:227], v[236:239], v[30:33]
	ds_read_b128 v[236:239], v245 offset:57664
	v_mfma_f32_16x16x32_bf16 v[10:13], v[224:227], v[240:243], v[10:13]
	ds_read_b128 v[240:243], v245 offset:59968
	v_mfma_f32_16x16x32_bf16 v[14:17], v[224:227], v[252:255], v[14:17]
	ds_read_b128 v[252:255], v245 offset:62272
	ds_read_b128 v[224:227], v244 offset:25408
	s_waitcnt lgkmcnt(4)
	v_mfma_f32_16x16x32_bf16 v[50:53], v[212:215], v[228:231], v[50:53]
	s_waitcnt lgkmcnt(3)
	v_mfma_f32_16x16x32_bf16 v[54:57], v[212:215], v[236:239], v[54:57]
	s_waitcnt lgkmcnt(2)
	v_mfma_f32_16x16x32_bf16 v[34:37], v[212:215], v[240:243], v[34:37]
	s_waitcnt lgkmcnt(1)
	v_mfma_f32_16x16x32_bf16 v[38:41], v[212:215], v[252:255], v[38:41]
	s_waitcnt vmcnt(11)
	ds_write_b128 v165, v[196:199] offset:36864
	s_waitcnt vmcnt(10)
	ds_write_b128 v165, v[200:203] offset:41472
	v_mfma_f32_16x16x32_bf16 v[58:61], v[216:219], v[228:231], v[58:61]
	v_mfma_f32_16x16x32_bf16 v[62:65], v[216:219], v[236:239], v[62:65]
	v_mfma_f32_16x16x32_bf16 v[42:45], v[216:219], v[240:243], v[42:45]
	v_mfma_f32_16x16x32_bf16 v[46:49], v[216:219], v[252:255], v[46:49]
	s_waitcnt vmcnt(9)
	ds_write_b128 v165, v[204:207] offset:46080
	s_waitcnt vmcnt(8)
	ds_write_b128 v165, v[208:211] offset:50688
	v_mfma_f32_16x16x32_bf16 v[18:21], v[220:223], v[228:231], v[18:21]
	v_mfma_f32_16x16x32_bf16 v[22:25], v[220:223], v[236:239], v[22:25]
	v_mfma_f32_16x16x32_bf16 v[2:5], v[220:223], v[240:243], v[2:5]
	v_mfma_f32_16x16x32_bf16 v[6:9], v[220:223], v[252:255], v[6:9]
	s_waitcnt lgkmcnt(4)
	v_mfma_f32_16x16x32_bf16 v[26:29], v[224:227], v[228:231], v[26:29]
	v_mfma_f32_16x16x32_bf16 v[30:33], v[224:227], v[236:239], v[30:33]
	v_mfma_f32_16x16x32_bf16 v[10:13], v[224:227], v[240:243], v[10:13]
	v_mfma_f32_16x16x32_bf16 v[14:17], v[224:227], v[252:255], v[14:17]
	s_waitcnt lgkmcnt(0)
	s_barrier
	s_setprio 0
	ds_read_b128 v[228:231], v245 offset:36864
	ds_read_b128 v[212:215], v244
	ds_read_b128 v[236:239], v245 offset:39168
	ds_read_b128 v[240:243], v245 offset:41472
	ds_read_b128 v[252:255], v245 offset:43776
	ds_read_b128 v[216:219], v244 offset:2304
	ds_read_b128 v[220:223], v244 offset:4608
	ds_read_b128 v[224:227], v244 offset:6912
	global_load_dwordx4 v[180:183], v[72:73], off offset:1280
	global_load_dwordx4 v[184:187], v[74:75], off offset:1280
	global_load_dwordx4 v[188:191], v[76:77], off offset:1280
	global_load_dwordx4 v[192:195], v[78:79], off offset:1280
	global_load_dwordx4 v[196:199], v[70:71], off offset:1280
	global_load_dwordx4 v[200:203], v[68:69], off offset:1280
	global_load_dwordx4 v[204:207], v[66:67], off offset:1280
	global_load_dwordx4 v[208:211], v[80:81], off offset:1280
	s_waitcnt lgkmcnt(6)
	v_mfma_f32_16x16x32_bf16 v[50:53], v[212:215], v[228:231], v[50:53]
	s_waitcnt lgkmcnt(5)
	v_mfma_f32_16x16x32_bf16 v[54:57], v[212:215], v[236:239], v[54:57]
	s_waitcnt lgkmcnt(4)
	v_mfma_f32_16x16x32_bf16 v[34:37], v[212:215], v[240:243], v[34:37]
	s_waitcnt lgkmcnt(3)
	v_mfma_f32_16x16x32_bf16 v[38:41], v[212:215], v[252:255], v[38:41]
	ds_read_b128 v[212:215], v244 offset:64
	s_waitcnt lgkmcnt(3)
	v_mfma_f32_16x16x32_bf16 v[58:61], v[216:219], v[228:231], v[58:61]
	v_mfma_f32_16x16x32_bf16 v[62:65], v[216:219], v[236:239], v[62:65]
	v_mfma_f32_16x16x32_bf16 v[42:45], v[216:219], v[240:243], v[42:45]
	v_mfma_f32_16x16x32_bf16 v[46:49], v[216:219], v[252:255], v[46:49]
	ds_read_b128 v[216:219], v244 offset:2368
	s_setprio 1
	s_waitcnt vmcnt(15)
	ds_write_b128 v165, v[122:125] offset:18432
	s_waitcnt vmcnt(14)
	ds_write_b128 v165, v[126:129] offset:23040
	s_waitcnt lgkmcnt(5)
	v_mfma_f32_16x16x32_bf16 v[18:21], v[220:223], v[228:231], v[18:21]
	v_mfma_f32_16x16x32_bf16 v[22:25], v[220:223], v[236:239], v[22:25]
	v_mfma_f32_16x16x32_bf16 v[2:5], v[220:223], v[240:243], v[2:5]
	v_mfma_f32_16x16x32_bf16 v[6:9], v[220:223], v[252:255], v[6:9]
	ds_read_b128 v[220:223], v244 offset:4672
	s_waitcnt vmcnt(13)
	ds_write_b128 v165, v[136:139] offset:27648
	s_waitcnt vmcnt(12)
	ds_write_b128 v165, v[140:143] offset:32256
	s_waitcnt lgkmcnt(7)
	v_mfma_f32_16x16x32_bf16 v[26:29], v[224:227], v[228:231], v[26:29]
	ds_read_b128 v[228:231], v245 offset:36928
	v_mfma_f32_16x16x32_bf16 v[30:33], v[224:227], v[236:239], v[30:33]
	ds_read_b128 v[236:239], v245 offset:39232
	v_mfma_f32_16x16x32_bf16 v[10:13], v[224:227], v[240:243], v[10:13]
	ds_read_b128 v[240:243], v245 offset:41536
	v_mfma_f32_16x16x32_bf16 v[14:17], v[224:227], v[252:255], v[14:17]
	ds_read_b128 v[252:255], v245 offset:43840
	ds_read_b128 v[224:227], v244 offset:6976
	s_waitcnt lgkmcnt(4)
	v_mfma_f32_16x16x32_bf16 v[50:53], v[212:215], v[228:231], v[50:53]
	s_waitcnt lgkmcnt(3)
	v_mfma_f32_16x16x32_bf16 v[54:57], v[212:215], v[236:239], v[54:57]
	s_waitcnt lgkmcnt(2)
	v_mfma_f32_16x16x32_bf16 v[34:37], v[212:215], v[240:243], v[34:37]
	s_waitcnt lgkmcnt(1)
	v_mfma_f32_16x16x32_bf16 v[38:41], v[212:215], v[252:255], v[38:41]
	s_waitcnt vmcnt(11)
	ds_write_b128 v165, v[144:147] offset:55296
	s_waitcnt vmcnt(10)
	ds_write_b128 v165, v[148:151] offset:59904
	v_mfma_f32_16x16x32_bf16 v[58:61], v[216:219], v[228:231], v[58:61]
	v_mfma_f32_16x16x32_bf16 v[62:65], v[216:219], v[236:239], v[62:65]
	v_mfma_f32_16x16x32_bf16 v[42:45], v[216:219], v[240:243], v[42:45]
	v_mfma_f32_16x16x32_bf16 v[46:49], v[216:219], v[252:255], v[46:49]
	s_waitcnt vmcnt(9)
	ds_write_b128 v165, v[172:175] offset:64512
	s_waitcnt vmcnt(8)
	ds_write_b128 v166, v[176:179] offset:32256
	v_mfma_f32_16x16x32_bf16 v[18:21], v[220:223], v[228:231], v[18:21]
	v_mfma_f32_16x16x32_bf16 v[22:25], v[220:223], v[236:239], v[22:25]
	v_mfma_f32_16x16x32_bf16 v[2:5], v[220:223], v[240:243], v[2:5]
	v_mfma_f32_16x16x32_bf16 v[6:9], v[220:223], v[252:255], v[6:9]
	s_waitcnt lgkmcnt(4)
	v_mfma_f32_16x16x32_bf16 v[26:29], v[224:227], v[228:231], v[26:29]
	v_mfma_f32_16x16x32_bf16 v[30:33], v[224:227], v[236:239], v[30:33]
	v_mfma_f32_16x16x32_bf16 v[10:13], v[224:227], v[240:243], v[10:13]
	v_mfma_f32_16x16x32_bf16 v[14:17], v[224:227], v[252:255], v[14:17]
	s_waitcnt lgkmcnt(0)
	s_barrier
	s_setprio 0
	ds_read_b128 v[228:231], v245 offset:55296
	ds_read_b128 v[212:215], v244 offset:18432
	ds_read_b128 v[236:239], v245 offset:57600
	ds_read_b128 v[240:243], v245 offset:59904
	ds_read_b128 v[252:255], v245 offset:62208
	ds_read_b128 v[216:219], v244 offset:20736
	ds_read_b128 v[220:223], v244 offset:23040
	ds_read_b128 v[224:227], v244 offset:25344
	global_load_dwordx4 v[122:125], v[72:73], off offset:1408
	global_load_dwordx4 v[126:129], v[74:75], off offset:1408
	global_load_dwordx4 v[136:139], v[76:77], off offset:1408
	global_load_dwordx4 v[140:143], v[78:79], off offset:1408
	global_load_dwordx4 v[144:147], v[70:71], off offset:1408
	global_load_dwordx4 v[148:151], v[68:69], off offset:1408
	global_load_dwordx4 v[172:175], v[66:67], off offset:1408
	global_load_dwordx4 v[176:179], v[80:81], off offset:1408
	s_waitcnt lgkmcnt(6)
	v_mfma_f32_16x16x32_bf16 v[50:53], v[212:215], v[228:231], v[50:53]
	s_waitcnt lgkmcnt(5)
	v_mfma_f32_16x16x32_bf16 v[54:57], v[212:215], v[236:239], v[54:57]
	s_waitcnt lgkmcnt(4)
	v_mfma_f32_16x16x32_bf16 v[34:37], v[212:215], v[240:243], v[34:37]
	s_waitcnt lgkmcnt(3)
	v_mfma_f32_16x16x32_bf16 v[38:41], v[212:215], v[252:255], v[38:41]
	ds_read_b128 v[212:215], v244 offset:18496
	s_waitcnt lgkmcnt(3)
	v_mfma_f32_16x16x32_bf16 v[58:61], v[216:219], v[228:231], v[58:61]
	v_mfma_f32_16x16x32_bf16 v[62:65], v[216:219], v[236:239], v[62:65]
	v_mfma_f32_16x16x32_bf16 v[42:45], v[216:219], v[240:243], v[42:45]
	v_mfma_f32_16x16x32_bf16 v[46:49], v[216:219], v[252:255], v[46:49]
	ds_read_b128 v[216:219], v244 offset:20800
	s_setprio 1
	s_waitcnt vmcnt(15)
	ds_write_b128 v165, v[180:183]
	s_waitcnt vmcnt(14)
	ds_write_b128 v165, v[184:187] offset:4608
	s_waitcnt lgkmcnt(5)
	v_mfma_f32_16x16x32_bf16 v[18:21], v[220:223], v[228:231], v[18:21]
	v_mfma_f32_16x16x32_bf16 v[22:25], v[220:223], v[236:239], v[22:25]
	v_mfma_f32_16x16x32_bf16 v[2:5], v[220:223], v[240:243], v[2:5]
	v_mfma_f32_16x16x32_bf16 v[6:9], v[220:223], v[252:255], v[6:9]
	ds_read_b128 v[220:223], v244 offset:23104
	s_waitcnt vmcnt(13)
	ds_write_b128 v165, v[188:191] offset:9216
	s_waitcnt vmcnt(12)
	ds_write_b128 v165, v[192:195] offset:13824
	s_waitcnt lgkmcnt(7)
	v_mfma_f32_16x16x32_bf16 v[26:29], v[224:227], v[228:231], v[26:29]
	ds_read_b128 v[228:231], v245 offset:55360
	v_mfma_f32_16x16x32_bf16 v[30:33], v[224:227], v[236:239], v[30:33]
	ds_read_b128 v[236:239], v245 offset:57664
	v_mfma_f32_16x16x32_bf16 v[10:13], v[224:227], v[240:243], v[10:13]
	ds_read_b128 v[240:243], v245 offset:59968
	v_mfma_f32_16x16x32_bf16 v[14:17], v[224:227], v[252:255], v[14:17]
	ds_read_b128 v[252:255], v245 offset:62272
	ds_read_b128 v[224:227], v244 offset:25408
	s_waitcnt lgkmcnt(4)
	v_mfma_f32_16x16x32_bf16 v[50:53], v[212:215], v[228:231], v[50:53]
	s_waitcnt lgkmcnt(3)
	v_mfma_f32_16x16x32_bf16 v[54:57], v[212:215], v[236:239], v[54:57]
	s_waitcnt lgkmcnt(2)
	v_mfma_f32_16x16x32_bf16 v[34:37], v[212:215], v[240:243], v[34:37]
	s_waitcnt lgkmcnt(1)
	v_mfma_f32_16x16x32_bf16 v[38:41], v[212:215], v[252:255], v[38:41]
	s_waitcnt vmcnt(11)
	ds_write_b128 v165, v[196:199] offset:36864
	s_waitcnt vmcnt(10)
	ds_write_b128 v165, v[200:203] offset:41472
	v_mfma_f32_16x16x32_bf16 v[58:61], v[216:219], v[228:231], v[58:61]
	v_mfma_f32_16x16x32_bf16 v[62:65], v[216:219], v[236:239], v[62:65]
	v_mfma_f32_16x16x32_bf16 v[42:45], v[216:219], v[240:243], v[42:45]
	v_mfma_f32_16x16x32_bf16 v[46:49], v[216:219], v[252:255], v[46:49]
	s_waitcnt vmcnt(9)
	ds_write_b128 v165, v[204:207] offset:46080
	s_waitcnt vmcnt(8)
	ds_write_b128 v165, v[208:211] offset:50688
	v_mfma_f32_16x16x32_bf16 v[18:21], v[220:223], v[228:231], v[18:21]
	v_mfma_f32_16x16x32_bf16 v[22:25], v[220:223], v[236:239], v[22:25]
	v_mfma_f32_16x16x32_bf16 v[2:5], v[220:223], v[240:243], v[2:5]
	v_mfma_f32_16x16x32_bf16 v[6:9], v[220:223], v[252:255], v[6:9]
	s_waitcnt lgkmcnt(4)
	v_mfma_f32_16x16x32_bf16 v[26:29], v[224:227], v[228:231], v[26:29]
	v_mfma_f32_16x16x32_bf16 v[30:33], v[224:227], v[236:239], v[30:33]
	v_mfma_f32_16x16x32_bf16 v[10:13], v[224:227], v[240:243], v[10:13]
	v_mfma_f32_16x16x32_bf16 v[14:17], v[224:227], v[252:255], v[14:17]
	s_waitcnt lgkmcnt(0)
	s_barrier
	s_setprio 0
	ds_read_b128 v[228:231], v245 offset:36864
	ds_read_b128 v[212:215], v244
	ds_read_b128 v[236:239], v245 offset:39168
	ds_read_b128 v[240:243], v245 offset:41472
	ds_read_b128 v[252:255], v245 offset:43776
	ds_read_b128 v[216:219], v244 offset:2304
	ds_read_b128 v[220:223], v244 offset:4608
	ds_read_b128 v[224:227], v244 offset:6912
	global_load_dwordx4 v[180:183], v[72:73], off offset:1536
	global_load_dwordx4 v[184:187], v[74:75], off offset:1536
	global_load_dwordx4 v[188:191], v[76:77], off offset:1536
	global_load_dwordx4 v[192:195], v[78:79], off offset:1536
	global_load_dwordx4 v[196:199], v[70:71], off offset:1536
	global_load_dwordx4 v[200:203], v[68:69], off offset:1536
	global_load_dwordx4 v[204:207], v[66:67], off offset:1536
	global_load_dwordx4 v[208:211], v[80:81], off offset:1536
	s_waitcnt lgkmcnt(6)
	v_mfma_f32_16x16x32_bf16 v[50:53], v[212:215], v[228:231], v[50:53]
	s_waitcnt lgkmcnt(5)
	v_mfma_f32_16x16x32_bf16 v[54:57], v[212:215], v[236:239], v[54:57]
	s_waitcnt lgkmcnt(4)
	v_mfma_f32_16x16x32_bf16 v[34:37], v[212:215], v[240:243], v[34:37]
	s_waitcnt lgkmcnt(3)
	v_mfma_f32_16x16x32_bf16 v[38:41], v[212:215], v[252:255], v[38:41]
	ds_read_b128 v[212:215], v244 offset:64
	s_waitcnt lgkmcnt(3)
	v_mfma_f32_16x16x32_bf16 v[58:61], v[216:219], v[228:231], v[58:61]
	v_mfma_f32_16x16x32_bf16 v[62:65], v[216:219], v[236:239], v[62:65]
	v_mfma_f32_16x16x32_bf16 v[42:45], v[216:219], v[240:243], v[42:45]
	v_mfma_f32_16x16x32_bf16 v[46:49], v[216:219], v[252:255], v[46:49]
	ds_read_b128 v[216:219], v244 offset:2368
	s_setprio 1
	s_waitcnt vmcnt(15)
	ds_write_b128 v165, v[122:125] offset:18432
	s_waitcnt vmcnt(14)
	ds_write_b128 v165, v[126:129] offset:23040
	s_waitcnt lgkmcnt(5)
	v_mfma_f32_16x16x32_bf16 v[18:21], v[220:223], v[228:231], v[18:21]
	v_mfma_f32_16x16x32_bf16 v[22:25], v[220:223], v[236:239], v[22:25]
	v_mfma_f32_16x16x32_bf16 v[2:5], v[220:223], v[240:243], v[2:5]
	v_mfma_f32_16x16x32_bf16 v[6:9], v[220:223], v[252:255], v[6:9]
	ds_read_b128 v[220:223], v244 offset:4672
	s_waitcnt vmcnt(13)
	ds_write_b128 v165, v[136:139] offset:27648
	s_waitcnt vmcnt(12)
	ds_write_b128 v165, v[140:143] offset:32256
	s_waitcnt lgkmcnt(7)
	v_mfma_f32_16x16x32_bf16 v[26:29], v[224:227], v[228:231], v[26:29]
	ds_read_b128 v[228:231], v245 offset:36928
	v_mfma_f32_16x16x32_bf16 v[30:33], v[224:227], v[236:239], v[30:33]
	ds_read_b128 v[236:239], v245 offset:39232
	v_mfma_f32_16x16x32_bf16 v[10:13], v[224:227], v[240:243], v[10:13]
	ds_read_b128 v[240:243], v245 offset:41536
	v_mfma_f32_16x16x32_bf16 v[14:17], v[224:227], v[252:255], v[14:17]
	ds_read_b128 v[252:255], v245 offset:43840
	ds_read_b128 v[224:227], v244 offset:6976
	s_waitcnt lgkmcnt(4)
	v_mfma_f32_16x16x32_bf16 v[50:53], v[212:215], v[228:231], v[50:53]
	s_waitcnt lgkmcnt(3)
	v_mfma_f32_16x16x32_bf16 v[54:57], v[212:215], v[236:239], v[54:57]
	s_waitcnt lgkmcnt(2)
	v_mfma_f32_16x16x32_bf16 v[34:37], v[212:215], v[240:243], v[34:37]
	s_waitcnt lgkmcnt(1)
	v_mfma_f32_16x16x32_bf16 v[38:41], v[212:215], v[252:255], v[38:41]
	s_waitcnt vmcnt(11)
	ds_write_b128 v165, v[144:147] offset:55296
	s_waitcnt vmcnt(10)
	ds_write_b128 v165, v[148:151] offset:59904
	v_mfma_f32_16x16x32_bf16 v[58:61], v[216:219], v[228:231], v[58:61]
	v_mfma_f32_16x16x32_bf16 v[62:65], v[216:219], v[236:239], v[62:65]
	v_mfma_f32_16x16x32_bf16 v[42:45], v[216:219], v[240:243], v[42:45]
	v_mfma_f32_16x16x32_bf16 v[46:49], v[216:219], v[252:255], v[46:49]
	s_waitcnt vmcnt(9)
	ds_write_b128 v165, v[172:175] offset:64512
	s_waitcnt vmcnt(8)
	ds_write_b128 v166, v[176:179] offset:32256
	v_mfma_f32_16x16x32_bf16 v[18:21], v[220:223], v[228:231], v[18:21]
	v_mfma_f32_16x16x32_bf16 v[22:25], v[220:223], v[236:239], v[22:25]
	v_mfma_f32_16x16x32_bf16 v[2:5], v[220:223], v[240:243], v[2:5]
	v_mfma_f32_16x16x32_bf16 v[6:9], v[220:223], v[252:255], v[6:9]
	s_waitcnt lgkmcnt(4)
	v_mfma_f32_16x16x32_bf16 v[26:29], v[224:227], v[228:231], v[26:29]
	v_mfma_f32_16x16x32_bf16 v[30:33], v[224:227], v[236:239], v[30:33]
	v_mfma_f32_16x16x32_bf16 v[10:13], v[224:227], v[240:243], v[10:13]
	v_mfma_f32_16x16x32_bf16 v[14:17], v[224:227], v[252:255], v[14:17]
	s_waitcnt lgkmcnt(0)
	s_barrier
	s_setprio 0
	ds_read_b128 v[228:231], v245 offset:55296
	ds_read_b128 v[212:215], v244 offset:18432
	ds_read_b128 v[236:239], v245 offset:57600
	ds_read_b128 v[240:243], v245 offset:59904
	ds_read_b128 v[252:255], v245 offset:62208
	ds_read_b128 v[216:219], v244 offset:20736
	ds_read_b128 v[220:223], v244 offset:23040
	ds_read_b128 v[224:227], v244 offset:25344
	global_load_dwordx4 v[122:125], v[72:73], off offset:1664
	global_load_dwordx4 v[126:129], v[74:75], off offset:1664
	global_load_dwordx4 v[136:139], v[76:77], off offset:1664
	global_load_dwordx4 v[140:143], v[78:79], off offset:1664
	global_load_dwordx4 v[144:147], v[70:71], off offset:1664
	global_load_dwordx4 v[148:151], v[68:69], off offset:1664
	global_load_dwordx4 v[172:175], v[66:67], off offset:1664
	global_load_dwordx4 v[176:179], v[80:81], off offset:1664
	s_waitcnt lgkmcnt(6)
	v_mfma_f32_16x16x32_bf16 v[50:53], v[212:215], v[228:231], v[50:53]
	s_waitcnt lgkmcnt(5)
	v_mfma_f32_16x16x32_bf16 v[54:57], v[212:215], v[236:239], v[54:57]
	s_waitcnt lgkmcnt(4)
	v_mfma_f32_16x16x32_bf16 v[34:37], v[212:215], v[240:243], v[34:37]
	s_waitcnt lgkmcnt(3)
	v_mfma_f32_16x16x32_bf16 v[38:41], v[212:215], v[252:255], v[38:41]
	ds_read_b128 v[212:215], v244 offset:18496
	s_waitcnt lgkmcnt(3)
	v_mfma_f32_16x16x32_bf16 v[58:61], v[216:219], v[228:231], v[58:61]
	v_mfma_f32_16x16x32_bf16 v[62:65], v[216:219], v[236:239], v[62:65]
	v_mfma_f32_16x16x32_bf16 v[42:45], v[216:219], v[240:243], v[42:45]
	v_mfma_f32_16x16x32_bf16 v[46:49], v[216:219], v[252:255], v[46:49]
	ds_read_b128 v[216:219], v244 offset:20800
	s_setprio 1
	s_waitcnt vmcnt(15)
	ds_write_b128 v165, v[180:183]
	s_waitcnt vmcnt(14)
	ds_write_b128 v165, v[184:187] offset:4608
	s_waitcnt lgkmcnt(5)
	v_mfma_f32_16x16x32_bf16 v[18:21], v[220:223], v[228:231], v[18:21]
	v_mfma_f32_16x16x32_bf16 v[22:25], v[220:223], v[236:239], v[22:25]
	v_mfma_f32_16x16x32_bf16 v[2:5], v[220:223], v[240:243], v[2:5]
	v_mfma_f32_16x16x32_bf16 v[6:9], v[220:223], v[252:255], v[6:9]
	ds_read_b128 v[220:223], v244 offset:23104
	s_waitcnt vmcnt(13)
	ds_write_b128 v165, v[188:191] offset:9216
	s_waitcnt vmcnt(12)
	ds_write_b128 v165, v[192:195] offset:13824
	s_waitcnt lgkmcnt(7)
	v_mfma_f32_16x16x32_bf16 v[26:29], v[224:227], v[228:231], v[26:29]
	ds_read_b128 v[228:231], v245 offset:55360
	v_mfma_f32_16x16x32_bf16 v[30:33], v[224:227], v[236:239], v[30:33]
	ds_read_b128 v[236:239], v245 offset:57664
	v_mfma_f32_16x16x32_bf16 v[10:13], v[224:227], v[240:243], v[10:13]
	ds_read_b128 v[240:243], v245 offset:59968
	v_mfma_f32_16x16x32_bf16 v[14:17], v[224:227], v[252:255], v[14:17]
	ds_read_b128 v[252:255], v245 offset:62272
	ds_read_b128 v[224:227], v244 offset:25408
	s_waitcnt lgkmcnt(4)
	v_mfma_f32_16x16x32_bf16 v[50:53], v[212:215], v[228:231], v[50:53]
	s_waitcnt lgkmcnt(3)
	v_mfma_f32_16x16x32_bf16 v[54:57], v[212:215], v[236:239], v[54:57]
	s_waitcnt lgkmcnt(2)
	v_mfma_f32_16x16x32_bf16 v[34:37], v[212:215], v[240:243], v[34:37]
	s_waitcnt lgkmcnt(1)
	v_mfma_f32_16x16x32_bf16 v[38:41], v[212:215], v[252:255], v[38:41]
	s_waitcnt vmcnt(11)
	ds_write_b128 v165, v[196:199] offset:36864
	s_waitcnt vmcnt(10)
	ds_write_b128 v165, v[200:203] offset:41472
	v_mfma_f32_16x16x32_bf16 v[58:61], v[216:219], v[228:231], v[58:61]
	v_mfma_f32_16x16x32_bf16 v[62:65], v[216:219], v[236:239], v[62:65]
	v_mfma_f32_16x16x32_bf16 v[42:45], v[216:219], v[240:243], v[42:45]
	v_mfma_f32_16x16x32_bf16 v[46:49], v[216:219], v[252:255], v[46:49]
	s_waitcnt vmcnt(9)
	ds_write_b128 v165, v[204:207] offset:46080
	s_waitcnt vmcnt(8)
	ds_write_b128 v165, v[208:211] offset:50688
	v_mfma_f32_16x16x32_bf16 v[18:21], v[220:223], v[228:231], v[18:21]
	v_mfma_f32_16x16x32_bf16 v[22:25], v[220:223], v[236:239], v[22:25]
	v_mfma_f32_16x16x32_bf16 v[2:5], v[220:223], v[240:243], v[2:5]
	v_mfma_f32_16x16x32_bf16 v[6:9], v[220:223], v[252:255], v[6:9]
	s_waitcnt lgkmcnt(4)
	v_mfma_f32_16x16x32_bf16 v[26:29], v[224:227], v[228:231], v[26:29]
	v_mfma_f32_16x16x32_bf16 v[30:33], v[224:227], v[236:239], v[30:33]
	v_mfma_f32_16x16x32_bf16 v[10:13], v[224:227], v[240:243], v[10:13]
	v_mfma_f32_16x16x32_bf16 v[14:17], v[224:227], v[252:255], v[14:17]
	s_waitcnt lgkmcnt(0)
	s_barrier
	s_setprio 0
	ds_read_b128 v[228:231], v245 offset:36864
	ds_read_b128 v[212:215], v244
	ds_read_b128 v[236:239], v245 offset:39168
	ds_read_b128 v[240:243], v245 offset:41472
	ds_read_b128 v[252:255], v245 offset:43776
	ds_read_b128 v[216:219], v244 offset:2304
	ds_read_b128 v[220:223], v244 offset:4608
	ds_read_b128 v[224:227], v244 offset:6912
	global_load_dwordx4 v[180:183], v[72:73], off offset:1792
	global_load_dwordx4 v[184:187], v[74:75], off offset:1792
	global_load_dwordx4 v[188:191], v[76:77], off offset:1792
	global_load_dwordx4 v[192:195], v[78:79], off offset:1792
	global_load_dwordx4 v[196:199], v[70:71], off offset:1792
	global_load_dwordx4 v[200:203], v[68:69], off offset:1792
	global_load_dwordx4 v[204:207], v[66:67], off offset:1792
	global_load_dwordx4 v[208:211], v[80:81], off offset:1792
	s_waitcnt lgkmcnt(6)
	v_mfma_f32_16x16x32_bf16 v[50:53], v[212:215], v[228:231], v[50:53]
	s_waitcnt lgkmcnt(5)
	v_mfma_f32_16x16x32_bf16 v[54:57], v[212:215], v[236:239], v[54:57]
	s_waitcnt lgkmcnt(4)
	v_mfma_f32_16x16x32_bf16 v[34:37], v[212:215], v[240:243], v[34:37]
	s_waitcnt lgkmcnt(3)
	v_mfma_f32_16x16x32_bf16 v[38:41], v[212:215], v[252:255], v[38:41]
	ds_read_b128 v[212:215], v244 offset:64
	s_waitcnt lgkmcnt(3)
	v_mfma_f32_16x16x32_bf16 v[58:61], v[216:219], v[228:231], v[58:61]
	v_mfma_f32_16x16x32_bf16 v[62:65], v[216:219], v[236:239], v[62:65]
	v_mfma_f32_16x16x32_bf16 v[42:45], v[216:219], v[240:243], v[42:45]
	v_mfma_f32_16x16x32_bf16 v[46:49], v[216:219], v[252:255], v[46:49]
	ds_read_b128 v[216:219], v244 offset:2368
	s_setprio 1
	s_waitcnt vmcnt(15)
	ds_write_b128 v165, v[122:125] offset:18432
	s_waitcnt vmcnt(14)
	ds_write_b128 v165, v[126:129] offset:23040
	s_waitcnt lgkmcnt(5)
	v_mfma_f32_16x16x32_bf16 v[18:21], v[220:223], v[228:231], v[18:21]
	v_mfma_f32_16x16x32_bf16 v[22:25], v[220:223], v[236:239], v[22:25]
	v_mfma_f32_16x16x32_bf16 v[2:5], v[220:223], v[240:243], v[2:5]
	v_mfma_f32_16x16x32_bf16 v[6:9], v[220:223], v[252:255], v[6:9]
	ds_read_b128 v[220:223], v244 offset:4672
	s_waitcnt vmcnt(13)
	ds_write_b128 v165, v[136:139] offset:27648
	s_waitcnt vmcnt(12)
	ds_write_b128 v165, v[140:143] offset:32256
	s_waitcnt lgkmcnt(7)
	v_mfma_f32_16x16x32_bf16 v[26:29], v[224:227], v[228:231], v[26:29]
	ds_read_b128 v[228:231], v245 offset:36928
	v_mfma_f32_16x16x32_bf16 v[30:33], v[224:227], v[236:239], v[30:33]
	ds_read_b128 v[236:239], v245 offset:39232
	v_mfma_f32_16x16x32_bf16 v[10:13], v[224:227], v[240:243], v[10:13]
	ds_read_b128 v[240:243], v245 offset:41536
	v_mfma_f32_16x16x32_bf16 v[14:17], v[224:227], v[252:255], v[14:17]
	ds_read_b128 v[252:255], v245 offset:43840
	ds_read_b128 v[224:227], v244 offset:6976
	s_waitcnt lgkmcnt(4)
	v_mfma_f32_16x16x32_bf16 v[50:53], v[212:215], v[228:231], v[50:53]
	s_waitcnt lgkmcnt(3)
	v_mfma_f32_16x16x32_bf16 v[54:57], v[212:215], v[236:239], v[54:57]
	s_waitcnt lgkmcnt(2)
	v_mfma_f32_16x16x32_bf16 v[34:37], v[212:215], v[240:243], v[34:37]
	s_waitcnt lgkmcnt(1)
	v_mfma_f32_16x16x32_bf16 v[38:41], v[212:215], v[252:255], v[38:41]
	s_waitcnt vmcnt(11)
	ds_write_b128 v165, v[144:147] offset:55296
	s_waitcnt vmcnt(10)
	ds_write_b128 v165, v[148:151] offset:59904
	v_mfma_f32_16x16x32_bf16 v[58:61], v[216:219], v[228:231], v[58:61]
	v_mfma_f32_16x16x32_bf16 v[62:65], v[216:219], v[236:239], v[62:65]
	v_mfma_f32_16x16x32_bf16 v[42:45], v[216:219], v[240:243], v[42:45]
	v_mfma_f32_16x16x32_bf16 v[46:49], v[216:219], v[252:255], v[46:49]
	s_waitcnt vmcnt(9)
	ds_write_b128 v165, v[172:175] offset:64512
	s_waitcnt vmcnt(8)
	ds_write_b128 v166, v[176:179] offset:32256
	v_mfma_f32_16x16x32_bf16 v[18:21], v[220:223], v[228:231], v[18:21]
	v_mfma_f32_16x16x32_bf16 v[22:25], v[220:223], v[236:239], v[22:25]
	v_mfma_f32_16x16x32_bf16 v[2:5], v[220:223], v[240:243], v[2:5]
	v_mfma_f32_16x16x32_bf16 v[6:9], v[220:223], v[252:255], v[6:9]
	s_waitcnt lgkmcnt(4)
	v_mfma_f32_16x16x32_bf16 v[26:29], v[224:227], v[228:231], v[26:29]
	v_mfma_f32_16x16x32_bf16 v[30:33], v[224:227], v[236:239], v[30:33]
	v_mfma_f32_16x16x32_bf16 v[10:13], v[224:227], v[240:243], v[10:13]
	v_mfma_f32_16x16x32_bf16 v[14:17], v[224:227], v[252:255], v[14:17]
	s_waitcnt lgkmcnt(0)
	s_barrier
	s_setprio 0
	global_load_dwordx4 v[122:125], v[72:73], off offset:1920
	s_nop 0
	global_load_dwordx4 v[72:75], v[74:75], off offset:1920
	s_nop 0
	global_load_dwordx4 v[126:129], v[76:77], off offset:1920
	s_nop 0
	global_load_dwordx4 v[76:79], v[78:79], off offset:1920
	s_nop 0
	global_load_dwordx4 v[136:139], v[70:71], off offset:1920
	s_nop 0
	global_load_dwordx4 v[68:71], v[68:69], off offset:1920
	s_nop 0
	global_load_dwordx4 v[140:143], v[66:67], off offset:1920
	global_load_dwordx4 v[144:147], v[80:81], off offset:1920
	ds_read_b128 v[228:231], v245 offset:55296
	ds_read_b128 v[212:215], v244 offset:18432
	ds_read_b128 v[236:239], v245 offset:57600
	ds_read_b128 v[240:243], v245 offset:59904
	ds_read_b128 v[252:255], v245 offset:62208
	ds_read_b128 v[216:219], v244 offset:20736
	ds_read_b128 v[220:223], v244 offset:23040
	ds_read_b128 v[224:227], v244 offset:25344
	s_waitcnt lgkmcnt(6)
	v_mfma_f32_16x16x32_bf16 v[50:53], v[212:215], v[228:231], v[50:53]
	s_waitcnt lgkmcnt(5)
	v_mfma_f32_16x16x32_bf16 v[54:57], v[212:215], v[236:239], v[54:57]
	s_waitcnt lgkmcnt(4)
	v_mfma_f32_16x16x32_bf16 v[34:37], v[212:215], v[240:243], v[34:37]
	s_waitcnt lgkmcnt(3)
	v_mfma_f32_16x16x32_bf16 v[38:41], v[212:215], v[252:255], v[38:41]
	ds_read_b128 v[212:215], v244 offset:18496
	s_waitcnt lgkmcnt(3)
	v_mfma_f32_16x16x32_bf16 v[58:61], v[216:219], v[228:231], v[58:61]
	v_mfma_f32_16x16x32_bf16 v[62:65], v[216:219], v[236:239], v[62:65]
	v_mfma_f32_16x16x32_bf16 v[42:45], v[216:219], v[240:243], v[42:45]
	v_mfma_f32_16x16x32_bf16 v[46:49], v[216:219], v[252:255], v[46:49]
	ds_read_b128 v[216:219], v244 offset:20800
	s_setprio 1
	s_waitcnt vmcnt(15)
	ds_write_b128 v165, v[180:183]
	s_waitcnt vmcnt(14)
	ds_write_b128 v165, v[184:187] offset:4608
	s_waitcnt lgkmcnt(5)
	v_mfma_f32_16x16x32_bf16 v[18:21], v[220:223], v[228:231], v[18:21]
	v_mfma_f32_16x16x32_bf16 v[22:25], v[220:223], v[236:239], v[22:25]
	v_mfma_f32_16x16x32_bf16 v[2:5], v[220:223], v[240:243], v[2:5]
	v_mfma_f32_16x16x32_bf16 v[6:9], v[220:223], v[252:255], v[6:9]
	ds_read_b128 v[220:223], v244 offset:23104
	s_waitcnt vmcnt(13)
	ds_write_b128 v165, v[188:191] offset:9216
	s_waitcnt vmcnt(12)
	ds_write_b128 v165, v[192:195] offset:13824
	s_waitcnt lgkmcnt(7)
	v_mfma_f32_16x16x32_bf16 v[26:29], v[224:227], v[228:231], v[26:29]
	ds_read_b128 v[228:231], v245 offset:55360
	v_mfma_f32_16x16x32_bf16 v[30:33], v[224:227], v[236:239], v[30:33]
	ds_read_b128 v[236:239], v245 offset:57664
	v_mfma_f32_16x16x32_bf16 v[10:13], v[224:227], v[240:243], v[10:13]
	ds_read_b128 v[240:243], v245 offset:59968
	v_mfma_f32_16x16x32_bf16 v[14:17], v[224:227], v[252:255], v[14:17]
	ds_read_b128 v[252:255], v245 offset:62272
	ds_read_b128 v[224:227], v244 offset:25408
	s_waitcnt lgkmcnt(4)
	v_mfma_f32_16x16x32_bf16 v[50:53], v[212:215], v[228:231], v[50:53]
	s_waitcnt lgkmcnt(3)
	v_mfma_f32_16x16x32_bf16 v[54:57], v[212:215], v[236:239], v[54:57]
	s_waitcnt lgkmcnt(2)
	v_mfma_f32_16x16x32_bf16 v[34:37], v[212:215], v[240:243], v[34:37]
	s_waitcnt lgkmcnt(1)
	v_mfma_f32_16x16x32_bf16 v[38:41], v[212:215], v[252:255], v[38:41]
	s_waitcnt vmcnt(11)
	ds_write_b128 v165, v[196:199] offset:36864
	s_waitcnt vmcnt(10)
	ds_write_b128 v165, v[200:203] offset:41472
	v_mfma_f32_16x16x32_bf16 v[58:61], v[216:219], v[228:231], v[58:61]
	v_mfma_f32_16x16x32_bf16 v[62:65], v[216:219], v[236:239], v[62:65]
	v_mfma_f32_16x16x32_bf16 v[42:45], v[216:219], v[240:243], v[42:45]
	v_mfma_f32_16x16x32_bf16 v[46:49], v[216:219], v[252:255], v[46:49]
	s_waitcnt vmcnt(9)
	ds_write_b128 v165, v[204:207] offset:46080
	s_waitcnt vmcnt(8)
	ds_write_b128 v165, v[208:211] offset:50688
	v_mfma_f32_16x16x32_bf16 v[18:21], v[220:223], v[228:231], v[18:21]
	v_mfma_f32_16x16x32_bf16 v[22:25], v[220:223], v[236:239], v[22:25]
	v_mfma_f32_16x16x32_bf16 v[2:5], v[220:223], v[240:243], v[2:5]
	v_mfma_f32_16x16x32_bf16 v[6:9], v[220:223], v[252:255], v[6:9]
	s_waitcnt lgkmcnt(4)
	v_mfma_f32_16x16x32_bf16 v[26:29], v[224:227], v[228:231], v[26:29]
	v_mfma_f32_16x16x32_bf16 v[30:33], v[224:227], v[236:239], v[30:33]
	v_mfma_f32_16x16x32_bf16 v[10:13], v[224:227], v[240:243], v[10:13]
	v_mfma_f32_16x16x32_bf16 v[14:17], v[224:227], v[252:255], v[14:17]
	s_waitcnt lgkmcnt(0)
	s_barrier
	s_setprio 0
	ds_read_b128 v[228:231], v245 offset:36864
	ds_read_b128 v[212:215], v244
	ds_read_b128 v[236:239], v245 offset:39168
	ds_read_b128 v[240:243], v245 offset:41472
	ds_read_b128 v[252:255], v245 offset:43776
	ds_read_b128 v[216:219], v244 offset:2304
	ds_read_b128 v[220:223], v244 offset:4608
	ds_read_b128 v[224:227], v244 offset:6912
	s_waitcnt lgkmcnt(6)
	v_mfma_f32_16x16x32_bf16 v[50:53], v[212:215], v[228:231], v[50:53]
	s_waitcnt lgkmcnt(5)
	v_mfma_f32_16x16x32_bf16 v[54:57], v[212:215], v[236:239], v[54:57]
	s_waitcnt lgkmcnt(4)
	v_mfma_f32_16x16x32_bf16 v[34:37], v[212:215], v[240:243], v[34:37]
	s_waitcnt lgkmcnt(3)
	v_mfma_f32_16x16x32_bf16 v[38:41], v[212:215], v[252:255], v[38:41]
	ds_read_b128 v[212:215], v244 offset:64
	s_waitcnt lgkmcnt(3)
	v_mfma_f32_16x16x32_bf16 v[58:61], v[216:219], v[228:231], v[58:61]
	v_mfma_f32_16x16x32_bf16 v[62:65], v[216:219], v[236:239], v[62:65]
	v_mfma_f32_16x16x32_bf16 v[42:45], v[216:219], v[240:243], v[42:45]
	v_mfma_f32_16x16x32_bf16 v[46:49], v[216:219], v[252:255], v[46:49]
	ds_read_b128 v[216:219], v244 offset:2368
	s_setprio 1
	s_waitcnt vmcnt(7)
	ds_write_b128 v165, v[122:125] offset:18432
	s_waitcnt vmcnt(6)
	ds_write_b128 v165, v[72:75] offset:23040
	s_waitcnt lgkmcnt(5)
	v_mfma_f32_16x16x32_bf16 v[18:21], v[220:223], v[228:231], v[18:21]
	v_mfma_f32_16x16x32_bf16 v[22:25], v[220:223], v[236:239], v[22:25]
	v_mfma_f32_16x16x32_bf16 v[2:5], v[220:223], v[240:243], v[2:5]
	v_mfma_f32_16x16x32_bf16 v[6:9], v[220:223], v[252:255], v[6:9]
	ds_read_b128 v[220:223], v244 offset:4672
	s_waitcnt vmcnt(5)
	ds_write_b128 v165, v[126:129] offset:27648
	s_waitcnt vmcnt(4)
	ds_write_b128 v165, v[76:79] offset:32256
	s_waitcnt lgkmcnt(7)
	v_mfma_f32_16x16x32_bf16 v[26:29], v[224:227], v[228:231], v[26:29]
	ds_read_b128 v[228:231], v245 offset:36928
	v_mfma_f32_16x16x32_bf16 v[30:33], v[224:227], v[236:239], v[30:33]
	ds_read_b128 v[236:239], v245 offset:39232
	v_mfma_f32_16x16x32_bf16 v[10:13], v[224:227], v[240:243], v[10:13]
	ds_read_b128 v[240:243], v245 offset:41536
	v_mfma_f32_16x16x32_bf16 v[14:17], v[224:227], v[252:255], v[14:17]
	ds_read_b128 v[252:255], v245 offset:43840
	ds_read_b128 v[224:227], v244 offset:6976
	s_waitcnt lgkmcnt(4)
	v_mfma_f32_16x16x32_bf16 v[50:53], v[212:215], v[228:231], v[50:53]
	s_waitcnt lgkmcnt(3)
	v_mfma_f32_16x16x32_bf16 v[54:57], v[212:215], v[236:239], v[54:57]
	s_waitcnt lgkmcnt(2)
	v_mfma_f32_16x16x32_bf16 v[34:37], v[212:215], v[240:243], v[34:37]
	s_waitcnt lgkmcnt(1)
	v_mfma_f32_16x16x32_bf16 v[38:41], v[212:215], v[252:255], v[38:41]
	s_waitcnt vmcnt(3)
	ds_write_b128 v165, v[136:139] offset:55296
	s_waitcnt vmcnt(2)
	ds_write_b128 v165, v[68:71] offset:59904
	v_mfma_f32_16x16x32_bf16 v[58:61], v[216:219], v[228:231], v[58:61]
	v_mfma_f32_16x16x32_bf16 v[62:65], v[216:219], v[236:239], v[62:65]
	v_mfma_f32_16x16x32_bf16 v[42:45], v[216:219], v[240:243], v[42:45]
	v_mfma_f32_16x16x32_bf16 v[46:49], v[216:219], v[252:255], v[46:49]
	s_waitcnt vmcnt(1)
	ds_write_b128 v165, v[140:143] offset:64512
	s_waitcnt vmcnt(0)
	ds_write_b128 v166, v[144:147] offset:32256
	v_mfma_f32_16x16x32_bf16 v[18:21], v[220:223], v[228:231], v[18:21]
	v_mfma_f32_16x16x32_bf16 v[22:25], v[220:223], v[236:239], v[22:25]
	v_mfma_f32_16x16x32_bf16 v[2:5], v[220:223], v[240:243], v[2:5]
	v_mfma_f32_16x16x32_bf16 v[6:9], v[220:223], v[252:255], v[6:9]
	s_waitcnt lgkmcnt(4)
	v_mfma_f32_16x16x32_bf16 v[26:29], v[224:227], v[228:231], v[26:29]
	v_mfma_f32_16x16x32_bf16 v[30:33], v[224:227], v[236:239], v[30:33]
	v_mfma_f32_16x16x32_bf16 v[10:13], v[224:227], v[240:243], v[10:13]
	v_mfma_f32_16x16x32_bf16 v[14:17], v[224:227], v[252:255], v[14:17]
	s_waitcnt lgkmcnt(0)
	s_barrier
	s_setprio 0
	ds_read_b128 v[228:231], v245 offset:55296
	ds_read_b128 v[212:215], v244 offset:18432
	ds_read_b128 v[236:239], v245 offset:57600
	ds_read_b128 v[240:243], v245 offset:59904
	ds_read_b128 v[252:255], v245 offset:62208
	ds_read_b128 v[216:219], v244 offset:20736
	ds_read_b128 v[220:223], v244 offset:23040
	ds_read_b128 v[224:227], v244 offset:25344
	s_waitcnt lgkmcnt(6)
	v_mfma_f32_16x16x32_bf16 v[50:53], v[212:215], v[228:231], v[50:53]
	s_waitcnt lgkmcnt(5)
	v_mfma_f32_16x16x32_bf16 v[54:57], v[212:215], v[236:239], v[54:57]
	s_waitcnt lgkmcnt(4)
	v_mfma_f32_16x16x32_bf16 v[34:37], v[212:215], v[240:243], v[34:37]
	s_waitcnt lgkmcnt(3)
	v_mfma_f32_16x16x32_bf16 v[38:41], v[212:215], v[252:255], v[38:41]
	ds_read_b128 v[212:215], v244 offset:18496
	s_waitcnt lgkmcnt(3)
	v_mfma_f32_16x16x32_bf16 v[58:61], v[216:219], v[228:231], v[58:61]
	v_mfma_f32_16x16x32_bf16 v[62:65], v[216:219], v[236:239], v[62:65]
	v_mfma_f32_16x16x32_bf16 v[42:45], v[216:219], v[240:243], v[42:45]
	v_mfma_f32_16x16x32_bf16 v[46:49], v[216:219], v[252:255], v[46:49]
	ds_read_b128 v[216:219], v244 offset:20800
	s_waitcnt lgkmcnt(3)
	v_mfma_f32_16x16x32_bf16 v[18:21], v[220:223], v[228:231], v[18:21]
	v_mfma_f32_16x16x32_bf16 v[22:25], v[220:223], v[236:239], v[22:25]
	v_mfma_f32_16x16x32_bf16 v[2:5], v[220:223], v[240:243], v[2:5]
	v_mfma_f32_16x16x32_bf16 v[6:9], v[220:223], v[252:255], v[6:9]
	ds_read_b128 v[220:223], v244 offset:23104
	s_waitcnt lgkmcnt(3)
	v_mfma_f32_16x16x32_bf16 v[26:29], v[224:227], v[228:231], v[26:29]
	ds_read_b128 v[228:231], v245 offset:55360
	v_mfma_f32_16x16x32_bf16 v[30:33], v[224:227], v[236:239], v[30:33]
	ds_read_b128 v[236:239], v245 offset:57664
	v_mfma_f32_16x16x32_bf16 v[10:13], v[224:227], v[240:243], v[10:13]
	ds_read_b128 v[240:243], v245 offset:59968
	v_mfma_f32_16x16x32_bf16 v[14:17], v[224:227], v[252:255], v[14:17]
	ds_read_b128 v[252:255], v245 offset:62272
	ds_read_b128 v[224:227], v244 offset:25408
	s_waitcnt lgkmcnt(4)
	v_mfma_f32_16x16x32_bf16 v[50:53], v[212:215], v[228:231], v[50:53]
	s_waitcnt lgkmcnt(3)
	v_mfma_f32_16x16x32_bf16 v[54:57], v[212:215], v[236:239], v[54:57]
	s_waitcnt lgkmcnt(2)
	v_mfma_f32_16x16x32_bf16 v[34:37], v[212:215], v[240:243], v[34:37]
	s_waitcnt lgkmcnt(1)
	v_mfma_f32_16x16x32_bf16 v[38:41], v[212:215], v[252:255], v[38:41]
	v_mfma_f32_16x16x32_bf16 v[58:61], v[216:219], v[228:231], v[58:61]
	v_mfma_f32_16x16x32_bf16 v[62:65], v[216:219], v[236:239], v[62:65]
	v_mfma_f32_16x16x32_bf16 v[42:45], v[216:219], v[240:243], v[42:45]
	v_mfma_f32_16x16x32_bf16 v[46:49], v[216:219], v[252:255], v[46:49]
	v_mfma_f32_16x16x32_bf16 v[18:21], v[220:223], v[228:231], v[18:21]
	v_mfma_f32_16x16x32_bf16 v[22:25], v[220:223], v[236:239], v[22:25]
	v_mfma_f32_16x16x32_bf16 v[2:5], v[220:223], v[240:243], v[2:5]
	v_mfma_f32_16x16x32_bf16 v[6:9], v[220:223], v[252:255], v[6:9]
	s_waitcnt lgkmcnt(0)
	v_mfma_f32_16x16x32_bf16 v[26:29], v[224:227], v[228:231], v[26:29]
	v_mfma_f32_16x16x32_bf16 v[30:33], v[224:227], v[236:239], v[30:33]
	v_mfma_f32_16x16x32_bf16 v[10:13], v[224:227], v[240:243], v[10:13]
	v_mfma_f32_16x16x32_bf16 v[14:17], v[224:227], v[252:255], v[14:17]
	s_mov_b64 s[2:3], 0
	s_waitcnt lgkmcnt(0)
	s_barrier
	s_nop 7
	v_permlane16_swap_b32_e32 v50, v54
	v_permlane16_swap_b32_e32 v51, v55
	v_permlane16_swap_b32_e32 v52, v56
	v_permlane16_swap_b32_e32 v53, v57
	v_permlane16_swap_b32_e32 v58, v62
	v_permlane16_swap_b32_e32 v59, v63
	v_permlane16_swap_b32_e32 v60, v64
	v_permlane16_swap_b32_e32 v61, v65
	v_permlane16_swap_b32_e32 v34, v38
	v_permlane16_swap_b32_e32 v35, v39
	v_permlane16_swap_b32_e32 v36, v40
	v_permlane16_swap_b32_e32 v37, v41
	v_permlane16_swap_b32_e32 v42, v46
	v_permlane16_swap_b32_e32 v43, v47
	v_permlane16_swap_b32_e32 v44, v48
	v_permlane16_swap_b32_e32 v45, v49
	v_permlane16_swap_b32_e32 v18, v22
	v_permlane16_swap_b32_e32 v19, v23
	v_permlane16_swap_b32_e32 v20, v24
	v_permlane16_swap_b32_e32 v21, v25
	v_permlane16_swap_b32_e32 v26, v30
	v_permlane16_swap_b32_e32 v27, v31
	v_permlane16_swap_b32_e32 v28, v32
	v_permlane16_swap_b32_e32 v29, v33
	v_permlane16_swap_b32_e32 v2, v6
	v_permlane16_swap_b32_e32 v3, v7
	v_permlane16_swap_b32_e32 v4, v8
	v_permlane16_swap_b32_e32 v5, v9
	v_permlane16_swap_b32_e32 v10, v14
	v_permlane16_swap_b32_e32 v11, v15
	v_permlane16_swap_b32_e32 v12, v16
	v_permlane16_swap_b32_e32 v13, v17
	v_permlane32_swap_b32_e32 v50, v54
	v_permlane32_swap_b32_e32 v51, v55
	v_permlane32_swap_b32_e32 v52, v56
	v_permlane32_swap_b32_e32 v53, v57
	v_permlane32_swap_b32_e32 v58, v62
	v_permlane32_swap_b32_e32 v59, v63
	v_permlane32_swap_b32_e32 v60, v64
	v_permlane32_swap_b32_e32 v61, v65
	v_permlane32_swap_b32_e32 v34, v38
	v_permlane32_swap_b32_e32 v35, v39
	v_permlane32_swap_b32_e32 v36, v40
	v_permlane32_swap_b32_e32 v37, v41
	v_permlane32_swap_b32_e32 v42, v46
	v_permlane32_swap_b32_e32 v43, v47
	v_permlane32_swap_b32_e32 v44, v48
	v_permlane32_swap_b32_e32 v45, v49
	v_permlane32_swap_b32_e32 v18, v22
	v_permlane32_swap_b32_e32 v19, v23
	v_permlane32_swap_b32_e32 v20, v24
	v_permlane32_swap_b32_e32 v21, v25
	v_permlane32_swap_b32_e32 v26, v30
	v_permlane32_swap_b32_e32 v27, v31
	v_permlane32_swap_b32_e32 v28, v32
	v_permlane32_swap_b32_e32 v29, v33
	v_permlane32_swap_b32_e32 v2, v6
	v_permlane32_swap_b32_e32 v3, v7
	v_permlane32_swap_b32_e32 v4, v8
	v_permlane32_swap_b32_e32 v5, v9
	v_permlane32_swap_b32_e32 v10, v14
	v_permlane32_swap_b32_e32 v11, v15
	v_permlane32_swap_b32_e32 v12, v16
	v_permlane32_swap_b32_e32 v13, v17

.LBB0_275:
	v_ashrrev_i32_e32 v3, 31, v2
	v_lshlrev_b64 v[2:3], 11, v[2:3]
	v_ashrrev_i32_e32 v9, 31, v8
	v_lshl_add_u64 v[70:71], v[86:87], 0, v[2:3]
	v_lshlrev_b64 v[2:3], 11, v[8:9]
	v_lshl_add_u64 v[72:73], v[86:87], 0, v[2:3]
	v_or_b32_e32 v2, s56, v154
	v_ashrrev_i32_e32 v3, 31, v2
	v_lshlrev_b64 v[2:3], 11, v[2:3]
	v_lshl_add_u64 v[74:75], v[84:85], 0, v[2:3]
	v_add_u32_e32 v2, s56, v155
	v_ashrrev_i32_e32 v3, 31, v2
	v_lshlrev_b64 v[2:3], 11, v[2:3]
	v_lshl_add_u64 v[76:77], v[84:85], 0, v[2:3]
	v_add_u32_e32 v2, s56, v156
	v_ashrrev_i32_e32 v3, 31, v2
	v_lshlrev_b64 v[2:3], 11, v[2:3]
	v_lshl_add_u64 v[78:79], v[84:85], 0, v[2:3]
	v_add_u32_e32 v2, s56, v157
	v_ashrrev_i32_e32 v7, 31, v6
	v_ashrrev_i32_e32 v5, 31, v4
	v_ashrrev_i32_e32 v3, 31, v2
	v_lshlrev_b64 v[6:7], 11, v[6:7]
	v_lshlrev_b64 v[4:5], 11, v[4:5]
	v_lshlrev_b64 v[2:3], 11, v[2:3]
	v_lshl_add_u64 v[66:67], v[86:87], 0, v[6:7]
	v_lshl_add_u64 v[68:69], v[86:87], 0, v[4:5]
	v_lshl_add_u64 v[80:81], v[84:85], 0, v[2:3]
	global_load_dwordx4 v[2:5], v[70:71], off
	global_load_dwordx4 v[6:9], v[68:69], off
	global_load_dwordx4 v[10:13], v[66:67], off
	global_load_dwordx4 v[14:17], v[72:73], off
	global_load_dwordx4 v[18:21], v[74:75], off
	global_load_dwordx4 v[22:25], v[76:77], off
	global_load_dwordx4 v[26:29], v[78:79], off
	global_load_dwordx4 v[30:33], v[80:81], off
	global_load_dwordx4 v[122:125], v[70:71], off offset:128
	global_load_dwordx4 v[126:129], v[68:69], off offset:128
	global_load_dwordx4 v[136:139], v[66:67], off offset:128
	global_load_dwordx4 v[140:143], v[72:73], off offset:128
	global_load_dwordx4 v[144:147], v[74:75], off offset:128
	global_load_dwordx4 v[148:151], v[76:77], off offset:128
	global_load_dwordx4 v[172:175], v[78:79], off offset:128
	global_load_dwordx4 v[176:179], v[80:81], off offset:128
	s_waitcnt vmcnt(15)
	ds_write_b128 v165, v[2:5]
	s_waitcnt vmcnt(14)
	ds_write_b128 v165, v[6:9] offset:4608
	s_waitcnt vmcnt(13)
	ds_write_b128 v165, v[10:13] offset:9216
	s_waitcnt vmcnt(12)
	ds_write_b128 v165, v[14:17] offset:13824
	s_waitcnt vmcnt(11)
	ds_write_b128 v165, v[18:21] offset:36864
	s_waitcnt vmcnt(10)
	ds_write_b128 v165, v[22:25] offset:41472
	s_waitcnt vmcnt(9)
	ds_write_b128 v165, v[26:29] offset:46080
	s_waitcnt vmcnt(8)
	ds_write_b128 v165, v[30:33] offset:50688
	s_waitcnt lgkmcnt(0)
	s_barrier
	global_load_dwordx4 v[180:183], v[68:69], off offset:256
	global_load_dwordx4 v[184:187], v[66:67], off offset:256
	global_load_dwordx4 v[188:191], v[70:71], off offset:256
	global_load_dwordx4 v[192:195], v[72:73], off offset:256
	global_load_dwordx4 v[196:199], v[74:75], off offset:256
	global_load_dwordx4 v[200:203], v[76:77], off offset:256
	global_load_dwordx4 v[204:207], v[78:79], off offset:256
	global_load_dwordx4 v[208:211], v[80:81], off offset:256
	v_and_b32_e32 v246, 15, v1
	v_add_u32_e32 v246, 4, v246
	v_bfe_u32 v246, v246, 3, 1
	v_bfe_u32 v249, v1, 4, 2
	v_xor_b32_e32 v246, v246, v249
	v_bfe_u32 v249, v1, 5, 1
	v_sub_u32_e32 v246, v246, v249
	v_lshlrev_b32_e32 v246, 4, v246
	v_bfe_u32 v249, v1, 4, 1
	v_mul_u32_u24_e32 v249, 0x900, v249
	v_sub_u32_e32 v246, v246, v249
	v_add_u32_e32 v244, v246, v162
	v_add_u32_e32 v245, v246, v164
	ds_read_b128 v[228:231], v245 offset:36864
	ds_read_b128 v[212:215], v244
	ds_read_b128 v[236:239], v245 offset:39168
	ds_read_b128 v[240:243], v245 offset:41472
	ds_read_b128 v[252:255], v245 offset:43776
	ds_read_b128 v[216:219], v244 offset:2304
	ds_read_b128 v[220:223], v244 offset:4608
	ds_read_b128 v[224:227], v244 offset:6912
	s_waitcnt lgkmcnt(6)
	v_mfma_f32_16x16x32_bf16 v[50:53], v[212:215], v[228:231], 0
	s_waitcnt lgkmcnt(5)
	v_mfma_f32_16x16x32_bf16 v[54:57], v[212:215], v[236:239], 0
	s_waitcnt lgkmcnt(4)
	v_mfma_f32_16x16x32_bf16 v[34:37], v[212:215], v[240:243], 0
	s_waitcnt lgkmcnt(3)
	v_mfma_f32_16x16x32_bf16 v[38:41], v[212:215], v[252:255], 0
	ds_read_b128 v[212:215], v244 offset:64
	s_waitcnt lgkmcnt(3)
	v_mfma_f32_16x16x32_bf16 v[58:61], v[216:219], v[228:231], 0
	v_mfma_f32_16x16x32_bf16 v[62:65], v[216:219], v[236:239], 0
	v_mfma_f32_16x16x32_bf16 v[42:45], v[216:219], v[240:243], 0
	v_mfma_f32_16x16x32_bf16 v[46:49], v[216:219], v[252:255], 0
	ds_read_b128 v[216:219], v244 offset:2368
	s_setprio 1
	s_waitcnt vmcnt(15)
	ds_write_b128 v165, v[122:125] offset:18432
	s_waitcnt vmcnt(14)
	ds_write_b128 v165, v[126:129] offset:23040
	s_waitcnt lgkmcnt(5)
	v_mfma_f32_16x16x32_bf16 v[18:21], v[220:223], v[228:231], 0
	v_mfma_f32_16x16x32_bf16 v[22:25], v[220:223], v[236:239], 0
	v_mfma_f32_16x16x32_bf16 v[2:5], v[220:223], v[240:243], 0
	v_mfma_f32_16x16x32_bf16 v[6:9], v[220:223], v[252:255], 0
	ds_read_b128 v[220:223], v244 offset:4672
	s_waitcnt vmcnt(13)
	ds_write_b128 v165, v[136:139] offset:27648
	s_waitcnt vmcnt(12)
	ds_write_b128 v165, v[140:143] offset:32256
	s_waitcnt lgkmcnt(7)
	v_mfma_f32_16x16x32_bf16 v[26:29], v[224:227], v[228:231], 0
	ds_read_b128 v[228:231], v245 offset:36928
	v_mfma_f32_16x16x32_bf16 v[30:33], v[224:227], v[236:239], 0
	ds_read_b128 v[236:239], v245 offset:39232
	v_mfma_f32_16x16x32_bf16 v[10:13], v[224:227], v[240:243], 0
	ds_read_b128 v[240:243], v245 offset:41536
	v_mfma_f32_16x16x32_bf16 v[14:17], v[224:227], v[252:255], 0
	ds_read_b128 v[252:255], v245 offset:43840
	ds_read_b128 v[224:227], v244 offset:6976
	s_waitcnt lgkmcnt(4)
	v_mfma_f32_16x16x32_bf16 v[50:53], v[212:215], v[228:231], v[50:53]
	s_waitcnt lgkmcnt(3)
	v_mfma_f32_16x16x32_bf16 v[54:57], v[212:215], v[236:239], v[54:57]
	s_waitcnt lgkmcnt(2)
	v_mfma_f32_16x16x32_bf16 v[34:37], v[212:215], v[240:243], v[34:37]
	s_waitcnt lgkmcnt(1)
	v_mfma_f32_16x16x32_bf16 v[38:41], v[212:215], v[252:255], v[38:41]
	s_waitcnt vmcnt(11)
	ds_write_b128 v165, v[144:147] offset:55296
	s_waitcnt vmcnt(10)
	ds_write_b128 v165, v[148:151] offset:59904
	v_mfma_f32_16x16x32_bf16 v[58:61], v[216:219], v[228:231], v[58:61]
	v_mfma_f32_16x16x32_bf16 v[62:65], v[216:219], v[236:239], v[62:65]
	v_mfma_f32_16x16x32_bf16 v[42:45], v[216:219], v[240:243], v[42:45]
	v_mfma_f32_16x16x32_bf16 v[46:49], v[216:219], v[252:255], v[46:49]
	s_waitcnt vmcnt(9)
	ds_write_b128 v165, v[172:175] offset:64512
	s_waitcnt vmcnt(8)
	ds_write_b128 v166, v[176:179] offset:32256
	v_mfma_f32_16x16x32_bf16 v[18:21], v[220:223], v[228:231], v[18:21]
	v_mfma_f32_16x16x32_bf16 v[22:25], v[220:223], v[236:239], v[22:25]
	v_mfma_f32_16x16x32_bf16 v[2:5], v[220:223], v[240:243], v[2:5]
	v_mfma_f32_16x16x32_bf16 v[6:9], v[220:223], v[252:255], v[6:9]
	s_waitcnt lgkmcnt(4)
	v_mfma_f32_16x16x32_bf16 v[26:29], v[224:227], v[228:231], v[26:29]
	v_mfma_f32_16x16x32_bf16 v[30:33], v[224:227], v[236:239], v[30:33]
	v_mfma_f32_16x16x32_bf16 v[10:13], v[224:227], v[240:243], v[10:13]
	v_mfma_f32_16x16x32_bf16 v[14:17], v[224:227], v[252:255], v[14:17]
	s_waitcnt lgkmcnt(0)
	s_barrier
	s_setprio 0
	ds_read_b128 v[228:231], v245 offset:55296
	ds_read_b128 v[212:215], v244 offset:18432
	ds_read_b128 v[236:239], v245 offset:57600
	ds_read_b128 v[240:243], v245 offset:59904
	ds_read_b128 v[252:255], v245 offset:62208
	ds_read_b128 v[216:219], v244 offset:20736
	ds_read_b128 v[220:223], v244 offset:23040
	ds_read_b128 v[224:227], v244 offset:25344
	global_load_dwordx4 v[122:125], v[70:71], off offset:384
	global_load_dwordx4 v[126:129], v[68:69], off offset:384
	global_load_dwordx4 v[136:139], v[66:67], off offset:384
	global_load_dwordx4 v[140:143], v[72:73], off offset:384
	global_load_dwordx4 v[144:147], v[74:75], off offset:384
	global_load_dwordx4 v[148:151], v[76:77], off offset:384
	global_load_dwordx4 v[172:175], v[78:79], off offset:384
	global_load_dwordx4 v[176:179], v[80:81], off offset:384
	s_waitcnt lgkmcnt(6)
	v_mfma_f32_16x16x32_bf16 v[50:53], v[212:215], v[228:231], v[50:53]
	s_waitcnt lgkmcnt(5)
	v_mfma_f32_16x16x32_bf16 v[54:57], v[212:215], v[236:239], v[54:57]
	s_waitcnt lgkmcnt(4)
	v_mfma_f32_16x16x32_bf16 v[34:37], v[212:215], v[240:243], v[34:37]
	s_waitcnt lgkmcnt(3)
	v_mfma_f32_16x16x32_bf16 v[38:41], v[212:215], v[252:255], v[38:41]
	ds_read_b128 v[212:215], v244 offset:18496
	s_waitcnt lgkmcnt(3)
	v_mfma_f32_16x16x32_bf16 v[58:61], v[216:219], v[228:231], v[58:61]
	v_mfma_f32_16x16x32_bf16 v[62:65], v[216:219], v[236:239], v[62:65]
	v_mfma_f32_16x16x32_bf16 v[42:45], v[216:219], v[240:243], v[42:45]
	v_mfma_f32_16x16x32_bf16 v[46:49], v[216:219], v[252:255], v[46:49]
	ds_read_b128 v[216:219], v244 offset:20800
	s_setprio 1
	s_waitcnt vmcnt(13)
	ds_write_b128 v165, v[188:191]
	ds_write_b128 v165, v[180:183] offset:4608
	s_waitcnt lgkmcnt(5)
	v_mfma_f32_16x16x32_bf16 v[18:21], v[220:223], v[228:231], v[18:21]
	v_mfma_f32_16x16x32_bf16 v[22:25], v[220:223], v[236:239], v[22:25]
	v_mfma_f32_16x16x32_bf16 v[2:5], v[220:223], v[240:243], v[2:5]
	v_mfma_f32_16x16x32_bf16 v[6:9], v[220:223], v[252:255], v[6:9]
	ds_read_b128 v[220:223], v244 offset:23104
	ds_write_b128 v165, v[184:187] offset:9216
	s_waitcnt vmcnt(12)
	ds_write_b128 v165, v[192:195] offset:13824
	s_waitcnt lgkmcnt(7)
	v_mfma_f32_16x16x32_bf16 v[26:29], v[224:227], v[228:231], v[26:29]
	ds_read_b128 v[228:231], v245 offset:55360
	v_mfma_f32_16x16x32_bf16 v[30:33], v[224:227], v[236:239], v[30:33]
	ds_read_b128 v[236:239], v245 offset:57664
	v_mfma_f32_16x16x32_bf16 v[10:13], v[224:227], v[240:243], v[10:13]
	ds_read_b128 v[240:243], v245 offset:59968
	v_mfma_f32_16x16x32_bf16 v[14:17], v[224:227], v[252:255], v[14:17]
	ds_read_b128 v[252:255], v245 offset:62272
	ds_read_b128 v[224:227], v244 offset:25408
	s_waitcnt lgkmcnt(4)
	v_mfma_f32_16x16x32_bf16 v[50:53], v[212:215], v[228:231], v[50:53]
	s_waitcnt lgkmcnt(3)
	v_mfma_f32_16x16x32_bf16 v[54:57], v[212:215], v[236:239], v[54:57]
	s_waitcnt lgkmcnt(2)
	v_mfma_f32_16x16x32_bf16 v[34:37], v[212:215], v[240:243], v[34:37]
	s_waitcnt lgkmcnt(1)
	v_mfma_f32_16x16x32_bf16 v[38:41], v[212:215], v[252:255], v[38:41]
	s_waitcnt vmcnt(11)
	ds_write_b128 v165, v[196:199] offset:36864
	s_waitcnt vmcnt(10)
	ds_write_b128 v165, v[200:203] offset:41472
	v_mfma_f32_16x16x32_bf16 v[58:61], v[216:219], v[228:231], v[58:61]
	v_mfma_f32_16x16x32_bf16 v[62:65], v[216:219], v[236:239], v[62:65]
	v_mfma_f32_16x16x32_bf16 v[42:45], v[216:219], v[240:243], v[42:45]
	v_mfma_f32_16x16x32_bf16 v[46:49], v[216:219], v[252:255], v[46:49]
	s_waitcnt vmcnt(9)
	ds_write_b128 v165, v[204:207] offset:46080
	s_waitcnt vmcnt(8)
	ds_write_b128 v165, v[208:211] offset:50688
	v_mfma_f32_16x16x32_bf16 v[18:21], v[220:223], v[228:231], v[18:21]
	v_mfma_f32_16x16x32_bf16 v[22:25], v[220:223], v[236:239], v[22:25]
	v_mfma_f32_16x16x32_bf16 v[2:5], v[220:223], v[240:243], v[2:5]
	v_mfma_f32_16x16x32_bf16 v[6:9], v[220:223], v[252:255], v[6:9]
	s_waitcnt lgkmcnt(4)
	v_mfma_f32_16x16x32_bf16 v[26:29], v[224:227], v[228:231], v[26:29]
	v_mfma_f32_16x16x32_bf16 v[30:33], v[224:227], v[236:239], v[30:33]
	v_mfma_f32_16x16x32_bf16 v[10:13], v[224:227], v[240:243], v[10:13]
	v_mfma_f32_16x16x32_bf16 v[14:17], v[224:227], v[252:255], v[14:17]
	s_waitcnt lgkmcnt(0)
	s_barrier
	s_setprio 0
	ds_read_b128 v[228:231], v245 offset:36864
	ds_read_b128 v[212:215], v244
	ds_read_b128 v[236:239], v245 offset:39168
	ds_read_b128 v[240:243], v245 offset:41472
	ds_read_b128 v[252:255], v245 offset:43776
	ds_read_b128 v[216:219], v244 offset:2304
	ds_read_b128 v[220:223], v244 offset:4608
	ds_read_b128 v[224:227], v244 offset:6912
	global_load_dwordx4 v[180:183], v[70:71], off offset:512
	global_load_dwordx4 v[184:187], v[68:69], off offset:512
	global_load_dwordx4 v[188:191], v[66:67], off offset:512
	global_load_dwordx4 v[192:195], v[72:73], off offset:512
	global_load_dwordx4 v[196:199], v[74:75], off offset:512
	global_load_dwordx4 v[200:203], v[76:77], off offset:512
	global_load_dwordx4 v[204:207], v[78:79], off offset:512
	global_load_dwordx4 v[208:211], v[80:81], off offset:512
	s_waitcnt lgkmcnt(6)
	v_mfma_f32_16x16x32_bf16 v[50:53], v[212:215], v[228:231], v[50:53]
	s_waitcnt lgkmcnt(5)
	v_mfma_f32_16x16x32_bf16 v[54:57], v[212:215], v[236:239], v[54:57]
	s_waitcnt lgkmcnt(4)
	v_mfma_f32_16x16x32_bf16 v[34:37], v[212:215], v[240:243], v[34:37]
	s_waitcnt lgkmcnt(3)
	v_mfma_f32_16x16x32_bf16 v[38:41], v[212:215], v[252:255], v[38:41]
	ds_read_b128 v[212:215], v244 offset:64
	s_waitcnt lgkmcnt(3)
	v_mfma_f32_16x16x32_bf16 v[58:61], v[216:219], v[228:231], v[58:61]
	v_mfma_f32_16x16x32_bf16 v[62:65], v[216:219], v[236:239], v[62:65]
	v_mfma_f32_16x16x32_bf16 v[42:45], v[216:219], v[240:243], v[42:45]
	v_mfma_f32_16x16x32_bf16 v[46:49], v[216:219], v[252:255], v[46:49]
	ds_read_b128 v[216:219], v244 offset:2368
	s_setprio 1
	s_waitcnt vmcnt(15)
	ds_write_b128 v165, v[122:125] offset:18432
	s_waitcnt vmcnt(14)
	ds_write_b128 v165, v[126:129] offset:23040
	s_waitcnt lgkmcnt(5)
	v_mfma_f32_16x16x32_bf16 v[18:21], v[220:223], v[228:231], v[18:21]
	v_mfma_f32_16x16x32_bf16 v[22:25], v[220:223], v[236:239], v[22:25]
	v_mfma_f32_16x16x32_bf16 v[2:5], v[220:223], v[240:243], v[2:5]
	v_mfma_f32_16x16x32_bf16 v[6:9], v[220:223], v[252:255], v[6:9]
	ds_read_b128 v[220:223], v244 offset:4672
	s_waitcnt vmcnt(13)
	ds_write_b128 v165, v[136:139] offset:27648
	s_waitcnt vmcnt(12)
	ds_write_b128 v165, v[140:143] offset:32256
	s_waitcnt lgkmcnt(7)
	v_mfma_f32_16x16x32_bf16 v[26:29], v[224:227], v[228:231], v[26:29]
	ds_read_b128 v[228:231], v245 offset:36928
	v_mfma_f32_16x16x32_bf16 v[30:33], v[224:227], v[236:239], v[30:33]
	ds_read_b128 v[236:239], v245 offset:39232
	v_mfma_f32_16x16x32_bf16 v[10:13], v[224:227], v[240:243], v[10:13]
	ds_read_b128 v[240:243], v245 offset:41536
	v_mfma_f32_16x16x32_bf16 v[14:17], v[224:227], v[252:255], v[14:17]
	ds_read_b128 v[252:255], v245 offset:43840
	ds_read_b128 v[224:227], v244 offset:6976
	s_waitcnt lgkmcnt(4)
	v_mfma_f32_16x16x32_bf16 v[50:53], v[212:215], v[228:231], v[50:53]
	s_waitcnt lgkmcnt(3)
	v_mfma_f32_16x16x32_bf16 v[54:57], v[212:215], v[236:239], v[54:57]
	s_waitcnt lgkmcnt(2)
	v_mfma_f32_16x16x32_bf16 v[34:37], v[212:215], v[240:243], v[34:37]
	s_waitcnt lgkmcnt(1)
	v_mfma_f32_16x16x32_bf16 v[38:41], v[212:215], v[252:255], v[38:41]
	s_waitcnt vmcnt(11)
	ds_write_b128 v165, v[144:147] offset:55296
	s_waitcnt vmcnt(10)
	ds_write_b128 v165, v[148:151] offset:59904
	v_mfma_f32_16x16x32_bf16 v[58:61], v[216:219], v[228:231], v[58:61]
	v_mfma_f32_16x16x32_bf16 v[62:65], v[216:219], v[236:239], v[62:65]
	v_mfma_f32_16x16x32_bf16 v[42:45], v[216:219], v[240:243], v[42:45]
	v_mfma_f32_16x16x32_bf16 v[46:49], v[216:219], v[252:255], v[46:49]
	s_waitcnt vmcnt(9)
	ds_write_b128 v165, v[172:175] offset:64512
	s_waitcnt vmcnt(8)
	ds_write_b128 v166, v[176:179] offset:32256
	v_mfma_f32_16x16x32_bf16 v[18:21], v[220:223], v[228:231], v[18:21]
	v_mfma_f32_16x16x32_bf16 v[22:25], v[220:223], v[236:239], v[22:25]
	v_mfma_f32_16x16x32_bf16 v[2:5], v[220:223], v[240:243], v[2:5]
	v_mfma_f32_16x16x32_bf16 v[6:9], v[220:223], v[252:255], v[6:9]
	s_waitcnt lgkmcnt(4)
	v_mfma_f32_16x16x32_bf16 v[26:29], v[224:227], v[228:231], v[26:29]
	v_mfma_f32_16x16x32_bf16 v[30:33], v[224:227], v[236:239], v[30:33]
	v_mfma_f32_16x16x32_bf16 v[10:13], v[224:227], v[240:243], v[10:13]
	v_mfma_f32_16x16x32_bf16 v[14:17], v[224:227], v[252:255], v[14:17]
	s_waitcnt lgkmcnt(0)
	s_barrier
	s_setprio 0
	ds_read_b128 v[228:231], v245 offset:55296
	ds_read_b128 v[212:215], v244 offset:18432
	ds_read_b128 v[236:239], v245 offset:57600
	ds_read_b128 v[240:243], v245 offset:59904
	ds_read_b128 v[252:255], v245 offset:62208
	ds_read_b128 v[216:219], v244 offset:20736
	ds_read_b128 v[220:223], v244 offset:23040
	ds_read_b128 v[224:227], v244 offset:25344
	global_load_dwordx4 v[122:125], v[70:71], off offset:640
	global_load_dwordx4 v[126:129], v[68:69], off offset:640
	global_load_dwordx4 v[136:139], v[66:67], off offset:640
	global_load_dwordx4 v[140:143], v[72:73], off offset:640
	global_load_dwordx4 v[144:147], v[74:75], off offset:640
	global_load_dwordx4 v[148:151], v[76:77], off offset:640
	global_load_dwordx4 v[172:175], v[78:79], off offset:640
	global_load_dwordx4 v[176:179], v[80:81], off offset:640
	s_waitcnt lgkmcnt(6)
	v_mfma_f32_16x16x32_bf16 v[50:53], v[212:215], v[228:231], v[50:53]
	s_waitcnt lgkmcnt(5)
	v_mfma_f32_16x16x32_bf16 v[54:57], v[212:215], v[236:239], v[54:57]
	s_waitcnt lgkmcnt(4)
	v_mfma_f32_16x16x32_bf16 v[34:37], v[212:215], v[240:243], v[34:37]
	s_waitcnt lgkmcnt(3)
	v_mfma_f32_16x16x32_bf16 v[38:41], v[212:215], v[252:255], v[38:41]
	ds_read_b128 v[212:215], v244 offset:18496
	s_waitcnt lgkmcnt(3)
	v_mfma_f32_16x16x32_bf16 v[58:61], v[216:219], v[228:231], v[58:61]
	v_mfma_f32_16x16x32_bf16 v[62:65], v[216:219], v[236:239], v[62:65]
	v_mfma_f32_16x16x32_bf16 v[42:45], v[216:219], v[240:243], v[42:45]
	v_mfma_f32_16x16x32_bf16 v[46:49], v[216:219], v[252:255], v[46:49]
	ds_read_b128 v[216:219], v244 offset:20800
	s_setprio 1
	s_waitcnt vmcnt(15)
	ds_write_b128 v165, v[180:183]
	s_waitcnt vmcnt(14)
	ds_write_b128 v165, v[184:187] offset:4608
	s_waitcnt lgkmcnt(5)
	v_mfma_f32_16x16x32_bf16 v[18:21], v[220:223], v[228:231], v[18:21]
	v_mfma_f32_16x16x32_bf16 v[22:25], v[220:223], v[236:239], v[22:25]
	v_mfma_f32_16x16x32_bf16 v[2:5], v[220:223], v[240:243], v[2:5]
	v_mfma_f32_16x16x32_bf16 v[6:9], v[220:223], v[252:255], v[6:9]
	ds_read_b128 v[220:223], v244 offset:23104
	s_waitcnt vmcnt(13)
	ds_write_b128 v165, v[188:191] offset:9216
	s_waitcnt vmcnt(12)
	ds_write_b128 v165, v[192:195] offset:13824
	s_waitcnt lgkmcnt(7)
	v_mfma_f32_16x16x32_bf16 v[26:29], v[224:227], v[228:231], v[26:29]
	ds_read_b128 v[228:231], v245 offset:55360
	v_mfma_f32_16x16x32_bf16 v[30:33], v[224:227], v[236:239], v[30:33]
	ds_read_b128 v[236:239], v245 offset:57664
	v_mfma_f32_16x16x32_bf16 v[10:13], v[224:227], v[240:243], v[10:13]
	ds_read_b128 v[240:243], v245 offset:59968
	v_mfma_f32_16x16x32_bf16 v[14:17], v[224:227], v[252:255], v[14:17]
	ds_read_b128 v[252:255], v245 offset:62272
	ds_read_b128 v[224:227], v244 offset:25408
	s_waitcnt lgkmcnt(4)
	v_mfma_f32_16x16x32_bf16 v[50:53], v[212:215], v[228:231], v[50:53]
	s_waitcnt lgkmcnt(3)
	v_mfma_f32_16x16x32_bf16 v[54:57], v[212:215], v[236:239], v[54:57]
	s_waitcnt lgkmcnt(2)
	v_mfma_f32_16x16x32_bf16 v[34:37], v[212:215], v[240:243], v[34:37]
	s_waitcnt lgkmcnt(1)
	v_mfma_f32_16x16x32_bf16 v[38:41], v[212:215], v[252:255], v[38:41]
	s_waitcnt vmcnt(11)
	ds_write_b128 v165, v[196:199] offset:36864
	s_waitcnt vmcnt(10)
	ds_write_b128 v165, v[200:203] offset:41472
	v_mfma_f32_16x16x32_bf16 v[58:61], v[216:219], v[228:231], v[58:61]
	v_mfma_f32_16x16x32_bf16 v[62:65], v[216:219], v[236:239], v[62:65]
	v_mfma_f32_16x16x32_bf16 v[42:45], v[216:219], v[240:243], v[42:45]
	v_mfma_f32_16x16x32_bf16 v[46:49], v[216:219], v[252:255], v[46:49]
	s_waitcnt vmcnt(9)
	ds_write_b128 v165, v[204:207] offset:46080
	s_waitcnt vmcnt(8)
	ds_write_b128 v165, v[208:211] offset:50688
	v_mfma_f32_16x16x32_bf16 v[18:21], v[220:223], v[228:231], v[18:21]
	v_mfma_f32_16x16x32_bf16 v[22:25], v[220:223], v[236:239], v[22:25]
	v_mfma_f32_16x16x32_bf16 v[2:5], v[220:223], v[240:243], v[2:5]
	v_mfma_f32_16x16x32_bf16 v[6:9], v[220:223], v[252:255], v[6:9]
	s_waitcnt lgkmcnt(4)
	v_mfma_f32_16x16x32_bf16 v[26:29], v[224:227], v[228:231], v[26:29]
	v_mfma_f32_16x16x32_bf16 v[30:33], v[224:227], v[236:239], v[30:33]
	v_mfma_f32_16x16x32_bf16 v[10:13], v[224:227], v[240:243], v[10:13]
	v_mfma_f32_16x16x32_bf16 v[14:17], v[224:227], v[252:255], v[14:17]
	s_waitcnt lgkmcnt(0)
	s_barrier
	s_setprio 0
	ds_read_b128 v[228:231], v245 offset:36864
	ds_read_b128 v[212:215], v244
	ds_read_b128 v[236:239], v245 offset:39168
	ds_read_b128 v[240:243], v245 offset:41472
	ds_read_b128 v[252:255], v245 offset:43776
	ds_read_b128 v[216:219], v244 offset:2304
	ds_read_b128 v[220:223], v244 offset:4608
	ds_read_b128 v[224:227], v244 offset:6912
	global_load_dwordx4 v[180:183], v[70:71], off offset:768
	global_load_dwordx4 v[184:187], v[68:69], off offset:768
	global_load_dwordx4 v[188:191], v[66:67], off offset:768
	global_load_dwordx4 v[192:195], v[72:73], off offset:768
	global_load_dwordx4 v[196:199], v[74:75], off offset:768
	global_load_dwordx4 v[200:203], v[76:77], off offset:768
	global_load_dwordx4 v[204:207], v[78:79], off offset:768
	global_load_dwordx4 v[208:211], v[80:81], off offset:768
	s_waitcnt lgkmcnt(6)
	v_mfma_f32_16x16x32_bf16 v[50:53], v[212:215], v[228:231], v[50:53]
	s_waitcnt lgkmcnt(5)
	v_mfma_f32_16x16x32_bf16 v[54:57], v[212:215], v[236:239], v[54:57]
	s_waitcnt lgkmcnt(4)
	v_mfma_f32_16x16x32_bf16 v[34:37], v[212:215], v[240:243], v[34:37]
	s_waitcnt lgkmcnt(3)
	v_mfma_f32_16x16x32_bf16 v[38:41], v[212:215], v[252:255], v[38:41]
	ds_read_b128 v[212:215], v244 offset:64
	s_waitcnt lgkmcnt(3)
	v_mfma_f32_16x16x32_bf16 v[58:61], v[216:219], v[228:231], v[58:61]
	v_mfma_f32_16x16x32_bf16 v[62:65], v[216:219], v[236:239], v[62:65]
	v_mfma_f32_16x16x32_bf16 v[42:45], v[216:219], v[240:243], v[42:45]
	v_mfma_f32_16x16x32_bf16 v[46:49], v[216:219], v[252:255], v[46:49]
	ds_read_b128 v[216:219], v244 offset:2368
	s_setprio 1
	s_waitcnt vmcnt(15)
	ds_write_b128 v165, v[122:125] offset:18432
	s_waitcnt vmcnt(14)
	ds_write_b128 v165, v[126:129] offset:23040
	s_waitcnt lgkmcnt(5)
	v_mfma_f32_16x16x32_bf16 v[18:21], v[220:223], v[228:231], v[18:21]
	v_mfma_f32_16x16x32_bf16 v[22:25], v[220:223], v[236:239], v[22:25]
	v_mfma_f32_16x16x32_bf16 v[2:5], v[220:223], v[240:243], v[2:5]
	v_mfma_f32_16x16x32_bf16 v[6:9], v[220:223], v[252:255], v[6:9]
	ds_read_b128 v[220:223], v244 offset:4672
	s_waitcnt vmcnt(13)
	ds_write_b128 v165, v[136:139] offset:27648
	s_waitcnt vmcnt(12)
	ds_write_b128 v165, v[140:143] offset:32256
	s_waitcnt lgkmcnt(7)
	v_mfma_f32_16x16x32_bf16 v[26:29], v[224:227], v[228:231], v[26:29]
	ds_read_b128 v[228:231], v245 offset:36928
	v_mfma_f32_16x16x32_bf16 v[30:33], v[224:227], v[236:239], v[30:33]
	ds_read_b128 v[236:239], v245 offset:39232
	v_mfma_f32_16x16x32_bf16 v[10:13], v[224:227], v[240:243], v[10:13]
	ds_read_b128 v[240:243], v245 offset:41536
	v_mfma_f32_16x16x32_bf16 v[14:17], v[224:227], v[252:255], v[14:17]
	ds_read_b128 v[252:255], v245 offset:43840
	ds_read_b128 v[224:227], v244 offset:6976
	s_waitcnt lgkmcnt(4)
	v_mfma_f32_16x16x32_bf16 v[50:53], v[212:215], v[228:231], v[50:53]
	s_waitcnt lgkmcnt(3)
	v_mfma_f32_16x16x32_bf16 v[54:57], v[212:215], v[236:239], v[54:57]
	s_waitcnt lgkmcnt(2)
	v_mfma_f32_16x16x32_bf16 v[34:37], v[212:215], v[240:243], v[34:37]
	s_waitcnt lgkmcnt(1)
	v_mfma_f32_16x16x32_bf16 v[38:41], v[212:215], v[252:255], v[38:41]
	s_waitcnt vmcnt(11)
	ds_write_b128 v165, v[144:147] offset:55296
	s_waitcnt vmcnt(10)
	ds_write_b128 v165, v[148:151] offset:59904
	v_mfma_f32_16x16x32_bf16 v[58:61], v[216:219], v[228:231], v[58:61]
	v_mfma_f32_16x16x32_bf16 v[62:65], v[216:219], v[236:239], v[62:65]
	v_mfma_f32_16x16x32_bf16 v[42:45], v[216:219], v[240:243], v[42:45]
	v_mfma_f32_16x16x32_bf16 v[46:49], v[216:219], v[252:255], v[46:49]
	s_waitcnt vmcnt(9)
	ds_write_b128 v165, v[172:175] offset:64512
	s_waitcnt vmcnt(8)
	ds_write_b128 v166, v[176:179] offset:32256
	v_mfma_f32_16x16x32_bf16 v[18:21], v[220:223], v[228:231], v[18:21]
	v_mfma_f32_16x16x32_bf16 v[22:25], v[220:223], v[236:239], v[22:25]
	v_mfma_f32_16x16x32_bf16 v[2:5], v[220:223], v[240:243], v[2:5]
	v_mfma_f32_16x16x32_bf16 v[6:9], v[220:223], v[252:255], v[6:9]
	s_waitcnt lgkmcnt(4)
	v_mfma_f32_16x16x32_bf16 v[26:29], v[224:227], v[228:231], v[26:29]
	v_mfma_f32_16x16x32_bf16 v[30:33], v[224:227], v[236:239], v[30:33]
	v_mfma_f32_16x16x32_bf16 v[10:13], v[224:227], v[240:243], v[10:13]
	v_mfma_f32_16x16x32_bf16 v[14:17], v[224:227], v[252:255], v[14:17]
	s_waitcnt lgkmcnt(0)
	s_barrier
	s_setprio 0
	ds_read_b128 v[228:231], v245 offset:55296
	ds_read_b128 v[212:215], v244 offset:18432
	ds_read_b128 v[236:239], v245 offset:57600
	ds_read_b128 v[240:243], v245 offset:59904
	ds_read_b128 v[252:255], v245 offset:62208
	ds_read_b128 v[216:219], v244 offset:20736
	ds_read_b128 v[220:223], v244 offset:23040
	ds_read_b128 v[224:227], v244 offset:25344
	global_load_dwordx4 v[122:125], v[70:71], off offset:896
	global_load_dwordx4 v[126:129], v[68:69], off offset:896
	global_load_dwordx4 v[136:139], v[66:67], off offset:896
	global_load_dwordx4 v[140:143], v[72:73], off offset:896
	global_load_dwordx4 v[144:147], v[74:75], off offset:896
	global_load_dwordx4 v[148:151], v[76:77], off offset:896
	global_load_dwordx4 v[172:175], v[78:79], off offset:896
	global_load_dwordx4 v[176:179], v[80:81], off offset:896
	s_waitcnt lgkmcnt(6)
	v_mfma_f32_16x16x32_bf16 v[50:53], v[212:215], v[228:231], v[50:53]
	s_waitcnt lgkmcnt(5)
	v_mfma_f32_16x16x32_bf16 v[54:57], v[212:215], v[236:239], v[54:57]
	s_waitcnt lgkmcnt(4)
	v_mfma_f32_16x16x32_bf16 v[34:37], v[212:215], v[240:243], v[34:37]
	s_waitcnt lgkmcnt(3)
	v_mfma_f32_16x16x32_bf16 v[38:41], v[212:215], v[252:255], v[38:41]
	ds_read_b128 v[212:215], v244 offset:18496
	s_waitcnt lgkmcnt(3)
	v_mfma_f32_16x16x32_bf16 v[58:61], v[216:219], v[228:231], v[58:61]
	v_mfma_f32_16x16x32_bf16 v[62:65], v[216:219], v[236:239], v[62:65]
	v_mfma_f32_16x16x32_bf16 v[42:45], v[216:219], v[240:243], v[42:45]
	v_mfma_f32_16x16x32_bf16 v[46:49], v[216:219], v[252:255], v[46:49]
	ds_read_b128 v[216:219], v244 offset:20800
	s_setprio 1
	s_waitcnt vmcnt(15)
	ds_write_b128 v165, v[180:183]
	s_waitcnt vmcnt(14)
	ds_write_b128 v165, v[184:187] offset:4608
	s_waitcnt lgkmcnt(5)
	v_mfma_f32_16x16x32_bf16 v[18:21], v[220:223], v[228:231], v[18:21]
	v_mfma_f32_16x16x32_bf16 v[22:25], v[220:223], v[236:239], v[22:25]
	v_mfma_f32_16x16x32_bf16 v[2:5], v[220:223], v[240:243], v[2:5]
	v_mfma_f32_16x16x32_bf16 v[6:9], v[220:223], v[252:255], v[6:9]
	ds_read_b128 v[220:223], v244 offset:23104
	s_waitcnt vmcnt(13)
	ds_write_b128 v165, v[188:191] offset:9216
	s_waitcnt vmcnt(12)
	ds_write_b128 v165, v[192:195] offset:13824
	s_waitcnt lgkmcnt(7)
	v_mfma_f32_16x16x32_bf16 v[26:29], v[224:227], v[228:231], v[26:29]
	ds_read_b128 v[228:231], v245 offset:55360
	v_mfma_f32_16x16x32_bf16 v[30:33], v[224:227], v[236:239], v[30:33]
	ds_read_b128 v[236:239], v245 offset:57664
	v_mfma_f32_16x16x32_bf16 v[10:13], v[224:227], v[240:243], v[10:13]
	ds_read_b128 v[240:243], v245 offset:59968
	v_mfma_f32_16x16x32_bf16 v[14:17], v[224:227], v[252:255], v[14:17]
	ds_read_b128 v[252:255], v245 offset:62272
	ds_read_b128 v[224:227], v244 offset:25408
	s_waitcnt lgkmcnt(4)
	v_mfma_f32_16x16x32_bf16 v[50:53], v[212:215], v[228:231], v[50:53]
	s_waitcnt lgkmcnt(3)
	v_mfma_f32_16x16x32_bf16 v[54:57], v[212:215], v[236:239], v[54:57]
	s_waitcnt lgkmcnt(2)
	v_mfma_f32_16x16x32_bf16 v[34:37], v[212:215], v[240:243], v[34:37]
	s_waitcnt lgkmcnt(1)
	v_mfma_f32_16x16x32_bf16 v[38:41], v[212:215], v[252:255], v[38:41]
	s_waitcnt vmcnt(11)
	ds_write_b128 v165, v[196:199] offset:36864
	s_waitcnt vmcnt(10)
	ds_write_b128 v165, v[200:203] offset:41472
	v_mfma_f32_16x16x32_bf16 v[58:61], v[216:219], v[228:231], v[58:61]
	v_mfma_f32_16x16x32_bf16 v[62:65], v[216:219], v[236:239], v[62:65]
	v_mfma_f32_16x16x32_bf16 v[42:45], v[216:219], v[240:243], v[42:45]
	v_mfma_f32_16x16x32_bf16 v[46:49], v[216:219], v[252:255], v[46:49]
	s_waitcnt vmcnt(9)
	ds_write_b128 v165, v[204:207] offset:46080
	s_waitcnt vmcnt(8)
	ds_write_b128 v165, v[208:211] offset:50688
	v_mfma_f32_16x16x32_bf16 v[18:21], v[220:223], v[228:231], v[18:21]
	v_mfma_f32_16x16x32_bf16 v[22:25], v[220:223], v[236:239], v[22:25]
	v_mfma_f32_16x16x32_bf16 v[2:5], v[220:223], v[240:243], v[2:5]
	v_mfma_f32_16x16x32_bf16 v[6:9], v[220:223], v[252:255], v[6:9]
	s_waitcnt lgkmcnt(4)
	v_mfma_f32_16x16x32_bf16 v[26:29], v[224:227], v[228:231], v[26:29]
	v_mfma_f32_16x16x32_bf16 v[30:33], v[224:227], v[236:239], v[30:33]
	v_mfma_f32_16x16x32_bf16 v[10:13], v[224:227], v[240:243], v[10:13]
	v_mfma_f32_16x16x32_bf16 v[14:17], v[224:227], v[252:255], v[14:17]
	s_waitcnt lgkmcnt(0)
	s_barrier
	s_setprio 0
	ds_read_b128 v[228:231], v245 offset:36864
	ds_read_b128 v[212:215], v244
	ds_read_b128 v[236:239], v245 offset:39168
	ds_read_b128 v[240:243], v245 offset:41472
	ds_read_b128 v[252:255], v245 offset:43776
	ds_read_b128 v[216:219], v244 offset:2304
	ds_read_b128 v[220:223], v244 offset:4608
	ds_read_b128 v[224:227], v244 offset:6912
	global_load_dwordx4 v[180:183], v[70:71], off offset:1024
	global_load_dwordx4 v[184:187], v[68:69], off offset:1024
	global_load_dwordx4 v[188:191], v[66:67], off offset:1024
	global_load_dwordx4 v[192:195], v[72:73], off offset:1024
	global_load_dwordx4 v[196:199], v[74:75], off offset:1024
	global_load_dwordx4 v[200:203], v[76:77], off offset:1024
	global_load_dwordx4 v[204:207], v[78:79], off offset:1024
	global_load_dwordx4 v[208:211], v[80:81], off offset:1024
	s_waitcnt lgkmcnt(6)
	v_mfma_f32_16x16x32_bf16 v[50:53], v[212:215], v[228:231], v[50:53]
	s_waitcnt lgkmcnt(5)
	v_mfma_f32_16x16x32_bf16 v[54:57], v[212:215], v[236:239], v[54:57]
	s_waitcnt lgkmcnt(4)
	v_mfma_f32_16x16x32_bf16 v[34:37], v[212:215], v[240:243], v[34:37]
	s_waitcnt lgkmcnt(3)
	v_mfma_f32_16x16x32_bf16 v[38:41], v[212:215], v[252:255], v[38:41]
	ds_read_b128 v[212:215], v244 offset:64
	s_waitcnt lgkmcnt(3)
	v_mfma_f32_16x16x32_bf16 v[58:61], v[216:219], v[228:231], v[58:61]
	v_mfma_f32_16x16x32_bf16 v[62:65], v[216:219], v[236:239], v[62:65]
	v_mfma_f32_16x16x32_bf16 v[42:45], v[216:219], v[240:243], v[42:45]
	v_mfma_f32_16x16x32_bf16 v[46:49], v[216:219], v[252:255], v[46:49]
	ds_read_b128 v[216:219], v244 offset:2368
	s_setprio 1
	s_waitcnt vmcnt(15)
	ds_write_b128 v165, v[122:125] offset:18432
	s_waitcnt vmcnt(14)
	ds_write_b128 v165, v[126:129] offset:23040
	s_waitcnt lgkmcnt(5)
	v_mfma_f32_16x16x32_bf16 v[18:21], v[220:223], v[228:231], v[18:21]
	v_mfma_f32_16x16x32_bf16 v[22:25], v[220:223], v[236:239], v[22:25]
	v_mfma_f32_16x16x32_bf16 v[2:5], v[220:223], v[240:243], v[2:5]
	v_mfma_f32_16x16x32_bf16 v[6:9], v[220:223], v[252:255], v[6:9]
	ds_read_b128 v[220:223], v244 offset:4672
	s_waitcnt vmcnt(13)
	ds_write_b128 v165, v[136:139] offset:27648
	s_waitcnt vmcnt(12)
	ds_write_b128 v165, v[140:143] offset:32256
	s_waitcnt lgkmcnt(7)
	v_mfma_f32_16x16x32_bf16 v[26:29], v[224:227], v[228:231], v[26:29]
	ds_read_b128 v[228:231], v245 offset:36928
	v_mfma_f32_16x16x32_bf16 v[30:33], v[224:227], v[236:239], v[30:33]
	ds_read_b128 v[236:239], v245 offset:39232
	v_mfma_f32_16x16x32_bf16 v[10:13], v[224:227], v[240:243], v[10:13]
	ds_read_b128 v[240:243], v245 offset:41536
	v_mfma_f32_16x16x32_bf16 v[14:17], v[224:227], v[252:255], v[14:17]
	ds_read_b128 v[252:255], v245 offset:43840
	ds_read_b128 v[224:227], v244 offset:6976
	s_waitcnt lgkmcnt(4)
	v_mfma_f32_16x16x32_bf16 v[50:53], v[212:215], v[228:231], v[50:53]
	s_waitcnt lgkmcnt(3)
	v_mfma_f32_16x16x32_bf16 v[54:57], v[212:215], v[236:239], v[54:57]
	s_waitcnt lgkmcnt(2)
	v_mfma_f32_16x16x32_bf16 v[34:37], v[212:215], v[240:243], v[34:37]
	s_waitcnt lgkmcnt(1)
	v_mfma_f32_16x16x32_bf16 v[38:41], v[212:215], v[252:255], v[38:41]
	s_waitcnt vmcnt(11)
	ds_write_b128 v165, v[144:147] offset:55296
	s_waitcnt vmcnt(10)
	ds_write_b128 v165, v[148:151] offset:59904
	v_mfma_f32_16x16x32_bf16 v[58:61], v[216:219], v[228:231], v[58:61]
	v_mfma_f32_16x16x32_bf16 v[62:65], v[216:219], v[236:239], v[62:65]
	v_mfma_f32_16x16x32_bf16 v[42:45], v[216:219], v[240:243], v[42:45]
	v_mfma_f32_16x16x32_bf16 v[46:49], v[216:219], v[252:255], v[46:49]
	s_waitcnt vmcnt(9)
	ds_write_b128 v165, v[172:175] offset:64512
	s_waitcnt vmcnt(8)
	ds_write_b128 v166, v[176:179] offset:32256
	v_mfma_f32_16x16x32_bf16 v[18:21], v[220:223], v[228:231], v[18:21]
	v_mfma_f32_16x16x32_bf16 v[22:25], v[220:223], v[236:239], v[22:25]
	v_mfma_f32_16x16x32_bf16 v[2:5], v[220:223], v[240:243], v[2:5]
	v_mfma_f32_16x16x32_bf16 v[6:9], v[220:223], v[252:255], v[6:9]
	s_waitcnt lgkmcnt(4)
	v_mfma_f32_16x16x32_bf16 v[26:29], v[224:227], v[228:231], v[26:29]
	v_mfma_f32_16x16x32_bf16 v[30:33], v[224:227], v[236:239], v[30:33]
	v_mfma_f32_16x16x32_bf16 v[10:13], v[224:227], v[240:243], v[10:13]
	v_mfma_f32_16x16x32_bf16 v[14:17], v[224:227], v[252:255], v[14:17]
	s_waitcnt lgkmcnt(0)
	s_barrier
	s_setprio 0
	ds_read_b128 v[228:231], v245 offset:55296
	ds_read_b128 v[212:215], v244 offset:18432
	ds_read_b128 v[236:239], v245 offset:57600
	ds_read_b128 v[240:243], v245 offset:59904
	ds_read_b128 v[252:255], v245 offset:62208
	ds_read_b128 v[216:219], v244 offset:20736
	ds_read_b128 v[220:223], v244 offset:23040
	ds_read_b128 v[224:227], v244 offset:25344
	global_load_dwordx4 v[122:125], v[70:71], off offset:1152
	global_load_dwordx4 v[126:129], v[68:69], off offset:1152
	global_load_dwordx4 v[136:139], v[66:67], off offset:1152
	global_load_dwordx4 v[140:143], v[72:73], off offset:1152
	global_load_dwordx4 v[144:147], v[74:75], off offset:1152
	global_load_dwordx4 v[148:151], v[76:77], off offset:1152
	global_load_dwordx4 v[172:175], v[78:79], off offset:1152
	global_load_dwordx4 v[176:179], v[80:81], off offset:1152
	s_waitcnt lgkmcnt(6)
	v_mfma_f32_16x16x32_bf16 v[50:53], v[212:215], v[228:231], v[50:53]
	s_waitcnt lgkmcnt(5)
	v_mfma_f32_16x16x32_bf16 v[54:57], v[212:215], v[236:239], v[54:57]
	s_waitcnt lgkmcnt(4)
	v_mfma_f32_16x16x32_bf16 v[34:37], v[212:215], v[240:243], v[34:37]
	s_waitcnt lgkmcnt(3)
	v_mfma_f32_16x16x32_bf16 v[38:41], v[212:215], v[252:255], v[38:41]
	ds_read_b128 v[212:215], v244 offset:18496
	s_waitcnt lgkmcnt(3)
	v_mfma_f32_16x16x32_bf16 v[58:61], v[216:219], v[228:231], v[58:61]
	v_mfma_f32_16x16x32_bf16 v[62:65], v[216:219], v[236:239], v[62:65]
	v_mfma_f32_16x16x32_bf16 v[42:45], v[216:219], v[240:243], v[42:45]
	v_mfma_f32_16x16x32_bf16 v[46:49], v[216:219], v[252:255], v[46:49]
	ds_read_b128 v[216:219], v244 offset:20800
	s_setprio 1
	s_waitcnt vmcnt(15)
	ds_write_b128 v165, v[180:183]
	s_waitcnt vmcnt(14)
	ds_write_b128 v165, v[184:187] offset:4608
	s_waitcnt lgkmcnt(5)
	v_mfma_f32_16x16x32_bf16 v[18:21], v[220:223], v[228:231], v[18:21]
	v_mfma_f32_16x16x32_bf16 v[22:25], v[220:223], v[236:239], v[22:25]
	v_mfma_f32_16x16x32_bf16 v[2:5], v[220:223], v[240:243], v[2:5]
	v_mfma_f32_16x16x32_bf16 v[6:9], v[220:223], v[252:255], v[6:9]
	ds_read_b128 v[220:223], v244 offset:23104
	s_waitcnt vmcnt(13)
	ds_write_b128 v165, v[188:191] offset:9216
	s_waitcnt vmcnt(12)
	ds_write_b128 v165, v[192:195] offset:13824
	s_waitcnt lgkmcnt(7)
	v_mfma_f32_16x16x32_bf16 v[26:29], v[224:227], v[228:231], v[26:29]
	ds_read_b128 v[228:231], v245 offset:55360
	v_mfma_f32_16x16x32_bf16 v[30:33], v[224:227], v[236:239], v[30:33]
	ds_read_b128 v[236:239], v245 offset:57664
	v_mfma_f32_16x16x32_bf16 v[10:13], v[224:227], v[240:243], v[10:13]
	ds_read_b128 v[240:243], v245 offset:59968
	v_mfma_f32_16x16x32_bf16 v[14:17], v[224:227], v[252:255], v[14:17]
	ds_read_b128 v[252:255], v245 offset:62272
	ds_read_b128 v[224:227], v244 offset:25408
	s_waitcnt lgkmcnt(4)
	v_mfma_f32_16x16x32_bf16 v[50:53], v[212:215], v[228:231], v[50:53]
	s_waitcnt lgkmcnt(3)
	v_mfma_f32_16x16x32_bf16 v[54:57], v[212:215], v[236:239], v[54:57]
	s_waitcnt lgkmcnt(2)
	v_mfma_f32_16x16x32_bf16 v[34:37], v[212:215], v[240:243], v[34:37]
	s_waitcnt lgkmcnt(1)
	v_mfma_f32_16x16x32_bf16 v[38:41], v[212:215], v[252:255], v[38:41]
	s_waitcnt vmcnt(11)
	ds_write_b128 v165, v[196:199] offset:36864
	s_waitcnt vmcnt(10)
	ds_write_b128 v165, v[200:203] offset:41472
	v_mfma_f32_16x16x32_bf16 v[58:61], v[216:219], v[228:231], v[58:61]
	v_mfma_f32_16x16x32_bf16 v[62:65], v[216:219], v[236:239], v[62:65]
	v_mfma_f32_16x16x32_bf16 v[42:45], v[216:219], v[240:243], v[42:45]
	v_mfma_f32_16x16x32_bf16 v[46:49], v[216:219], v[252:255], v[46:49]
	s_waitcnt vmcnt(9)
	ds_write_b128 v165, v[204:207] offset:46080
	s_waitcnt vmcnt(8)
	ds_write_b128 v165, v[208:211] offset:50688
	v_mfma_f32_16x16x32_bf16 v[18:21], v[220:223], v[228:231], v[18:21]
	v_mfma_f32_16x16x32_bf16 v[22:25], v[220:223], v[236:239], v[22:25]
	v_mfma_f32_16x16x32_bf16 v[2:5], v[220:223], v[240:243], v[2:5]
	v_mfma_f32_16x16x32_bf16 v[6:9], v[220:223], v[252:255], v[6:9]
	s_waitcnt lgkmcnt(4)
	v_mfma_f32_16x16x32_bf16 v[26:29], v[224:227], v[228:231], v[26:29]
	v_mfma_f32_16x16x32_bf16 v[30:33], v[224:227], v[236:239], v[30:33]
	v_mfma_f32_16x16x32_bf16 v[10:13], v[224:227], v[240:243], v[10:13]
	v_mfma_f32_16x16x32_bf16 v[14:17], v[224:227], v[252:255], v[14:17]
	s_waitcnt lgkmcnt(0)
	s_barrier
	s_setprio 0
	ds_read_b128 v[228:231], v245 offset:36864
	ds_read_b128 v[212:215], v244
	ds_read_b128 v[236:239], v245 offset:39168
	ds_read_b128 v[240:243], v245 offset:41472
	ds_read_b128 v[252:255], v245 offset:43776
	ds_read_b128 v[216:219], v244 offset:2304
	ds_read_b128 v[220:223], v244 offset:4608
	ds_read_b128 v[224:227], v244 offset:6912
	global_load_dwordx4 v[180:183], v[70:71], off offset:1280
	global_load_dwordx4 v[184:187], v[68:69], off offset:1280
	global_load_dwordx4 v[188:191], v[66:67], off offset:1280
	global_load_dwordx4 v[192:195], v[72:73], off offset:1280
	global_load_dwordx4 v[196:199], v[74:75], off offset:1280
	global_load_dwordx4 v[200:203], v[76:77], off offset:1280
	global_load_dwordx4 v[204:207], v[78:79], off offset:1280
	global_load_dwordx4 v[208:211], v[80:81], off offset:1280
	s_waitcnt lgkmcnt(6)
	v_mfma_f32_16x16x32_bf16 v[50:53], v[212:215], v[228:231], v[50:53]
	s_waitcnt lgkmcnt(5)
	v_mfma_f32_16x16x32_bf16 v[54:57], v[212:215], v[236:239], v[54:57]
	s_waitcnt lgkmcnt(4)
	v_mfma_f32_16x16x32_bf16 v[34:37], v[212:215], v[240:243], v[34:37]
	s_waitcnt lgkmcnt(3)
	v_mfma_f32_16x16x32_bf16 v[38:41], v[212:215], v[252:255], v[38:41]
	ds_read_b128 v[212:215], v244 offset:64
	s_waitcnt lgkmcnt(3)
	v_mfma_f32_16x16x32_bf16 v[58:61], v[216:219], v[228:231], v[58:61]
	v_mfma_f32_16x16x32_bf16 v[62:65], v[216:219], v[236:239], v[62:65]
	v_mfma_f32_16x16x32_bf16 v[42:45], v[216:219], v[240:243], v[42:45]
	v_mfma_f32_16x16x32_bf16 v[46:49], v[216:219], v[252:255], v[46:49]
	ds_read_b128 v[216:219], v244 offset:2368
	s_setprio 1
	s_waitcnt vmcnt(15)
	ds_write_b128 v165, v[122:125] offset:18432
	s_waitcnt vmcnt(14)
	ds_write_b128 v165, v[126:129] offset:23040
	s_waitcnt lgkmcnt(5)
	v_mfma_f32_16x16x32_bf16 v[18:21], v[220:223], v[228:231], v[18:21]
	v_mfma_f32_16x16x32_bf16 v[22:25], v[220:223], v[236:239], v[22:25]
	v_mfma_f32_16x16x32_bf16 v[2:5], v[220:223], v[240:243], v[2:5]
	v_mfma_f32_16x16x32_bf16 v[6:9], v[220:223], v[252:255], v[6:9]
	ds_read_b128 v[220:223], v244 offset:4672
	s_waitcnt vmcnt(13)
	ds_write_b128 v165, v[136:139] offset:27648
	s_waitcnt vmcnt(12)
	ds_write_b128 v165, v[140:143] offset:32256
	s_waitcnt lgkmcnt(7)
	v_mfma_f32_16x16x32_bf16 v[26:29], v[224:227], v[228:231], v[26:29]
	ds_read_b128 v[228:231], v245 offset:36928
	v_mfma_f32_16x16x32_bf16 v[30:33], v[224:227], v[236:239], v[30:33]
	ds_read_b128 v[236:239], v245 offset:39232
	v_mfma_f32_16x16x32_bf16 v[10:13], v[224:227], v[240:243], v[10:13]
	ds_read_b128 v[240:243], v245 offset:41536
	v_mfma_f32_16x16x32_bf16 v[14:17], v[224:227], v[252:255], v[14:17]
	ds_read_b128 v[252:255], v245 offset:43840
	ds_read_b128 v[224:227], v244 offset:6976
	s_waitcnt lgkmcnt(4)
	v_mfma_f32_16x16x32_bf16 v[50:53], v[212:215], v[228:231], v[50:53]
	s_waitcnt lgkmcnt(3)
	v_mfma_f32_16x16x32_bf16 v[54:57], v[212:215], v[236:239], v[54:57]
	s_waitcnt lgkmcnt(2)
	v_mfma_f32_16x16x32_bf16 v[34:37], v[212:215], v[240:243], v[34:37]
	s_waitcnt lgkmcnt(1)
	v_mfma_f32_16x16x32_bf16 v[38:41], v[212:215], v[252:255], v[38:41]
	s_waitcnt vmcnt(11)
	ds_write_b128 v165, v[144:147] offset:55296
	s_waitcnt vmcnt(10)
	ds_write_b128 v165, v[148:151] offset:59904
	v_mfma_f32_16x16x32_bf16 v[58:61], v[216:219], v[228:231], v[58:61]
	v_mfma_f32_16x16x32_bf16 v[62:65], v[216:219], v[236:239], v[62:65]
	v_mfma_f32_16x16x32_bf16 v[42:45], v[216:219], v[240:243], v[42:45]
	v_mfma_f32_16x16x32_bf16 v[46:49], v[216:219], v[252:255], v[46:49]
	s_waitcnt vmcnt(9)
	ds_write_b128 v165, v[172:175] offset:64512
	s_waitcnt vmcnt(8)
	ds_write_b128 v166, v[176:179] offset:32256
	v_mfma_f32_16x16x32_bf16 v[18:21], v[220:223], v[228:231], v[18:21]
	v_mfma_f32_16x16x32_bf16 v[22:25], v[220:223], v[236:239], v[22:25]
	v_mfma_f32_16x16x32_bf16 v[2:5], v[220:223], v[240:243], v[2:5]
	v_mfma_f32_16x16x32_bf16 v[6:9], v[220:223], v[252:255], v[6:9]
	s_waitcnt lgkmcnt(4)
	v_mfma_f32_16x16x32_bf16 v[26:29], v[224:227], v[228:231], v[26:29]
	v_mfma_f32_16x16x32_bf16 v[30:33], v[224:227], v[236:239], v[30:33]
	v_mfma_f32_16x16x32_bf16 v[10:13], v[224:227], v[240:243], v[10:13]
	v_mfma_f32_16x16x32_bf16 v[14:17], v[224:227], v[252:255], v[14:17]
	s_waitcnt lgkmcnt(0)
	s_barrier
	s_setprio 0
	ds_read_b128 v[228:231], v245 offset:55296
	ds_read_b128 v[212:215], v244 offset:18432
	ds_read_b128 v[236:239], v245 offset:57600
	ds_read_b128 v[240:243], v245 offset:59904
	ds_read_b128 v[252:255], v245 offset:62208
	ds_read_b128 v[216:219], v244 offset:20736
	ds_read_b128 v[220:223], v244 offset:23040
	ds_read_b128 v[224:227], v244 offset:25344
	global_load_dwordx4 v[122:125], v[70:71], off offset:1408
	global_load_dwordx4 v[126:129], v[68:69], off offset:1408
	global_load_dwordx4 v[136:139], v[66:67], off offset:1408
	global_load_dwordx4 v[140:143], v[72:73], off offset:1408
	global_load_dwordx4 v[144:147], v[74:75], off offset:1408
	global_load_dwordx4 v[148:151], v[76:77], off offset:1408
	global_load_dwordx4 v[172:175], v[78:79], off offset:1408
	global_load_dwordx4 v[176:179], v[80:81], off offset:1408
	s_waitcnt lgkmcnt(6)
	v_mfma_f32_16x16x32_bf16 v[50:53], v[212:215], v[228:231], v[50:53]
	s_waitcnt lgkmcnt(5)
	v_mfma_f32_16x16x32_bf16 v[54:57], v[212:215], v[236:239], v[54:57]
	s_waitcnt lgkmcnt(4)
	v_mfma_f32_16x16x32_bf16 v[34:37], v[212:215], v[240:243], v[34:37]
	s_waitcnt lgkmcnt(3)
	v_mfma_f32_16x16x32_bf16 v[38:41], v[212:215], v[252:255], v[38:41]
	ds_read_b128 v[212:215], v244 offset:18496
	s_waitcnt lgkmcnt(3)
	v_mfma_f32_16x16x32_bf16 v[58:61], v[216:219], v[228:231], v[58:61]
	v_mfma_f32_16x16x32_bf16 v[62:65], v[216:219], v[236:239], v[62:65]
	v_mfma_f32_16x16x32_bf16 v[42:45], v[216:219], v[240:243], v[42:45]
	v_mfma_f32_16x16x32_bf16 v[46:49], v[216:219], v[252:255], v[46:49]
	ds_read_b128 v[216:219], v244 offset:20800
	s_setprio 1
	s_waitcnt vmcnt(15)
	ds_write_b128 v165, v[180:183]
	s_waitcnt vmcnt(14)
	ds_write_b128 v165, v[184:187] offset:4608
	s_waitcnt lgkmcnt(5)
	v_mfma_f32_16x16x32_bf16 v[18:21], v[220:223], v[228:231], v[18:21]
	v_mfma_f32_16x16x32_bf16 v[22:25], v[220:223], v[236:239], v[22:25]
	v_mfma_f32_16x16x32_bf16 v[2:5], v[220:223], v[240:243], v[2:5]
	v_mfma_f32_16x16x32_bf16 v[6:9], v[220:223], v[252:255], v[6:9]
	ds_read_b128 v[220:223], v244 offset:23104
	s_waitcnt vmcnt(13)
	ds_write_b128 v165, v[188:191] offset:9216
	s_waitcnt vmcnt(12)
	ds_write_b128 v165, v[192:195] offset:13824
	s_waitcnt lgkmcnt(7)
	v_mfma_f32_16x16x32_bf16 v[26:29], v[224:227], v[228:231], v[26:29]
	ds_read_b128 v[228:231], v245 offset:55360
	v_mfma_f32_16x16x32_bf16 v[30:33], v[224:227], v[236:239], v[30:33]
	ds_read_b128 v[236:239], v245 offset:57664
	v_mfma_f32_16x16x32_bf16 v[10:13], v[224:227], v[240:243], v[10:13]
	ds_read_b128 v[240:243], v245 offset:59968
	v_mfma_f32_16x16x32_bf16 v[14:17], v[224:227], v[252:255], v[14:17]
	ds_read_b128 v[252:255], v245 offset:62272
	ds_read_b128 v[224:227], v244 offset:25408
	s_waitcnt lgkmcnt(4)
	v_mfma_f32_16x16x32_bf16 v[50:53], v[212:215], v[228:231], v[50:53]
	s_waitcnt lgkmcnt(3)
	v_mfma_f32_16x16x32_bf16 v[54:57], v[212:215], v[236:239], v[54:57]
	s_waitcnt lgkmcnt(2)
	v_mfma_f32_16x16x32_bf16 v[34:37], v[212:215], v[240:243], v[34:37]
	s_waitcnt lgkmcnt(1)
	v_mfma_f32_16x16x32_bf16 v[38:41], v[212:215], v[252:255], v[38:41]
	s_waitcnt vmcnt(11)
	ds_write_b128 v165, v[196:199] offset:36864
	s_waitcnt vmcnt(10)
	ds_write_b128 v165, v[200:203] offset:41472
	v_mfma_f32_16x16x32_bf16 v[58:61], v[216:219], v[228:231], v[58:61]
	v_mfma_f32_16x16x32_bf16 v[62:65], v[216:219], v[236:239], v[62:65]
	v_mfma_f32_16x16x32_bf16 v[42:45], v[216:219], v[240:243], v[42:45]
	v_mfma_f32_16x16x32_bf16 v[46:49], v[216:219], v[252:255], v[46:49]
	s_waitcnt vmcnt(9)
	ds_write_b128 v165, v[204:207] offset:46080
	s_waitcnt vmcnt(8)
	ds_write_b128 v165, v[208:211] offset:50688
	v_mfma_f32_16x16x32_bf16 v[18:21], v[220:223], v[228:231], v[18:21]
	v_mfma_f32_16x16x32_bf16 v[22:25], v[220:223], v[236:239], v[22:25]
	v_mfma_f32_16x16x32_bf16 v[2:5], v[220:223], v[240:243], v[2:5]
	v_mfma_f32_16x16x32_bf16 v[6:9], v[220:223], v[252:255], v[6:9]
	s_waitcnt lgkmcnt(4)
	v_mfma_f32_16x16x32_bf16 v[26:29], v[224:227], v[228:231], v[26:29]
	v_mfma_f32_16x16x32_bf16 v[30:33], v[224:227], v[236:239], v[30:33]
	v_mfma_f32_16x16x32_bf16 v[10:13], v[224:227], v[240:243], v[10:13]
	v_mfma_f32_16x16x32_bf16 v[14:17], v[224:227], v[252:255], v[14:17]
	s_waitcnt lgkmcnt(0)
	s_barrier
	s_setprio 0
	ds_read_b128 v[228:231], v245 offset:36864
	ds_read_b128 v[212:215], v244
	ds_read_b128 v[236:239], v245 offset:39168
	ds_read_b128 v[240:243], v245 offset:41472
	ds_read_b128 v[252:255], v245 offset:43776
	ds_read_b128 v[216:219], v244 offset:2304
	ds_read_b128 v[220:223], v244 offset:4608
	ds_read_b128 v[224:227], v244 offset:6912
	global_load_dwordx4 v[180:183], v[70:71], off offset:1536
	global_load_dwordx4 v[184:187], v[68:69], off offset:1536
	global_load_dwordx4 v[188:191], v[66:67], off offset:1536
	global_load_dwordx4 v[192:195], v[72:73], off offset:1536
	global_load_dwordx4 v[196:199], v[74:75], off offset:1536
	global_load_dwordx4 v[200:203], v[76:77], off offset:1536
	global_load_dwordx4 v[204:207], v[78:79], off offset:1536
	global_load_dwordx4 v[208:211], v[80:81], off offset:1536
	s_waitcnt lgkmcnt(6)
	v_mfma_f32_16x16x32_bf16 v[50:53], v[212:215], v[228:231], v[50:53]
	s_waitcnt lgkmcnt(5)
	v_mfma_f32_16x16x32_bf16 v[54:57], v[212:215], v[236:239], v[54:57]
	s_waitcnt lgkmcnt(4)
	v_mfma_f32_16x16x32_bf16 v[34:37], v[212:215], v[240:243], v[34:37]
	s_waitcnt lgkmcnt(3)
	v_mfma_f32_16x16x32_bf16 v[38:41], v[212:215], v[252:255], v[38:41]
	ds_read_b128 v[212:215], v244 offset:64
	s_waitcnt lgkmcnt(3)
	v_mfma_f32_16x16x32_bf16 v[58:61], v[216:219], v[228:231], v[58:61]
	v_mfma_f32_16x16x32_bf16 v[62:65], v[216:219], v[236:239], v[62:65]
	v_mfma_f32_16x16x32_bf16 v[42:45], v[216:219], v[240:243], v[42:45]
	v_mfma_f32_16x16x32_bf16 v[46:49], v[216:219], v[252:255], v[46:49]
	ds_read_b128 v[216:219], v244 offset:2368
	s_setprio 1
	s_waitcnt vmcnt(15)
	ds_write_b128 v165, v[122:125] offset:18432
	s_waitcnt vmcnt(14)
	ds_write_b128 v165, v[126:129] offset:23040
	s_waitcnt lgkmcnt(5)
	v_mfma_f32_16x16x32_bf16 v[18:21], v[220:223], v[228:231], v[18:21]
	v_mfma_f32_16x16x32_bf16 v[22:25], v[220:223], v[236:239], v[22:25]
	v_mfma_f32_16x16x32_bf16 v[2:5], v[220:223], v[240:243], v[2:5]
	v_mfma_f32_16x16x32_bf16 v[6:9], v[220:223], v[252:255], v[6:9]
	ds_read_b128 v[220:223], v244 offset:4672
	s_waitcnt vmcnt(13)
	ds_write_b128 v165, v[136:139] offset:27648
	s_waitcnt vmcnt(12)
	ds_write_b128 v165, v[140:143] offset:32256
	s_waitcnt lgkmcnt(7)
	v_mfma_f32_16x16x32_bf16 v[26:29], v[224:227], v[228:231], v[26:29]
	ds_read_b128 v[228:231], v245 offset:36928
	v_mfma_f32_16x16x32_bf16 v[30:33], v[224:227], v[236:239], v[30:33]
	ds_read_b128 v[236:239], v245 offset:39232
	v_mfma_f32_16x16x32_bf16 v[10:13], v[224:227], v[240:243], v[10:13]
	ds_read_b128 v[240:243], v245 offset:41536
	v_mfma_f32_16x16x32_bf16 v[14:17], v[224:227], v[252:255], v[14:17]
	ds_read_b128 v[252:255], v245 offset:43840
	ds_read_b128 v[224:227], v244 offset:6976
	s_waitcnt lgkmcnt(4)
	v_mfma_f32_16x16x32_bf16 v[50:53], v[212:215], v[228:231], v[50:53]
	s_waitcnt lgkmcnt(3)
	v_mfma_f32_16x16x32_bf16 v[54:57], v[212:215], v[236:239], v[54:57]
	s_waitcnt lgkmcnt(2)
	v_mfma_f32_16x16x32_bf16 v[34:37], v[212:215], v[240:243], v[34:37]
	s_waitcnt lgkmcnt(1)
	v_mfma_f32_16x16x32_bf16 v[38:41], v[212:215], v[252:255], v[38:41]
	s_waitcnt vmcnt(11)
	ds_write_b128 v165, v[144:147] offset:55296
	s_waitcnt vmcnt(10)
	ds_write_b128 v165, v[148:151] offset:59904
	v_mfma_f32_16x16x32_bf16 v[58:61], v[216:219], v[228:231], v[58:61]
	v_mfma_f32_16x16x32_bf16 v[62:65], v[216:219], v[236:239], v[62:65]
	v_mfma_f32_16x16x32_bf16 v[42:45], v[216:219], v[240:243], v[42:45]
	v_mfma_f32_16x16x32_bf16 v[46:49], v[216:219], v[252:255], v[46:49]
	s_waitcnt vmcnt(9)
	ds_write_b128 v165, v[172:175] offset:64512
	s_waitcnt vmcnt(8)
	ds_write_b128 v166, v[176:179] offset:32256
	v_mfma_f32_16x16x32_bf16 v[18:21], v[220:223], v[228:231], v[18:21]
	v_mfma_f32_16x16x32_bf16 v[22:25], v[220:223], v[236:239], v[22:25]
	v_mfma_f32_16x16x32_bf16 v[2:5], v[220:223], v[240:243], v[2:5]
	v_mfma_f32_16x16x32_bf16 v[6:9], v[220:223], v[252:255], v[6:9]
	s_waitcnt lgkmcnt(4)
	v_mfma_f32_16x16x32_bf16 v[26:29], v[224:227], v[228:231], v[26:29]
	v_mfma_f32_16x16x32_bf16 v[30:33], v[224:227], v[236:239], v[30:33]
	v_mfma_f32_16x16x32_bf16 v[10:13], v[224:227], v[240:243], v[10:13]
	v_mfma_f32_16x16x32_bf16 v[14:17], v[224:227], v[252:255], v[14:17]
	s_waitcnt lgkmcnt(0)
	s_barrier
	s_setprio 0
	ds_read_b128 v[228:231], v245 offset:55296
	ds_read_b128 v[212:215], v244 offset:18432
	ds_read_b128 v[236:239], v245 offset:57600
	ds_read_b128 v[240:243], v245 offset:59904
	ds_read_b128 v[252:255], v245 offset:62208
	ds_read_b128 v[216:219], v244 offset:20736
	ds_read_b128 v[220:223], v244 offset:23040
	ds_read_b128 v[224:227], v244 offset:25344
	global_load_dwordx4 v[122:125], v[70:71], off offset:1664
	global_load_dwordx4 v[126:129], v[68:69], off offset:1664
	global_load_dwordx4 v[136:139], v[66:67], off offset:1664
	global_load_dwordx4 v[140:143], v[72:73], off offset:1664
	global_load_dwordx4 v[144:147], v[74:75], off offset:1664
	global_load_dwordx4 v[148:151], v[76:77], off offset:1664
	global_load_dwordx4 v[172:175], v[78:79], off offset:1664
	global_load_dwordx4 v[176:179], v[80:81], off offset:1664
	s_waitcnt lgkmcnt(6)
	v_mfma_f32_16x16x32_bf16 v[50:53], v[212:215], v[228:231], v[50:53]
	s_waitcnt lgkmcnt(5)
	v_mfma_f32_16x16x32_bf16 v[54:57], v[212:215], v[236:239], v[54:57]
	s_waitcnt lgkmcnt(4)
	v_mfma_f32_16x16x32_bf16 v[34:37], v[212:215], v[240:243], v[34:37]
	s_waitcnt lgkmcnt(3)
	v_mfma_f32_16x16x32_bf16 v[38:41], v[212:215], v[252:255], v[38:41]
	ds_read_b128 v[212:215], v244 offset:18496
	s_waitcnt lgkmcnt(3)
	v_mfma_f32_16x16x32_bf16 v[58:61], v[216:219], v[228:231], v[58:61]
	v_mfma_f32_16x16x32_bf16 v[62:65], v[216:219], v[236:239], v[62:65]
	v_mfma_f32_16x16x32_bf16 v[42:45], v[216:219], v[240:243], v[42:45]
	v_mfma_f32_16x16x32_bf16 v[46:49], v[216:219], v[252:255], v[46:49]
	ds_read_b128 v[216:219], v244 offset:20800
	s_setprio 1
	s_waitcnt vmcnt(15)
	ds_write_b128 v165, v[180:183]
	s_waitcnt vmcnt(14)
	ds_write_b128 v165, v[184:187] offset:4608
	s_waitcnt lgkmcnt(5)
	v_mfma_f32_16x16x32_bf16 v[18:21], v[220:223], v[228:231], v[18:21]
	v_mfma_f32_16x16x32_bf16 v[22:25], v[220:223], v[236:239], v[22:25]
	v_mfma_f32_16x16x32_bf16 v[2:5], v[220:223], v[240:243], v[2:5]
	v_mfma_f32_16x16x32_bf16 v[6:9], v[220:223], v[252:255], v[6:9]
	ds_read_b128 v[220:223], v244 offset:23104
	s_waitcnt vmcnt(13)
	ds_write_b128 v165, v[188:191] offset:9216
	s_waitcnt vmcnt(12)
	ds_write_b128 v165, v[192:195] offset:13824
	s_waitcnt lgkmcnt(7)
	v_mfma_f32_16x16x32_bf16 v[26:29], v[224:227], v[228:231], v[26:29]
	ds_read_b128 v[228:231], v245 offset:55360
	v_mfma_f32_16x16x32_bf16 v[30:33], v[224:227], v[236:239], v[30:33]
	ds_read_b128 v[236:239], v245 offset:57664
	v_mfma_f32_16x16x32_bf16 v[10:13], v[224:227], v[240:243], v[10:13]
	ds_read_b128 v[240:243], v245 offset:59968
	v_mfma_f32_16x16x32_bf16 v[14:17], v[224:227], v[252:255], v[14:17]
	ds_read_b128 v[252:255], v245 offset:62272
	ds_read_b128 v[224:227], v244 offset:25408
	s_waitcnt lgkmcnt(4)
	v_mfma_f32_16x16x32_bf16 v[50:53], v[212:215], v[228:231], v[50:53]
	s_waitcnt lgkmcnt(3)
	v_mfma_f32_16x16x32_bf16 v[54:57], v[212:215], v[236:239], v[54:57]
	s_waitcnt lgkmcnt(2)
	v_mfma_f32_16x16x32_bf16 v[34:37], v[212:215], v[240:243], v[34:37]
	s_waitcnt lgkmcnt(1)
	v_mfma_f32_16x16x32_bf16 v[38:41], v[212:215], v[252:255], v[38:41]
	s_waitcnt vmcnt(11)
	ds_write_b128 v165, v[196:199] offset:36864
	s_waitcnt vmcnt(10)
	ds_write_b128 v165, v[200:203] offset:41472
	v_mfma_f32_16x16x32_bf16 v[58:61], v[216:219], v[228:231], v[58:61]
	v_mfma_f32_16x16x32_bf16 v[62:65], v[216:219], v[236:239], v[62:65]
	v_mfma_f32_16x16x32_bf16 v[42:45], v[216:219], v[240:243], v[42:45]
	v_mfma_f32_16x16x32_bf16 v[46:49], v[216:219], v[252:255], v[46:49]
	s_waitcnt vmcnt(9)
	ds_write_b128 v165, v[204:207] offset:46080
	s_waitcnt vmcnt(8)
	ds_write_b128 v165, v[208:211] offset:50688
	v_mfma_f32_16x16x32_bf16 v[18:21], v[220:223], v[228:231], v[18:21]
	v_mfma_f32_16x16x32_bf16 v[22:25], v[220:223], v[236:239], v[22:25]
	v_mfma_f32_16x16x32_bf16 v[2:5], v[220:223], v[240:243], v[2:5]
	v_mfma_f32_16x16x32_bf16 v[6:9], v[220:223], v[252:255], v[6:9]
	s_waitcnt lgkmcnt(4)
	v_mfma_f32_16x16x32_bf16 v[26:29], v[224:227], v[228:231], v[26:29]
	v_mfma_f32_16x16x32_bf16 v[30:33], v[224:227], v[236:239], v[30:33]
	v_mfma_f32_16x16x32_bf16 v[10:13], v[224:227], v[240:243], v[10:13]
	v_mfma_f32_16x16x32_bf16 v[14:17], v[224:227], v[252:255], v[14:17]
	s_waitcnt lgkmcnt(0)
	s_barrier
	s_setprio 0
	ds_read_b128 v[228:231], v245 offset:36864
	ds_read_b128 v[212:215], v244
	ds_read_b128 v[236:239], v245 offset:39168
	ds_read_b128 v[240:243], v245 offset:41472
	ds_read_b128 v[252:255], v245 offset:43776
	ds_read_b128 v[216:219], v244 offset:2304
	ds_read_b128 v[220:223], v244 offset:4608
	ds_read_b128 v[224:227], v244 offset:6912
	global_load_dwordx4 v[180:183], v[70:71], off offset:1792
	global_load_dwordx4 v[184:187], v[68:69], off offset:1792
	global_load_dwordx4 v[188:191], v[66:67], off offset:1792
	global_load_dwordx4 v[192:195], v[72:73], off offset:1792
	global_load_dwordx4 v[196:199], v[74:75], off offset:1792
	global_load_dwordx4 v[200:203], v[76:77], off offset:1792
	global_load_dwordx4 v[204:207], v[78:79], off offset:1792
	global_load_dwordx4 v[208:211], v[80:81], off offset:1792
	s_waitcnt lgkmcnt(6)
	v_mfma_f32_16x16x32_bf16 v[50:53], v[212:215], v[228:231], v[50:53]
	s_waitcnt lgkmcnt(5)
	v_mfma_f32_16x16x32_bf16 v[54:57], v[212:215], v[236:239], v[54:57]
	s_waitcnt lgkmcnt(4)
	v_mfma_f32_16x16x32_bf16 v[34:37], v[212:215], v[240:243], v[34:37]
	s_waitcnt lgkmcnt(3)
	v_mfma_f32_16x16x32_bf16 v[38:41], v[212:215], v[252:255], v[38:41]
	ds_read_b128 v[212:215], v244 offset:64
	s_waitcnt lgkmcnt(3)
	v_mfma_f32_16x16x32_bf16 v[58:61], v[216:219], v[228:231], v[58:61]
	v_mfma_f32_16x16x32_bf16 v[62:65], v[216:219], v[236:239], v[62:65]
	v_mfma_f32_16x16x32_bf16 v[42:45], v[216:219], v[240:243], v[42:45]
	v_mfma_f32_16x16x32_bf16 v[46:49], v[216:219], v[252:255], v[46:49]
	ds_read_b128 v[216:219], v244 offset:2368
	s_setprio 1
	s_waitcnt vmcnt(15)
	ds_write_b128 v165, v[122:125] offset:18432
	s_waitcnt vmcnt(14)
	ds_write_b128 v165, v[126:129] offset:23040
	s_waitcnt lgkmcnt(5)
	v_mfma_f32_16x16x32_bf16 v[18:21], v[220:223], v[228:231], v[18:21]
	v_mfma_f32_16x16x32_bf16 v[22:25], v[220:223], v[236:239], v[22:25]
	v_mfma_f32_16x16x32_bf16 v[2:5], v[220:223], v[240:243], v[2:5]
	v_mfma_f32_16x16x32_bf16 v[6:9], v[220:223], v[252:255], v[6:9]
	ds_read_b128 v[220:223], v244 offset:4672
	s_waitcnt vmcnt(13)
	ds_write_b128 v165, v[136:139] offset:27648
	s_waitcnt vmcnt(12)
	ds_write_b128 v165, v[140:143] offset:32256
	s_waitcnt lgkmcnt(7)
	v_mfma_f32_16x16x32_bf16 v[26:29], v[224:227], v[228:231], v[26:29]
	ds_read_b128 v[228:231], v245 offset:36928
	v_mfma_f32_16x16x32_bf16 v[30:33], v[224:227], v[236:239], v[30:33]
	ds_read_b128 v[236:239], v245 offset:39232
	v_mfma_f32_16x16x32_bf16 v[10:13], v[224:227], v[240:243], v[10:13]
	ds_read_b128 v[240:243], v245 offset:41536
	v_mfma_f32_16x16x32_bf16 v[14:17], v[224:227], v[252:255], v[14:17]
	ds_read_b128 v[252:255], v245 offset:43840
	ds_read_b128 v[224:227], v244 offset:6976
	s_waitcnt lgkmcnt(4)
	v_mfma_f32_16x16x32_bf16 v[50:53], v[212:215], v[228:231], v[50:53]
	s_waitcnt lgkmcnt(3)
	v_mfma_f32_16x16x32_bf16 v[54:57], v[212:215], v[236:239], v[54:57]
	s_waitcnt lgkmcnt(2)
	v_mfma_f32_16x16x32_bf16 v[34:37], v[212:215], v[240:243], v[34:37]
	s_waitcnt lgkmcnt(1)
	v_mfma_f32_16x16x32_bf16 v[38:41], v[212:215], v[252:255], v[38:41]
	s_waitcnt vmcnt(11)
	ds_write_b128 v165, v[144:147] offset:55296
	s_waitcnt vmcnt(10)
	ds_write_b128 v165, v[148:151] offset:59904
	v_mfma_f32_16x16x32_bf16 v[58:61], v[216:219], v[228:231], v[58:61]
	v_mfma_f32_16x16x32_bf16 v[62:65], v[216:219], v[236:239], v[62:65]
	v_mfma_f32_16x16x32_bf16 v[42:45], v[216:219], v[240:243], v[42:45]
	v_mfma_f32_16x16x32_bf16 v[46:49], v[216:219], v[252:255], v[46:49]
	s_waitcnt vmcnt(9)
	ds_write_b128 v165, v[172:175] offset:64512
	s_waitcnt vmcnt(8)
	ds_write_b128 v166, v[176:179] offset:32256
	v_mfma_f32_16x16x32_bf16 v[18:21], v[220:223], v[228:231], v[18:21]
	v_mfma_f32_16x16x32_bf16 v[22:25], v[220:223], v[236:239], v[22:25]
	v_mfma_f32_16x16x32_bf16 v[2:5], v[220:223], v[240:243], v[2:5]
	v_mfma_f32_16x16x32_bf16 v[6:9], v[220:223], v[252:255], v[6:9]
	s_waitcnt lgkmcnt(4)
	v_mfma_f32_16x16x32_bf16 v[26:29], v[224:227], v[228:231], v[26:29]
	v_mfma_f32_16x16x32_bf16 v[30:33], v[224:227], v[236:239], v[30:33]
	v_mfma_f32_16x16x32_bf16 v[10:13], v[224:227], v[240:243], v[10:13]
	v_mfma_f32_16x16x32_bf16 v[14:17], v[224:227], v[252:255], v[14:17]
	s_waitcnt lgkmcnt(0)
	s_barrier
	s_setprio 0
	global_load_dwordx4 v[122:125], v[70:71], off offset:1920
	s_nop 0
	global_load_dwordx4 v[68:71], v[68:69], off offset:1920
	s_nop 0
	global_load_dwordx4 v[126:129], v[66:67], off offset:1920
	global_load_dwordx4 v[136:139], v[72:73], off offset:1920
	s_nop 0
	global_load_dwordx4 v[72:75], v[74:75], off offset:1920
	s_nop 0
	global_load_dwordx4 v[140:143], v[76:77], off offset:1920
	s_nop 0
	global_load_dwordx4 v[76:79], v[78:79], off offset:1920
	s_nop 0
	global_load_dwordx4 v[144:147], v[80:81], off offset:1920
	ds_read_b128 v[228:231], v245 offset:55296
	ds_read_b128 v[212:215], v244 offset:18432
	ds_read_b128 v[236:239], v245 offset:57600
	ds_read_b128 v[240:243], v245 offset:59904
	ds_read_b128 v[252:255], v245 offset:62208
	ds_read_b128 v[216:219], v244 offset:20736
	ds_read_b128 v[220:223], v244 offset:23040
	ds_read_b128 v[224:227], v244 offset:25344
	s_waitcnt lgkmcnt(6)
	v_mfma_f32_16x16x32_bf16 v[50:53], v[212:215], v[228:231], v[50:53]
	s_waitcnt lgkmcnt(5)
	v_mfma_f32_16x16x32_bf16 v[54:57], v[212:215], v[236:239], v[54:57]
	s_waitcnt lgkmcnt(4)
	v_mfma_f32_16x16x32_bf16 v[34:37], v[212:215], v[240:243], v[34:37]
	s_waitcnt lgkmcnt(3)
	v_mfma_f32_16x16x32_bf16 v[38:41], v[212:215], v[252:255], v[38:41]
	ds_read_b128 v[212:215], v244 offset:18496
	s_waitcnt lgkmcnt(3)
	v_mfma_f32_16x16x32_bf16 v[58:61], v[216:219], v[228:231], v[58:61]
	v_mfma_f32_16x16x32_bf16 v[62:65], v[216:219], v[236:239], v[62:65]
	v_mfma_f32_16x16x32_bf16 v[42:45], v[216:219], v[240:243], v[42:45]
	v_mfma_f32_16x16x32_bf16 v[46:49], v[216:219], v[252:255], v[46:49]
	ds_read_b128 v[216:219], v244 offset:20800
	s_setprio 1
	s_waitcnt vmcnt(15)
	ds_write_b128 v165, v[180:183]
	s_waitcnt vmcnt(14)
	ds_write_b128 v165, v[184:187] offset:4608
	s_waitcnt lgkmcnt(5)
	v_mfma_f32_16x16x32_bf16 v[18:21], v[220:223], v[228:231], v[18:21]
	v_mfma_f32_16x16x32_bf16 v[22:25], v[220:223], v[236:239], v[22:25]
	v_mfma_f32_16x16x32_bf16 v[2:5], v[220:223], v[240:243], v[2:5]
	v_mfma_f32_16x16x32_bf16 v[6:9], v[220:223], v[252:255], v[6:9]
	ds_read_b128 v[220:223], v244 offset:23104
	s_waitcnt vmcnt(13)
	ds_write_b128 v165, v[188:191] offset:9216
	s_waitcnt vmcnt(12)
	ds_write_b128 v165, v[192:195] offset:13824
	s_waitcnt lgkmcnt(7)
	v_mfma_f32_16x16x32_bf16 v[26:29], v[224:227], v[228:231], v[26:29]
	ds_read_b128 v[228:231], v245 offset:55360
	v_mfma_f32_16x16x32_bf16 v[30:33], v[224:227], v[236:239], v[30:33]
	ds_read_b128 v[236:239], v245 offset:57664
	v_mfma_f32_16x16x32_bf16 v[10:13], v[224:227], v[240:243], v[10:13]
	ds_read_b128 v[240:243], v245 offset:59968
	v_mfma_f32_16x16x32_bf16 v[14:17], v[224:227], v[252:255], v[14:17]
	ds_read_b128 v[252:255], v245 offset:62272
	ds_read_b128 v[224:227], v244 offset:25408
	s_waitcnt lgkmcnt(4)
	v_mfma_f32_16x16x32_bf16 v[50:53], v[212:215], v[228:231], v[50:53]
	s_waitcnt lgkmcnt(3)
	v_mfma_f32_16x16x32_bf16 v[54:57], v[212:215], v[236:239], v[54:57]
	s_waitcnt lgkmcnt(2)
	v_mfma_f32_16x16x32_bf16 v[34:37], v[212:215], v[240:243], v[34:37]
	s_waitcnt lgkmcnt(1)
	v_mfma_f32_16x16x32_bf16 v[38:41], v[212:215], v[252:255], v[38:41]
	s_waitcnt vmcnt(11)
	ds_write_b128 v165, v[196:199] offset:36864
	s_waitcnt vmcnt(10)
	ds_write_b128 v165, v[200:203] offset:41472
	v_mfma_f32_16x16x32_bf16 v[58:61], v[216:219], v[228:231], v[58:61]
	v_mfma_f32_16x16x32_bf16 v[62:65], v[216:219], v[236:239], v[62:65]
	v_mfma_f32_16x16x32_bf16 v[42:45], v[216:219], v[240:243], v[42:45]
	v_mfma_f32_16x16x32_bf16 v[46:49], v[216:219], v[252:255], v[46:49]
	s_waitcnt vmcnt(9)
	ds_write_b128 v165, v[204:207] offset:46080
	s_waitcnt vmcnt(8)
	ds_write_b128 v165, v[208:211] offset:50688
	v_mfma_f32_16x16x32_bf16 v[18:21], v[220:223], v[228:231], v[18:21]
	v_mfma_f32_16x16x32_bf16 v[22:25], v[220:223], v[236:239], v[22:25]
	v_mfma_f32_16x16x32_bf16 v[2:5], v[220:223], v[240:243], v[2:5]
	v_mfma_f32_16x16x32_bf16 v[6:9], v[220:223], v[252:255], v[6:9]
	s_waitcnt lgkmcnt(4)
	v_mfma_f32_16x16x32_bf16 v[26:29], v[224:227], v[228:231], v[26:29]
	v_mfma_f32_16x16x32_bf16 v[30:33], v[224:227], v[236:239], v[30:33]
	v_mfma_f32_16x16x32_bf16 v[10:13], v[224:227], v[240:243], v[10:13]
	v_mfma_f32_16x16x32_bf16 v[14:17], v[224:227], v[252:255], v[14:17]
	s_waitcnt lgkmcnt(0)
	s_barrier
	s_setprio 0
	ds_read_b128 v[228:231], v245 offset:36864
	ds_read_b128 v[212:215], v244
	ds_read_b128 v[236:239], v245 offset:39168
	ds_read_b128 v[240:243], v245 offset:41472
	ds_read_b128 v[252:255], v245 offset:43776
	ds_read_b128 v[216:219], v244 offset:2304
	ds_read_b128 v[220:223], v244 offset:4608
	ds_read_b128 v[224:227], v244 offset:6912
	s_waitcnt lgkmcnt(6)
	v_mfma_f32_16x16x32_bf16 v[50:53], v[212:215], v[228:231], v[50:53]
	s_waitcnt lgkmcnt(5)
	v_mfma_f32_16x16x32_bf16 v[54:57], v[212:215], v[236:239], v[54:57]
	s_waitcnt lgkmcnt(4)
	v_mfma_f32_16x16x32_bf16 v[34:37], v[212:215], v[240:243], v[34:37]
	s_waitcnt lgkmcnt(3)
	v_mfma_f32_16x16x32_bf16 v[38:41], v[212:215], v[252:255], v[38:41]
	ds_read_b128 v[212:215], v244 offset:64
	s_waitcnt lgkmcnt(3)
	v_mfma_f32_16x16x32_bf16 v[58:61], v[216:219], v[228:231], v[58:61]
	v_mfma_f32_16x16x32_bf16 v[62:65], v[216:219], v[236:239], v[62:65]
	v_mfma_f32_16x16x32_bf16 v[42:45], v[216:219], v[240:243], v[42:45]
	v_mfma_f32_16x16x32_bf16 v[46:49], v[216:219], v[252:255], v[46:49]
	ds_read_b128 v[216:219], v244 offset:2368
	s_setprio 1
	s_waitcnt vmcnt(7)
	ds_write_b128 v165, v[122:125] offset:18432
	s_waitcnt vmcnt(6)
	ds_write_b128 v165, v[68:71] offset:23040
	s_waitcnt lgkmcnt(5)
	v_mfma_f32_16x16x32_bf16 v[18:21], v[220:223], v[228:231], v[18:21]
	v_mfma_f32_16x16x32_bf16 v[22:25], v[220:223], v[236:239], v[22:25]
	v_mfma_f32_16x16x32_bf16 v[2:5], v[220:223], v[240:243], v[2:5]
	v_mfma_f32_16x16x32_bf16 v[6:9], v[220:223], v[252:255], v[6:9]
	ds_read_b128 v[220:223], v244 offset:4672
	s_waitcnt vmcnt(5)
	ds_write_b128 v165, v[126:129] offset:27648
	s_waitcnt vmcnt(4)
	ds_write_b128 v165, v[136:139] offset:32256
	s_waitcnt lgkmcnt(7)
	v_mfma_f32_16x16x32_bf16 v[26:29], v[224:227], v[228:231], v[26:29]
	ds_read_b128 v[228:231], v245 offset:36928
	v_mfma_f32_16x16x32_bf16 v[30:33], v[224:227], v[236:239], v[30:33]
	ds_read_b128 v[236:239], v245 offset:39232
	v_mfma_f32_16x16x32_bf16 v[10:13], v[224:227], v[240:243], v[10:13]
	ds_read_b128 v[240:243], v245 offset:41536
	v_mfma_f32_16x16x32_bf16 v[14:17], v[224:227], v[252:255], v[14:17]
	ds_read_b128 v[252:255], v245 offset:43840
	ds_read_b128 v[224:227], v244 offset:6976
	s_waitcnt lgkmcnt(4)
	v_mfma_f32_16x16x32_bf16 v[50:53], v[212:215], v[228:231], v[50:53]
	s_waitcnt lgkmcnt(3)
	v_mfma_f32_16x16x32_bf16 v[54:57], v[212:215], v[236:239], v[54:57]
	s_waitcnt lgkmcnt(2)
	v_mfma_f32_16x16x32_bf16 v[34:37], v[212:215], v[240:243], v[34:37]
	s_waitcnt lgkmcnt(1)
	v_mfma_f32_16x16x32_bf16 v[38:41], v[212:215], v[252:255], v[38:41]
	s_waitcnt vmcnt(3)
	ds_write_b128 v165, v[72:75] offset:55296
	s_waitcnt vmcnt(2)
	ds_write_b128 v165, v[140:143] offset:59904
	v_mfma_f32_16x16x32_bf16 v[58:61], v[216:219], v[228:231], v[58:61]
	v_mfma_f32_16x16x32_bf16 v[62:65], v[216:219], v[236:239], v[62:65]
	v_mfma_f32_16x16x32_bf16 v[42:45], v[216:219], v[240:243], v[42:45]
	v_mfma_f32_16x16x32_bf16 v[46:49], v[216:219], v[252:255], v[46:49]
	s_waitcnt vmcnt(1)
	ds_write_b128 v165, v[76:79] offset:64512
	s_waitcnt vmcnt(0)
	ds_write_b128 v166, v[144:147] offset:32256
	v_mfma_f32_16x16x32_bf16 v[18:21], v[220:223], v[228:231], v[18:21]
	v_mfma_f32_16x16x32_bf16 v[22:25], v[220:223], v[236:239], v[22:25]
	v_mfma_f32_16x16x32_bf16 v[2:5], v[220:223], v[240:243], v[2:5]
	v_mfma_f32_16x16x32_bf16 v[6:9], v[220:223], v[252:255], v[6:9]
	s_waitcnt lgkmcnt(4)
	v_mfma_f32_16x16x32_bf16 v[26:29], v[224:227], v[228:231], v[26:29]
	v_mfma_f32_16x16x32_bf16 v[30:33], v[224:227], v[236:239], v[30:33]
	v_mfma_f32_16x16x32_bf16 v[10:13], v[224:227], v[240:243], v[10:13]
	v_mfma_f32_16x16x32_bf16 v[14:17], v[224:227], v[252:255], v[14:17]
	s_waitcnt lgkmcnt(0)
	s_barrier
	s_setprio 0
	ds_read_b128 v[228:231], v245 offset:55296
	ds_read_b128 v[212:215], v244 offset:18432
	ds_read_b128 v[236:239], v245 offset:57600
	ds_read_b128 v[240:243], v245 offset:59904
	ds_read_b128 v[252:255], v245 offset:62208
	ds_read_b128 v[216:219], v244 offset:20736
	ds_read_b128 v[220:223], v244 offset:23040
	ds_read_b128 v[224:227], v244 offset:25344
	s_waitcnt lgkmcnt(6)
	v_mfma_f32_16x16x32_bf16 v[50:53], v[212:215], v[228:231], v[50:53]
	s_waitcnt lgkmcnt(5)
	v_mfma_f32_16x16x32_bf16 v[54:57], v[212:215], v[236:239], v[54:57]
	s_waitcnt lgkmcnt(4)
	v_mfma_f32_16x16x32_bf16 v[34:37], v[212:215], v[240:243], v[34:37]
	s_waitcnt lgkmcnt(3)
	v_mfma_f32_16x16x32_bf16 v[38:41], v[212:215], v[252:255], v[38:41]
	ds_read_b128 v[212:215], v244 offset:18496
	s_waitcnt lgkmcnt(3)
	v_mfma_f32_16x16x32_bf16 v[58:61], v[216:219], v[228:231], v[58:61]
	v_mfma_f32_16x16x32_bf16 v[62:65], v[216:219], v[236:239], v[62:65]
	v_mfma_f32_16x16x32_bf16 v[42:45], v[216:219], v[240:243], v[42:45]
	v_mfma_f32_16x16x32_bf16 v[46:49], v[216:219], v[252:255], v[46:49]
	ds_read_b128 v[216:219], v244 offset:20800
	s_waitcnt lgkmcnt(3)
	v_mfma_f32_16x16x32_bf16 v[18:21], v[220:223], v[228:231], v[18:21]
	v_mfma_f32_16x16x32_bf16 v[22:25], v[220:223], v[236:239], v[22:25]
	v_mfma_f32_16x16x32_bf16 v[2:5], v[220:223], v[240:243], v[2:5]
	v_mfma_f32_16x16x32_bf16 v[6:9], v[220:223], v[252:255], v[6:9]
	ds_read_b128 v[220:223], v244 offset:23104
	s_waitcnt lgkmcnt(3)
	v_mfma_f32_16x16x32_bf16 v[26:29], v[224:227], v[228:231], v[26:29]
	ds_read_b128 v[228:231], v245 offset:55360
	v_mfma_f32_16x16x32_bf16 v[30:33], v[224:227], v[236:239], v[30:33]
	ds_read_b128 v[236:239], v245 offset:57664
	v_mfma_f32_16x16x32_bf16 v[10:13], v[224:227], v[240:243], v[10:13]
	ds_read_b128 v[240:243], v245 offset:59968
	v_mfma_f32_16x16x32_bf16 v[14:17], v[224:227], v[252:255], v[14:17]
	ds_read_b128 v[252:255], v245 offset:62272
	ds_read_b128 v[224:227], v244 offset:25408
	s_waitcnt lgkmcnt(4)
	v_mfma_f32_16x16x32_bf16 v[50:53], v[212:215], v[228:231], v[50:53]
	s_waitcnt lgkmcnt(3)
	v_mfma_f32_16x16x32_bf16 v[54:57], v[212:215], v[236:239], v[54:57]
	s_waitcnt lgkmcnt(2)
	v_mfma_f32_16x16x32_bf16 v[34:37], v[212:215], v[240:243], v[34:37]
	s_waitcnt lgkmcnt(1)
	v_mfma_f32_16x16x32_bf16 v[38:41], v[212:215], v[252:255], v[38:41]
	v_mfma_f32_16x16x32_bf16 v[58:61], v[216:219], v[228:231], v[58:61]
	v_mfma_f32_16x16x32_bf16 v[62:65], v[216:219], v[236:239], v[62:65]
	v_mfma_f32_16x16x32_bf16 v[42:45], v[216:219], v[240:243], v[42:45]
	v_mfma_f32_16x16x32_bf16 v[46:49], v[216:219], v[252:255], v[46:49]
	v_mfma_f32_16x16x32_bf16 v[18:21], v[220:223], v[228:231], v[18:21]
	v_mfma_f32_16x16x32_bf16 v[22:25], v[220:223], v[236:239], v[22:25]
	v_mfma_f32_16x16x32_bf16 v[2:5], v[220:223], v[240:243], v[2:5]
	v_mfma_f32_16x16x32_bf16 v[6:9], v[220:223], v[252:255], v[6:9]
	s_waitcnt lgkmcnt(0)
	v_mfma_f32_16x16x32_bf16 v[26:29], v[224:227], v[228:231], v[26:29]
	v_mfma_f32_16x16x32_bf16 v[30:33], v[224:227], v[236:239], v[30:33]
	v_mfma_f32_16x16x32_bf16 v[10:13], v[224:227], v[240:243], v[10:13]
	v_mfma_f32_16x16x32_bf16 v[14:17], v[224:227], v[252:255], v[14:17]
	s_waitcnt lgkmcnt(0)
	s_barrier
	s_nop 7
	v_permlane16_swap_b32_e32 v50, v54
	v_permlane16_swap_b32_e32 v51, v55
	v_permlane16_swap_b32_e32 v52, v56
	v_permlane16_swap_b32_e32 v53, v57
	v_permlane16_swap_b32_e32 v58, v62
	v_permlane16_swap_b32_e32 v59, v63
	v_permlane16_swap_b32_e32 v60, v64
	v_permlane16_swap_b32_e32 v61, v65
	v_permlane16_swap_b32_e32 v34, v38
	v_permlane16_swap_b32_e32 v35, v39
	v_permlane16_swap_b32_e32 v36, v40
	v_permlane16_swap_b32_e32 v37, v41
	v_permlane16_swap_b32_e32 v42, v46
	v_permlane16_swap_b32_e32 v43, v47
	v_permlane16_swap_b32_e32 v44, v48
	v_permlane16_swap_b32_e32 v45, v49
	v_permlane16_swap_b32_e32 v18, v22
	v_permlane16_swap_b32_e32 v19, v23
	v_permlane16_swap_b32_e32 v20, v24
	v_permlane16_swap_b32_e32 v21, v25
	v_permlane16_swap_b32_e32 v26, v30
	v_permlane16_swap_b32_e32 v27, v31
	v_permlane16_swap_b32_e32 v28, v32
	v_permlane16_swap_b32_e32 v29, v33
	v_permlane16_swap_b32_e32 v2, v6
	v_permlane16_swap_b32_e32 v3, v7
	v_permlane16_swap_b32_e32 v4, v8
	v_permlane16_swap_b32_e32 v5, v9
	v_permlane16_swap_b32_e32 v10, v14
	v_permlane16_swap_b32_e32 v11, v15
	v_permlane16_swap_b32_e32 v12, v16
	v_permlane16_swap_b32_e32 v13, v17
	v_permlane32_swap_b32_e32 v50, v54
	v_permlane32_swap_b32_e32 v51, v55
	v_permlane32_swap_b32_e32 v52, v56
	v_permlane32_swap_b32_e32 v53, v57
	v_permlane32_swap_b32_e32 v58, v62
	v_permlane32_swap_b32_e32 v59, v63
	v_permlane32_swap_b32_e32 v60, v64
	v_permlane32_swap_b32_e32 v61, v65
	v_permlane32_swap_b32_e32 v34, v38
	v_permlane32_swap_b32_e32 v35, v39
	v_permlane32_swap_b32_e32 v36, v40
	v_permlane32_swap_b32_e32 v37, v41
	v_permlane32_swap_b32_e32 v42, v46
	v_permlane32_swap_b32_e32 v43, v47
	v_permlane32_swap_b32_e32 v44, v48
	v_permlane32_swap_b32_e32 v45, v49
	v_permlane32_swap_b32_e32 v18, v22
	v_permlane32_swap_b32_e32 v19, v23
	v_permlane32_swap_b32_e32 v20, v24
	v_permlane32_swap_b32_e32 v21, v25
	v_permlane32_swap_b32_e32 v26, v30
	v_permlane32_swap_b32_e32 v27, v31
	v_permlane32_swap_b32_e32 v28, v32
	v_permlane32_swap_b32_e32 v29, v33
	v_permlane32_swap_b32_e32 v2, v6
	v_permlane32_swap_b32_e32 v3, v7
	v_permlane32_swap_b32_e32 v4, v8
	v_permlane32_swap_b32_e32 v5, v9
	v_permlane32_swap_b32_e32 v10, v14
	v_permlane32_swap_b32_e32 v11, v15
	v_permlane32_swap_b32_e32 v12, v16
	v_permlane32_swap_b32_e32 v13, v17

.LBB0_1149:
	v_ashrrev_i32_e32 v3, 31, v2
	v_lshlrev_b64 v[2:3], 11, v[2:3]
	v_lshl_add_u64 v[70:71], v[86:87], 0, v[2:3]
	v_or_b32_e32 v2, s56, v154
	v_ashrrev_i32_e32 v3, 31, v2
	v_lshlrev_b64 v[2:3], 11, v[2:3]
	v_lshl_add_u64 v[72:73], v[84:85], 0, v[2:3]
	v_add_u32_e32 v2, s56, v155
	v_ashrrev_i32_e32 v3, 31, v2
	v_lshlrev_b64 v[2:3], 11, v[2:3]
	v_lshl_add_u64 v[74:75], v[84:85], 0, v[2:3]
	v_add_u32_e32 v2, s56, v156
	v_ashrrev_i32_e32 v3, 31, v2
	v_lshlrev_b64 v[2:3], 11, v[2:3]
	v_lshl_add_u64 v[76:77], v[84:85], 0, v[2:3]
	v_add_u32_e32 v2, s56, v157
	v_ashrrev_i32_e32 v3, 31, v2
	v_ashrrev_i32_e32 v9, 31, v8
	v_ashrrev_i32_e32 v5, 31, v4
	v_lshlrev_b64 v[2:3], 11, v[2:3]
	v_ashrrev_i32_e32 v7, 31, v6
	v_lshlrev_b64 v[8:9], 11, v[8:9]
	v_lshlrev_b64 v[4:5], 11, v[4:5]
	v_lshl_add_u64 v[78:79], v[84:85], 0, v[2:3]
	v_lshlrev_b64 v[2:3], 11, v[6:7]
	v_lshl_add_u64 v[66:67], v[86:87], 0, v[8:9]
	v_lshl_add_u64 v[68:69], v[86:87], 0, v[4:5]
	v_lshl_add_u64 v[80:81], v[86:87], 0, v[2:3]
	global_load_dwordx4 v[2:5], v[70:71], off
	global_load_dwordx4 v[6:9], v[68:69], off
	global_load_dwordx4 v[10:13], v[66:67], off
	global_load_dwordx4 v[14:17], v[80:81], off
	global_load_dwordx4 v[18:21], v[72:73], off
	global_load_dwordx4 v[22:25], v[74:75], off
	global_load_dwordx4 v[26:29], v[76:77], off
	global_load_dwordx4 v[30:33], v[78:79], off
	global_load_dwordx4 v[122:125], v[70:71], off offset:128
	global_load_dwordx4 v[126:129], v[68:69], off offset:128
	global_load_dwordx4 v[136:139], v[66:67], off offset:128
	global_load_dwordx4 v[140:143], v[80:81], off offset:128
	global_load_dwordx4 v[144:147], v[72:73], off offset:128
	global_load_dwordx4 v[148:151], v[74:75], off offset:128
	global_load_dwordx4 v[172:175], v[76:77], off offset:128
	global_load_dwordx4 v[176:179], v[78:79], off offset:128
	s_waitcnt vmcnt(15)
	ds_write_b128 v164, v[2:5] offset:36864
	s_waitcnt vmcnt(14)
	ds_write_b128 v164, v[6:9] offset:41472
	s_waitcnt vmcnt(13)
	ds_write_b128 v164, v[10:13] offset:46080
	s_waitcnt vmcnt(12)
	ds_write_b128 v164, v[14:17] offset:50688
	s_waitcnt vmcnt(11)
	ds_write_b128 v164, v[18:21]
	s_waitcnt vmcnt(10)
	ds_write_b128 v164, v[22:25] offset:4608
	s_waitcnt vmcnt(9)
	ds_write_b128 v164, v[26:29] offset:9216
	s_waitcnt vmcnt(8)
	ds_write_b128 v164, v[30:33] offset:13824
	s_waitcnt lgkmcnt(0)
	s_barrier
	global_load_dwordx4 v[180:183], v[74:75], off offset:256
	global_load_dwordx4 v[188:191], v[76:77], off offset:256
	global_load_dwordx4 v[192:195], v[72:73], off offset:256
	global_load_dwordx4 v[196:199], v[70:71], off offset:256
	global_load_dwordx4 v[200:203], v[68:69], off offset:256
	global_load_dwordx4 v[204:207], v[66:67], off offset:256
	global_load_dwordx4 v[208:211], v[78:79], off offset:256
	global_load_dwordx4 v[212:215], v[80:81], off offset:256
	v_and_b32_e32 v246, 15, v1
	v_add_u32_e32 v246, 4, v246
	v_bfe_u32 v246, v246, 3, 1
	v_bfe_u32 v249, v1, 4, 2
	v_xor_b32_e32 v246, v246, v249
	v_bfe_u32 v249, v1, 5, 1
	v_sub_u32_e32 v246, v246, v249
	v_lshlrev_b32_e32 v246, 4, v246
	v_bfe_u32 v249, v1, 4, 1
	v_mul_u32_u24_e32 v249, 0x900, v249
	v_sub_u32_e32 v246, v246, v249
	v_add_u32_e32 v244, v246, v161
	v_add_u32_e32 v245, v246, v163
	ds_read_b128 v[232:235], v245 offset:36864
	ds_read_b128 v[216:219], v244
	ds_read_b128 v[236:239], v245 offset:39168
	ds_read_b128 v[240:243], v245 offset:41472
	ds_read_b128 v[252:255], v245 offset:43776
	ds_read_b128 v[220:223], v244 offset:2304
	ds_read_b128 v[224:227], v244 offset:4608
	ds_read_b128 v[228:231], v244 offset:6912
	s_waitcnt lgkmcnt(6)
	v_mfma_f32_16x16x32_bf16 v[50:53], v[216:219], v[232:235], 0
	s_waitcnt lgkmcnt(5)
	v_mfma_f32_16x16x32_bf16 v[54:57], v[216:219], v[236:239], 0
	s_waitcnt lgkmcnt(4)
	v_mfma_f32_16x16x32_bf16 v[34:37], v[216:219], v[240:243], 0
	s_waitcnt lgkmcnt(3)
	v_mfma_f32_16x16x32_bf16 v[38:41], v[216:219], v[252:255], 0
	ds_read_b128 v[216:219], v244 offset:64
	s_waitcnt lgkmcnt(3)
	v_mfma_f32_16x16x32_bf16 v[58:61], v[220:223], v[232:235], 0
	v_mfma_f32_16x16x32_bf16 v[62:65], v[220:223], v[236:239], 0
	v_mfma_f32_16x16x32_bf16 v[42:45], v[220:223], v[240:243], 0
	v_mfma_f32_16x16x32_bf16 v[46:49], v[220:223], v[252:255], 0
	ds_read_b128 v[220:223], v244 offset:2368
	s_setprio 1
	s_waitcnt vmcnt(11)
	ds_write_b128 v164, v[144:147] offset:18432
	s_waitcnt vmcnt(10)
	ds_write_b128 v164, v[148:151] offset:23040
	s_waitcnt lgkmcnt(5)
	v_mfma_f32_16x16x32_bf16 v[18:21], v[224:227], v[232:235], 0
	v_mfma_f32_16x16x32_bf16 v[22:25], v[224:227], v[236:239], 0
	v_mfma_f32_16x16x32_bf16 v[2:5], v[224:227], v[240:243], 0
	v_mfma_f32_16x16x32_bf16 v[6:9], v[224:227], v[252:255], 0
	ds_read_b128 v[224:227], v244 offset:4672
	s_waitcnt vmcnt(9)
	ds_write_b128 v164, v[172:175] offset:27648
	s_waitcnt vmcnt(8)
	ds_write_b128 v164, v[176:179] offset:32256
	s_waitcnt lgkmcnt(7)
	v_mfma_f32_16x16x32_bf16 v[26:29], v[228:231], v[232:235], 0
	ds_read_b128 v[232:235], v245 offset:36928
	v_mfma_f32_16x16x32_bf16 v[30:33], v[228:231], v[236:239], 0
	ds_read_b128 v[236:239], v245 offset:39232
	v_mfma_f32_16x16x32_bf16 v[10:13], v[228:231], v[240:243], 0
	ds_read_b128 v[240:243], v245 offset:41536
	v_mfma_f32_16x16x32_bf16 v[14:17], v[228:231], v[252:255], 0
	ds_read_b128 v[252:255], v245 offset:43840
	ds_read_b128 v[228:231], v244 offset:6976
	s_waitcnt lgkmcnt(4)
	v_mfma_f32_16x16x32_bf16 v[50:53], v[216:219], v[232:235], v[50:53]
	s_waitcnt lgkmcnt(3)
	v_mfma_f32_16x16x32_bf16 v[54:57], v[216:219], v[236:239], v[54:57]
	s_waitcnt lgkmcnt(2)
	v_mfma_f32_16x16x32_bf16 v[34:37], v[216:219], v[240:243], v[34:37]
	s_waitcnt lgkmcnt(1)
	v_mfma_f32_16x16x32_bf16 v[38:41], v[216:219], v[252:255], v[38:41]
	ds_write_b128 v164, v[122:125] offset:55296
	ds_write_b128 v164, v[126:129] offset:59904
	v_mfma_f32_16x16x32_bf16 v[58:61], v[220:223], v[232:235], v[58:61]
	v_mfma_f32_16x16x32_bf16 v[62:65], v[220:223], v[236:239], v[62:65]
	v_mfma_f32_16x16x32_bf16 v[42:45], v[220:223], v[240:243], v[42:45]
	v_mfma_f32_16x16x32_bf16 v[46:49], v[220:223], v[252:255], v[46:49]
	ds_write_b128 v164, v[136:139] offset:64512
	ds_write_b128 v165, v[140:143] offset:32256
	v_mfma_f32_16x16x32_bf16 v[18:21], v[224:227], v[232:235], v[18:21]
	v_mfma_f32_16x16x32_bf16 v[22:25], v[224:227], v[236:239], v[22:25]
	v_mfma_f32_16x16x32_bf16 v[2:5], v[224:227], v[240:243], v[2:5]
	v_mfma_f32_16x16x32_bf16 v[6:9], v[224:227], v[252:255], v[6:9]
	s_waitcnt lgkmcnt(4)
	v_mfma_f32_16x16x32_bf16 v[26:29], v[228:231], v[232:235], v[26:29]
	v_mfma_f32_16x16x32_bf16 v[30:33], v[228:231], v[236:239], v[30:33]
	v_mfma_f32_16x16x32_bf16 v[10:13], v[228:231], v[240:243], v[10:13]
	v_mfma_f32_16x16x32_bf16 v[14:17], v[228:231], v[252:255], v[14:17]
	s_waitcnt lgkmcnt(0)
	s_barrier
	s_setprio 0
	ds_read_b128 v[232:235], v245 offset:55296
	ds_read_b128 v[216:219], v244 offset:18432
	ds_read_b128 v[236:239], v245 offset:57600
	ds_read_b128 v[240:243], v245 offset:59904
	ds_read_b128 v[252:255], v245 offset:62208
	ds_read_b128 v[220:223], v244 offset:20736
	ds_read_b128 v[224:227], v244 offset:23040
	ds_read_b128 v[228:231], v244 offset:25344
	global_load_dwordx4 v[122:125], v[72:73], off offset:384
	global_load_dwordx4 v[126:129], v[74:75], off offset:384
	global_load_dwordx4 v[136:139], v[76:77], off offset:384
	global_load_dwordx4 v[140:143], v[78:79], off offset:384
	global_load_dwordx4 v[144:147], v[70:71], off offset:384
	global_load_dwordx4 v[148:151], v[68:69], off offset:384
	global_load_dwordx4 v[172:175], v[66:67], off offset:384
	global_load_dwordx4 v[176:179], v[80:81], off offset:384
	s_waitcnt lgkmcnt(6)
	v_mfma_f32_16x16x32_bf16 v[50:53], v[216:219], v[232:235], v[50:53]
	s_waitcnt lgkmcnt(5)
	v_mfma_f32_16x16x32_bf16 v[54:57], v[216:219], v[236:239], v[54:57]
	s_waitcnt lgkmcnt(4)
	v_mfma_f32_16x16x32_bf16 v[34:37], v[216:219], v[240:243], v[34:37]
	s_waitcnt lgkmcnt(3)
	v_mfma_f32_16x16x32_bf16 v[38:41], v[216:219], v[252:255], v[38:41]
	ds_read_b128 v[216:219], v244 offset:18496
	s_waitcnt lgkmcnt(3)
	v_mfma_f32_16x16x32_bf16 v[58:61], v[220:223], v[232:235], v[58:61]
	v_mfma_f32_16x16x32_bf16 v[62:65], v[220:223], v[236:239], v[62:65]
	v_mfma_f32_16x16x32_bf16 v[42:45], v[220:223], v[240:243], v[42:45]
	v_mfma_f32_16x16x32_bf16 v[46:49], v[220:223], v[252:255], v[46:49]
	ds_read_b128 v[220:223], v244 offset:20800
	s_setprio 1
	s_waitcnt vmcnt(13)
	ds_write_b128 v164, v[192:195]
	ds_write_b128 v164, v[180:183] offset:4608
	s_waitcnt lgkmcnt(5)
	v_mfma_f32_16x16x32_bf16 v[18:21], v[224:227], v[232:235], v[18:21]
	v_mfma_f32_16x16x32_bf16 v[22:25], v[224:227], v[236:239], v[22:25]
	v_mfma_f32_16x16x32_bf16 v[2:5], v[224:227], v[240:243], v[2:5]
	v_mfma_f32_16x16x32_bf16 v[6:9], v[224:227], v[252:255], v[6:9]
	ds_read_b128 v[224:227], v244 offset:23104
	ds_write_b128 v164, v[188:191] offset:9216
	s_waitcnt vmcnt(9)
	ds_write_b128 v164, v[208:211] offset:13824
	s_waitcnt lgkmcnt(7)
	v_mfma_f32_16x16x32_bf16 v[26:29], v[228:231], v[232:235], v[26:29]
	ds_read_b128 v[232:235], v245 offset:55360
	v_mfma_f32_16x16x32_bf16 v[30:33], v[228:231], v[236:239], v[30:33]
	ds_read_b128 v[236:239], v245 offset:57664
	v_mfma_f32_16x16x32_bf16 v[10:13], v[228:231], v[240:243], v[10:13]
	ds_read_b128 v[240:243], v245 offset:59968
	v_mfma_f32_16x16x32_bf16 v[14:17], v[228:231], v[252:255], v[14:17]
	ds_read_b128 v[252:255], v245 offset:62272
	ds_read_b128 v[228:231], v244 offset:25408
	s_waitcnt lgkmcnt(4)
	v_mfma_f32_16x16x32_bf16 v[50:53], v[216:219], v[232:235], v[50:53]
	s_waitcnt lgkmcnt(3)
	v_mfma_f32_16x16x32_bf16 v[54:57], v[216:219], v[236:239], v[54:57]
	s_waitcnt lgkmcnt(2)
	v_mfma_f32_16x16x32_bf16 v[34:37], v[216:219], v[240:243], v[34:37]
	s_waitcnt lgkmcnt(1)
	v_mfma_f32_16x16x32_bf16 v[38:41], v[216:219], v[252:255], v[38:41]
	ds_write_b128 v164, v[196:199] offset:36864
	ds_write_b128 v164, v[200:203] offset:41472
	v_mfma_f32_16x16x32_bf16 v[58:61], v[220:223], v[232:235], v[58:61]
	v_mfma_f32_16x16x32_bf16 v[62:65], v[220:223], v[236:239], v[62:65]
	v_mfma_f32_16x16x32_bf16 v[42:45], v[220:223], v[240:243], v[42:45]
	v_mfma_f32_16x16x32_bf16 v[46:49], v[220:223], v[252:255], v[46:49]
	ds_write_b128 v164, v[204:207] offset:46080
	s_waitcnt vmcnt(8)
	ds_write_b128 v164, v[212:215] offset:50688
	v_mfma_f32_16x16x32_bf16 v[18:21], v[224:227], v[232:235], v[18:21]
	v_mfma_f32_16x16x32_bf16 v[22:25], v[224:227], v[236:239], v[22:25]
	v_mfma_f32_16x16x32_bf16 v[2:5], v[224:227], v[240:243], v[2:5]
	v_mfma_f32_16x16x32_bf16 v[6:9], v[224:227], v[252:255], v[6:9]
	s_waitcnt lgkmcnt(4)
	v_mfma_f32_16x16x32_bf16 v[26:29], v[228:231], v[232:235], v[26:29]
	v_mfma_f32_16x16x32_bf16 v[30:33], v[228:231], v[236:239], v[30:33]
	v_mfma_f32_16x16x32_bf16 v[10:13], v[228:231], v[240:243], v[10:13]
	v_mfma_f32_16x16x32_bf16 v[14:17], v[228:231], v[252:255], v[14:17]
	s_waitcnt lgkmcnt(0)
	s_barrier
	s_setprio 0
	ds_read_b128 v[232:235], v245 offset:36864
	ds_read_b128 v[216:219], v244
	ds_read_b128 v[236:239], v245 offset:39168
	ds_read_b128 v[240:243], v245 offset:41472
	ds_read_b128 v[252:255], v245 offset:43776
	ds_read_b128 v[220:223], v244 offset:2304
	ds_read_b128 v[224:227], v244 offset:4608
	ds_read_b128 v[228:231], v244 offset:6912
	global_load_dwordx4 v[180:183], v[72:73], off offset:512
	global_load_dwordx4 v[188:191], v[74:75], off offset:512
	global_load_dwordx4 v[192:195], v[76:77], off offset:512
	global_load_dwordx4 v[196:199], v[78:79], off offset:512
	global_load_dwordx4 v[200:203], v[70:71], off offset:512
	global_load_dwordx4 v[204:207], v[68:69], off offset:512
	global_load_dwordx4 v[208:211], v[66:67], off offset:512
	global_load_dwordx4 v[212:215], v[80:81], off offset:512
	s_waitcnt lgkmcnt(6)
	v_mfma_f32_16x16x32_bf16 v[50:53], v[216:219], v[232:235], v[50:53]
	s_waitcnt lgkmcnt(5)
	v_mfma_f32_16x16x32_bf16 v[54:57], v[216:219], v[236:239], v[54:57]
	s_waitcnt lgkmcnt(4)
	v_mfma_f32_16x16x32_bf16 v[34:37], v[216:219], v[240:243], v[34:37]
	s_waitcnt lgkmcnt(3)
	v_mfma_f32_16x16x32_bf16 v[38:41], v[216:219], v[252:255], v[38:41]
	ds_read_b128 v[216:219], v244 offset:64
	s_waitcnt lgkmcnt(3)
	v_mfma_f32_16x16x32_bf16 v[58:61], v[220:223], v[232:235], v[58:61]
	v_mfma_f32_16x16x32_bf16 v[62:65], v[220:223], v[236:239], v[62:65]
	v_mfma_f32_16x16x32_bf16 v[42:45], v[220:223], v[240:243], v[42:45]
	v_mfma_f32_16x16x32_bf16 v[46:49], v[220:223], v[252:255], v[46:49]
	ds_read_b128 v[220:223], v244 offset:2368
	s_setprio 1
	s_waitcnt vmcnt(15)
	ds_write_b128 v164, v[122:125] offset:18432
	s_waitcnt vmcnt(14)
	ds_write_b128 v164, v[126:129] offset:23040
	s_waitcnt lgkmcnt(5)
	v_mfma_f32_16x16x32_bf16 v[18:21], v[224:227], v[232:235], v[18:21]
	v_mfma_f32_16x16x32_bf16 v[22:25], v[224:227], v[236:239], v[22:25]
	v_mfma_f32_16x16x32_bf16 v[2:5], v[224:227], v[240:243], v[2:5]
	v_mfma_f32_16x16x32_bf16 v[6:9], v[224:227], v[252:255], v[6:9]
	ds_read_b128 v[224:227], v244 offset:4672
	s_waitcnt vmcnt(13)
	ds_write_b128 v164, v[136:139] offset:27648
	s_waitcnt vmcnt(12)
	ds_write_b128 v164, v[140:143] offset:32256
	s_waitcnt lgkmcnt(7)
	v_mfma_f32_16x16x32_bf16 v[26:29], v[228:231], v[232:235], v[26:29]
	ds_read_b128 v[232:235], v245 offset:36928
	v_mfma_f32_16x16x32_bf16 v[30:33], v[228:231], v[236:239], v[30:33]
	ds_read_b128 v[236:239], v245 offset:39232
	v_mfma_f32_16x16x32_bf16 v[10:13], v[228:231], v[240:243], v[10:13]
	ds_read_b128 v[240:243], v245 offset:41536
	v_mfma_f32_16x16x32_bf16 v[14:17], v[228:231], v[252:255], v[14:17]
	ds_read_b128 v[252:255], v245 offset:43840
	ds_read_b128 v[228:231], v244 offset:6976
	s_waitcnt lgkmcnt(4)
	v_mfma_f32_16x16x32_bf16 v[50:53], v[216:219], v[232:235], v[50:53]
	s_waitcnt lgkmcnt(3)
	v_mfma_f32_16x16x32_bf16 v[54:57], v[216:219], v[236:239], v[54:57]
	s_waitcnt lgkmcnt(2)
	v_mfma_f32_16x16x32_bf16 v[34:37], v[216:219], v[240:243], v[34:37]
	s_waitcnt lgkmcnt(1)
	v_mfma_f32_16x16x32_bf16 v[38:41], v[216:219], v[252:255], v[38:41]
	s_waitcnt vmcnt(11)
	ds_write_b128 v164, v[144:147] offset:55296
	s_waitcnt vmcnt(10)
	ds_write_b128 v164, v[148:151] offset:59904
	v_mfma_f32_16x16x32_bf16 v[58:61], v[220:223], v[232:235], v[58:61]
	v_mfma_f32_16x16x32_bf16 v[62:65], v[220:223], v[236:239], v[62:65]
	v_mfma_f32_16x16x32_bf16 v[42:45], v[220:223], v[240:243], v[42:45]
	v_mfma_f32_16x16x32_bf16 v[46:49], v[220:223], v[252:255], v[46:49]
	s_waitcnt vmcnt(9)
	ds_write_b128 v164, v[172:175] offset:64512
	s_waitcnt vmcnt(8)
	ds_write_b128 v165, v[176:179] offset:32256
	v_mfma_f32_16x16x32_bf16 v[18:21], v[224:227], v[232:235], v[18:21]
	v_mfma_f32_16x16x32_bf16 v[22:25], v[224:227], v[236:239], v[22:25]
	v_mfma_f32_16x16x32_bf16 v[2:5], v[224:227], v[240:243], v[2:5]
	v_mfma_f32_16x16x32_bf16 v[6:9], v[224:227], v[252:255], v[6:9]
	s_waitcnt lgkmcnt(4)
	v_mfma_f32_16x16x32_bf16 v[26:29], v[228:231], v[232:235], v[26:29]
	v_mfma_f32_16x16x32_bf16 v[30:33], v[228:231], v[236:239], v[30:33]
	v_mfma_f32_16x16x32_bf16 v[10:13], v[228:231], v[240:243], v[10:13]
	v_mfma_f32_16x16x32_bf16 v[14:17], v[228:231], v[252:255], v[14:17]
	s_waitcnt lgkmcnt(0)
	s_barrier
	s_setprio 0
	ds_read_b128 v[232:235], v245 offset:55296
	ds_read_b128 v[216:219], v244 offset:18432
	ds_read_b128 v[236:239], v245 offset:57600
	ds_read_b128 v[240:243], v245 offset:59904
	ds_read_b128 v[252:255], v245 offset:62208
	ds_read_b128 v[220:223], v244 offset:20736
	ds_read_b128 v[224:227], v244 offset:23040
	ds_read_b128 v[228:231], v244 offset:25344
	global_load_dwordx4 v[122:125], v[72:73], off offset:640
	global_load_dwordx4 v[126:129], v[74:75], off offset:640
	global_load_dwordx4 v[136:139], v[76:77], off offset:640
	global_load_dwordx4 v[140:143], v[78:79], off offset:640
	global_load_dwordx4 v[144:147], v[70:71], off offset:640
	global_load_dwordx4 v[148:151], v[68:69], off offset:640
	global_load_dwordx4 v[172:175], v[66:67], off offset:640
	global_load_dwordx4 v[176:179], v[80:81], off offset:640
	s_waitcnt lgkmcnt(6)
	v_mfma_f32_16x16x32_bf16 v[50:53], v[216:219], v[232:235], v[50:53]
	s_waitcnt lgkmcnt(5)
	v_mfma_f32_16x16x32_bf16 v[54:57], v[216:219], v[236:239], v[54:57]
	s_waitcnt lgkmcnt(4)
	v_mfma_f32_16x16x32_bf16 v[34:37], v[216:219], v[240:243], v[34:37]
	s_waitcnt lgkmcnt(3)
	v_mfma_f32_16x16x32_bf16 v[38:41], v[216:219], v[252:255], v[38:41]
	ds_read_b128 v[216:219], v244 offset:18496
	s_waitcnt lgkmcnt(3)
	v_mfma_f32_16x16x32_bf16 v[58:61], v[220:223], v[232:235], v[58:61]
	v_mfma_f32_16x16x32_bf16 v[62:65], v[220:223], v[236:239], v[62:65]
	v_mfma_f32_16x16x32_bf16 v[42:45], v[220:223], v[240:243], v[42:45]
	v_mfma_f32_16x16x32_bf16 v[46:49], v[220:223], v[252:255], v[46:49]
	ds_read_b128 v[220:223], v244 offset:20800
	s_setprio 1
	s_waitcnt vmcnt(15)
	ds_write_b128 v164, v[180:183]
	s_waitcnt vmcnt(14)
	ds_write_b128 v164, v[188:191] offset:4608
	s_waitcnt lgkmcnt(5)
	v_mfma_f32_16x16x32_bf16 v[18:21], v[224:227], v[232:235], v[18:21]
	v_mfma_f32_16x16x32_bf16 v[22:25], v[224:227], v[236:239], v[22:25]
	v_mfma_f32_16x16x32_bf16 v[2:5], v[224:227], v[240:243], v[2:5]
	v_mfma_f32_16x16x32_bf16 v[6:9], v[224:227], v[252:255], v[6:9]
	ds_read_b128 v[224:227], v244 offset:23104
	s_waitcnt vmcnt(13)
	ds_write_b128 v164, v[192:195] offset:9216
	s_waitcnt vmcnt(12)
	ds_write_b128 v164, v[196:199] offset:13824
	s_waitcnt lgkmcnt(7)
	v_mfma_f32_16x16x32_bf16 v[26:29], v[228:231], v[232:235], v[26:29]
	ds_read_b128 v[232:235], v245 offset:55360
	v_mfma_f32_16x16x32_bf16 v[30:33], v[228:231], v[236:239], v[30:33]
	ds_read_b128 v[236:239], v245 offset:57664
	v_mfma_f32_16x16x32_bf16 v[10:13], v[228:231], v[240:243], v[10:13]
	ds_read_b128 v[240:243], v245 offset:59968
	v_mfma_f32_16x16x32_bf16 v[14:17], v[228:231], v[252:255], v[14:17]
	ds_read_b128 v[252:255], v245 offset:62272
	ds_read_b128 v[228:231], v244 offset:25408
	s_waitcnt lgkmcnt(4)
	v_mfma_f32_16x16x32_bf16 v[50:53], v[216:219], v[232:235], v[50:53]
	s_waitcnt lgkmcnt(3)
	v_mfma_f32_16x16x32_bf16 v[54:57], v[216:219], v[236:239], v[54:57]
	s_waitcnt lgkmcnt(2)
	v_mfma_f32_16x16x32_bf16 v[34:37], v[216:219], v[240:243], v[34:37]
	s_waitcnt lgkmcnt(1)
	v_mfma_f32_16x16x32_bf16 v[38:41], v[216:219], v[252:255], v[38:41]
	s_waitcnt vmcnt(11)
	ds_write_b128 v164, v[200:203] offset:36864
	s_waitcnt vmcnt(10)
	ds_write_b128 v164, v[204:207] offset:41472
	v_mfma_f32_16x16x32_bf16 v[58:61], v[220:223], v[232:235], v[58:61]
	v_mfma_f32_16x16x32_bf16 v[62:65], v[220:223], v[236:239], v[62:65]
	v_mfma_f32_16x16x32_bf16 v[42:45], v[220:223], v[240:243], v[42:45]
	v_mfma_f32_16x16x32_bf16 v[46:49], v[220:223], v[252:255], v[46:49]
	s_waitcnt vmcnt(9)
	ds_write_b128 v164, v[208:211] offset:46080
	s_waitcnt vmcnt(8)
	ds_write_b128 v164, v[212:215] offset:50688
	v_mfma_f32_16x16x32_bf16 v[18:21], v[224:227], v[232:235], v[18:21]
	v_mfma_f32_16x16x32_bf16 v[22:25], v[224:227], v[236:239], v[22:25]
	v_mfma_f32_16x16x32_bf16 v[2:5], v[224:227], v[240:243], v[2:5]
	v_mfma_f32_16x16x32_bf16 v[6:9], v[224:227], v[252:255], v[6:9]
	s_waitcnt lgkmcnt(4)
	v_mfma_f32_16x16x32_bf16 v[26:29], v[228:231], v[232:235], v[26:29]
	v_mfma_f32_16x16x32_bf16 v[30:33], v[228:231], v[236:239], v[30:33]
	v_mfma_f32_16x16x32_bf16 v[10:13], v[228:231], v[240:243], v[10:13]
	v_mfma_f32_16x16x32_bf16 v[14:17], v[228:231], v[252:255], v[14:17]
	s_waitcnt lgkmcnt(0)
	s_barrier
	s_setprio 0
	ds_read_b128 v[232:235], v245 offset:36864
	ds_read_b128 v[216:219], v244
	ds_read_b128 v[236:239], v245 offset:39168
	ds_read_b128 v[240:243], v245 offset:41472
	ds_read_b128 v[252:255], v245 offset:43776
	ds_read_b128 v[220:223], v244 offset:2304
	ds_read_b128 v[224:227], v244 offset:4608
	ds_read_b128 v[228:231], v244 offset:6912
	global_load_dwordx4 v[180:183], v[72:73], off offset:768
	global_load_dwordx4 v[188:191], v[74:75], off offset:768
	global_load_dwordx4 v[192:195], v[76:77], off offset:768
	global_load_dwordx4 v[196:199], v[78:79], off offset:768
	global_load_dwordx4 v[200:203], v[70:71], off offset:768
	global_load_dwordx4 v[204:207], v[68:69], off offset:768
	global_load_dwordx4 v[208:211], v[66:67], off offset:768
	global_load_dwordx4 v[212:215], v[80:81], off offset:768
	s_waitcnt lgkmcnt(6)
	v_mfma_f32_16x16x32_bf16 v[50:53], v[216:219], v[232:235], v[50:53]
	s_waitcnt lgkmcnt(5)
	v_mfma_f32_16x16x32_bf16 v[54:57], v[216:219], v[236:239], v[54:57]
	s_waitcnt lgkmcnt(4)
	v_mfma_f32_16x16x32_bf16 v[34:37], v[216:219], v[240:243], v[34:37]
	s_waitcnt lgkmcnt(3)
	v_mfma_f32_16x16x32_bf16 v[38:41], v[216:219], v[252:255], v[38:41]
	ds_read_b128 v[216:219], v244 offset:64
	s_waitcnt lgkmcnt(3)
	v_mfma_f32_16x16x32_bf16 v[58:61], v[220:223], v[232:235], v[58:61]
	v_mfma_f32_16x16x32_bf16 v[62:65], v[220:223], v[236:239], v[62:65]
	v_mfma_f32_16x16x32_bf16 v[42:45], v[220:223], v[240:243], v[42:45]
	v_mfma_f32_16x16x32_bf16 v[46:49], v[220:223], v[252:255], v[46:49]
	ds_read_b128 v[220:223], v244 offset:2368
	s_setprio 1
	s_waitcnt vmcnt(15)
	ds_write_b128 v164, v[122:125] offset:18432
	s_waitcnt vmcnt(14)
	ds_write_b128 v164, v[126:129] offset:23040
	s_waitcnt lgkmcnt(5)
	v_mfma_f32_16x16x32_bf16 v[18:21], v[224:227], v[232:235], v[18:21]
	v_mfma_f32_16x16x32_bf16 v[22:25], v[224:227], v[236:239], v[22:25]
	v_mfma_f32_16x16x32_bf16 v[2:5], v[224:227], v[240:243], v[2:5]
	v_mfma_f32_16x16x32_bf16 v[6:9], v[224:227], v[252:255], v[6:9]
	ds_read_b128 v[224:227], v244 offset:4672
	s_waitcnt vmcnt(13)
	ds_write_b128 v164, v[136:139] offset:27648
	s_waitcnt vmcnt(12)
	ds_write_b128 v164, v[140:143] offset:32256
	s_waitcnt lgkmcnt(7)
	v_mfma_f32_16x16x32_bf16 v[26:29], v[228:231], v[232:235], v[26:29]
	ds_read_b128 v[232:235], v245 offset:36928
	v_mfma_f32_16x16x32_bf16 v[30:33], v[228:231], v[236:239], v[30:33]
	ds_read_b128 v[236:239], v245 offset:39232
	v_mfma_f32_16x16x32_bf16 v[10:13], v[228:231], v[240:243], v[10:13]
	ds_read_b128 v[240:243], v245 offset:41536
	v_mfma_f32_16x16x32_bf16 v[14:17], v[228:231], v[252:255], v[14:17]
	ds_read_b128 v[252:255], v245 offset:43840
	ds_read_b128 v[228:231], v244 offset:6976
	s_waitcnt lgkmcnt(4)
	v_mfma_f32_16x16x32_bf16 v[50:53], v[216:219], v[232:235], v[50:53]
	s_waitcnt lgkmcnt(3)
	v_mfma_f32_16x16x32_bf16 v[54:57], v[216:219], v[236:239], v[54:57]
	s_waitcnt lgkmcnt(2)
	v_mfma_f32_16x16x32_bf16 v[34:37], v[216:219], v[240:243], v[34:37]
	s_waitcnt lgkmcnt(1)
	v_mfma_f32_16x16x32_bf16 v[38:41], v[216:219], v[252:255], v[38:41]
	s_waitcnt vmcnt(11)
	ds_write_b128 v164, v[144:147] offset:55296
	s_waitcnt vmcnt(10)
	ds_write_b128 v164, v[148:151] offset:59904
	v_mfma_f32_16x16x32_bf16 v[58:61], v[220:223], v[232:235], v[58:61]
	v_mfma_f32_16x16x32_bf16 v[62:65], v[220:223], v[236:239], v[62:65]
	v_mfma_f32_16x16x32_bf16 v[42:45], v[220:223], v[240:243], v[42:45]
	v_mfma_f32_16x16x32_bf16 v[46:49], v[220:223], v[252:255], v[46:49]
	s_waitcnt vmcnt(9)
	ds_write_b128 v164, v[172:175] offset:64512
	s_waitcnt vmcnt(8)
	ds_write_b128 v165, v[176:179] offset:32256
	v_mfma_f32_16x16x32_bf16 v[18:21], v[224:227], v[232:235], v[18:21]
	v_mfma_f32_16x16x32_bf16 v[22:25], v[224:227], v[236:239], v[22:25]
	v_mfma_f32_16x16x32_bf16 v[2:5], v[224:227], v[240:243], v[2:5]
	v_mfma_f32_16x16x32_bf16 v[6:9], v[224:227], v[252:255], v[6:9]
	s_waitcnt lgkmcnt(4)
	v_mfma_f32_16x16x32_bf16 v[26:29], v[228:231], v[232:235], v[26:29]
	v_mfma_f32_16x16x32_bf16 v[30:33], v[228:231], v[236:239], v[30:33]
	v_mfma_f32_16x16x32_bf16 v[10:13], v[228:231], v[240:243], v[10:13]
	v_mfma_f32_16x16x32_bf16 v[14:17], v[228:231], v[252:255], v[14:17]
	s_waitcnt lgkmcnt(0)
	s_barrier
	s_setprio 0
	ds_read_b128 v[232:235], v245 offset:55296
	ds_read_b128 v[216:219], v244 offset:18432
	ds_read_b128 v[236:239], v245 offset:57600
	ds_read_b128 v[240:243], v245 offset:59904
	ds_read_b128 v[252:255], v245 offset:62208
	ds_read_b128 v[220:223], v244 offset:20736
	ds_read_b128 v[224:227], v244 offset:23040
	ds_read_b128 v[228:231], v244 offset:25344
	global_load_dwordx4 v[122:125], v[72:73], off offset:896
	global_load_dwordx4 v[126:129], v[74:75], off offset:896
	global_load_dwordx4 v[136:139], v[76:77], off offset:896
	global_load_dwordx4 v[140:143], v[78:79], off offset:896
	global_load_dwordx4 v[144:147], v[70:71], off offset:896
	global_load_dwordx4 v[148:151], v[68:69], off offset:896
	global_load_dwordx4 v[172:175], v[66:67], off offset:896
	global_load_dwordx4 v[176:179], v[80:81], off offset:896
	s_waitcnt lgkmcnt(6)
	v_mfma_f32_16x16x32_bf16 v[50:53], v[216:219], v[232:235], v[50:53]
	s_waitcnt lgkmcnt(5)
	v_mfma_f32_16x16x32_bf16 v[54:57], v[216:219], v[236:239], v[54:57]
	s_waitcnt lgkmcnt(4)
	v_mfma_f32_16x16x32_bf16 v[34:37], v[216:219], v[240:243], v[34:37]
	s_waitcnt lgkmcnt(3)
	v_mfma_f32_16x16x32_bf16 v[38:41], v[216:219], v[252:255], v[38:41]
	ds_read_b128 v[216:219], v244 offset:18496
	s_waitcnt lgkmcnt(3)
	v_mfma_f32_16x16x32_bf16 v[58:61], v[220:223], v[232:235], v[58:61]
	v_mfma_f32_16x16x32_bf16 v[62:65], v[220:223], v[236:239], v[62:65]
	v_mfma_f32_16x16x32_bf16 v[42:45], v[220:223], v[240:243], v[42:45]
	v_mfma_f32_16x16x32_bf16 v[46:49], v[220:223], v[252:255], v[46:49]
	ds_read_b128 v[220:223], v244 offset:20800
	s_setprio 1
	s_waitcnt vmcnt(15)
	ds_write_b128 v164, v[180:183]
	s_waitcnt vmcnt(14)
	ds_write_b128 v164, v[188:191] offset:4608
	s_waitcnt lgkmcnt(5)
	v_mfma_f32_16x16x32_bf16 v[18:21], v[224:227], v[232:235], v[18:21]
	v_mfma_f32_16x16x32_bf16 v[22:25], v[224:227], v[236:239], v[22:25]
	v_mfma_f32_16x16x32_bf16 v[2:5], v[224:227], v[240:243], v[2:5]
	v_mfma_f32_16x16x32_bf16 v[6:9], v[224:227], v[252:255], v[6:9]
	ds_read_b128 v[224:227], v244 offset:23104
	s_waitcnt vmcnt(13)
	ds_write_b128 v164, v[192:195] offset:9216
	s_waitcnt vmcnt(12)
	ds_write_b128 v164, v[196:199] offset:13824
	s_waitcnt lgkmcnt(7)
	v_mfma_f32_16x16x32_bf16 v[26:29], v[228:231], v[232:235], v[26:29]
	ds_read_b128 v[232:235], v245 offset:55360
	v_mfma_f32_16x16x32_bf16 v[30:33], v[228:231], v[236:239], v[30:33]
	ds_read_b128 v[236:239], v245 offset:57664
	v_mfma_f32_16x16x32_bf16 v[10:13], v[228:231], v[240:243], v[10:13]
	ds_read_b128 v[240:243], v245 offset:59968
	v_mfma_f32_16x16x32_bf16 v[14:17], v[228:231], v[252:255], v[14:17]
	ds_read_b128 v[252:255], v245 offset:62272
	ds_read_b128 v[228:231], v244 offset:25408
	s_waitcnt lgkmcnt(4)
	v_mfma_f32_16x16x32_bf16 v[50:53], v[216:219], v[232:235], v[50:53]
	s_waitcnt lgkmcnt(3)
	v_mfma_f32_16x16x32_bf16 v[54:57], v[216:219], v[236:239], v[54:57]
	s_waitcnt lgkmcnt(2)
	v_mfma_f32_16x16x32_bf16 v[34:37], v[216:219], v[240:243], v[34:37]
	s_waitcnt lgkmcnt(1)
	v_mfma_f32_16x16x32_bf16 v[38:41], v[216:219], v[252:255], v[38:41]
	s_waitcnt vmcnt(11)
	ds_write_b128 v164, v[200:203] offset:36864
	s_waitcnt vmcnt(10)
	ds_write_b128 v164, v[204:207] offset:41472
	v_mfma_f32_16x16x32_bf16 v[58:61], v[220:223], v[232:235], v[58:61]
	v_mfma_f32_16x16x32_bf16 v[62:65], v[220:223], v[236:239], v[62:65]
	v_mfma_f32_16x16x32_bf16 v[42:45], v[220:223], v[240:243], v[42:45]
	v_mfma_f32_16x16x32_bf16 v[46:49], v[220:223], v[252:255], v[46:49]
	s_waitcnt vmcnt(9)
	ds_write_b128 v164, v[208:211] offset:46080
	s_waitcnt vmcnt(8)
	ds_write_b128 v164, v[212:215] offset:50688
	v_mfma_f32_16x16x32_bf16 v[18:21], v[224:227], v[232:235], v[18:21]
	v_mfma_f32_16x16x32_bf16 v[22:25], v[224:227], v[236:239], v[22:25]
	v_mfma_f32_16x16x32_bf16 v[2:5], v[224:227], v[240:243], v[2:5]
	v_mfma_f32_16x16x32_bf16 v[6:9], v[224:227], v[252:255], v[6:9]
	s_waitcnt lgkmcnt(4)
	v_mfma_f32_16x16x32_bf16 v[26:29], v[228:231], v[232:235], v[26:29]
	v_mfma_f32_16x16x32_bf16 v[30:33], v[228:231], v[236:239], v[30:33]
	v_mfma_f32_16x16x32_bf16 v[10:13], v[228:231], v[240:243], v[10:13]
	v_mfma_f32_16x16x32_bf16 v[14:17], v[228:231], v[252:255], v[14:17]
	s_waitcnt lgkmcnt(0)
	s_barrier
	s_setprio 0
	ds_read_b128 v[232:235], v245 offset:36864
	ds_read_b128 v[216:219], v244
	ds_read_b128 v[236:239], v245 offset:39168
	ds_read_b128 v[240:243], v245 offset:41472
	ds_read_b128 v[252:255], v245 offset:43776
	ds_read_b128 v[220:223], v244 offset:2304
	ds_read_b128 v[224:227], v244 offset:4608
	ds_read_b128 v[228:231], v244 offset:6912
	global_load_dwordx4 v[180:183], v[72:73], off offset:1024
	global_load_dwordx4 v[188:191], v[74:75], off offset:1024
	global_load_dwordx4 v[192:195], v[76:77], off offset:1024
	global_load_dwordx4 v[196:199], v[78:79], off offset:1024
	global_load_dwordx4 v[200:203], v[70:71], off offset:1024
	global_load_dwordx4 v[204:207], v[68:69], off offset:1024
	global_load_dwordx4 v[208:211], v[66:67], off offset:1024
	global_load_dwordx4 v[212:215], v[80:81], off offset:1024
	s_waitcnt lgkmcnt(6)
	v_mfma_f32_16x16x32_bf16 v[50:53], v[216:219], v[232:235], v[50:53]
	s_waitcnt lgkmcnt(5)
	v_mfma_f32_16x16x32_bf16 v[54:57], v[216:219], v[236:239], v[54:57]
	s_waitcnt lgkmcnt(4)
	v_mfma_f32_16x16x32_bf16 v[34:37], v[216:219], v[240:243], v[34:37]
	s_waitcnt lgkmcnt(3)
	v_mfma_f32_16x16x32_bf16 v[38:41], v[216:219], v[252:255], v[38:41]
	ds_read_b128 v[216:219], v244 offset:64
	s_waitcnt lgkmcnt(3)
	v_mfma_f32_16x16x32_bf16 v[58:61], v[220:223], v[232:235], v[58:61]
	v_mfma_f32_16x16x32_bf16 v[62:65], v[220:223], v[236:239], v[62:65]
	v_mfma_f32_16x16x32_bf16 v[42:45], v[220:223], v[240:243], v[42:45]
	v_mfma_f32_16x16x32_bf16 v[46:49], v[220:223], v[252:255], v[46:49]
	ds_read_b128 v[220:223], v244 offset:2368
	s_setprio 1
	s_waitcnt vmcnt(15)
	ds_write_b128 v164, v[122:125] offset:18432
	s_waitcnt vmcnt(14)
	ds_write_b128 v164, v[126:129] offset:23040
	s_waitcnt lgkmcnt(5)
	v_mfma_f32_16x16x32_bf16 v[18:21], v[224:227], v[232:235], v[18:21]
	v_mfma_f32_16x16x32_bf16 v[22:25], v[224:227], v[236:239], v[22:25]
	v_mfma_f32_16x16x32_bf16 v[2:5], v[224:227], v[240:243], v[2:5]
	v_mfma_f32_16x16x32_bf16 v[6:9], v[224:227], v[252:255], v[6:9]
	ds_read_b128 v[224:227], v244 offset:4672
	s_waitcnt vmcnt(13)
	ds_write_b128 v164, v[136:139] offset:27648
	s_waitcnt vmcnt(12)
	ds_write_b128 v164, v[140:143] offset:32256
	s_waitcnt lgkmcnt(7)
	v_mfma_f32_16x16x32_bf16 v[26:29], v[228:231], v[232:235], v[26:29]
	ds_read_b128 v[232:235], v245 offset:36928
	v_mfma_f32_16x16x32_bf16 v[30:33], v[228:231], v[236:239], v[30:33]
	ds_read_b128 v[236:239], v245 offset:39232
	v_mfma_f32_16x16x32_bf16 v[10:13], v[228:231], v[240:243], v[10:13]
	ds_read_b128 v[240:243], v245 offset:41536
	v_mfma_f32_16x16x32_bf16 v[14:17], v[228:231], v[252:255], v[14:17]
	ds_read_b128 v[252:255], v245 offset:43840
	ds_read_b128 v[228:231], v244 offset:6976
	s_waitcnt lgkmcnt(4)
	v_mfma_f32_16x16x32_bf16 v[50:53], v[216:219], v[232:235], v[50:53]
	s_waitcnt lgkmcnt(3)
	v_mfma_f32_16x16x32_bf16 v[54:57], v[216:219], v[236:239], v[54:57]
	s_waitcnt lgkmcnt(2)
	v_mfma_f32_16x16x32_bf16 v[34:37], v[216:219], v[240:243], v[34:37]
	s_waitcnt lgkmcnt(1)
	v_mfma_f32_16x16x32_bf16 v[38:41], v[216:219], v[252:255], v[38:41]
	s_waitcnt vmcnt(11)
	ds_write_b128 v164, v[144:147] offset:55296
	s_waitcnt vmcnt(10)
	ds_write_b128 v164, v[148:151] offset:59904
	v_mfma_f32_16x16x32_bf16 v[58:61], v[220:223], v[232:235], v[58:61]
	v_mfma_f32_16x16x32_bf16 v[62:65], v[220:223], v[236:239], v[62:65]
	v_mfma_f32_16x16x32_bf16 v[42:45], v[220:223], v[240:243], v[42:45]
	v_mfma_f32_16x16x32_bf16 v[46:49], v[220:223], v[252:255], v[46:49]
	s_waitcnt vmcnt(9)
	ds_write_b128 v164, v[172:175] offset:64512
	s_waitcnt vmcnt(8)
	ds_write_b128 v165, v[176:179] offset:32256
	v_mfma_f32_16x16x32_bf16 v[18:21], v[224:227], v[232:235], v[18:21]
	v_mfma_f32_16x16x32_bf16 v[22:25], v[224:227], v[236:239], v[22:25]
	v_mfma_f32_16x16x32_bf16 v[2:5], v[224:227], v[240:243], v[2:5]
	v_mfma_f32_16x16x32_bf16 v[6:9], v[224:227], v[252:255], v[6:9]
	s_waitcnt lgkmcnt(4)
	v_mfma_f32_16x16x32_bf16 v[26:29], v[228:231], v[232:235], v[26:29]
	v_mfma_f32_16x16x32_bf16 v[30:33], v[228:231], v[236:239], v[30:33]
	v_mfma_f32_16x16x32_bf16 v[10:13], v[228:231], v[240:243], v[10:13]
	v_mfma_f32_16x16x32_bf16 v[14:17], v[228:231], v[252:255], v[14:17]
	s_waitcnt lgkmcnt(0)
	s_barrier
	s_setprio 0
	ds_read_b128 v[232:235], v245 offset:55296
	ds_read_b128 v[216:219], v244 offset:18432
	ds_read_b128 v[236:239], v245 offset:57600
	ds_read_b128 v[240:243], v245 offset:59904
	ds_read_b128 v[252:255], v245 offset:62208
	ds_read_b128 v[220:223], v244 offset:20736
	ds_read_b128 v[224:227], v244 offset:23040
	ds_read_b128 v[228:231], v244 offset:25344
	global_load_dwordx4 v[122:125], v[72:73], off offset:1152
	global_load_dwordx4 v[126:129], v[74:75], off offset:1152
	global_load_dwordx4 v[136:139], v[76:77], off offset:1152
	global_load_dwordx4 v[140:143], v[78:79], off offset:1152
	global_load_dwordx4 v[144:147], v[70:71], off offset:1152
	global_load_dwordx4 v[148:151], v[68:69], off offset:1152
	global_load_dwordx4 v[172:175], v[66:67], off offset:1152
	global_load_dwordx4 v[176:179], v[80:81], off offset:1152
	s_waitcnt lgkmcnt(6)
	v_mfma_f32_16x16x32_bf16 v[50:53], v[216:219], v[232:235], v[50:53]
	s_waitcnt lgkmcnt(5)
	v_mfma_f32_16x16x32_bf16 v[54:57], v[216:219], v[236:239], v[54:57]
	s_waitcnt lgkmcnt(4)
	v_mfma_f32_16x16x32_bf16 v[34:37], v[216:219], v[240:243], v[34:37]
	s_waitcnt lgkmcnt(3)
	v_mfma_f32_16x16x32_bf16 v[38:41], v[216:219], v[252:255], v[38:41]
	ds_read_b128 v[216:219], v244 offset:18496
	s_waitcnt lgkmcnt(3)
	v_mfma_f32_16x16x32_bf16 v[58:61], v[220:223], v[232:235], v[58:61]
	v_mfma_f32_16x16x32_bf16 v[62:65], v[220:223], v[236:239], v[62:65]
	v_mfma_f32_16x16x32_bf16 v[42:45], v[220:223], v[240:243], v[42:45]
	v_mfma_f32_16x16x32_bf16 v[46:49], v[220:223], v[252:255], v[46:49]
	ds_read_b128 v[220:223], v244 offset:20800
	s_setprio 1
	s_waitcnt vmcnt(15)
	ds_write_b128 v164, v[180:183]
	s_waitcnt vmcnt(14)
	ds_write_b128 v164, v[188:191] offset:4608
	s_waitcnt lgkmcnt(5)
	v_mfma_f32_16x16x32_bf16 v[18:21], v[224:227], v[232:235], v[18:21]
	v_mfma_f32_16x16x32_bf16 v[22:25], v[224:227], v[236:239], v[22:25]
	v_mfma_f32_16x16x32_bf16 v[2:5], v[224:227], v[240:243], v[2:5]
	v_mfma_f32_16x16x32_bf16 v[6:9], v[224:227], v[252:255], v[6:9]
	ds_read_b128 v[224:227], v244 offset:23104
	s_waitcnt vmcnt(13)
	ds_write_b128 v164, v[192:195] offset:9216
	s_waitcnt vmcnt(12)
	ds_write_b128 v164, v[196:199] offset:13824
	s_waitcnt lgkmcnt(7)
	v_mfma_f32_16x16x32_bf16 v[26:29], v[228:231], v[232:235], v[26:29]
	ds_read_b128 v[232:235], v245 offset:55360
	v_mfma_f32_16x16x32_bf16 v[30:33], v[228:231], v[236:239], v[30:33]
	ds_read_b128 v[236:239], v245 offset:57664
	v_mfma_f32_16x16x32_bf16 v[10:13], v[228:231], v[240:243], v[10:13]
	ds_read_b128 v[240:243], v245 offset:59968
	v_mfma_f32_16x16x32_bf16 v[14:17], v[228:231], v[252:255], v[14:17]
	ds_read_b128 v[252:255], v245 offset:62272
	ds_read_b128 v[228:231], v244 offset:25408
	s_waitcnt lgkmcnt(4)
	v_mfma_f32_16x16x32_bf16 v[50:53], v[216:219], v[232:235], v[50:53]
	s_waitcnt lgkmcnt(3)
	v_mfma_f32_16x16x32_bf16 v[54:57], v[216:219], v[236:239], v[54:57]
	s_waitcnt lgkmcnt(2)
	v_mfma_f32_16x16x32_bf16 v[34:37], v[216:219], v[240:243], v[34:37]
	s_waitcnt lgkmcnt(1)
	v_mfma_f32_16x16x32_bf16 v[38:41], v[216:219], v[252:255], v[38:41]
	s_waitcnt vmcnt(11)
	ds_write_b128 v164, v[200:203] offset:36864
	s_waitcnt vmcnt(10)
	ds_write_b128 v164, v[204:207] offset:41472
	v_mfma_f32_16x16x32_bf16 v[58:61], v[220:223], v[232:235], v[58:61]
	v_mfma_f32_16x16x32_bf16 v[62:65], v[220:223], v[236:239], v[62:65]
	v_mfma_f32_16x16x32_bf16 v[42:45], v[220:223], v[240:243], v[42:45]
	v_mfma_f32_16x16x32_bf16 v[46:49], v[220:223], v[252:255], v[46:49]
	s_waitcnt vmcnt(9)
	ds_write_b128 v164, v[208:211] offset:46080
	s_waitcnt vmcnt(8)
	ds_write_b128 v164, v[212:215] offset:50688
	v_mfma_f32_16x16x32_bf16 v[18:21], v[224:227], v[232:235], v[18:21]
	v_mfma_f32_16x16x32_bf16 v[22:25], v[224:227], v[236:239], v[22:25]
	v_mfma_f32_16x16x32_bf16 v[2:5], v[224:227], v[240:243], v[2:5]
	v_mfma_f32_16x16x32_bf16 v[6:9], v[224:227], v[252:255], v[6:9]
	s_waitcnt lgkmcnt(4)
	v_mfma_f32_16x16x32_bf16 v[26:29], v[228:231], v[232:235], v[26:29]
	v_mfma_f32_16x16x32_bf16 v[30:33], v[228:231], v[236:239], v[30:33]
	v_mfma_f32_16x16x32_bf16 v[10:13], v[228:231], v[240:243], v[10:13]
	v_mfma_f32_16x16x32_bf16 v[14:17], v[228:231], v[252:255], v[14:17]
	s_waitcnt lgkmcnt(0)
	s_barrier
	s_setprio 0
	ds_read_b128 v[232:235], v245 offset:36864
	ds_read_b128 v[216:219], v244
	ds_read_b128 v[236:239], v245 offset:39168
	ds_read_b128 v[240:243], v245 offset:41472
	ds_read_b128 v[252:255], v245 offset:43776
	ds_read_b128 v[220:223], v244 offset:2304
	ds_read_b128 v[224:227], v244 offset:4608
	ds_read_b128 v[228:231], v244 offset:6912
	global_load_dwordx4 v[180:183], v[72:73], off offset:1280
	global_load_dwordx4 v[188:191], v[74:75], off offset:1280
	global_load_dwordx4 v[192:195], v[76:77], off offset:1280
	global_load_dwordx4 v[196:199], v[78:79], off offset:1280
	global_load_dwordx4 v[200:203], v[70:71], off offset:1280
	global_load_dwordx4 v[204:207], v[68:69], off offset:1280
	global_load_dwordx4 v[208:211], v[66:67], off offset:1280
	global_load_dwordx4 v[212:215], v[80:81], off offset:1280
	s_waitcnt lgkmcnt(6)
	v_mfma_f32_16x16x32_bf16 v[50:53], v[216:219], v[232:235], v[50:53]
	s_waitcnt lgkmcnt(5)
	v_mfma_f32_16x16x32_bf16 v[54:57], v[216:219], v[236:239], v[54:57]
	s_waitcnt lgkmcnt(4)
	v_mfma_f32_16x16x32_bf16 v[34:37], v[216:219], v[240:243], v[34:37]
	s_waitcnt lgkmcnt(3)
	v_mfma_f32_16x16x32_bf16 v[38:41], v[216:219], v[252:255], v[38:41]
	ds_read_b128 v[216:219], v244 offset:64
	s_waitcnt lgkmcnt(3)
	v_mfma_f32_16x16x32_bf16 v[58:61], v[220:223], v[232:235], v[58:61]
	v_mfma_f32_16x16x32_bf16 v[62:65], v[220:223], v[236:239], v[62:65]
	v_mfma_f32_16x16x32_bf16 v[42:45], v[220:223], v[240:243], v[42:45]
	v_mfma_f32_16x16x32_bf16 v[46:49], v[220:223], v[252:255], v[46:49]
	ds_read_b128 v[220:223], v244 offset:2368
	s_setprio 1
	s_waitcnt vmcnt(15)
	ds_write_b128 v164, v[122:125] offset:18432
	s_waitcnt vmcnt(14)
	ds_write_b128 v164, v[126:129] offset:23040
	s_waitcnt lgkmcnt(5)
	v_mfma_f32_16x16x32_bf16 v[18:21], v[224:227], v[232:235], v[18:21]
	v_mfma_f32_16x16x32_bf16 v[22:25], v[224:227], v[236:239], v[22:25]
	v_mfma_f32_16x16x32_bf16 v[2:5], v[224:227], v[240:243], v[2:5]
	v_mfma_f32_16x16x32_bf16 v[6:9], v[224:227], v[252:255], v[6:9]
	ds_read_b128 v[224:227], v244 offset:4672
	s_waitcnt vmcnt(13)
	ds_write_b128 v164, v[136:139] offset:27648
	s_waitcnt vmcnt(12)
	ds_write_b128 v164, v[140:143] offset:32256
	s_waitcnt lgkmcnt(7)
	v_mfma_f32_16x16x32_bf16 v[26:29], v[228:231], v[232:235], v[26:29]
	ds_read_b128 v[232:235], v245 offset:36928
	v_mfma_f32_16x16x32_bf16 v[30:33], v[228:231], v[236:239], v[30:33]
	ds_read_b128 v[236:239], v245 offset:39232
	v_mfma_f32_16x16x32_bf16 v[10:13], v[228:231], v[240:243], v[10:13]
	ds_read_b128 v[240:243], v245 offset:41536
	v_mfma_f32_16x16x32_bf16 v[14:17], v[228:231], v[252:255], v[14:17]
	ds_read_b128 v[252:255], v245 offset:43840
	ds_read_b128 v[228:231], v244 offset:6976
	s_waitcnt lgkmcnt(4)
	v_mfma_f32_16x16x32_bf16 v[50:53], v[216:219], v[232:235], v[50:53]
	s_waitcnt lgkmcnt(3)
	v_mfma_f32_16x16x32_bf16 v[54:57], v[216:219], v[236:239], v[54:57]
	s_waitcnt lgkmcnt(2)
	v_mfma_f32_16x16x32_bf16 v[34:37], v[216:219], v[240:243], v[34:37]
	s_waitcnt lgkmcnt(1)
	v_mfma_f32_16x16x32_bf16 v[38:41], v[216:219], v[252:255], v[38:41]
	s_waitcnt vmcnt(11)
	ds_write_b128 v164, v[144:147] offset:55296
	s_waitcnt vmcnt(10)
	ds_write_b128 v164, v[148:151] offset:59904
	v_mfma_f32_16x16x32_bf16 v[58:61], v[220:223], v[232:235], v[58:61]
	v_mfma_f32_16x16x32_bf16 v[62:65], v[220:223], v[236:239], v[62:65]
	v_mfma_f32_16x16x32_bf16 v[42:45], v[220:223], v[240:243], v[42:45]
	v_mfma_f32_16x16x32_bf16 v[46:49], v[220:223], v[252:255], v[46:49]
	s_waitcnt vmcnt(9)
	ds_write_b128 v164, v[172:175] offset:64512
	s_waitcnt vmcnt(8)
	ds_write_b128 v165, v[176:179] offset:32256
	v_mfma_f32_16x16x32_bf16 v[18:21], v[224:227], v[232:235], v[18:21]
	v_mfma_f32_16x16x32_bf16 v[22:25], v[224:227], v[236:239], v[22:25]
	v_mfma_f32_16x16x32_bf16 v[2:5], v[224:227], v[240:243], v[2:5]
	v_mfma_f32_16x16x32_bf16 v[6:9], v[224:227], v[252:255], v[6:9]
	s_waitcnt lgkmcnt(4)
	v_mfma_f32_16x16x32_bf16 v[26:29], v[228:231], v[232:235], v[26:29]
	v_mfma_f32_16x16x32_bf16 v[30:33], v[228:231], v[236:239], v[30:33]
	v_mfma_f32_16x16x32_bf16 v[10:13], v[228:231], v[240:243], v[10:13]
	v_mfma_f32_16x16x32_bf16 v[14:17], v[228:231], v[252:255], v[14:17]
	s_waitcnt lgkmcnt(0)
	s_barrier
	s_setprio 0
	ds_read_b128 v[232:235], v245 offset:55296
	ds_read_b128 v[216:219], v244 offset:18432
	ds_read_b128 v[236:239], v245 offset:57600
	ds_read_b128 v[240:243], v245 offset:59904
	ds_read_b128 v[252:255], v245 offset:62208
	ds_read_b128 v[220:223], v244 offset:20736
	ds_read_b128 v[224:227], v244 offset:23040
	ds_read_b128 v[228:231], v244 offset:25344
	global_load_dwordx4 v[122:125], v[72:73], off offset:1408
	global_load_dwordx4 v[126:129], v[74:75], off offset:1408
	global_load_dwordx4 v[136:139], v[76:77], off offset:1408
	global_load_dwordx4 v[140:143], v[78:79], off offset:1408
	global_load_dwordx4 v[144:147], v[70:71], off offset:1408
	global_load_dwordx4 v[148:151], v[68:69], off offset:1408
	global_load_dwordx4 v[172:175], v[66:67], off offset:1408
	global_load_dwordx4 v[176:179], v[80:81], off offset:1408
	s_waitcnt lgkmcnt(6)
	v_mfma_f32_16x16x32_bf16 v[50:53], v[216:219], v[232:235], v[50:53]
	s_waitcnt lgkmcnt(5)
	v_mfma_f32_16x16x32_bf16 v[54:57], v[216:219], v[236:239], v[54:57]
	s_waitcnt lgkmcnt(4)
	v_mfma_f32_16x16x32_bf16 v[34:37], v[216:219], v[240:243], v[34:37]
	s_waitcnt lgkmcnt(3)
	v_mfma_f32_16x16x32_bf16 v[38:41], v[216:219], v[252:255], v[38:41]
	ds_read_b128 v[216:219], v244 offset:18496
	s_waitcnt lgkmcnt(3)
	v_mfma_f32_16x16x32_bf16 v[58:61], v[220:223], v[232:235], v[58:61]
	v_mfma_f32_16x16x32_bf16 v[62:65], v[220:223], v[236:239], v[62:65]
	v_mfma_f32_16x16x32_bf16 v[42:45], v[220:223], v[240:243], v[42:45]
	v_mfma_f32_16x16x32_bf16 v[46:49], v[220:223], v[252:255], v[46:49]
	ds_read_b128 v[220:223], v244 offset:20800
	s_setprio 1
	s_waitcnt vmcnt(15)
	ds_write_b128 v164, v[180:183]
	s_waitcnt vmcnt(14)
	ds_write_b128 v164, v[188:191] offset:4608
	s_waitcnt lgkmcnt(5)
	v_mfma_f32_16x16x32_bf16 v[18:21], v[224:227], v[232:235], v[18:21]
	v_mfma_f32_16x16x32_bf16 v[22:25], v[224:227], v[236:239], v[22:25]
	v_mfma_f32_16x16x32_bf16 v[2:5], v[224:227], v[240:243], v[2:5]
	v_mfma_f32_16x16x32_bf16 v[6:9], v[224:227], v[252:255], v[6:9]
	ds_read_b128 v[224:227], v244 offset:23104
	s_waitcnt vmcnt(13)
	ds_write_b128 v164, v[192:195] offset:9216
	s_waitcnt vmcnt(12)
	ds_write_b128 v164, v[196:199] offset:13824
	s_waitcnt lgkmcnt(7)
	v_mfma_f32_16x16x32_bf16 v[26:29], v[228:231], v[232:235], v[26:29]
	ds_read_b128 v[232:235], v245 offset:55360
	v_mfma_f32_16x16x32_bf16 v[30:33], v[228:231], v[236:239], v[30:33]
	ds_read_b128 v[236:239], v245 offset:57664
	v_mfma_f32_16x16x32_bf16 v[10:13], v[228:231], v[240:243], v[10:13]
	ds_read_b128 v[240:243], v245 offset:59968
	v_mfma_f32_16x16x32_bf16 v[14:17], v[228:231], v[252:255], v[14:17]
	ds_read_b128 v[252:255], v245 offset:62272
	ds_read_b128 v[228:231], v244 offset:25408
	s_waitcnt lgkmcnt(4)
	v_mfma_f32_16x16x32_bf16 v[50:53], v[216:219], v[232:235], v[50:53]
	s_waitcnt lgkmcnt(3)
	v_mfma_f32_16x16x32_bf16 v[54:57], v[216:219], v[236:239], v[54:57]
	s_waitcnt lgkmcnt(2)
	v_mfma_f32_16x16x32_bf16 v[34:37], v[216:219], v[240:243], v[34:37]
	s_waitcnt lgkmcnt(1)
	v_mfma_f32_16x16x32_bf16 v[38:41], v[216:219], v[252:255], v[38:41]
	s_waitcnt vmcnt(11)
	ds_write_b128 v164, v[200:203] offset:36864
	s_waitcnt vmcnt(10)
	ds_write_b128 v164, v[204:207] offset:41472
	v_mfma_f32_16x16x32_bf16 v[58:61], v[220:223], v[232:235], v[58:61]
	v_mfma_f32_16x16x32_bf16 v[62:65], v[220:223], v[236:239], v[62:65]
	v_mfma_f32_16x16x32_bf16 v[42:45], v[220:223], v[240:243], v[42:45]
	v_mfma_f32_16x16x32_bf16 v[46:49], v[220:223], v[252:255], v[46:49]
	s_waitcnt vmcnt(9)
	ds_write_b128 v164, v[208:211] offset:46080
	s_waitcnt vmcnt(8)
	ds_write_b128 v164, v[212:215] offset:50688
	v_mfma_f32_16x16x32_bf16 v[18:21], v[224:227], v[232:235], v[18:21]
	v_mfma_f32_16x16x32_bf16 v[22:25], v[224:227], v[236:239], v[22:25]
	v_mfma_f32_16x16x32_bf16 v[2:5], v[224:227], v[240:243], v[2:5]
	v_mfma_f32_16x16x32_bf16 v[6:9], v[224:227], v[252:255], v[6:9]
	s_waitcnt lgkmcnt(4)
	v_mfma_f32_16x16x32_bf16 v[26:29], v[228:231], v[232:235], v[26:29]
	v_mfma_f32_16x16x32_bf16 v[30:33], v[228:231], v[236:239], v[30:33]
	v_mfma_f32_16x16x32_bf16 v[10:13], v[228:231], v[240:243], v[10:13]
	v_mfma_f32_16x16x32_bf16 v[14:17], v[228:231], v[252:255], v[14:17]
	s_waitcnt lgkmcnt(0)
	s_barrier
	s_setprio 0
	ds_read_b128 v[232:235], v245 offset:36864
	ds_read_b128 v[216:219], v244
	ds_read_b128 v[236:239], v245 offset:39168
	ds_read_b128 v[240:243], v245 offset:41472
	ds_read_b128 v[252:255], v245 offset:43776
	ds_read_b128 v[220:223], v244 offset:2304
	ds_read_b128 v[224:227], v244 offset:4608
	ds_read_b128 v[228:231], v244 offset:6912
	global_load_dwordx4 v[180:183], v[72:73], off offset:1536
	global_load_dwordx4 v[188:191], v[74:75], off offset:1536
	global_load_dwordx4 v[192:195], v[76:77], off offset:1536
	global_load_dwordx4 v[196:199], v[78:79], off offset:1536
	global_load_dwordx4 v[200:203], v[70:71], off offset:1536
	global_load_dwordx4 v[204:207], v[68:69], off offset:1536
	global_load_dwordx4 v[208:211], v[66:67], off offset:1536
	global_load_dwordx4 v[212:215], v[80:81], off offset:1536
	s_waitcnt lgkmcnt(6)
	v_mfma_f32_16x16x32_bf16 v[50:53], v[216:219], v[232:235], v[50:53]
	s_waitcnt lgkmcnt(5)
	v_mfma_f32_16x16x32_bf16 v[54:57], v[216:219], v[236:239], v[54:57]
	s_waitcnt lgkmcnt(4)
	v_mfma_f32_16x16x32_bf16 v[34:37], v[216:219], v[240:243], v[34:37]
	s_waitcnt lgkmcnt(3)
	v_mfma_f32_16x16x32_bf16 v[38:41], v[216:219], v[252:255], v[38:41]
	ds_read_b128 v[216:219], v244 offset:64
	s_waitcnt lgkmcnt(3)
	v_mfma_f32_16x16x32_bf16 v[58:61], v[220:223], v[232:235], v[58:61]
	v_mfma_f32_16x16x32_bf16 v[62:65], v[220:223], v[236:239], v[62:65]
	v_mfma_f32_16x16x32_bf16 v[42:45], v[220:223], v[240:243], v[42:45]
	v_mfma_f32_16x16x32_bf16 v[46:49], v[220:223], v[252:255], v[46:49]
	ds_read_b128 v[220:223], v244 offset:2368
	s_setprio 1
	s_waitcnt vmcnt(15)
	ds_write_b128 v164, v[122:125] offset:18432
	s_waitcnt vmcnt(14)
	ds_write_b128 v164, v[126:129] offset:23040
	s_waitcnt lgkmcnt(5)
	v_mfma_f32_16x16x32_bf16 v[18:21], v[224:227], v[232:235], v[18:21]
	v_mfma_f32_16x16x32_bf16 v[22:25], v[224:227], v[236:239], v[22:25]
	v_mfma_f32_16x16x32_bf16 v[2:5], v[224:227], v[240:243], v[2:5]
	v_mfma_f32_16x16x32_bf16 v[6:9], v[224:227], v[252:255], v[6:9]
	ds_read_b128 v[224:227], v244 offset:4672
	s_waitcnt vmcnt(13)
	ds_write_b128 v164, v[136:139] offset:27648
	s_waitcnt vmcnt(12)
	ds_write_b128 v164, v[140:143] offset:32256
	s_waitcnt lgkmcnt(7)
	v_mfma_f32_16x16x32_bf16 v[26:29], v[228:231], v[232:235], v[26:29]
	ds_read_b128 v[232:235], v245 offset:36928
	v_mfma_f32_16x16x32_bf16 v[30:33], v[228:231], v[236:239], v[30:33]
	ds_read_b128 v[236:239], v245 offset:39232
	v_mfma_f32_16x16x32_bf16 v[10:13], v[228:231], v[240:243], v[10:13]
	ds_read_b128 v[240:243], v245 offset:41536
	v_mfma_f32_16x16x32_bf16 v[14:17], v[228:231], v[252:255], v[14:17]
	ds_read_b128 v[252:255], v245 offset:43840
	ds_read_b128 v[228:231], v244 offset:6976
	s_waitcnt lgkmcnt(4)
	v_mfma_f32_16x16x32_bf16 v[50:53], v[216:219], v[232:235], v[50:53]
	s_waitcnt lgkmcnt(3)
	v_mfma_f32_16x16x32_bf16 v[54:57], v[216:219], v[236:239], v[54:57]
	s_waitcnt lgkmcnt(2)
	v_mfma_f32_16x16x32_bf16 v[34:37], v[216:219], v[240:243], v[34:37]
	s_waitcnt lgkmcnt(1)
	v_mfma_f32_16x16x32_bf16 v[38:41], v[216:219], v[252:255], v[38:41]
	s_waitcnt vmcnt(11)
	ds_write_b128 v164, v[144:147] offset:55296
	s_waitcnt vmcnt(10)
	ds_write_b128 v164, v[148:151] offset:59904
	v_mfma_f32_16x16x32_bf16 v[58:61], v[220:223], v[232:235], v[58:61]
	v_mfma_f32_16x16x32_bf16 v[62:65], v[220:223], v[236:239], v[62:65]
	v_mfma_f32_16x16x32_bf16 v[42:45], v[220:223], v[240:243], v[42:45]
	v_mfma_f32_16x16x32_bf16 v[46:49], v[220:223], v[252:255], v[46:49]
	s_waitcnt vmcnt(9)
	ds_write_b128 v164, v[172:175] offset:64512
	s_waitcnt vmcnt(8)
	ds_write_b128 v165, v[176:179] offset:32256
	v_mfma_f32_16x16x32_bf16 v[18:21], v[224:227], v[232:235], v[18:21]
	v_mfma_f32_16x16x32_bf16 v[22:25], v[224:227], v[236:239], v[22:25]
	v_mfma_f32_16x16x32_bf16 v[2:5], v[224:227], v[240:243], v[2:5]
	v_mfma_f32_16x16x32_bf16 v[6:9], v[224:227], v[252:255], v[6:9]
	s_waitcnt lgkmcnt(4)
	v_mfma_f32_16x16x32_bf16 v[26:29], v[228:231], v[232:235], v[26:29]
	v_mfma_f32_16x16x32_bf16 v[30:33], v[228:231], v[236:239], v[30:33]
	v_mfma_f32_16x16x32_bf16 v[10:13], v[228:231], v[240:243], v[10:13]
	v_mfma_f32_16x16x32_bf16 v[14:17], v[228:231], v[252:255], v[14:17]
	s_waitcnt lgkmcnt(0)
	s_barrier
	s_setprio 0
	ds_read_b128 v[232:235], v245 offset:55296
	ds_read_b128 v[216:219], v244 offset:18432
	ds_read_b128 v[236:239], v245 offset:57600
	ds_read_b128 v[240:243], v245 offset:59904
	ds_read_b128 v[252:255], v245 offset:62208
	ds_read_b128 v[220:223], v244 offset:20736
	ds_read_b128 v[224:227], v244 offset:23040
	ds_read_b128 v[228:231], v244 offset:25344
	global_load_dwordx4 v[122:125], v[72:73], off offset:1664
	global_load_dwordx4 v[126:129], v[74:75], off offset:1664
	global_load_dwordx4 v[136:139], v[76:77], off offset:1664
	global_load_dwordx4 v[140:143], v[78:79], off offset:1664
	global_load_dwordx4 v[144:147], v[70:71], off offset:1664
	global_load_dwordx4 v[148:151], v[68:69], off offset:1664
	global_load_dwordx4 v[172:175], v[66:67], off offset:1664
	global_load_dwordx4 v[176:179], v[80:81], off offset:1664
	s_waitcnt lgkmcnt(6)
	v_mfma_f32_16x16x32_bf16 v[50:53], v[216:219], v[232:235], v[50:53]
	s_waitcnt lgkmcnt(5)
	v_mfma_f32_16x16x32_bf16 v[54:57], v[216:219], v[236:239], v[54:57]
	s_waitcnt lgkmcnt(4)
	v_mfma_f32_16x16x32_bf16 v[34:37], v[216:219], v[240:243], v[34:37]
	s_waitcnt lgkmcnt(3)
	v_mfma_f32_16x16x32_bf16 v[38:41], v[216:219], v[252:255], v[38:41]
	ds_read_b128 v[216:219], v244 offset:18496
	s_waitcnt lgkmcnt(3)
	v_mfma_f32_16x16x32_bf16 v[58:61], v[220:223], v[232:235], v[58:61]
	v_mfma_f32_16x16x32_bf16 v[62:65], v[220:223], v[236:239], v[62:65]
	v_mfma_f32_16x16x32_bf16 v[42:45], v[220:223], v[240:243], v[42:45]
	v_mfma_f32_16x16x32_bf16 v[46:49], v[220:223], v[252:255], v[46:49]
	ds_read_b128 v[220:223], v244 offset:20800
	s_setprio 1
	s_waitcnt vmcnt(15)
	ds_write_b128 v164, v[180:183]
	s_waitcnt vmcnt(14)
	ds_write_b128 v164, v[188:191] offset:4608
	s_waitcnt lgkmcnt(5)
	v_mfma_f32_16x16x32_bf16 v[18:21], v[224:227], v[232:235], v[18:21]
	v_mfma_f32_16x16x32_bf16 v[22:25], v[224:227], v[236:239], v[22:25]
	v_mfma_f32_16x16x32_bf16 v[2:5], v[224:227], v[240:243], v[2:5]
	v_mfma_f32_16x16x32_bf16 v[6:9], v[224:227], v[252:255], v[6:9]
	ds_read_b128 v[224:227], v244 offset:23104
	s_waitcnt vmcnt(13)
	ds_write_b128 v164, v[192:195] offset:9216
	s_waitcnt vmcnt(12)
	ds_write_b128 v164, v[196:199] offset:13824
	s_waitcnt lgkmcnt(7)
	v_mfma_f32_16x16x32_bf16 v[26:29], v[228:231], v[232:235], v[26:29]
	ds_read_b128 v[232:235], v245 offset:55360
	v_mfma_f32_16x16x32_bf16 v[30:33], v[228:231], v[236:239], v[30:33]
	ds_read_b128 v[236:239], v245 offset:57664
	v_mfma_f32_16x16x32_bf16 v[10:13], v[228:231], v[240:243], v[10:13]
	ds_read_b128 v[240:243], v245 offset:59968
	v_mfma_f32_16x16x32_bf16 v[14:17], v[228:231], v[252:255], v[14:17]
	ds_read_b128 v[252:255], v245 offset:62272
	ds_read_b128 v[228:231], v244 offset:25408
	s_waitcnt lgkmcnt(4)
	v_mfma_f32_16x16x32_bf16 v[50:53], v[216:219], v[232:235], v[50:53]
	s_waitcnt lgkmcnt(3)
	v_mfma_f32_16x16x32_bf16 v[54:57], v[216:219], v[236:239], v[54:57]
	s_waitcnt lgkmcnt(2)
	v_mfma_f32_16x16x32_bf16 v[34:37], v[216:219], v[240:243], v[34:37]
	s_waitcnt lgkmcnt(1)
	v_mfma_f32_16x16x32_bf16 v[38:41], v[216:219], v[252:255], v[38:41]
	s_waitcnt vmcnt(11)
	ds_write_b128 v164, v[200:203] offset:36864
	s_waitcnt vmcnt(10)
	ds_write_b128 v164, v[204:207] offset:41472
	v_mfma_f32_16x16x32_bf16 v[58:61], v[220:223], v[232:235], v[58:61]
	v_mfma_f32_16x16x32_bf16 v[62:65], v[220:223], v[236:239], v[62:65]
	v_mfma_f32_16x16x32_bf16 v[42:45], v[220:223], v[240:243], v[42:45]
	v_mfma_f32_16x16x32_bf16 v[46:49], v[220:223], v[252:255], v[46:49]
	s_waitcnt vmcnt(9)
	ds_write_b128 v164, v[208:211] offset:46080
	s_waitcnt vmcnt(8)
	ds_write_b128 v164, v[212:215] offset:50688
	v_mfma_f32_16x16x32_bf16 v[18:21], v[224:227], v[232:235], v[18:21]
	v_mfma_f32_16x16x32_bf16 v[22:25], v[224:227], v[236:239], v[22:25]
	v_mfma_f32_16x16x32_bf16 v[2:5], v[224:227], v[240:243], v[2:5]
	v_mfma_f32_16x16x32_bf16 v[6:9], v[224:227], v[252:255], v[6:9]
	s_waitcnt lgkmcnt(4)
	v_mfma_f32_16x16x32_bf16 v[26:29], v[228:231], v[232:235], v[26:29]
	v_mfma_f32_16x16x32_bf16 v[30:33], v[228:231], v[236:239], v[30:33]
	v_mfma_f32_16x16x32_bf16 v[10:13], v[228:231], v[240:243], v[10:13]
	v_mfma_f32_16x16x32_bf16 v[14:17], v[228:231], v[252:255], v[14:17]
	s_waitcnt lgkmcnt(0)
	s_barrier
	s_setprio 0
	ds_read_b128 v[232:235], v245 offset:36864
	ds_read_b128 v[216:219], v244
	ds_read_b128 v[236:239], v245 offset:39168
	ds_read_b128 v[240:243], v245 offset:41472
	ds_read_b128 v[252:255], v245 offset:43776
	ds_read_b128 v[220:223], v244 offset:2304
	ds_read_b128 v[224:227], v244 offset:4608
	ds_read_b128 v[228:231], v244 offset:6912
	global_load_dwordx4 v[180:183], v[72:73], off offset:1792
	global_load_dwordx4 v[188:191], v[74:75], off offset:1792
	global_load_dwordx4 v[192:195], v[76:77], off offset:1792
	global_load_dwordx4 v[196:199], v[78:79], off offset:1792
	global_load_dwordx4 v[200:203], v[70:71], off offset:1792
	global_load_dwordx4 v[204:207], v[68:69], off offset:1792
	global_load_dwordx4 v[208:211], v[66:67], off offset:1792
	global_load_dwordx4 v[212:215], v[80:81], off offset:1792
	s_waitcnt lgkmcnt(6)
	v_mfma_f32_16x16x32_bf16 v[50:53], v[216:219], v[232:235], v[50:53]
	s_waitcnt lgkmcnt(5)
	v_mfma_f32_16x16x32_bf16 v[54:57], v[216:219], v[236:239], v[54:57]
	s_waitcnt lgkmcnt(4)
	v_mfma_f32_16x16x32_bf16 v[34:37], v[216:219], v[240:243], v[34:37]
	s_waitcnt lgkmcnt(3)
	v_mfma_f32_16x16x32_bf16 v[38:41], v[216:219], v[252:255], v[38:41]
	ds_read_b128 v[216:219], v244 offset:64
	s_waitcnt lgkmcnt(3)
	v_mfma_f32_16x16x32_bf16 v[58:61], v[220:223], v[232:235], v[58:61]
	v_mfma_f32_16x16x32_bf16 v[62:65], v[220:223], v[236:239], v[62:65]
	v_mfma_f32_16x16x32_bf16 v[42:45], v[220:223], v[240:243], v[42:45]
	v_mfma_f32_16x16x32_bf16 v[46:49], v[220:223], v[252:255], v[46:49]
	ds_read_b128 v[220:223], v244 offset:2368
	s_setprio 1
	s_waitcnt vmcnt(15)
	ds_write_b128 v164, v[122:125] offset:18432
	s_waitcnt vmcnt(14)
	ds_write_b128 v164, v[126:129] offset:23040
	s_waitcnt lgkmcnt(5)
	v_mfma_f32_16x16x32_bf16 v[18:21], v[224:227], v[232:235], v[18:21]
	v_mfma_f32_16x16x32_bf16 v[22:25], v[224:227], v[236:239], v[22:25]
	v_mfma_f32_16x16x32_bf16 v[2:5], v[224:227], v[240:243], v[2:5]
	v_mfma_f32_16x16x32_bf16 v[6:9], v[224:227], v[252:255], v[6:9]
	ds_read_b128 v[224:227], v244 offset:4672
	s_waitcnt vmcnt(13)
	ds_write_b128 v164, v[136:139] offset:27648
	s_waitcnt vmcnt(12)
	ds_write_b128 v164, v[140:143] offset:32256
	s_waitcnt lgkmcnt(7)
	v_mfma_f32_16x16x32_bf16 v[26:29], v[228:231], v[232:235], v[26:29]
	ds_read_b128 v[232:235], v245 offset:36928
	v_mfma_f32_16x16x32_bf16 v[30:33], v[228:231], v[236:239], v[30:33]
	ds_read_b128 v[236:239], v245 offset:39232
	v_mfma_f32_16x16x32_bf16 v[10:13], v[228:231], v[240:243], v[10:13]
	ds_read_b128 v[240:243], v245 offset:41536
	v_mfma_f32_16x16x32_bf16 v[14:17], v[228:231], v[252:255], v[14:17]
	ds_read_b128 v[252:255], v245 offset:43840
	ds_read_b128 v[228:231], v244 offset:6976
	s_waitcnt lgkmcnt(4)
	v_mfma_f32_16x16x32_bf16 v[50:53], v[216:219], v[232:235], v[50:53]
	s_waitcnt lgkmcnt(3)
	v_mfma_f32_16x16x32_bf16 v[54:57], v[216:219], v[236:239], v[54:57]
	s_waitcnt lgkmcnt(2)
	v_mfma_f32_16x16x32_bf16 v[34:37], v[216:219], v[240:243], v[34:37]
	s_waitcnt lgkmcnt(1)
	v_mfma_f32_16x16x32_bf16 v[38:41], v[216:219], v[252:255], v[38:41]
	s_waitcnt vmcnt(11)
	ds_write_b128 v164, v[144:147] offset:55296
	s_waitcnt vmcnt(10)
	ds_write_b128 v164, v[148:151] offset:59904
	v_mfma_f32_16x16x32_bf16 v[58:61], v[220:223], v[232:235], v[58:61]
	v_mfma_f32_16x16x32_bf16 v[62:65], v[220:223], v[236:239], v[62:65]
	v_mfma_f32_16x16x32_bf16 v[42:45], v[220:223], v[240:243], v[42:45]
	v_mfma_f32_16x16x32_bf16 v[46:49], v[220:223], v[252:255], v[46:49]
	s_waitcnt vmcnt(9)
	ds_write_b128 v164, v[172:175] offset:64512
	s_waitcnt vmcnt(8)
	ds_write_b128 v165, v[176:179] offset:32256
	v_mfma_f32_16x16x32_bf16 v[18:21], v[224:227], v[232:235], v[18:21]
	v_mfma_f32_16x16x32_bf16 v[22:25], v[224:227], v[236:239], v[22:25]
	v_mfma_f32_16x16x32_bf16 v[2:5], v[224:227], v[240:243], v[2:5]
	v_mfma_f32_16x16x32_bf16 v[6:9], v[224:227], v[252:255], v[6:9]
	s_waitcnt lgkmcnt(4)
	v_mfma_f32_16x16x32_bf16 v[26:29], v[228:231], v[232:235], v[26:29]
	v_mfma_f32_16x16x32_bf16 v[30:33], v[228:231], v[236:239], v[30:33]
	v_mfma_f32_16x16x32_bf16 v[10:13], v[228:231], v[240:243], v[10:13]
	v_mfma_f32_16x16x32_bf16 v[14:17], v[228:231], v[252:255], v[14:17]
	s_waitcnt lgkmcnt(0)
	s_barrier
	s_setprio 0
	global_load_dwordx4 v[122:125], v[72:73], off offset:1920
	s_nop 0
	global_load_dwordx4 v[72:75], v[74:75], off offset:1920
	s_nop 0
	global_load_dwordx4 v[126:129], v[76:77], off offset:1920
	s_nop 0
	global_load_dwordx4 v[76:79], v[78:79], off offset:1920
	s_nop 0
	global_load_dwordx4 v[136:139], v[70:71], off offset:1920
	s_nop 0
	global_load_dwordx4 v[68:71], v[68:69], off offset:1920
	s_nop 0
	global_load_dwordx4 v[140:143], v[66:67], off offset:1920
	global_load_dwordx4 v[144:147], v[80:81], off offset:1920
	ds_read_b128 v[232:235], v245 offset:55296
	ds_read_b128 v[216:219], v244 offset:18432
	ds_read_b128 v[236:239], v245 offset:57600
	ds_read_b128 v[240:243], v245 offset:59904
	ds_read_b128 v[252:255], v245 offset:62208
	ds_read_b128 v[220:223], v244 offset:20736
	ds_read_b128 v[224:227], v244 offset:23040
	ds_read_b128 v[228:231], v244 offset:25344
	s_waitcnt lgkmcnt(6)
	v_mfma_f32_16x16x32_bf16 v[50:53], v[216:219], v[232:235], v[50:53]
	s_waitcnt lgkmcnt(5)
	v_mfma_f32_16x16x32_bf16 v[54:57], v[216:219], v[236:239], v[54:57]
	s_waitcnt lgkmcnt(4)
	v_mfma_f32_16x16x32_bf16 v[34:37], v[216:219], v[240:243], v[34:37]
	s_waitcnt lgkmcnt(3)
	v_mfma_f32_16x16x32_bf16 v[38:41], v[216:219], v[252:255], v[38:41]
	ds_read_b128 v[216:219], v244 offset:18496
	s_waitcnt lgkmcnt(3)
	v_mfma_f32_16x16x32_bf16 v[58:61], v[220:223], v[232:235], v[58:61]
	v_mfma_f32_16x16x32_bf16 v[62:65], v[220:223], v[236:239], v[62:65]
	v_mfma_f32_16x16x32_bf16 v[42:45], v[220:223], v[240:243], v[42:45]
	v_mfma_f32_16x16x32_bf16 v[46:49], v[220:223], v[252:255], v[46:49]
	ds_read_b128 v[220:223], v244 offset:20800
	s_setprio 1
	s_waitcnt vmcnt(15)
	ds_write_b128 v164, v[180:183]
	s_waitcnt vmcnt(14)
	ds_write_b128 v164, v[188:191] offset:4608
	s_waitcnt lgkmcnt(5)
	v_mfma_f32_16x16x32_bf16 v[18:21], v[224:227], v[232:235], v[18:21]
	v_mfma_f32_16x16x32_bf16 v[22:25], v[224:227], v[236:239], v[22:25]
	v_mfma_f32_16x16x32_bf16 v[2:5], v[224:227], v[240:243], v[2:5]
	v_mfma_f32_16x16x32_bf16 v[6:9], v[224:227], v[252:255], v[6:9]
	ds_read_b128 v[224:227], v244 offset:23104
	s_waitcnt vmcnt(13)
	ds_write_b128 v164, v[192:195] offset:9216
	s_waitcnt vmcnt(12)
	ds_write_b128 v164, v[196:199] offset:13824
	s_waitcnt lgkmcnt(7)
	v_mfma_f32_16x16x32_bf16 v[26:29], v[228:231], v[232:235], v[26:29]
	ds_read_b128 v[232:235], v245 offset:55360
	v_mfma_f32_16x16x32_bf16 v[30:33], v[228:231], v[236:239], v[30:33]
	ds_read_b128 v[236:239], v245 offset:57664
	v_mfma_f32_16x16x32_bf16 v[10:13], v[228:231], v[240:243], v[10:13]
	ds_read_b128 v[240:243], v245 offset:59968
	v_mfma_f32_16x16x32_bf16 v[14:17], v[228:231], v[252:255], v[14:17]
	ds_read_b128 v[252:255], v245 offset:62272
	ds_read_b128 v[228:231], v244 offset:25408
	s_waitcnt lgkmcnt(4)
	v_mfma_f32_16x16x32_bf16 v[50:53], v[216:219], v[232:235], v[50:53]
	s_waitcnt lgkmcnt(3)
	v_mfma_f32_16x16x32_bf16 v[54:57], v[216:219], v[236:239], v[54:57]
	s_waitcnt lgkmcnt(2)
	v_mfma_f32_16x16x32_bf16 v[34:37], v[216:219], v[240:243], v[34:37]
	s_waitcnt lgkmcnt(1)
	v_mfma_f32_16x16x32_bf16 v[38:41], v[216:219], v[252:255], v[38:41]
	s_waitcnt vmcnt(11)
	ds_write_b128 v164, v[200:203] offset:36864
	s_waitcnt vmcnt(10)
	ds_write_b128 v164, v[204:207] offset:41472
	v_mfma_f32_16x16x32_bf16 v[58:61], v[220:223], v[232:235], v[58:61]
	v_mfma_f32_16x16x32_bf16 v[62:65], v[220:223], v[236:239], v[62:65]
	v_mfma_f32_16x16x32_bf16 v[42:45], v[220:223], v[240:243], v[42:45]
	v_mfma_f32_16x16x32_bf16 v[46:49], v[220:223], v[252:255], v[46:49]
	s_waitcnt vmcnt(9)
	ds_write_b128 v164, v[208:211] offset:46080
	s_waitcnt vmcnt(8)
	ds_write_b128 v164, v[212:215] offset:50688
	v_mfma_f32_16x16x32_bf16 v[18:21], v[224:227], v[232:235], v[18:21]
	v_mfma_f32_16x16x32_bf16 v[22:25], v[224:227], v[236:239], v[22:25]
	v_mfma_f32_16x16x32_bf16 v[2:5], v[224:227], v[240:243], v[2:5]
	v_mfma_f32_16x16x32_bf16 v[6:9], v[224:227], v[252:255], v[6:9]
	s_waitcnt lgkmcnt(4)
	v_mfma_f32_16x16x32_bf16 v[26:29], v[228:231], v[232:235], v[26:29]
	v_mfma_f32_16x16x32_bf16 v[30:33], v[228:231], v[236:239], v[30:33]
	v_mfma_f32_16x16x32_bf16 v[10:13], v[228:231], v[240:243], v[10:13]
	v_mfma_f32_16x16x32_bf16 v[14:17], v[228:231], v[252:255], v[14:17]
	s_waitcnt lgkmcnt(0)
	s_barrier
	s_setprio 0
	ds_read_b128 v[232:235], v245 offset:36864
	ds_read_b128 v[216:219], v244
	ds_read_b128 v[236:239], v245 offset:39168
	ds_read_b128 v[240:243], v245 offset:41472
	ds_read_b128 v[252:255], v245 offset:43776
	ds_read_b128 v[220:223], v244 offset:2304
	ds_read_b128 v[224:227], v244 offset:4608
	ds_read_b128 v[228:231], v244 offset:6912
	s_waitcnt lgkmcnt(6)
	v_mfma_f32_16x16x32_bf16 v[50:53], v[216:219], v[232:235], v[50:53]
	s_waitcnt lgkmcnt(5)
	v_mfma_f32_16x16x32_bf16 v[54:57], v[216:219], v[236:239], v[54:57]
	s_waitcnt lgkmcnt(4)
	v_mfma_f32_16x16x32_bf16 v[34:37], v[216:219], v[240:243], v[34:37]
	s_waitcnt lgkmcnt(3)
	v_mfma_f32_16x16x32_bf16 v[38:41], v[216:219], v[252:255], v[38:41]
	ds_read_b128 v[216:219], v244 offset:64
	s_waitcnt lgkmcnt(3)
	v_mfma_f32_16x16x32_bf16 v[58:61], v[220:223], v[232:235], v[58:61]
	v_mfma_f32_16x16x32_bf16 v[62:65], v[220:223], v[236:239], v[62:65]
	v_mfma_f32_16x16x32_bf16 v[42:45], v[220:223], v[240:243], v[42:45]
	v_mfma_f32_16x16x32_bf16 v[46:49], v[220:223], v[252:255], v[46:49]
	ds_read_b128 v[220:223], v244 offset:2368
	s_setprio 1
	s_waitcnt vmcnt(7)
	ds_write_b128 v164, v[122:125] offset:18432
	s_waitcnt vmcnt(6)
	ds_write_b128 v164, v[72:75] offset:23040
	s_waitcnt lgkmcnt(5)
	v_mfma_f32_16x16x32_bf16 v[18:21], v[224:227], v[232:235], v[18:21]
	v_mfma_f32_16x16x32_bf16 v[22:25], v[224:227], v[236:239], v[22:25]
	v_mfma_f32_16x16x32_bf16 v[2:5], v[224:227], v[240:243], v[2:5]
	v_mfma_f32_16x16x32_bf16 v[6:9], v[224:227], v[252:255], v[6:9]
	ds_read_b128 v[224:227], v244 offset:4672
	s_waitcnt vmcnt(5)
	ds_write_b128 v164, v[126:129] offset:27648
	s_waitcnt vmcnt(4)
	ds_write_b128 v164, v[76:79] offset:32256
	s_waitcnt lgkmcnt(7)
	v_mfma_f32_16x16x32_bf16 v[26:29], v[228:231], v[232:235], v[26:29]
	ds_read_b128 v[232:235], v245 offset:36928
	v_mfma_f32_16x16x32_bf16 v[30:33], v[228:231], v[236:239], v[30:33]
	ds_read_b128 v[236:239], v245 offset:39232
	v_mfma_f32_16x16x32_bf16 v[10:13], v[228:231], v[240:243], v[10:13]
	ds_read_b128 v[240:243], v245 offset:41536
	v_mfma_f32_16x16x32_bf16 v[14:17], v[228:231], v[252:255], v[14:17]
	ds_read_b128 v[252:255], v245 offset:43840
	ds_read_b128 v[228:231], v244 offset:6976
	s_waitcnt lgkmcnt(4)
	v_mfma_f32_16x16x32_bf16 v[50:53], v[216:219], v[232:235], v[50:53]
	s_waitcnt lgkmcnt(3)
	v_mfma_f32_16x16x32_bf16 v[54:57], v[216:219], v[236:239], v[54:57]
	s_waitcnt lgkmcnt(2)
	v_mfma_f32_16x16x32_bf16 v[34:37], v[216:219], v[240:243], v[34:37]
	s_waitcnt lgkmcnt(1)
	v_mfma_f32_16x16x32_bf16 v[38:41], v[216:219], v[252:255], v[38:41]
	s_waitcnt vmcnt(3)
	ds_write_b128 v164, v[136:139] offset:55296
	s_waitcnt vmcnt(2)
	ds_write_b128 v164, v[68:71] offset:59904
	v_mfma_f32_16x16x32_bf16 v[58:61], v[220:223], v[232:235], v[58:61]
	v_mfma_f32_16x16x32_bf16 v[62:65], v[220:223], v[236:239], v[62:65]
	v_mfma_f32_16x16x32_bf16 v[42:45], v[220:223], v[240:243], v[42:45]
	v_mfma_f32_16x16x32_bf16 v[46:49], v[220:223], v[252:255], v[46:49]
	s_waitcnt vmcnt(1)
	ds_write_b128 v164, v[140:143] offset:64512
	s_waitcnt vmcnt(0)
	ds_write_b128 v165, v[144:147] offset:32256
	v_mfma_f32_16x16x32_bf16 v[18:21], v[224:227], v[232:235], v[18:21]
	v_mfma_f32_16x16x32_bf16 v[22:25], v[224:227], v[236:239], v[22:25]
	v_mfma_f32_16x16x32_bf16 v[2:5], v[224:227], v[240:243], v[2:5]
	v_mfma_f32_16x16x32_bf16 v[6:9], v[224:227], v[252:255], v[6:9]
	s_waitcnt lgkmcnt(4)
	v_mfma_f32_16x16x32_bf16 v[26:29], v[228:231], v[232:235], v[26:29]
	v_mfma_f32_16x16x32_bf16 v[30:33], v[228:231], v[236:239], v[30:33]
	v_mfma_f32_16x16x32_bf16 v[10:13], v[228:231], v[240:243], v[10:13]
	v_mfma_f32_16x16x32_bf16 v[14:17], v[228:231], v[252:255], v[14:17]
	s_waitcnt lgkmcnt(0)
	s_barrier
	s_setprio 0
	ds_read_b128 v[232:235], v245 offset:55296
	ds_read_b128 v[216:219], v244 offset:18432
	ds_read_b128 v[236:239], v245 offset:57600
	ds_read_b128 v[240:243], v245 offset:59904
	ds_read_b128 v[252:255], v245 offset:62208
	ds_read_b128 v[220:223], v244 offset:20736
	ds_read_b128 v[224:227], v244 offset:23040
	ds_read_b128 v[228:231], v244 offset:25344
	s_waitcnt lgkmcnt(6)
	v_mfma_f32_16x16x32_bf16 v[50:53], v[216:219], v[232:235], v[50:53]
	s_waitcnt lgkmcnt(5)
	v_mfma_f32_16x16x32_bf16 v[54:57], v[216:219], v[236:239], v[54:57]
	s_waitcnt lgkmcnt(4)
	v_mfma_f32_16x16x32_bf16 v[34:37], v[216:219], v[240:243], v[34:37]
	s_waitcnt lgkmcnt(3)
	v_mfma_f32_16x16x32_bf16 v[38:41], v[216:219], v[252:255], v[38:41]
	ds_read_b128 v[216:219], v244 offset:18496
	s_waitcnt lgkmcnt(3)
	v_mfma_f32_16x16x32_bf16 v[58:61], v[220:223], v[232:235], v[58:61]
	v_mfma_f32_16x16x32_bf16 v[62:65], v[220:223], v[236:239], v[62:65]
	v_mfma_f32_16x16x32_bf16 v[42:45], v[220:223], v[240:243], v[42:45]
	v_mfma_f32_16x16x32_bf16 v[46:49], v[220:223], v[252:255], v[46:49]
	ds_read_b128 v[220:223], v244 offset:20800
	s_waitcnt lgkmcnt(3)
	v_mfma_f32_16x16x32_bf16 v[18:21], v[224:227], v[232:235], v[18:21]
	v_mfma_f32_16x16x32_bf16 v[22:25], v[224:227], v[236:239], v[22:25]
	v_mfma_f32_16x16x32_bf16 v[2:5], v[224:227], v[240:243], v[2:5]
	v_mfma_f32_16x16x32_bf16 v[6:9], v[224:227], v[252:255], v[6:9]
	ds_read_b128 v[224:227], v244 offset:23104
	s_waitcnt lgkmcnt(3)
	v_mfma_f32_16x16x32_bf16 v[26:29], v[228:231], v[232:235], v[26:29]
	ds_read_b128 v[232:235], v245 offset:55360
	v_mfma_f32_16x16x32_bf16 v[30:33], v[228:231], v[236:239], v[30:33]
	ds_read_b128 v[236:239], v245 offset:57664
	v_mfma_f32_16x16x32_bf16 v[10:13], v[228:231], v[240:243], v[10:13]
	ds_read_b128 v[240:243], v245 offset:59968
	v_mfma_f32_16x16x32_bf16 v[14:17], v[228:231], v[252:255], v[14:17]
	ds_read_b128 v[252:255], v245 offset:62272
	ds_read_b128 v[228:231], v244 offset:25408
	s_waitcnt lgkmcnt(4)
	v_mfma_f32_16x16x32_bf16 v[50:53], v[216:219], v[232:235], v[50:53]
	s_waitcnt lgkmcnt(3)
	v_mfma_f32_16x16x32_bf16 v[54:57], v[216:219], v[236:239], v[54:57]
	s_waitcnt lgkmcnt(2)
	v_mfma_f32_16x16x32_bf16 v[34:37], v[216:219], v[240:243], v[34:37]
	s_waitcnt lgkmcnt(1)
	v_mfma_f32_16x16x32_bf16 v[38:41], v[216:219], v[252:255], v[38:41]
	v_mfma_f32_16x16x32_bf16 v[58:61], v[220:223], v[232:235], v[58:61]
	v_mfma_f32_16x16x32_bf16 v[62:65], v[220:223], v[236:239], v[62:65]
	v_mfma_f32_16x16x32_bf16 v[42:45], v[220:223], v[240:243], v[42:45]
	v_mfma_f32_16x16x32_bf16 v[46:49], v[220:223], v[252:255], v[46:49]
	v_mfma_f32_16x16x32_bf16 v[18:21], v[224:227], v[232:235], v[18:21]
	v_mfma_f32_16x16x32_bf16 v[22:25], v[224:227], v[236:239], v[22:25]
	v_mfma_f32_16x16x32_bf16 v[2:5], v[224:227], v[240:243], v[2:5]
	v_mfma_f32_16x16x32_bf16 v[6:9], v[224:227], v[252:255], v[6:9]
	s_waitcnt lgkmcnt(0)
	v_mfma_f32_16x16x32_bf16 v[26:29], v[228:231], v[232:235], v[26:29]
	v_mfma_f32_16x16x32_bf16 v[30:33], v[228:231], v[236:239], v[30:33]
	v_mfma_f32_16x16x32_bf16 v[10:13], v[228:231], v[240:243], v[10:13]
	v_mfma_f32_16x16x32_bf16 v[14:17], v[228:231], v[252:255], v[14:17]
	s_mov_b64 s[2:3], 0
	s_waitcnt lgkmcnt(0)
	s_barrier
	s_nop 7
	v_permlane16_swap_b32_e32 v50, v54
	v_permlane16_swap_b32_e32 v51, v55
	v_permlane16_swap_b32_e32 v52, v56
	v_permlane16_swap_b32_e32 v53, v57
	v_permlane16_swap_b32_e32 v58, v62
	v_permlane16_swap_b32_e32 v59, v63
	v_permlane16_swap_b32_e32 v60, v64
	v_permlane16_swap_b32_e32 v61, v65
	v_permlane16_swap_b32_e32 v34, v38
	v_permlane16_swap_b32_e32 v35, v39
	v_permlane16_swap_b32_e32 v36, v40
	v_permlane16_swap_b32_e32 v37, v41
	v_permlane16_swap_b32_e32 v42, v46
	v_permlane16_swap_b32_e32 v43, v47
	v_permlane16_swap_b32_e32 v44, v48
	v_permlane16_swap_b32_e32 v45, v49
	v_permlane16_swap_b32_e32 v18, v22
	v_permlane16_swap_b32_e32 v19, v23
	v_permlane16_swap_b32_e32 v20, v24
	v_permlane16_swap_b32_e32 v21, v25
	v_permlane16_swap_b32_e32 v26, v30
	v_permlane16_swap_b32_e32 v27, v31
	v_permlane16_swap_b32_e32 v28, v32
	v_permlane16_swap_b32_e32 v29, v33
	v_permlane16_swap_b32_e32 v2, v6
	v_permlane16_swap_b32_e32 v3, v7
	v_permlane16_swap_b32_e32 v4, v8
	v_permlane16_swap_b32_e32 v5, v9
	v_permlane16_swap_b32_e32 v10, v14
	v_permlane16_swap_b32_e32 v11, v15
	v_permlane16_swap_b32_e32 v12, v16
	v_permlane16_swap_b32_e32 v13, v17
	v_permlane32_swap_b32_e32 v50, v54
	v_permlane32_swap_b32_e32 v51, v55
	v_permlane32_swap_b32_e32 v52, v56
	v_permlane32_swap_b32_e32 v53, v57
	v_permlane32_swap_b32_e32 v58, v62
	v_permlane32_swap_b32_e32 v59, v63
	v_permlane32_swap_b32_e32 v60, v64
	v_permlane32_swap_b32_e32 v61, v65
	v_permlane32_swap_b32_e32 v34, v38
	v_permlane32_swap_b32_e32 v35, v39
	v_permlane32_swap_b32_e32 v36, v40
	v_permlane32_swap_b32_e32 v37, v41
	v_permlane32_swap_b32_e32 v42, v46
	v_permlane32_swap_b32_e32 v43, v47
	v_permlane32_swap_b32_e32 v44, v48
	v_permlane32_swap_b32_e32 v45, v49
	v_permlane32_swap_b32_e32 v18, v22
	v_permlane32_swap_b32_e32 v19, v23
	v_permlane32_swap_b32_e32 v20, v24
	v_permlane32_swap_b32_e32 v21, v25
	v_permlane32_swap_b32_e32 v26, v30
	v_permlane32_swap_b32_e32 v27, v31
	v_permlane32_swap_b32_e32 v28, v32
	v_permlane32_swap_b32_e32 v29, v33
	v_permlane32_swap_b32_e32 v2, v6
	v_permlane32_swap_b32_e32 v3, v7
	v_permlane32_swap_b32_e32 v4, v8
	v_permlane32_swap_b32_e32 v5, v9
	v_permlane32_swap_b32_e32 v10, v14
	v_permlane32_swap_b32_e32 v11, v15
	v_permlane32_swap_b32_e32 v12, v16
	v_permlane32_swap_b32_e32 v13, v17

.LBB0_1167:
	v_ashrrev_i32_e32 v3, 31, v2
	v_lshlrev_b64 v[2:3], 11, v[2:3]
	v_ashrrev_i32_e32 v9, 31, v8
	v_lshl_add_u64 v[70:71], v[86:87], 0, v[2:3]
	v_lshlrev_b64 v[2:3], 11, v[8:9]
	v_lshl_add_u64 v[72:73], v[86:87], 0, v[2:3]
	v_or_b32_e32 v2, s56, v154
	v_ashrrev_i32_e32 v3, 31, v2
	v_lshlrev_b64 v[2:3], 11, v[2:3]
	v_lshl_add_u64 v[74:75], v[84:85], 0, v[2:3]
	v_add_u32_e32 v2, s56, v155
	v_ashrrev_i32_e32 v3, 31, v2
	v_lshlrev_b64 v[2:3], 11, v[2:3]
	v_lshl_add_u64 v[76:77], v[84:85], 0, v[2:3]
	v_add_u32_e32 v2, s56, v156
	v_ashrrev_i32_e32 v3, 31, v2
	v_lshlrev_b64 v[2:3], 11, v[2:3]
	v_lshl_add_u64 v[78:79], v[84:85], 0, v[2:3]
	v_add_u32_e32 v2, s56, v157
	v_ashrrev_i32_e32 v7, 31, v6
	v_ashrrev_i32_e32 v5, 31, v4
	v_ashrrev_i32_e32 v3, 31, v2
	v_lshlrev_b64 v[6:7], 11, v[6:7]
	v_lshlrev_b64 v[4:5], 11, v[4:5]
	v_lshlrev_b64 v[2:3], 11, v[2:3]
	v_lshl_add_u64 v[66:67], v[86:87], 0, v[6:7]
	v_lshl_add_u64 v[68:69], v[86:87], 0, v[4:5]
	v_lshl_add_u64 v[80:81], v[84:85], 0, v[2:3]
	global_load_dwordx4 v[2:5], v[70:71], off
	global_load_dwordx4 v[6:9], v[68:69], off
	global_load_dwordx4 v[10:13], v[66:67], off
	global_load_dwordx4 v[14:17], v[72:73], off
	global_load_dwordx4 v[18:21], v[74:75], off
	global_load_dwordx4 v[22:25], v[76:77], off
	global_load_dwordx4 v[26:29], v[78:79], off
	global_load_dwordx4 v[30:33], v[80:81], off
	global_load_dwordx4 v[122:125], v[70:71], off offset:128
	global_load_dwordx4 v[126:129], v[68:69], off offset:128
	global_load_dwordx4 v[136:139], v[66:67], off offset:128
	global_load_dwordx4 v[140:143], v[72:73], off offset:128
	global_load_dwordx4 v[144:147], v[74:75], off offset:128
	global_load_dwordx4 v[148:151], v[76:77], off offset:128
	global_load_dwordx4 v[172:175], v[78:79], off offset:128
	global_load_dwordx4 v[176:179], v[80:81], off offset:128
	s_waitcnt vmcnt(15)
	ds_write_b128 v164, v[2:5]
	s_waitcnt vmcnt(14)
	ds_write_b128 v164, v[6:9] offset:4608
	s_waitcnt vmcnt(13)
	ds_write_b128 v164, v[10:13] offset:9216
	s_waitcnt vmcnt(12)
	ds_write_b128 v164, v[14:17] offset:13824
	s_waitcnt vmcnt(11)
	ds_write_b128 v164, v[18:21] offset:36864
	s_waitcnt vmcnt(10)
	ds_write_b128 v164, v[22:25] offset:41472
	s_waitcnt vmcnt(9)
	ds_write_b128 v164, v[26:29] offset:46080
	s_waitcnt vmcnt(8)
	ds_write_b128 v164, v[30:33] offset:50688
	s_waitcnt lgkmcnt(0)
	s_barrier
	global_load_dwordx4 v[180:183], v[68:69], off offset:256
	global_load_dwordx4 v[188:191], v[66:67], off offset:256
	global_load_dwordx4 v[192:195], v[70:71], off offset:256
	global_load_dwordx4 v[196:199], v[72:73], off offset:256
	global_load_dwordx4 v[200:203], v[74:75], off offset:256
	global_load_dwordx4 v[204:207], v[76:77], off offset:256
	global_load_dwordx4 v[208:211], v[78:79], off offset:256
	global_load_dwordx4 v[212:215], v[80:81], off offset:256
	v_and_b32_e32 v246, 15, v1
	v_add_u32_e32 v246, 4, v246
	v_bfe_u32 v246, v246, 3, 1
	v_bfe_u32 v249, v1, 4, 2
	v_xor_b32_e32 v246, v246, v249
	v_bfe_u32 v249, v1, 5, 1
	v_sub_u32_e32 v246, v246, v249
	v_lshlrev_b32_e32 v246, 4, v246
	v_bfe_u32 v249, v1, 4, 1
	v_mul_u32_u24_e32 v249, 0x900, v249
	v_sub_u32_e32 v246, v246, v249
	v_add_u32_e32 v244, v246, v161
	v_add_u32_e32 v245, v246, v163
	ds_read_b128 v[232:235], v245 offset:36864
	ds_read_b128 v[216:219], v244
	ds_read_b128 v[236:239], v245 offset:39168
	ds_read_b128 v[240:243], v245 offset:41472
	ds_read_b128 v[252:255], v245 offset:43776
	ds_read_b128 v[220:223], v244 offset:2304
	ds_read_b128 v[224:227], v244 offset:4608
	ds_read_b128 v[228:231], v244 offset:6912
	s_waitcnt lgkmcnt(6)
	v_mfma_f32_16x16x32_bf16 v[50:53], v[216:219], v[232:235], 0
	s_waitcnt lgkmcnt(5)
	v_mfma_f32_16x16x32_bf16 v[54:57], v[216:219], v[236:239], 0
	s_waitcnt lgkmcnt(4)
	v_mfma_f32_16x16x32_bf16 v[34:37], v[216:219], v[240:243], 0
	s_waitcnt lgkmcnt(3)
	v_mfma_f32_16x16x32_bf16 v[38:41], v[216:219], v[252:255], 0
	ds_read_b128 v[216:219], v244 offset:64
	s_waitcnt lgkmcnt(3)
	v_mfma_f32_16x16x32_bf16 v[58:61], v[220:223], v[232:235], 0
	v_mfma_f32_16x16x32_bf16 v[62:65], v[220:223], v[236:239], 0
	v_mfma_f32_16x16x32_bf16 v[42:45], v[220:223], v[240:243], 0
	v_mfma_f32_16x16x32_bf16 v[46:49], v[220:223], v[252:255], 0
	ds_read_b128 v[220:223], v244 offset:2368
	s_setprio 1
	s_waitcnt vmcnt(15)
	ds_write_b128 v164, v[122:125] offset:18432
	s_waitcnt vmcnt(14)
	ds_write_b128 v164, v[126:129] offset:23040
	s_waitcnt lgkmcnt(5)
	v_mfma_f32_16x16x32_bf16 v[18:21], v[224:227], v[232:235], 0
	v_mfma_f32_16x16x32_bf16 v[22:25], v[224:227], v[236:239], 0
	v_mfma_f32_16x16x32_bf16 v[2:5], v[224:227], v[240:243], 0
	v_mfma_f32_16x16x32_bf16 v[6:9], v[224:227], v[252:255], 0
	ds_read_b128 v[224:227], v244 offset:4672
	s_waitcnt vmcnt(13)
	ds_write_b128 v164, v[136:139] offset:27648
	s_waitcnt vmcnt(12)
	ds_write_b128 v164, v[140:143] offset:32256
	s_waitcnt lgkmcnt(7)
	v_mfma_f32_16x16x32_bf16 v[26:29], v[228:231], v[232:235], 0
	ds_read_b128 v[232:235], v245 offset:36928
	v_mfma_f32_16x16x32_bf16 v[30:33], v[228:231], v[236:239], 0
	ds_read_b128 v[236:239], v245 offset:39232
	v_mfma_f32_16x16x32_bf16 v[10:13], v[228:231], v[240:243], 0
	ds_read_b128 v[240:243], v245 offset:41536
	v_mfma_f32_16x16x32_bf16 v[14:17], v[228:231], v[252:255], 0
	ds_read_b128 v[252:255], v245 offset:43840
	ds_read_b128 v[228:231], v244 offset:6976
	s_waitcnt lgkmcnt(4)
	v_mfma_f32_16x16x32_bf16 v[50:53], v[216:219], v[232:235], v[50:53]
	s_waitcnt lgkmcnt(3)
	v_mfma_f32_16x16x32_bf16 v[54:57], v[216:219], v[236:239], v[54:57]
	s_waitcnt lgkmcnt(2)
	v_mfma_f32_16x16x32_bf16 v[34:37], v[216:219], v[240:243], v[34:37]
	s_waitcnt lgkmcnt(1)
	v_mfma_f32_16x16x32_bf16 v[38:41], v[216:219], v[252:255], v[38:41]
	s_waitcnt vmcnt(11)
	ds_write_b128 v164, v[144:147] offset:55296
	s_waitcnt vmcnt(10)
	ds_write_b128 v164, v[148:151] offset:59904
	v_mfma_f32_16x16x32_bf16 v[58:61], v[220:223], v[232:235], v[58:61]
	v_mfma_f32_16x16x32_bf16 v[62:65], v[220:223], v[236:239], v[62:65]
	v_mfma_f32_16x16x32_bf16 v[42:45], v[220:223], v[240:243], v[42:45]
	v_mfma_f32_16x16x32_bf16 v[46:49], v[220:223], v[252:255], v[46:49]
	s_waitcnt vmcnt(9)
	ds_write_b128 v164, v[172:175] offset:64512
	s_waitcnt vmcnt(8)
	ds_write_b128 v165, v[176:179] offset:32256
	v_mfma_f32_16x16x32_bf16 v[18:21], v[224:227], v[232:235], v[18:21]
	v_mfma_f32_16x16x32_bf16 v[22:25], v[224:227], v[236:239], v[22:25]
	v_mfma_f32_16x16x32_bf16 v[2:5], v[224:227], v[240:243], v[2:5]
	v_mfma_f32_16x16x32_bf16 v[6:9], v[224:227], v[252:255], v[6:9]
	s_waitcnt lgkmcnt(4)
	v_mfma_f32_16x16x32_bf16 v[26:29], v[228:231], v[232:235], v[26:29]
	v_mfma_f32_16x16x32_bf16 v[30:33], v[228:231], v[236:239], v[30:33]
	v_mfma_f32_16x16x32_bf16 v[10:13], v[228:231], v[240:243], v[10:13]
	v_mfma_f32_16x16x32_bf16 v[14:17], v[228:231], v[252:255], v[14:17]
	s_waitcnt lgkmcnt(0)
	s_barrier
	s_setprio 0
	ds_read_b128 v[232:235], v245 offset:55296
	ds_read_b128 v[216:219], v244 offset:18432
	ds_read_b128 v[236:239], v245 offset:57600
	ds_read_b128 v[240:243], v245 offset:59904
	ds_read_b128 v[252:255], v245 offset:62208
	ds_read_b128 v[220:223], v244 offset:20736
	ds_read_b128 v[224:227], v244 offset:23040
	ds_read_b128 v[228:231], v244 offset:25344
	global_load_dwordx4 v[122:125], v[70:71], off offset:384
	global_load_dwordx4 v[126:129], v[68:69], off offset:384
	global_load_dwordx4 v[136:139], v[66:67], off offset:384
	global_load_dwordx4 v[140:143], v[72:73], off offset:384
	global_load_dwordx4 v[144:147], v[74:75], off offset:384
	global_load_dwordx4 v[148:151], v[76:77], off offset:384
	global_load_dwordx4 v[172:175], v[78:79], off offset:384
	global_load_dwordx4 v[176:179], v[80:81], off offset:384
	s_waitcnt lgkmcnt(6)
	v_mfma_f32_16x16x32_bf16 v[50:53], v[216:219], v[232:235], v[50:53]
	s_waitcnt lgkmcnt(5)
	v_mfma_f32_16x16x32_bf16 v[54:57], v[216:219], v[236:239], v[54:57]
	s_waitcnt lgkmcnt(4)
	v_mfma_f32_16x16x32_bf16 v[34:37], v[216:219], v[240:243], v[34:37]
	s_waitcnt lgkmcnt(3)
	v_mfma_f32_16x16x32_bf16 v[38:41], v[216:219], v[252:255], v[38:41]
	ds_read_b128 v[216:219], v244 offset:18496
	s_waitcnt lgkmcnt(3)
	v_mfma_f32_16x16x32_bf16 v[58:61], v[220:223], v[232:235], v[58:61]
	v_mfma_f32_16x16x32_bf16 v[62:65], v[220:223], v[236:239], v[62:65]
	v_mfma_f32_16x16x32_bf16 v[42:45], v[220:223], v[240:243], v[42:45]
	v_mfma_f32_16x16x32_bf16 v[46:49], v[220:223], v[252:255], v[46:49]
	ds_read_b128 v[220:223], v244 offset:20800
	s_setprio 1
	s_waitcnt vmcnt(13)
	ds_write_b128 v164, v[192:195]
	ds_write_b128 v164, v[180:183] offset:4608
	s_waitcnt lgkmcnt(5)
	v_mfma_f32_16x16x32_bf16 v[18:21], v[224:227], v[232:235], v[18:21]
	v_mfma_f32_16x16x32_bf16 v[22:25], v[224:227], v[236:239], v[22:25]
	v_mfma_f32_16x16x32_bf16 v[2:5], v[224:227], v[240:243], v[2:5]
	v_mfma_f32_16x16x32_bf16 v[6:9], v[224:227], v[252:255], v[6:9]
	ds_read_b128 v[224:227], v244 offset:23104
	ds_write_b128 v164, v[188:191] offset:9216
	s_waitcnt vmcnt(12)
	ds_write_b128 v164, v[196:199] offset:13824
	s_waitcnt lgkmcnt(7)
	v_mfma_f32_16x16x32_bf16 v[26:29], v[228:231], v[232:235], v[26:29]
	ds_read_b128 v[232:235], v245 offset:55360
	v_mfma_f32_16x16x32_bf16 v[30:33], v[228:231], v[236:239], v[30:33]
	ds_read_b128 v[236:239], v245 offset:57664
	v_mfma_f32_16x16x32_bf16 v[10:13], v[228:231], v[240:243], v[10:13]
	ds_read_b128 v[240:243], v245 offset:59968
	v_mfma_f32_16x16x32_bf16 v[14:17], v[228:231], v[252:255], v[14:17]
	ds_read_b128 v[252:255], v245 offset:62272
	ds_read_b128 v[228:231], v244 offset:25408
	s_waitcnt lgkmcnt(4)
	v_mfma_f32_16x16x32_bf16 v[50:53], v[216:219], v[232:235], v[50:53]
	s_waitcnt lgkmcnt(3)
	v_mfma_f32_16x16x32_bf16 v[54:57], v[216:219], v[236:239], v[54:57]
	s_waitcnt lgkmcnt(2)
	v_mfma_f32_16x16x32_bf16 v[34:37], v[216:219], v[240:243], v[34:37]
	s_waitcnt lgkmcnt(1)
	v_mfma_f32_16x16x32_bf16 v[38:41], v[216:219], v[252:255], v[38:41]
	s_waitcnt vmcnt(11)
	ds_write_b128 v164, v[200:203] offset:36864
	s_waitcnt vmcnt(10)
	ds_write_b128 v164, v[204:207] offset:41472
	v_mfma_f32_16x16x32_bf16 v[58:61], v[220:223], v[232:235], v[58:61]
	v_mfma_f32_16x16x32_bf16 v[62:65], v[220:223], v[236:239], v[62:65]
	v_mfma_f32_16x16x32_bf16 v[42:45], v[220:223], v[240:243], v[42:45]
	v_mfma_f32_16x16x32_bf16 v[46:49], v[220:223], v[252:255], v[46:49]
	s_waitcnt vmcnt(9)
	ds_write_b128 v164, v[208:211] offset:46080
	s_waitcnt vmcnt(8)
	ds_write_b128 v164, v[212:215] offset:50688
	v_mfma_f32_16x16x32_bf16 v[18:21], v[224:227], v[232:235], v[18:21]
	v_mfma_f32_16x16x32_bf16 v[22:25], v[224:227], v[236:239], v[22:25]
	v_mfma_f32_16x16x32_bf16 v[2:5], v[224:227], v[240:243], v[2:5]
	v_mfma_f32_16x16x32_bf16 v[6:9], v[224:227], v[252:255], v[6:9]
	s_waitcnt lgkmcnt(4)
	v_mfma_f32_16x16x32_bf16 v[26:29], v[228:231], v[232:235], v[26:29]
	v_mfma_f32_16x16x32_bf16 v[30:33], v[228:231], v[236:239], v[30:33]
	v_mfma_f32_16x16x32_bf16 v[10:13], v[228:231], v[240:243], v[10:13]
	v_mfma_f32_16x16x32_bf16 v[14:17], v[228:231], v[252:255], v[14:17]
	s_waitcnt lgkmcnt(0)
	s_barrier
	s_setprio 0
	ds_read_b128 v[232:235], v245 offset:36864
	ds_read_b128 v[216:219], v244
	ds_read_b128 v[236:239], v245 offset:39168
	ds_read_b128 v[240:243], v245 offset:41472
	ds_read_b128 v[252:255], v245 offset:43776
	ds_read_b128 v[220:223], v244 offset:2304
	ds_read_b128 v[224:227], v244 offset:4608
	ds_read_b128 v[228:231], v244 offset:6912
	global_load_dwordx4 v[180:183], v[70:71], off offset:512
	global_load_dwordx4 v[188:191], v[68:69], off offset:512
	global_load_dwordx4 v[192:195], v[66:67], off offset:512
	global_load_dwordx4 v[196:199], v[72:73], off offset:512
	global_load_dwordx4 v[200:203], v[74:75], off offset:512
	global_load_dwordx4 v[204:207], v[76:77], off offset:512
	global_load_dwordx4 v[208:211], v[78:79], off offset:512
	global_load_dwordx4 v[212:215], v[80:81], off offset:512
	s_waitcnt lgkmcnt(6)
	v_mfma_f32_16x16x32_bf16 v[50:53], v[216:219], v[232:235], v[50:53]
	s_waitcnt lgkmcnt(5)
	v_mfma_f32_16x16x32_bf16 v[54:57], v[216:219], v[236:239], v[54:57]
	s_waitcnt lgkmcnt(4)
	v_mfma_f32_16x16x32_bf16 v[34:37], v[216:219], v[240:243], v[34:37]
	s_waitcnt lgkmcnt(3)
	v_mfma_f32_16x16x32_bf16 v[38:41], v[216:219], v[252:255], v[38:41]
	ds_read_b128 v[216:219], v244 offset:64
	s_waitcnt lgkmcnt(3)
	v_mfma_f32_16x16x32_bf16 v[58:61], v[220:223], v[232:235], v[58:61]
	v_mfma_f32_16x16x32_bf16 v[62:65], v[220:223], v[236:239], v[62:65]
	v_mfma_f32_16x16x32_bf16 v[42:45], v[220:223], v[240:243], v[42:45]
	v_mfma_f32_16x16x32_bf16 v[46:49], v[220:223], v[252:255], v[46:49]
	ds_read_b128 v[220:223], v244 offset:2368
	s_setprio 1
	s_waitcnt vmcnt(15)
	ds_write_b128 v164, v[122:125] offset:18432
	s_waitcnt vmcnt(14)
	ds_write_b128 v164, v[126:129] offset:23040
	s_waitcnt lgkmcnt(5)
	v_mfma_f32_16x16x32_bf16 v[18:21], v[224:227], v[232:235], v[18:21]
	v_mfma_f32_16x16x32_bf16 v[22:25], v[224:227], v[236:239], v[22:25]
	v_mfma_f32_16x16x32_bf16 v[2:5], v[224:227], v[240:243], v[2:5]
	v_mfma_f32_16x16x32_bf16 v[6:9], v[224:227], v[252:255], v[6:9]
	ds_read_b128 v[224:227], v244 offset:4672
	s_waitcnt vmcnt(13)
	ds_write_b128 v164, v[136:139] offset:27648
	s_waitcnt vmcnt(12)
	ds_write_b128 v164, v[140:143] offset:32256
	s_waitcnt lgkmcnt(7)
	v_mfma_f32_16x16x32_bf16 v[26:29], v[228:231], v[232:235], v[26:29]
	ds_read_b128 v[232:235], v245 offset:36928
	v_mfma_f32_16x16x32_bf16 v[30:33], v[228:231], v[236:239], v[30:33]
	ds_read_b128 v[236:239], v245 offset:39232
	v_mfma_f32_16x16x32_bf16 v[10:13], v[228:231], v[240:243], v[10:13]
	ds_read_b128 v[240:243], v245 offset:41536
	v_mfma_f32_16x16x32_bf16 v[14:17], v[228:231], v[252:255], v[14:17]
	ds_read_b128 v[252:255], v245 offset:43840
	ds_read_b128 v[228:231], v244 offset:6976
	s_waitcnt lgkmcnt(4)
	v_mfma_f32_16x16x32_bf16 v[50:53], v[216:219], v[232:235], v[50:53]
	s_waitcnt lgkmcnt(3)
	v_mfma_f32_16x16x32_bf16 v[54:57], v[216:219], v[236:239], v[54:57]
	s_waitcnt lgkmcnt(2)
	v_mfma_f32_16x16x32_bf16 v[34:37], v[216:219], v[240:243], v[34:37]
	s_waitcnt lgkmcnt(1)
	v_mfma_f32_16x16x32_bf16 v[38:41], v[216:219], v[252:255], v[38:41]
	s_waitcnt vmcnt(11)
	ds_write_b128 v164, v[144:147] offset:55296
	s_waitcnt vmcnt(10)
	ds_write_b128 v164, v[148:151] offset:59904
	v_mfma_f32_16x16x32_bf16 v[58:61], v[220:223], v[232:235], v[58:61]
	v_mfma_f32_16x16x32_bf16 v[62:65], v[220:223], v[236:239], v[62:65]
	v_mfma_f32_16x16x32_bf16 v[42:45], v[220:223], v[240:243], v[42:45]
	v_mfma_f32_16x16x32_bf16 v[46:49], v[220:223], v[252:255], v[46:49]
	s_waitcnt vmcnt(9)
	ds_write_b128 v164, v[172:175] offset:64512
	s_waitcnt vmcnt(8)
	ds_write_b128 v165, v[176:179] offset:32256
	v_mfma_f32_16x16x32_bf16 v[18:21], v[224:227], v[232:235], v[18:21]
	v_mfma_f32_16x16x32_bf16 v[22:25], v[224:227], v[236:239], v[22:25]
	v_mfma_f32_16x16x32_bf16 v[2:5], v[224:227], v[240:243], v[2:5]
	v_mfma_f32_16x16x32_bf16 v[6:9], v[224:227], v[252:255], v[6:9]
	s_waitcnt lgkmcnt(4)
	v_mfma_f32_16x16x32_bf16 v[26:29], v[228:231], v[232:235], v[26:29]
	v_mfma_f32_16x16x32_bf16 v[30:33], v[228:231], v[236:239], v[30:33]
	v_mfma_f32_16x16x32_bf16 v[10:13], v[228:231], v[240:243], v[10:13]
	v_mfma_f32_16x16x32_bf16 v[14:17], v[228:231], v[252:255], v[14:17]
	s_waitcnt lgkmcnt(0)
	s_barrier
	s_setprio 0
	ds_read_b128 v[232:235], v245 offset:55296
	ds_read_b128 v[216:219], v244 offset:18432
	ds_read_b128 v[236:239], v245 offset:57600
	ds_read_b128 v[240:243], v245 offset:59904
	ds_read_b128 v[252:255], v245 offset:62208
	ds_read_b128 v[220:223], v244 offset:20736
	ds_read_b128 v[224:227], v244 offset:23040
	ds_read_b128 v[228:231], v244 offset:25344
	global_load_dwordx4 v[122:125], v[70:71], off offset:640
	global_load_dwordx4 v[126:129], v[68:69], off offset:640
	global_load_dwordx4 v[136:139], v[66:67], off offset:640
	global_load_dwordx4 v[140:143], v[72:73], off offset:640
	global_load_dwordx4 v[144:147], v[74:75], off offset:640
	global_load_dwordx4 v[148:151], v[76:77], off offset:640
	global_load_dwordx4 v[172:175], v[78:79], off offset:640
	global_load_dwordx4 v[176:179], v[80:81], off offset:640
	s_waitcnt lgkmcnt(6)
	v_mfma_f32_16x16x32_bf16 v[50:53], v[216:219], v[232:235], v[50:53]
	s_waitcnt lgkmcnt(5)
	v_mfma_f32_16x16x32_bf16 v[54:57], v[216:219], v[236:239], v[54:57]
	s_waitcnt lgkmcnt(4)
	v_mfma_f32_16x16x32_bf16 v[34:37], v[216:219], v[240:243], v[34:37]
	s_waitcnt lgkmcnt(3)
	v_mfma_f32_16x16x32_bf16 v[38:41], v[216:219], v[252:255], v[38:41]
	ds_read_b128 v[216:219], v244 offset:18496
	s_waitcnt lgkmcnt(3)
	v_mfma_f32_16x16x32_bf16 v[58:61], v[220:223], v[232:235], v[58:61]
	v_mfma_f32_16x16x32_bf16 v[62:65], v[220:223], v[236:239], v[62:65]
	v_mfma_f32_16x16x32_bf16 v[42:45], v[220:223], v[240:243], v[42:45]
	v_mfma_f32_16x16x32_bf16 v[46:49], v[220:223], v[252:255], v[46:49]
	ds_read_b128 v[220:223], v244 offset:20800
	s_setprio 1
	s_waitcnt vmcnt(15)
	ds_write_b128 v164, v[180:183]
	s_waitcnt vmcnt(14)
	ds_write_b128 v164, v[188:191] offset:4608
	s_waitcnt lgkmcnt(5)
	v_mfma_f32_16x16x32_bf16 v[18:21], v[224:227], v[232:235], v[18:21]
	v_mfma_f32_16x16x32_bf16 v[22:25], v[224:227], v[236:239], v[22:25]
	v_mfma_f32_16x16x32_bf16 v[2:5], v[224:227], v[240:243], v[2:5]
	v_mfma_f32_16x16x32_bf16 v[6:9], v[224:227], v[252:255], v[6:9]
	ds_read_b128 v[224:227], v244 offset:23104
	s_waitcnt vmcnt(13)
	ds_write_b128 v164, v[192:195] offset:9216
	s_waitcnt vmcnt(12)
	ds_write_b128 v164, v[196:199] offset:13824
	s_waitcnt lgkmcnt(7)
	v_mfma_f32_16x16x32_bf16 v[26:29], v[228:231], v[232:235], v[26:29]
	ds_read_b128 v[232:235], v245 offset:55360
	v_mfma_f32_16x16x32_bf16 v[30:33], v[228:231], v[236:239], v[30:33]
	ds_read_b128 v[236:239], v245 offset:57664
	v_mfma_f32_16x16x32_bf16 v[10:13], v[228:231], v[240:243], v[10:13]
	ds_read_b128 v[240:243], v245 offset:59968
	v_mfma_f32_16x16x32_bf16 v[14:17], v[228:231], v[252:255], v[14:17]
	ds_read_b128 v[252:255], v245 offset:62272
	ds_read_b128 v[228:231], v244 offset:25408
	s_waitcnt lgkmcnt(4)
	v_mfma_f32_16x16x32_bf16 v[50:53], v[216:219], v[232:235], v[50:53]
	s_waitcnt lgkmcnt(3)
	v_mfma_f32_16x16x32_bf16 v[54:57], v[216:219], v[236:239], v[54:57]
	s_waitcnt lgkmcnt(2)
	v_mfma_f32_16x16x32_bf16 v[34:37], v[216:219], v[240:243], v[34:37]
	s_waitcnt lgkmcnt(1)
	v_mfma_f32_16x16x32_bf16 v[38:41], v[216:219], v[252:255], v[38:41]
	s_waitcnt vmcnt(11)
	ds_write_b128 v164, v[200:203] offset:36864
	s_waitcnt vmcnt(10)
	ds_write_b128 v164, v[204:207] offset:41472
	v_mfma_f32_16x16x32_bf16 v[58:61], v[220:223], v[232:235], v[58:61]
	v_mfma_f32_16x16x32_bf16 v[62:65], v[220:223], v[236:239], v[62:65]
	v_mfma_f32_16x16x32_bf16 v[42:45], v[220:223], v[240:243], v[42:45]
	v_mfma_f32_16x16x32_bf16 v[46:49], v[220:223], v[252:255], v[46:49]
	s_waitcnt vmcnt(9)
	ds_write_b128 v164, v[208:211] offset:46080
	s_waitcnt vmcnt(8)
	ds_write_b128 v164, v[212:215] offset:50688
	v_mfma_f32_16x16x32_bf16 v[18:21], v[224:227], v[232:235], v[18:21]
	v_mfma_f32_16x16x32_bf16 v[22:25], v[224:227], v[236:239], v[22:25]
	v_mfma_f32_16x16x32_bf16 v[2:5], v[224:227], v[240:243], v[2:5]
	v_mfma_f32_16x16x32_bf16 v[6:9], v[224:227], v[252:255], v[6:9]
	s_waitcnt lgkmcnt(4)
	v_mfma_f32_16x16x32_bf16 v[26:29], v[228:231], v[232:235], v[26:29]
	v_mfma_f32_16x16x32_bf16 v[30:33], v[228:231], v[236:239], v[30:33]
	v_mfma_f32_16x16x32_bf16 v[10:13], v[228:231], v[240:243], v[10:13]
	v_mfma_f32_16x16x32_bf16 v[14:17], v[228:231], v[252:255], v[14:17]
	s_waitcnt lgkmcnt(0)
	s_barrier
	s_setprio 0
	ds_read_b128 v[232:235], v245 offset:36864
	ds_read_b128 v[216:219], v244
	ds_read_b128 v[236:239], v245 offset:39168
	ds_read_b128 v[240:243], v245 offset:41472
	ds_read_b128 v[252:255], v245 offset:43776
	ds_read_b128 v[220:223], v244 offset:2304
	ds_read_b128 v[224:227], v244 offset:4608
	ds_read_b128 v[228:231], v244 offset:6912
	global_load_dwordx4 v[180:183], v[70:71], off offset:768
	global_load_dwordx4 v[188:191], v[68:69], off offset:768
	global_load_dwordx4 v[192:195], v[66:67], off offset:768
	global_load_dwordx4 v[196:199], v[72:73], off offset:768
	global_load_dwordx4 v[200:203], v[74:75], off offset:768
	global_load_dwordx4 v[204:207], v[76:77], off offset:768
	global_load_dwordx4 v[208:211], v[78:79], off offset:768
	global_load_dwordx4 v[212:215], v[80:81], off offset:768
	s_waitcnt lgkmcnt(6)
	v_mfma_f32_16x16x32_bf16 v[50:53], v[216:219], v[232:235], v[50:53]
	s_waitcnt lgkmcnt(5)
	v_mfma_f32_16x16x32_bf16 v[54:57], v[216:219], v[236:239], v[54:57]
	s_waitcnt lgkmcnt(4)
	v_mfma_f32_16x16x32_bf16 v[34:37], v[216:219], v[240:243], v[34:37]
	s_waitcnt lgkmcnt(3)
	v_mfma_f32_16x16x32_bf16 v[38:41], v[216:219], v[252:255], v[38:41]
	ds_read_b128 v[216:219], v244 offset:64
	s_waitcnt lgkmcnt(3)
	v_mfma_f32_16x16x32_bf16 v[58:61], v[220:223], v[232:235], v[58:61]
	v_mfma_f32_16x16x32_bf16 v[62:65], v[220:223], v[236:239], v[62:65]
	v_mfma_f32_16x16x32_bf16 v[42:45], v[220:223], v[240:243], v[42:45]
	v_mfma_f32_16x16x32_bf16 v[46:49], v[220:223], v[252:255], v[46:49]
	ds_read_b128 v[220:223], v244 offset:2368
	s_setprio 1
	s_waitcnt vmcnt(15)
	ds_write_b128 v164, v[122:125] offset:18432
	s_waitcnt vmcnt(14)
	ds_write_b128 v164, v[126:129] offset:23040
	s_waitcnt lgkmcnt(5)
	v_mfma_f32_16x16x32_bf16 v[18:21], v[224:227], v[232:235], v[18:21]
	v_mfma_f32_16x16x32_bf16 v[22:25], v[224:227], v[236:239], v[22:25]
	v_mfma_f32_16x16x32_bf16 v[2:5], v[224:227], v[240:243], v[2:5]
	v_mfma_f32_16x16x32_bf16 v[6:9], v[224:227], v[252:255], v[6:9]
	ds_read_b128 v[224:227], v244 offset:4672
	s_waitcnt vmcnt(13)
	ds_write_b128 v164, v[136:139] offset:27648
	s_waitcnt vmcnt(12)
	ds_write_b128 v164, v[140:143] offset:32256
	s_waitcnt lgkmcnt(7)
	v_mfma_f32_16x16x32_bf16 v[26:29], v[228:231], v[232:235], v[26:29]
	ds_read_b128 v[232:235], v245 offset:36928
	v_mfma_f32_16x16x32_bf16 v[30:33], v[228:231], v[236:239], v[30:33]
	ds_read_b128 v[236:239], v245 offset:39232
	v_mfma_f32_16x16x32_bf16 v[10:13], v[228:231], v[240:243], v[10:13]
	ds_read_b128 v[240:243], v245 offset:41536
	v_mfma_f32_16x16x32_bf16 v[14:17], v[228:231], v[252:255], v[14:17]
	ds_read_b128 v[252:255], v245 offset:43840
	ds_read_b128 v[228:231], v244 offset:6976
	s_waitcnt lgkmcnt(4)
	v_mfma_f32_16x16x32_bf16 v[50:53], v[216:219], v[232:235], v[50:53]
	s_waitcnt lgkmcnt(3)
	v_mfma_f32_16x16x32_bf16 v[54:57], v[216:219], v[236:239], v[54:57]
	s_waitcnt lgkmcnt(2)
	v_mfma_f32_16x16x32_bf16 v[34:37], v[216:219], v[240:243], v[34:37]
	s_waitcnt lgkmcnt(1)
	v_mfma_f32_16x16x32_bf16 v[38:41], v[216:219], v[252:255], v[38:41]
	s_waitcnt vmcnt(11)
	ds_write_b128 v164, v[144:147] offset:55296
	s_waitcnt vmcnt(10)
	ds_write_b128 v164, v[148:151] offset:59904
	v_mfma_f32_16x16x32_bf16 v[58:61], v[220:223], v[232:235], v[58:61]
	v_mfma_f32_16x16x32_bf16 v[62:65], v[220:223], v[236:239], v[62:65]
	v_mfma_f32_16x16x32_bf16 v[42:45], v[220:223], v[240:243], v[42:45]
	v_mfma_f32_16x16x32_bf16 v[46:49], v[220:223], v[252:255], v[46:49]
	s_waitcnt vmcnt(9)
	ds_write_b128 v164, v[172:175] offset:64512
	s_waitcnt vmcnt(8)
	ds_write_b128 v165, v[176:179] offset:32256
	v_mfma_f32_16x16x32_bf16 v[18:21], v[224:227], v[232:235], v[18:21]
	v_mfma_f32_16x16x32_bf16 v[22:25], v[224:227], v[236:239], v[22:25]
	v_mfma_f32_16x16x32_bf16 v[2:5], v[224:227], v[240:243], v[2:5]
	v_mfma_f32_16x16x32_bf16 v[6:9], v[224:227], v[252:255], v[6:9]
	s_waitcnt lgkmcnt(4)
	v_mfma_f32_16x16x32_bf16 v[26:29], v[228:231], v[232:235], v[26:29]
	v_mfma_f32_16x16x32_bf16 v[30:33], v[228:231], v[236:239], v[30:33]
	v_mfma_f32_16x16x32_bf16 v[10:13], v[228:231], v[240:243], v[10:13]
	v_mfma_f32_16x16x32_bf16 v[14:17], v[228:231], v[252:255], v[14:17]
	s_waitcnt lgkmcnt(0)
	s_barrier
	s_setprio 0
	ds_read_b128 v[232:235], v245 offset:55296
	ds_read_b128 v[216:219], v244 offset:18432
	ds_read_b128 v[236:239], v245 offset:57600
	ds_read_b128 v[240:243], v245 offset:59904
	ds_read_b128 v[252:255], v245 offset:62208
	ds_read_b128 v[220:223], v244 offset:20736
	ds_read_b128 v[224:227], v244 offset:23040
	ds_read_b128 v[228:231], v244 offset:25344
	global_load_dwordx4 v[122:125], v[70:71], off offset:896
	global_load_dwordx4 v[126:129], v[68:69], off offset:896
	global_load_dwordx4 v[136:139], v[66:67], off offset:896
	global_load_dwordx4 v[140:143], v[72:73], off offset:896
	global_load_dwordx4 v[144:147], v[74:75], off offset:896
	global_load_dwordx4 v[148:151], v[76:77], off offset:896
	global_load_dwordx4 v[172:175], v[78:79], off offset:896
	global_load_dwordx4 v[176:179], v[80:81], off offset:896
	s_waitcnt lgkmcnt(6)
	v_mfma_f32_16x16x32_bf16 v[50:53], v[216:219], v[232:235], v[50:53]
	s_waitcnt lgkmcnt(5)
	v_mfma_f32_16x16x32_bf16 v[54:57], v[216:219], v[236:239], v[54:57]
	s_waitcnt lgkmcnt(4)
	v_mfma_f32_16x16x32_bf16 v[34:37], v[216:219], v[240:243], v[34:37]
	s_waitcnt lgkmcnt(3)
	v_mfma_f32_16x16x32_bf16 v[38:41], v[216:219], v[252:255], v[38:41]
	ds_read_b128 v[216:219], v244 offset:18496
	s_waitcnt lgkmcnt(3)
	v_mfma_f32_16x16x32_bf16 v[58:61], v[220:223], v[232:235], v[58:61]
	v_mfma_f32_16x16x32_bf16 v[62:65], v[220:223], v[236:239], v[62:65]
	v_mfma_f32_16x16x32_bf16 v[42:45], v[220:223], v[240:243], v[42:45]
	v_mfma_f32_16x16x32_bf16 v[46:49], v[220:223], v[252:255], v[46:49]
	ds_read_b128 v[220:223], v244 offset:20800
	s_setprio 1
	s_waitcnt vmcnt(15)
	ds_write_b128 v164, v[180:183]
	s_waitcnt vmcnt(14)
	ds_write_b128 v164, v[188:191] offset:4608
	s_waitcnt lgkmcnt(5)
	v_mfma_f32_16x16x32_bf16 v[18:21], v[224:227], v[232:235], v[18:21]
	v_mfma_f32_16x16x32_bf16 v[22:25], v[224:227], v[236:239], v[22:25]
	v_mfma_f32_16x16x32_bf16 v[2:5], v[224:227], v[240:243], v[2:5]
	v_mfma_f32_16x16x32_bf16 v[6:9], v[224:227], v[252:255], v[6:9]
	ds_read_b128 v[224:227], v244 offset:23104
	s_waitcnt vmcnt(13)
	ds_write_b128 v164, v[192:195] offset:9216
	s_waitcnt vmcnt(12)
	ds_write_b128 v164, v[196:199] offset:13824
	s_waitcnt lgkmcnt(7)
	v_mfma_f32_16x16x32_bf16 v[26:29], v[228:231], v[232:235], v[26:29]
	ds_read_b128 v[232:235], v245 offset:55360
	v_mfma_f32_16x16x32_bf16 v[30:33], v[228:231], v[236:239], v[30:33]
	ds_read_b128 v[236:239], v245 offset:57664
	v_mfma_f32_16x16x32_bf16 v[10:13], v[228:231], v[240:243], v[10:13]
	ds_read_b128 v[240:243], v245 offset:59968
	v_mfma_f32_16x16x32_bf16 v[14:17], v[228:231], v[252:255], v[14:17]
	ds_read_b128 v[252:255], v245 offset:62272
	ds_read_b128 v[228:231], v244 offset:25408
	s_waitcnt lgkmcnt(4)
	v_mfma_f32_16x16x32_bf16 v[50:53], v[216:219], v[232:235], v[50:53]
	s_waitcnt lgkmcnt(3)
	v_mfma_f32_16x16x32_bf16 v[54:57], v[216:219], v[236:239], v[54:57]
	s_waitcnt lgkmcnt(2)
	v_mfma_f32_16x16x32_bf16 v[34:37], v[216:219], v[240:243], v[34:37]
	s_waitcnt lgkmcnt(1)
	v_mfma_f32_16x16x32_bf16 v[38:41], v[216:219], v[252:255], v[38:41]
	s_waitcnt vmcnt(11)
	ds_write_b128 v164, v[200:203] offset:36864
	s_waitcnt vmcnt(10)
	ds_write_b128 v164, v[204:207] offset:41472
	v_mfma_f32_16x16x32_bf16 v[58:61], v[220:223], v[232:235], v[58:61]
	v_mfma_f32_16x16x32_bf16 v[62:65], v[220:223], v[236:239], v[62:65]
	v_mfma_f32_16x16x32_bf16 v[42:45], v[220:223], v[240:243], v[42:45]
	v_mfma_f32_16x16x32_bf16 v[46:49], v[220:223], v[252:255], v[46:49]
	s_waitcnt vmcnt(9)
	ds_write_b128 v164, v[208:211] offset:46080
	s_waitcnt vmcnt(8)
	ds_write_b128 v164, v[212:215] offset:50688
	v_mfma_f32_16x16x32_bf16 v[18:21], v[224:227], v[232:235], v[18:21]
	v_mfma_f32_16x16x32_bf16 v[22:25], v[224:227], v[236:239], v[22:25]
	v_mfma_f32_16x16x32_bf16 v[2:5], v[224:227], v[240:243], v[2:5]
	v_mfma_f32_16x16x32_bf16 v[6:9], v[224:227], v[252:255], v[6:9]
	s_waitcnt lgkmcnt(4)
	v_mfma_f32_16x16x32_bf16 v[26:29], v[228:231], v[232:235], v[26:29]
	v_mfma_f32_16x16x32_bf16 v[30:33], v[228:231], v[236:239], v[30:33]
	v_mfma_f32_16x16x32_bf16 v[10:13], v[228:231], v[240:243], v[10:13]
	v_mfma_f32_16x16x32_bf16 v[14:17], v[228:231], v[252:255], v[14:17]
	s_waitcnt lgkmcnt(0)
	s_barrier
	s_setprio 0
	ds_read_b128 v[232:235], v245 offset:36864
	ds_read_b128 v[216:219], v244
	ds_read_b128 v[236:239], v245 offset:39168
	ds_read_b128 v[240:243], v245 offset:41472
	ds_read_b128 v[252:255], v245 offset:43776
	ds_read_b128 v[220:223], v244 offset:2304
	ds_read_b128 v[224:227], v244 offset:4608
	ds_read_b128 v[228:231], v244 offset:6912
	global_load_dwordx4 v[180:183], v[70:71], off offset:1024
	global_load_dwordx4 v[188:191], v[68:69], off offset:1024
	global_load_dwordx4 v[192:195], v[66:67], off offset:1024
	global_load_dwordx4 v[196:199], v[72:73], off offset:1024
	global_load_dwordx4 v[200:203], v[74:75], off offset:1024
	global_load_dwordx4 v[204:207], v[76:77], off offset:1024
	global_load_dwordx4 v[208:211], v[78:79], off offset:1024
	global_load_dwordx4 v[212:215], v[80:81], off offset:1024
	s_waitcnt lgkmcnt(6)
	v_mfma_f32_16x16x32_bf16 v[50:53], v[216:219], v[232:235], v[50:53]
	s_waitcnt lgkmcnt(5)
	v_mfma_f32_16x16x32_bf16 v[54:57], v[216:219], v[236:239], v[54:57]
	s_waitcnt lgkmcnt(4)
	v_mfma_f32_16x16x32_bf16 v[34:37], v[216:219], v[240:243], v[34:37]
	s_waitcnt lgkmcnt(3)
	v_mfma_f32_16x16x32_bf16 v[38:41], v[216:219], v[252:255], v[38:41]
	ds_read_b128 v[216:219], v244 offset:64
	s_waitcnt lgkmcnt(3)
	v_mfma_f32_16x16x32_bf16 v[58:61], v[220:223], v[232:235], v[58:61]
	v_mfma_f32_16x16x32_bf16 v[62:65], v[220:223], v[236:239], v[62:65]
	v_mfma_f32_16x16x32_bf16 v[42:45], v[220:223], v[240:243], v[42:45]
	v_mfma_f32_16x16x32_bf16 v[46:49], v[220:223], v[252:255], v[46:49]
	ds_read_b128 v[220:223], v244 offset:2368
	s_setprio 1
	s_waitcnt vmcnt(15)
	ds_write_b128 v164, v[122:125] offset:18432
	s_waitcnt vmcnt(14)
	ds_write_b128 v164, v[126:129] offset:23040
	s_waitcnt lgkmcnt(5)
	v_mfma_f32_16x16x32_bf16 v[18:21], v[224:227], v[232:235], v[18:21]
	v_mfma_f32_16x16x32_bf16 v[22:25], v[224:227], v[236:239], v[22:25]
	v_mfma_f32_16x16x32_bf16 v[2:5], v[224:227], v[240:243], v[2:5]
	v_mfma_f32_16x16x32_bf16 v[6:9], v[224:227], v[252:255], v[6:9]
	ds_read_b128 v[224:227], v244 offset:4672
	s_waitcnt vmcnt(13)
	ds_write_b128 v164, v[136:139] offset:27648
	s_waitcnt vmcnt(12)
	ds_write_b128 v164, v[140:143] offset:32256
	s_waitcnt lgkmcnt(7)
	v_mfma_f32_16x16x32_bf16 v[26:29], v[228:231], v[232:235], v[26:29]
	ds_read_b128 v[232:235], v245 offset:36928
	v_mfma_f32_16x16x32_bf16 v[30:33], v[228:231], v[236:239], v[30:33]
	ds_read_b128 v[236:239], v245 offset:39232
	v_mfma_f32_16x16x32_bf16 v[10:13], v[228:231], v[240:243], v[10:13]
	ds_read_b128 v[240:243], v245 offset:41536
	v_mfma_f32_16x16x32_bf16 v[14:17], v[228:231], v[252:255], v[14:17]
	ds_read_b128 v[252:255], v245 offset:43840
	ds_read_b128 v[228:231], v244 offset:6976
	s_waitcnt lgkmcnt(4)
	v_mfma_f32_16x16x32_bf16 v[50:53], v[216:219], v[232:235], v[50:53]
	s_waitcnt lgkmcnt(3)
	v_mfma_f32_16x16x32_bf16 v[54:57], v[216:219], v[236:239], v[54:57]
	s_waitcnt lgkmcnt(2)
	v_mfma_f32_16x16x32_bf16 v[34:37], v[216:219], v[240:243], v[34:37]
	s_waitcnt lgkmcnt(1)
	v_mfma_f32_16x16x32_bf16 v[38:41], v[216:219], v[252:255], v[38:41]
	s_waitcnt vmcnt(11)
	ds_write_b128 v164, v[144:147] offset:55296
	s_waitcnt vmcnt(10)
	ds_write_b128 v164, v[148:151] offset:59904
	v_mfma_f32_16x16x32_bf16 v[58:61], v[220:223], v[232:235], v[58:61]
	v_mfma_f32_16x16x32_bf16 v[62:65], v[220:223], v[236:239], v[62:65]
	v_mfma_f32_16x16x32_bf16 v[42:45], v[220:223], v[240:243], v[42:45]
	v_mfma_f32_16x16x32_bf16 v[46:49], v[220:223], v[252:255], v[46:49]
	s_waitcnt vmcnt(9)
	ds_write_b128 v164, v[172:175] offset:64512
	s_waitcnt vmcnt(8)
	ds_write_b128 v165, v[176:179] offset:32256
	v_mfma_f32_16x16x32_bf16 v[18:21], v[224:227], v[232:235], v[18:21]
	v_mfma_f32_16x16x32_bf16 v[22:25], v[224:227], v[236:239], v[22:25]
	v_mfma_f32_16x16x32_bf16 v[2:5], v[224:227], v[240:243], v[2:5]
	v_mfma_f32_16x16x32_bf16 v[6:9], v[224:227], v[252:255], v[6:9]
	s_waitcnt lgkmcnt(4)
	v_mfma_f32_16x16x32_bf16 v[26:29], v[228:231], v[232:235], v[26:29]
	v_mfma_f32_16x16x32_bf16 v[30:33], v[228:231], v[236:239], v[30:33]
	v_mfma_f32_16x16x32_bf16 v[10:13], v[228:231], v[240:243], v[10:13]
	v_mfma_f32_16x16x32_bf16 v[14:17], v[228:231], v[252:255], v[14:17]
	s_waitcnt lgkmcnt(0)
	s_barrier
	s_setprio 0
	ds_read_b128 v[232:235], v245 offset:55296
	ds_read_b128 v[216:219], v244 offset:18432
	ds_read_b128 v[236:239], v245 offset:57600
	ds_read_b128 v[240:243], v245 offset:59904
	ds_read_b128 v[252:255], v245 offset:62208
	ds_read_b128 v[220:223], v244 offset:20736
	ds_read_b128 v[224:227], v244 offset:23040
	ds_read_b128 v[228:231], v244 offset:25344
	global_load_dwordx4 v[122:125], v[70:71], off offset:1152
	global_load_dwordx4 v[126:129], v[68:69], off offset:1152
	global_load_dwordx4 v[136:139], v[66:67], off offset:1152
	global_load_dwordx4 v[140:143], v[72:73], off offset:1152
	global_load_dwordx4 v[144:147], v[74:75], off offset:1152
	global_load_dwordx4 v[148:151], v[76:77], off offset:1152
	global_load_dwordx4 v[172:175], v[78:79], off offset:1152
	global_load_dwordx4 v[176:179], v[80:81], off offset:1152
	s_waitcnt lgkmcnt(6)
	v_mfma_f32_16x16x32_bf16 v[50:53], v[216:219], v[232:235], v[50:53]
	s_waitcnt lgkmcnt(5)
	v_mfma_f32_16x16x32_bf16 v[54:57], v[216:219], v[236:239], v[54:57]
	s_waitcnt lgkmcnt(4)
	v_mfma_f32_16x16x32_bf16 v[34:37], v[216:219], v[240:243], v[34:37]
	s_waitcnt lgkmcnt(3)
	v_mfma_f32_16x16x32_bf16 v[38:41], v[216:219], v[252:255], v[38:41]
	ds_read_b128 v[216:219], v244 offset:18496
	s_waitcnt lgkmcnt(3)
	v_mfma_f32_16x16x32_bf16 v[58:61], v[220:223], v[232:235], v[58:61]
	v_mfma_f32_16x16x32_bf16 v[62:65], v[220:223], v[236:239], v[62:65]
	v_mfma_f32_16x16x32_bf16 v[42:45], v[220:223], v[240:243], v[42:45]
	v_mfma_f32_16x16x32_bf16 v[46:49], v[220:223], v[252:255], v[46:49]
	ds_read_b128 v[220:223], v244 offset:20800
	s_setprio 1
	s_waitcnt vmcnt(15)
	ds_write_b128 v164, v[180:183]
	s_waitcnt vmcnt(14)
	ds_write_b128 v164, v[188:191] offset:4608
	s_waitcnt lgkmcnt(5)
	v_mfma_f32_16x16x32_bf16 v[18:21], v[224:227], v[232:235], v[18:21]
	v_mfma_f32_16x16x32_bf16 v[22:25], v[224:227], v[236:239], v[22:25]
	v_mfma_f32_16x16x32_bf16 v[2:5], v[224:227], v[240:243], v[2:5]
	v_mfma_f32_16x16x32_bf16 v[6:9], v[224:227], v[252:255], v[6:9]
	ds_read_b128 v[224:227], v244 offset:23104
	s_waitcnt vmcnt(13)
	ds_write_b128 v164, v[192:195] offset:9216
	s_waitcnt vmcnt(12)
	ds_write_b128 v164, v[196:199] offset:13824
	s_waitcnt lgkmcnt(7)
	v_mfma_f32_16x16x32_bf16 v[26:29], v[228:231], v[232:235], v[26:29]
	ds_read_b128 v[232:235], v245 offset:55360
	v_mfma_f32_16x16x32_bf16 v[30:33], v[228:231], v[236:239], v[30:33]
	ds_read_b128 v[236:239], v245 offset:57664
	v_mfma_f32_16x16x32_bf16 v[10:13], v[228:231], v[240:243], v[10:13]
	ds_read_b128 v[240:243], v245 offset:59968
	v_mfma_f32_16x16x32_bf16 v[14:17], v[228:231], v[252:255], v[14:17]
	ds_read_b128 v[252:255], v245 offset:62272
	ds_read_b128 v[228:231], v244 offset:25408
	s_waitcnt lgkmcnt(4)
	v_mfma_f32_16x16x32_bf16 v[50:53], v[216:219], v[232:235], v[50:53]
	s_waitcnt lgkmcnt(3)
	v_mfma_f32_16x16x32_bf16 v[54:57], v[216:219], v[236:239], v[54:57]
	s_waitcnt lgkmcnt(2)
	v_mfma_f32_16x16x32_bf16 v[34:37], v[216:219], v[240:243], v[34:37]
	s_waitcnt lgkmcnt(1)
	v_mfma_f32_16x16x32_bf16 v[38:41], v[216:219], v[252:255], v[38:41]
	s_waitcnt vmcnt(11)
	ds_write_b128 v164, v[200:203] offset:36864
	s_waitcnt vmcnt(10)
	ds_write_b128 v164, v[204:207] offset:41472
	v_mfma_f32_16x16x32_bf16 v[58:61], v[220:223], v[232:235], v[58:61]
	v_mfma_f32_16x16x32_bf16 v[62:65], v[220:223], v[236:239], v[62:65]
	v_mfma_f32_16x16x32_bf16 v[42:45], v[220:223], v[240:243], v[42:45]
	v_mfma_f32_16x16x32_bf16 v[46:49], v[220:223], v[252:255], v[46:49]
	s_waitcnt vmcnt(9)
	ds_write_b128 v164, v[208:211] offset:46080
	s_waitcnt vmcnt(8)
	ds_write_b128 v164, v[212:215] offset:50688
	v_mfma_f32_16x16x32_bf16 v[18:21], v[224:227], v[232:235], v[18:21]
	v_mfma_f32_16x16x32_bf16 v[22:25], v[224:227], v[236:239], v[22:25]
	v_mfma_f32_16x16x32_bf16 v[2:5], v[224:227], v[240:243], v[2:5]
	v_mfma_f32_16x16x32_bf16 v[6:9], v[224:227], v[252:255], v[6:9]
	s_waitcnt lgkmcnt(4)
	v_mfma_f32_16x16x32_bf16 v[26:29], v[228:231], v[232:235], v[26:29]
	v_mfma_f32_16x16x32_bf16 v[30:33], v[228:231], v[236:239], v[30:33]
	v_mfma_f32_16x16x32_bf16 v[10:13], v[228:231], v[240:243], v[10:13]
	v_mfma_f32_16x16x32_bf16 v[14:17], v[228:231], v[252:255], v[14:17]
	s_waitcnt lgkmcnt(0)
	s_barrier
	s_setprio 0
	ds_read_b128 v[232:235], v245 offset:36864
	ds_read_b128 v[216:219], v244
	ds_read_b128 v[236:239], v245 offset:39168
	ds_read_b128 v[240:243], v245 offset:41472
	ds_read_b128 v[252:255], v245 offset:43776
	ds_read_b128 v[220:223], v244 offset:2304
	ds_read_b128 v[224:227], v244 offset:4608
	ds_read_b128 v[228:231], v244 offset:6912
	global_load_dwordx4 v[180:183], v[70:71], off offset:1280
	global_load_dwordx4 v[188:191], v[68:69], off offset:1280
	global_load_dwordx4 v[192:195], v[66:67], off offset:1280
	global_load_dwordx4 v[196:199], v[72:73], off offset:1280
	global_load_dwordx4 v[200:203], v[74:75], off offset:1280
	global_load_dwordx4 v[204:207], v[76:77], off offset:1280
	global_load_dwordx4 v[208:211], v[78:79], off offset:1280
	global_load_dwordx4 v[212:215], v[80:81], off offset:1280
	s_waitcnt lgkmcnt(6)
	v_mfma_f32_16x16x32_bf16 v[50:53], v[216:219], v[232:235], v[50:53]
	s_waitcnt lgkmcnt(5)
	v_mfma_f32_16x16x32_bf16 v[54:57], v[216:219], v[236:239], v[54:57]
	s_waitcnt lgkmcnt(4)
	v_mfma_f32_16x16x32_bf16 v[34:37], v[216:219], v[240:243], v[34:37]
	s_waitcnt lgkmcnt(3)
	v_mfma_f32_16x16x32_bf16 v[38:41], v[216:219], v[252:255], v[38:41]
	ds_read_b128 v[216:219], v244 offset:64
	s_waitcnt lgkmcnt(3)
	v_mfma_f32_16x16x32_bf16 v[58:61], v[220:223], v[232:235], v[58:61]
	v_mfma_f32_16x16x32_bf16 v[62:65], v[220:223], v[236:239], v[62:65]
	v_mfma_f32_16x16x32_bf16 v[42:45], v[220:223], v[240:243], v[42:45]
	v_mfma_f32_16x16x32_bf16 v[46:49], v[220:223], v[252:255], v[46:49]
	ds_read_b128 v[220:223], v244 offset:2368
	s_setprio 1
	s_waitcnt vmcnt(15)
	ds_write_b128 v164, v[122:125] offset:18432
	s_waitcnt vmcnt(14)
	ds_write_b128 v164, v[126:129] offset:23040
	s_waitcnt lgkmcnt(5)
	v_mfma_f32_16x16x32_bf16 v[18:21], v[224:227], v[232:235], v[18:21]
	v_mfma_f32_16x16x32_bf16 v[22:25], v[224:227], v[236:239], v[22:25]
	v_mfma_f32_16x16x32_bf16 v[2:5], v[224:227], v[240:243], v[2:5]
	v_mfma_f32_16x16x32_bf16 v[6:9], v[224:227], v[252:255], v[6:9]
	ds_read_b128 v[224:227], v244 offset:4672
	s_waitcnt vmcnt(13)
	ds_write_b128 v164, v[136:139] offset:27648
	s_waitcnt vmcnt(12)
	ds_write_b128 v164, v[140:143] offset:32256
	s_waitcnt lgkmcnt(7)
	v_mfma_f32_16x16x32_bf16 v[26:29], v[228:231], v[232:235], v[26:29]
	ds_read_b128 v[232:235], v245 offset:36928
	v_mfma_f32_16x16x32_bf16 v[30:33], v[228:231], v[236:239], v[30:33]
	ds_read_b128 v[236:239], v245 offset:39232
	v_mfma_f32_16x16x32_bf16 v[10:13], v[228:231], v[240:243], v[10:13]
	ds_read_b128 v[240:243], v245 offset:41536
	v_mfma_f32_16x16x32_bf16 v[14:17], v[228:231], v[252:255], v[14:17]
	ds_read_b128 v[252:255], v245 offset:43840
	ds_read_b128 v[228:231], v244 offset:6976
	s_waitcnt lgkmcnt(4)
	v_mfma_f32_16x16x32_bf16 v[50:53], v[216:219], v[232:235], v[50:53]
	s_waitcnt lgkmcnt(3)
	v_mfma_f32_16x16x32_bf16 v[54:57], v[216:219], v[236:239], v[54:57]
	s_waitcnt lgkmcnt(2)
	v_mfma_f32_16x16x32_bf16 v[34:37], v[216:219], v[240:243], v[34:37]
	s_waitcnt lgkmcnt(1)
	v_mfma_f32_16x16x32_bf16 v[38:41], v[216:219], v[252:255], v[38:41]
	s_waitcnt vmcnt(11)
	ds_write_b128 v164, v[144:147] offset:55296
	s_waitcnt vmcnt(10)
	ds_write_b128 v164, v[148:151] offset:59904
	v_mfma_f32_16x16x32_bf16 v[58:61], v[220:223], v[232:235], v[58:61]
	v_mfma_f32_16x16x32_bf16 v[62:65], v[220:223], v[236:239], v[62:65]
	v_mfma_f32_16x16x32_bf16 v[42:45], v[220:223], v[240:243], v[42:45]
	v_mfma_f32_16x16x32_bf16 v[46:49], v[220:223], v[252:255], v[46:49]
	s_waitcnt vmcnt(9)
	ds_write_b128 v164, v[172:175] offset:64512
	s_waitcnt vmcnt(8)
	ds_write_b128 v165, v[176:179] offset:32256
	v_mfma_f32_16x16x32_bf16 v[18:21], v[224:227], v[232:235], v[18:21]
	v_mfma_f32_16x16x32_bf16 v[22:25], v[224:227], v[236:239], v[22:25]
	v_mfma_f32_16x16x32_bf16 v[2:5], v[224:227], v[240:243], v[2:5]
	v_mfma_f32_16x16x32_bf16 v[6:9], v[224:227], v[252:255], v[6:9]
	s_waitcnt lgkmcnt(4)
	v_mfma_f32_16x16x32_bf16 v[26:29], v[228:231], v[232:235], v[26:29]
	v_mfma_f32_16x16x32_bf16 v[30:33], v[228:231], v[236:239], v[30:33]
	v_mfma_f32_16x16x32_bf16 v[10:13], v[228:231], v[240:243], v[10:13]
	v_mfma_f32_16x16x32_bf16 v[14:17], v[228:231], v[252:255], v[14:17]
	s_waitcnt lgkmcnt(0)
	s_barrier
	s_setprio 0
	ds_read_b128 v[232:235], v245 offset:55296
	ds_read_b128 v[216:219], v244 offset:18432
	ds_read_b128 v[236:239], v245 offset:57600
	ds_read_b128 v[240:243], v245 offset:59904
	ds_read_b128 v[252:255], v245 offset:62208
	ds_read_b128 v[220:223], v244 offset:20736
	ds_read_b128 v[224:227], v244 offset:23040
	ds_read_b128 v[228:231], v244 offset:25344
	global_load_dwordx4 v[122:125], v[70:71], off offset:1408
	global_load_dwordx4 v[126:129], v[68:69], off offset:1408
	global_load_dwordx4 v[136:139], v[66:67], off offset:1408
	global_load_dwordx4 v[140:143], v[72:73], off offset:1408
	global_load_dwordx4 v[144:147], v[74:75], off offset:1408
	global_load_dwordx4 v[148:151], v[76:77], off offset:1408
	global_load_dwordx4 v[172:175], v[78:79], off offset:1408
	global_load_dwordx4 v[176:179], v[80:81], off offset:1408
	s_waitcnt lgkmcnt(6)
	v_mfma_f32_16x16x32_bf16 v[50:53], v[216:219], v[232:235], v[50:53]
	s_waitcnt lgkmcnt(5)
	v_mfma_f32_16x16x32_bf16 v[54:57], v[216:219], v[236:239], v[54:57]
	s_waitcnt lgkmcnt(4)
	v_mfma_f32_16x16x32_bf16 v[34:37], v[216:219], v[240:243], v[34:37]
	s_waitcnt lgkmcnt(3)
	v_mfma_f32_16x16x32_bf16 v[38:41], v[216:219], v[252:255], v[38:41]
	ds_read_b128 v[216:219], v244 offset:18496
	s_waitcnt lgkmcnt(3)
	v_mfma_f32_16x16x32_bf16 v[58:61], v[220:223], v[232:235], v[58:61]
	v_mfma_f32_16x16x32_bf16 v[62:65], v[220:223], v[236:239], v[62:65]
	v_mfma_f32_16x16x32_bf16 v[42:45], v[220:223], v[240:243], v[42:45]
	v_mfma_f32_16x16x32_bf16 v[46:49], v[220:223], v[252:255], v[46:49]
	ds_read_b128 v[220:223], v244 offset:20800
	s_setprio 1
	s_waitcnt vmcnt(15)
	ds_write_b128 v164, v[180:183]
	s_waitcnt vmcnt(14)
	ds_write_b128 v164, v[188:191] offset:4608
	s_waitcnt lgkmcnt(5)
	v_mfma_f32_16x16x32_bf16 v[18:21], v[224:227], v[232:235], v[18:21]
	v_mfma_f32_16x16x32_bf16 v[22:25], v[224:227], v[236:239], v[22:25]
	v_mfma_f32_16x16x32_bf16 v[2:5], v[224:227], v[240:243], v[2:5]
	v_mfma_f32_16x16x32_bf16 v[6:9], v[224:227], v[252:255], v[6:9]
	ds_read_b128 v[224:227], v244 offset:23104
	s_waitcnt vmcnt(13)
	ds_write_b128 v164, v[192:195] offset:9216
	s_waitcnt vmcnt(12)
	ds_write_b128 v164, v[196:199] offset:13824
	s_waitcnt lgkmcnt(7)
	v_mfma_f32_16x16x32_bf16 v[26:29], v[228:231], v[232:235], v[26:29]
	ds_read_b128 v[232:235], v245 offset:55360
	v_mfma_f32_16x16x32_bf16 v[30:33], v[228:231], v[236:239], v[30:33]
	ds_read_b128 v[236:239], v245 offset:57664
	v_mfma_f32_16x16x32_bf16 v[10:13], v[228:231], v[240:243], v[10:13]
	ds_read_b128 v[240:243], v245 offset:59968
	v_mfma_f32_16x16x32_bf16 v[14:17], v[228:231], v[252:255], v[14:17]
	ds_read_b128 v[252:255], v245 offset:62272
	ds_read_b128 v[228:231], v244 offset:25408
	s_waitcnt lgkmcnt(4)
	v_mfma_f32_16x16x32_bf16 v[50:53], v[216:219], v[232:235], v[50:53]
	s_waitcnt lgkmcnt(3)
	v_mfma_f32_16x16x32_bf16 v[54:57], v[216:219], v[236:239], v[54:57]
	s_waitcnt lgkmcnt(2)
	v_mfma_f32_16x16x32_bf16 v[34:37], v[216:219], v[240:243], v[34:37]
	s_waitcnt lgkmcnt(1)
	v_mfma_f32_16x16x32_bf16 v[38:41], v[216:219], v[252:255], v[38:41]
	s_waitcnt vmcnt(11)
	ds_write_b128 v164, v[200:203] offset:36864
	s_waitcnt vmcnt(10)
	ds_write_b128 v164, v[204:207] offset:41472
	v_mfma_f32_16x16x32_bf16 v[58:61], v[220:223], v[232:235], v[58:61]
	v_mfma_f32_16x16x32_bf16 v[62:65], v[220:223], v[236:239], v[62:65]
	v_mfma_f32_16x16x32_bf16 v[42:45], v[220:223], v[240:243], v[42:45]
	v_mfma_f32_16x16x32_bf16 v[46:49], v[220:223], v[252:255], v[46:49]
	s_waitcnt vmcnt(9)
	ds_write_b128 v164, v[208:211] offset:46080
	s_waitcnt vmcnt(8)
	ds_write_b128 v164, v[212:215] offset:50688
	v_mfma_f32_16x16x32_bf16 v[18:21], v[224:227], v[232:235], v[18:21]
	v_mfma_f32_16x16x32_bf16 v[22:25], v[224:227], v[236:239], v[22:25]
	v_mfma_f32_16x16x32_bf16 v[2:5], v[224:227], v[240:243], v[2:5]
	v_mfma_f32_16x16x32_bf16 v[6:9], v[224:227], v[252:255], v[6:9]
	s_waitcnt lgkmcnt(4)
	v_mfma_f32_16x16x32_bf16 v[26:29], v[228:231], v[232:235], v[26:29]
	v_mfma_f32_16x16x32_bf16 v[30:33], v[228:231], v[236:239], v[30:33]
	v_mfma_f32_16x16x32_bf16 v[10:13], v[228:231], v[240:243], v[10:13]
	v_mfma_f32_16x16x32_bf16 v[14:17], v[228:231], v[252:255], v[14:17]
	s_waitcnt lgkmcnt(0)
	s_barrier
	s_setprio 0
	ds_read_b128 v[232:235], v245 offset:36864
	ds_read_b128 v[216:219], v244
	ds_read_b128 v[236:239], v245 offset:39168
	ds_read_b128 v[240:243], v245 offset:41472
	ds_read_b128 v[252:255], v245 offset:43776
	ds_read_b128 v[220:223], v244 offset:2304
	ds_read_b128 v[224:227], v244 offset:4608
	ds_read_b128 v[228:231], v244 offset:6912
	global_load_dwordx4 v[180:183], v[70:71], off offset:1536
	global_load_dwordx4 v[188:191], v[68:69], off offset:1536
	global_load_dwordx4 v[192:195], v[66:67], off offset:1536
	global_load_dwordx4 v[196:199], v[72:73], off offset:1536
	global_load_dwordx4 v[200:203], v[74:75], off offset:1536
	global_load_dwordx4 v[204:207], v[76:77], off offset:1536
	global_load_dwordx4 v[208:211], v[78:79], off offset:1536
	global_load_dwordx4 v[212:215], v[80:81], off offset:1536
	s_waitcnt lgkmcnt(6)
	v_mfma_f32_16x16x32_bf16 v[50:53], v[216:219], v[232:235], v[50:53]
	s_waitcnt lgkmcnt(5)
	v_mfma_f32_16x16x32_bf16 v[54:57], v[216:219], v[236:239], v[54:57]
	s_waitcnt lgkmcnt(4)
	v_mfma_f32_16x16x32_bf16 v[34:37], v[216:219], v[240:243], v[34:37]
	s_waitcnt lgkmcnt(3)
	v_mfma_f32_16x16x32_bf16 v[38:41], v[216:219], v[252:255], v[38:41]
	ds_read_b128 v[216:219], v244 offset:64
	s_waitcnt lgkmcnt(3)
	v_mfma_f32_16x16x32_bf16 v[58:61], v[220:223], v[232:235], v[58:61]
	v_mfma_f32_16x16x32_bf16 v[62:65], v[220:223], v[236:239], v[62:65]
	v_mfma_f32_16x16x32_bf16 v[42:45], v[220:223], v[240:243], v[42:45]
	v_mfma_f32_16x16x32_bf16 v[46:49], v[220:223], v[252:255], v[46:49]
	ds_read_b128 v[220:223], v244 offset:2368
	s_setprio 1
	s_waitcnt vmcnt(15)
	ds_write_b128 v164, v[122:125] offset:18432
	s_waitcnt vmcnt(14)
	ds_write_b128 v164, v[126:129] offset:23040
	s_waitcnt lgkmcnt(5)
	v_mfma_f32_16x16x32_bf16 v[18:21], v[224:227], v[232:235], v[18:21]
	v_mfma_f32_16x16x32_bf16 v[22:25], v[224:227], v[236:239], v[22:25]
	v_mfma_f32_16x16x32_bf16 v[2:5], v[224:227], v[240:243], v[2:5]
	v_mfma_f32_16x16x32_bf16 v[6:9], v[224:227], v[252:255], v[6:9]
	ds_read_b128 v[224:227], v244 offset:4672
	s_waitcnt vmcnt(13)
	ds_write_b128 v164, v[136:139] offset:27648
	s_waitcnt vmcnt(12)
	ds_write_b128 v164, v[140:143] offset:32256
	s_waitcnt lgkmcnt(7)
	v_mfma_f32_16x16x32_bf16 v[26:29], v[228:231], v[232:235], v[26:29]
	ds_read_b128 v[232:235], v245 offset:36928
	v_mfma_f32_16x16x32_bf16 v[30:33], v[228:231], v[236:239], v[30:33]
	ds_read_b128 v[236:239], v245 offset:39232
	v_mfma_f32_16x16x32_bf16 v[10:13], v[228:231], v[240:243], v[10:13]
	ds_read_b128 v[240:243], v245 offset:41536
	v_mfma_f32_16x16x32_bf16 v[14:17], v[228:231], v[252:255], v[14:17]
	ds_read_b128 v[252:255], v245 offset:43840
	ds_read_b128 v[228:231], v244 offset:6976
	s_waitcnt lgkmcnt(4)
	v_mfma_f32_16x16x32_bf16 v[50:53], v[216:219], v[232:235], v[50:53]
	s_waitcnt lgkmcnt(3)
	v_mfma_f32_16x16x32_bf16 v[54:57], v[216:219], v[236:239], v[54:57]
	s_waitcnt lgkmcnt(2)
	v_mfma_f32_16x16x32_bf16 v[34:37], v[216:219], v[240:243], v[34:37]
	s_waitcnt lgkmcnt(1)
	v_mfma_f32_16x16x32_bf16 v[38:41], v[216:219], v[252:255], v[38:41]
	s_waitcnt vmcnt(11)
	ds_write_b128 v164, v[144:147] offset:55296
	s_waitcnt vmcnt(10)
	ds_write_b128 v164, v[148:151] offset:59904
	v_mfma_f32_16x16x32_bf16 v[58:61], v[220:223], v[232:235], v[58:61]
	v_mfma_f32_16x16x32_bf16 v[62:65], v[220:223], v[236:239], v[62:65]
	v_mfma_f32_16x16x32_bf16 v[42:45], v[220:223], v[240:243], v[42:45]
	v_mfma_f32_16x16x32_bf16 v[46:49], v[220:223], v[252:255], v[46:49]
	s_waitcnt vmcnt(9)
	ds_write_b128 v164, v[172:175] offset:64512
	s_waitcnt vmcnt(8)
	ds_write_b128 v165, v[176:179] offset:32256
	v_mfma_f32_16x16x32_bf16 v[18:21], v[224:227], v[232:235], v[18:21]
	v_mfma_f32_16x16x32_bf16 v[22:25], v[224:227], v[236:239], v[22:25]
	v_mfma_f32_16x16x32_bf16 v[2:5], v[224:227], v[240:243], v[2:5]
	v_mfma_f32_16x16x32_bf16 v[6:9], v[224:227], v[252:255], v[6:9]
	s_waitcnt lgkmcnt(4)
	v_mfma_f32_16x16x32_bf16 v[26:29], v[228:231], v[232:235], v[26:29]
	v_mfma_f32_16x16x32_bf16 v[30:33], v[228:231], v[236:239], v[30:33]
	v_mfma_f32_16x16x32_bf16 v[10:13], v[228:231], v[240:243], v[10:13]
	v_mfma_f32_16x16x32_bf16 v[14:17], v[228:231], v[252:255], v[14:17]
	s_waitcnt lgkmcnt(0)
	s_barrier
	s_setprio 0
	ds_read_b128 v[232:235], v245 offset:55296
	ds_read_b128 v[216:219], v244 offset:18432
	ds_read_b128 v[236:239], v245 offset:57600
	ds_read_b128 v[240:243], v245 offset:59904
	ds_read_b128 v[252:255], v245 offset:62208
	ds_read_b128 v[220:223], v244 offset:20736
	ds_read_b128 v[224:227], v244 offset:23040
	ds_read_b128 v[228:231], v244 offset:25344
	global_load_dwordx4 v[122:125], v[70:71], off offset:1664
	global_load_dwordx4 v[126:129], v[68:69], off offset:1664
	global_load_dwordx4 v[136:139], v[66:67], off offset:1664
	global_load_dwordx4 v[140:143], v[72:73], off offset:1664
	global_load_dwordx4 v[144:147], v[74:75], off offset:1664
	global_load_dwordx4 v[148:151], v[76:77], off offset:1664
	global_load_dwordx4 v[172:175], v[78:79], off offset:1664
	global_load_dwordx4 v[176:179], v[80:81], off offset:1664
	s_waitcnt lgkmcnt(6)
	v_mfma_f32_16x16x32_bf16 v[50:53], v[216:219], v[232:235], v[50:53]
	s_waitcnt lgkmcnt(5)
	v_mfma_f32_16x16x32_bf16 v[54:57], v[216:219], v[236:239], v[54:57]
	s_waitcnt lgkmcnt(4)
	v_mfma_f32_16x16x32_bf16 v[34:37], v[216:219], v[240:243], v[34:37]
	s_waitcnt lgkmcnt(3)
	v_mfma_f32_16x16x32_bf16 v[38:41], v[216:219], v[252:255], v[38:41]
	ds_read_b128 v[216:219], v244 offset:18496
	s_waitcnt lgkmcnt(3)
	v_mfma_f32_16x16x32_bf16 v[58:61], v[220:223], v[232:235], v[58:61]
	v_mfma_f32_16x16x32_bf16 v[62:65], v[220:223], v[236:239], v[62:65]
	v_mfma_f32_16x16x32_bf16 v[42:45], v[220:223], v[240:243], v[42:45]
	v_mfma_f32_16x16x32_bf16 v[46:49], v[220:223], v[252:255], v[46:49]
	ds_read_b128 v[220:223], v244 offset:20800
	s_setprio 1
	s_waitcnt vmcnt(15)
	ds_write_b128 v164, v[180:183]
	s_waitcnt vmcnt(14)
	ds_write_b128 v164, v[188:191] offset:4608
	s_waitcnt lgkmcnt(5)
	v_mfma_f32_16x16x32_bf16 v[18:21], v[224:227], v[232:235], v[18:21]
	v_mfma_f32_16x16x32_bf16 v[22:25], v[224:227], v[236:239], v[22:25]
	v_mfma_f32_16x16x32_bf16 v[2:5], v[224:227], v[240:243], v[2:5]
	v_mfma_f32_16x16x32_bf16 v[6:9], v[224:227], v[252:255], v[6:9]
	ds_read_b128 v[224:227], v244 offset:23104
	s_waitcnt vmcnt(13)
	ds_write_b128 v164, v[192:195] offset:9216
	s_waitcnt vmcnt(12)
	ds_write_b128 v164, v[196:199] offset:13824
	s_waitcnt lgkmcnt(7)
	v_mfma_f32_16x16x32_bf16 v[26:29], v[228:231], v[232:235], v[26:29]
	ds_read_b128 v[232:235], v245 offset:55360
	v_mfma_f32_16x16x32_bf16 v[30:33], v[228:231], v[236:239], v[30:33]
	ds_read_b128 v[236:239], v245 offset:57664
	v_mfma_f32_16x16x32_bf16 v[10:13], v[228:231], v[240:243], v[10:13]
	ds_read_b128 v[240:243], v245 offset:59968
	v_mfma_f32_16x16x32_bf16 v[14:17], v[228:231], v[252:255], v[14:17]
	ds_read_b128 v[252:255], v245 offset:62272
	ds_read_b128 v[228:231], v244 offset:25408
	s_waitcnt lgkmcnt(4)
	v_mfma_f32_16x16x32_bf16 v[50:53], v[216:219], v[232:235], v[50:53]
	s_waitcnt lgkmcnt(3)
	v_mfma_f32_16x16x32_bf16 v[54:57], v[216:219], v[236:239], v[54:57]
	s_waitcnt lgkmcnt(2)
	v_mfma_f32_16x16x32_bf16 v[34:37], v[216:219], v[240:243], v[34:37]
	s_waitcnt lgkmcnt(1)
	v_mfma_f32_16x16x32_bf16 v[38:41], v[216:219], v[252:255], v[38:41]
	s_waitcnt vmcnt(11)
	ds_write_b128 v164, v[200:203] offset:36864
	s_waitcnt vmcnt(10)
	ds_write_b128 v164, v[204:207] offset:41472
	v_mfma_f32_16x16x32_bf16 v[58:61], v[220:223], v[232:235], v[58:61]
	v_mfma_f32_16x16x32_bf16 v[62:65], v[220:223], v[236:239], v[62:65]
	v_mfma_f32_16x16x32_bf16 v[42:45], v[220:223], v[240:243], v[42:45]
	v_mfma_f32_16x16x32_bf16 v[46:49], v[220:223], v[252:255], v[46:49]
	s_waitcnt vmcnt(9)
	ds_write_b128 v164, v[208:211] offset:46080
	s_waitcnt vmcnt(8)
	ds_write_b128 v164, v[212:215] offset:50688
	v_mfma_f32_16x16x32_bf16 v[18:21], v[224:227], v[232:235], v[18:21]
	v_mfma_f32_16x16x32_bf16 v[22:25], v[224:227], v[236:239], v[22:25]
	v_mfma_f32_16x16x32_bf16 v[2:5], v[224:227], v[240:243], v[2:5]
	v_mfma_f32_16x16x32_bf16 v[6:9], v[224:227], v[252:255], v[6:9]
	s_waitcnt lgkmcnt(4)
	v_mfma_f32_16x16x32_bf16 v[26:29], v[228:231], v[232:235], v[26:29]
	v_mfma_f32_16x16x32_bf16 v[30:33], v[228:231], v[236:239], v[30:33]
	v_mfma_f32_16x16x32_bf16 v[10:13], v[228:231], v[240:243], v[10:13]
	v_mfma_f32_16x16x32_bf16 v[14:17], v[228:231], v[252:255], v[14:17]
	s_waitcnt lgkmcnt(0)
	s_barrier
	s_setprio 0
	ds_read_b128 v[232:235], v245 offset:36864
	ds_read_b128 v[216:219], v244
	ds_read_b128 v[236:239], v245 offset:39168
	ds_read_b128 v[240:243], v245 offset:41472
	ds_read_b128 v[252:255], v245 offset:43776
	ds_read_b128 v[220:223], v244 offset:2304
	ds_read_b128 v[224:227], v244 offset:4608
	ds_read_b128 v[228:231], v244 offset:6912
	global_load_dwordx4 v[180:183], v[70:71], off offset:1792
	global_load_dwordx4 v[188:191], v[68:69], off offset:1792
	global_load_dwordx4 v[192:195], v[66:67], off offset:1792
	global_load_dwordx4 v[196:199], v[72:73], off offset:1792
	global_load_dwordx4 v[200:203], v[74:75], off offset:1792
	global_load_dwordx4 v[204:207], v[76:77], off offset:1792
	global_load_dwordx4 v[208:211], v[78:79], off offset:1792
	global_load_dwordx4 v[212:215], v[80:81], off offset:1792
	s_waitcnt lgkmcnt(6)
	v_mfma_f32_16x16x32_bf16 v[50:53], v[216:219], v[232:235], v[50:53]
	s_waitcnt lgkmcnt(5)
	v_mfma_f32_16x16x32_bf16 v[54:57], v[216:219], v[236:239], v[54:57]
	s_waitcnt lgkmcnt(4)
	v_mfma_f32_16x16x32_bf16 v[34:37], v[216:219], v[240:243], v[34:37]
	s_waitcnt lgkmcnt(3)
	v_mfma_f32_16x16x32_bf16 v[38:41], v[216:219], v[252:255], v[38:41]
	ds_read_b128 v[216:219], v244 offset:64
	s_waitcnt lgkmcnt(3)
	v_mfma_f32_16x16x32_bf16 v[58:61], v[220:223], v[232:235], v[58:61]
	v_mfma_f32_16x16x32_bf16 v[62:65], v[220:223], v[236:239], v[62:65]
	v_mfma_f32_16x16x32_bf16 v[42:45], v[220:223], v[240:243], v[42:45]
	v_mfma_f32_16x16x32_bf16 v[46:49], v[220:223], v[252:255], v[46:49]
	ds_read_b128 v[220:223], v244 offset:2368
	s_setprio 1
	s_waitcnt vmcnt(15)
	ds_write_b128 v164, v[122:125] offset:18432
	s_waitcnt vmcnt(14)
	ds_write_b128 v164, v[126:129] offset:23040
	s_waitcnt lgkmcnt(5)
	v_mfma_f32_16x16x32_bf16 v[18:21], v[224:227], v[232:235], v[18:21]
	v_mfma_f32_16x16x32_bf16 v[22:25], v[224:227], v[236:239], v[22:25]
	v_mfma_f32_16x16x32_bf16 v[2:5], v[224:227], v[240:243], v[2:5]
	v_mfma_f32_16x16x32_bf16 v[6:9], v[224:227], v[252:255], v[6:9]
	ds_read_b128 v[224:227], v244 offset:4672
	s_waitcnt vmcnt(13)
	ds_write_b128 v164, v[136:139] offset:27648
	s_waitcnt vmcnt(12)
	ds_write_b128 v164, v[140:143] offset:32256
	s_waitcnt lgkmcnt(7)
	v_mfma_f32_16x16x32_bf16 v[26:29], v[228:231], v[232:235], v[26:29]
	ds_read_b128 v[232:235], v245 offset:36928
	v_mfma_f32_16x16x32_bf16 v[30:33], v[228:231], v[236:239], v[30:33]
	ds_read_b128 v[236:239], v245 offset:39232
	v_mfma_f32_16x16x32_bf16 v[10:13], v[228:231], v[240:243], v[10:13]
	ds_read_b128 v[240:243], v245 offset:41536
	v_mfma_f32_16x16x32_bf16 v[14:17], v[228:231], v[252:255], v[14:17]
	ds_read_b128 v[252:255], v245 offset:43840
	ds_read_b128 v[228:231], v244 offset:6976
	s_waitcnt lgkmcnt(4)
	v_mfma_f32_16x16x32_bf16 v[50:53], v[216:219], v[232:235], v[50:53]
	s_waitcnt lgkmcnt(3)
	v_mfma_f32_16x16x32_bf16 v[54:57], v[216:219], v[236:239], v[54:57]
	s_waitcnt lgkmcnt(2)
	v_mfma_f32_16x16x32_bf16 v[34:37], v[216:219], v[240:243], v[34:37]
	s_waitcnt lgkmcnt(1)
	v_mfma_f32_16x16x32_bf16 v[38:41], v[216:219], v[252:255], v[38:41]
	s_waitcnt vmcnt(11)
	ds_write_b128 v164, v[144:147] offset:55296
	s_waitcnt vmcnt(10)
	ds_write_b128 v164, v[148:151] offset:59904
	v_mfma_f32_16x16x32_bf16 v[58:61], v[220:223], v[232:235], v[58:61]
	v_mfma_f32_16x16x32_bf16 v[62:65], v[220:223], v[236:239], v[62:65]
	v_mfma_f32_16x16x32_bf16 v[42:45], v[220:223], v[240:243], v[42:45]
	v_mfma_f32_16x16x32_bf16 v[46:49], v[220:223], v[252:255], v[46:49]
	s_waitcnt vmcnt(9)
	ds_write_b128 v164, v[172:175] offset:64512
	s_waitcnt vmcnt(8)
	ds_write_b128 v165, v[176:179] offset:32256
	v_mfma_f32_16x16x32_bf16 v[18:21], v[224:227], v[232:235], v[18:21]
	v_mfma_f32_16x16x32_bf16 v[22:25], v[224:227], v[236:239], v[22:25]
	v_mfma_f32_16x16x32_bf16 v[2:5], v[224:227], v[240:243], v[2:5]
	v_mfma_f32_16x16x32_bf16 v[6:9], v[224:227], v[252:255], v[6:9]
	s_waitcnt lgkmcnt(4)
	v_mfma_f32_16x16x32_bf16 v[26:29], v[228:231], v[232:235], v[26:29]
	v_mfma_f32_16x16x32_bf16 v[30:33], v[228:231], v[236:239], v[30:33]
	v_mfma_f32_16x16x32_bf16 v[10:13], v[228:231], v[240:243], v[10:13]
	v_mfma_f32_16x16x32_bf16 v[14:17], v[228:231], v[252:255], v[14:17]
	s_waitcnt lgkmcnt(0)
	s_barrier
	s_setprio 0
	global_load_dwordx4 v[122:125], v[70:71], off offset:1920
	s_nop 0
	global_load_dwordx4 v[68:71], v[68:69], off offset:1920
	s_nop 0
	global_load_dwordx4 v[126:129], v[66:67], off offset:1920
	global_load_dwordx4 v[136:139], v[72:73], off offset:1920
	s_nop 0
	global_load_dwordx4 v[72:75], v[74:75], off offset:1920
	s_nop 0
	global_load_dwordx4 v[140:143], v[76:77], off offset:1920
	s_nop 0
	global_load_dwordx4 v[76:79], v[78:79], off offset:1920
	s_nop 0
	global_load_dwordx4 v[144:147], v[80:81], off offset:1920
	ds_read_b128 v[232:235], v245 offset:55296
	ds_read_b128 v[216:219], v244 offset:18432
	ds_read_b128 v[236:239], v245 offset:57600
	ds_read_b128 v[240:243], v245 offset:59904
	ds_read_b128 v[252:255], v245 offset:62208
	ds_read_b128 v[220:223], v244 offset:20736
	ds_read_b128 v[224:227], v244 offset:23040
	ds_read_b128 v[228:231], v244 offset:25344
	s_waitcnt lgkmcnt(6)
	v_mfma_f32_16x16x32_bf16 v[50:53], v[216:219], v[232:235], v[50:53]
	s_waitcnt lgkmcnt(5)
	v_mfma_f32_16x16x32_bf16 v[54:57], v[216:219], v[236:239], v[54:57]
	s_waitcnt lgkmcnt(4)
	v_mfma_f32_16x16x32_bf16 v[34:37], v[216:219], v[240:243], v[34:37]
	s_waitcnt lgkmcnt(3)
	v_mfma_f32_16x16x32_bf16 v[38:41], v[216:219], v[252:255], v[38:41]
	ds_read_b128 v[216:219], v244 offset:18496
	s_waitcnt lgkmcnt(3)
	v_mfma_f32_16x16x32_bf16 v[58:61], v[220:223], v[232:235], v[58:61]
	v_mfma_f32_16x16x32_bf16 v[62:65], v[220:223], v[236:239], v[62:65]
	v_mfma_f32_16x16x32_bf16 v[42:45], v[220:223], v[240:243], v[42:45]
	v_mfma_f32_16x16x32_bf16 v[46:49], v[220:223], v[252:255], v[46:49]
	ds_read_b128 v[220:223], v244 offset:20800
	s_setprio 1
	s_waitcnt vmcnt(15)
	ds_write_b128 v164, v[180:183]
	s_waitcnt vmcnt(14)
	ds_write_b128 v164, v[188:191] offset:4608
	s_waitcnt lgkmcnt(5)
	v_mfma_f32_16x16x32_bf16 v[18:21], v[224:227], v[232:235], v[18:21]
	v_mfma_f32_16x16x32_bf16 v[22:25], v[224:227], v[236:239], v[22:25]
	v_mfma_f32_16x16x32_bf16 v[2:5], v[224:227], v[240:243], v[2:5]
	v_mfma_f32_16x16x32_bf16 v[6:9], v[224:227], v[252:255], v[6:9]
	ds_read_b128 v[224:227], v244 offset:23104
	s_waitcnt vmcnt(13)
	ds_write_b128 v164, v[192:195] offset:9216
	s_waitcnt vmcnt(12)
	ds_write_b128 v164, v[196:199] offset:13824
	s_waitcnt lgkmcnt(7)
	v_mfma_f32_16x16x32_bf16 v[26:29], v[228:231], v[232:235], v[26:29]
	ds_read_b128 v[232:235], v245 offset:55360
	v_mfma_f32_16x16x32_bf16 v[30:33], v[228:231], v[236:239], v[30:33]
	ds_read_b128 v[236:239], v245 offset:57664
	v_mfma_f32_16x16x32_bf16 v[10:13], v[228:231], v[240:243], v[10:13]
	ds_read_b128 v[240:243], v245 offset:59968
	v_mfma_f32_16x16x32_bf16 v[14:17], v[228:231], v[252:255], v[14:17]
	ds_read_b128 v[252:255], v245 offset:62272
	ds_read_b128 v[228:231], v244 offset:25408
	s_waitcnt lgkmcnt(4)
	v_mfma_f32_16x16x32_bf16 v[50:53], v[216:219], v[232:235], v[50:53]
	s_waitcnt lgkmcnt(3)
	v_mfma_f32_16x16x32_bf16 v[54:57], v[216:219], v[236:239], v[54:57]
	s_waitcnt lgkmcnt(2)
	v_mfma_f32_16x16x32_bf16 v[34:37], v[216:219], v[240:243], v[34:37]
	s_waitcnt lgkmcnt(1)
	v_mfma_f32_16x16x32_bf16 v[38:41], v[216:219], v[252:255], v[38:41]
	s_waitcnt vmcnt(11)
	ds_write_b128 v164, v[200:203] offset:36864
	s_waitcnt vmcnt(10)
	ds_write_b128 v164, v[204:207] offset:41472
	v_mfma_f32_16x16x32_bf16 v[58:61], v[220:223], v[232:235], v[58:61]
	v_mfma_f32_16x16x32_bf16 v[62:65], v[220:223], v[236:239], v[62:65]
	v_mfma_f32_16x16x32_bf16 v[42:45], v[220:223], v[240:243], v[42:45]
	v_mfma_f32_16x16x32_bf16 v[46:49], v[220:223], v[252:255], v[46:49]
	s_waitcnt vmcnt(9)
	ds_write_b128 v164, v[208:211] offset:46080
	s_waitcnt vmcnt(8)
	ds_write_b128 v164, v[212:215] offset:50688
	v_mfma_f32_16x16x32_bf16 v[18:21], v[224:227], v[232:235], v[18:21]
	v_mfma_f32_16x16x32_bf16 v[22:25], v[224:227], v[236:239], v[22:25]
	v_mfma_f32_16x16x32_bf16 v[2:5], v[224:227], v[240:243], v[2:5]
	v_mfma_f32_16x16x32_bf16 v[6:9], v[224:227], v[252:255], v[6:9]
	s_waitcnt lgkmcnt(4)
	v_mfma_f32_16x16x32_bf16 v[26:29], v[228:231], v[232:235], v[26:29]
	v_mfma_f32_16x16x32_bf16 v[30:33], v[228:231], v[236:239], v[30:33]
	v_mfma_f32_16x16x32_bf16 v[10:13], v[228:231], v[240:243], v[10:13]
	v_mfma_f32_16x16x32_bf16 v[14:17], v[228:231], v[252:255], v[14:17]
	s_waitcnt lgkmcnt(0)
	s_barrier
	s_setprio 0
	ds_read_b128 v[232:235], v245 offset:36864
	ds_read_b128 v[216:219], v244
	ds_read_b128 v[236:239], v245 offset:39168
	ds_read_b128 v[240:243], v245 offset:41472
	ds_read_b128 v[252:255], v245 offset:43776
	ds_read_b128 v[220:223], v244 offset:2304
	ds_read_b128 v[224:227], v244 offset:4608
	ds_read_b128 v[228:231], v244 offset:6912
	s_waitcnt lgkmcnt(6)
	v_mfma_f32_16x16x32_bf16 v[50:53], v[216:219], v[232:235], v[50:53]
	s_waitcnt lgkmcnt(5)
	v_mfma_f32_16x16x32_bf16 v[54:57], v[216:219], v[236:239], v[54:57]
	s_waitcnt lgkmcnt(4)
	v_mfma_f32_16x16x32_bf16 v[34:37], v[216:219], v[240:243], v[34:37]
	s_waitcnt lgkmcnt(3)
	v_mfma_f32_16x16x32_bf16 v[38:41], v[216:219], v[252:255], v[38:41]
	ds_read_b128 v[216:219], v244 offset:64
	s_waitcnt lgkmcnt(3)
	v_mfma_f32_16x16x32_bf16 v[58:61], v[220:223], v[232:235], v[58:61]
	v_mfma_f32_16x16x32_bf16 v[62:65], v[220:223], v[236:239], v[62:65]
	v_mfma_f32_16x16x32_bf16 v[42:45], v[220:223], v[240:243], v[42:45]
	v_mfma_f32_16x16x32_bf16 v[46:49], v[220:223], v[252:255], v[46:49]
	ds_read_b128 v[220:223], v244 offset:2368
	s_setprio 1
	s_waitcnt vmcnt(7)
	ds_write_b128 v164, v[122:125] offset:18432
	s_waitcnt vmcnt(6)
	ds_write_b128 v164, v[68:71] offset:23040
	s_waitcnt lgkmcnt(5)
	v_mfma_f32_16x16x32_bf16 v[18:21], v[224:227], v[232:235], v[18:21]
	v_mfma_f32_16x16x32_bf16 v[22:25], v[224:227], v[236:239], v[22:25]
	v_mfma_f32_16x16x32_bf16 v[2:5], v[224:227], v[240:243], v[2:5]
	v_mfma_f32_16x16x32_bf16 v[6:9], v[224:227], v[252:255], v[6:9]
	ds_read_b128 v[224:227], v244 offset:4672
	s_waitcnt vmcnt(5)
	ds_write_b128 v164, v[126:129] offset:27648
	s_waitcnt vmcnt(4)
	ds_write_b128 v164, v[136:139] offset:32256
	s_waitcnt lgkmcnt(7)
	v_mfma_f32_16x16x32_bf16 v[26:29], v[228:231], v[232:235], v[26:29]
	ds_read_b128 v[232:235], v245 offset:36928
	v_mfma_f32_16x16x32_bf16 v[30:33], v[228:231], v[236:239], v[30:33]
	ds_read_b128 v[236:239], v245 offset:39232
	v_mfma_f32_16x16x32_bf16 v[10:13], v[228:231], v[240:243], v[10:13]
	ds_read_b128 v[240:243], v245 offset:41536
	v_mfma_f32_16x16x32_bf16 v[14:17], v[228:231], v[252:255], v[14:17]
	ds_read_b128 v[252:255], v245 offset:43840
	ds_read_b128 v[228:231], v244 offset:6976
	s_waitcnt lgkmcnt(4)
	v_mfma_f32_16x16x32_bf16 v[50:53], v[216:219], v[232:235], v[50:53]
	s_waitcnt lgkmcnt(3)
	v_mfma_f32_16x16x32_bf16 v[54:57], v[216:219], v[236:239], v[54:57]
	s_waitcnt lgkmcnt(2)
	v_mfma_f32_16x16x32_bf16 v[34:37], v[216:219], v[240:243], v[34:37]
	s_waitcnt lgkmcnt(1)
	v_mfma_f32_16x16x32_bf16 v[38:41], v[216:219], v[252:255], v[38:41]
	s_waitcnt vmcnt(3)
	ds_write_b128 v164, v[72:75] offset:55296
	s_waitcnt vmcnt(2)
	ds_write_b128 v164, v[140:143] offset:59904
	v_mfma_f32_16x16x32_bf16 v[58:61], v[220:223], v[232:235], v[58:61]
	v_mfma_f32_16x16x32_bf16 v[62:65], v[220:223], v[236:239], v[62:65]
	v_mfma_f32_16x16x32_bf16 v[42:45], v[220:223], v[240:243], v[42:45]
	v_mfma_f32_16x16x32_bf16 v[46:49], v[220:223], v[252:255], v[46:49]
	s_waitcnt vmcnt(1)
	ds_write_b128 v164, v[76:79] offset:64512
	s_waitcnt vmcnt(0)
	ds_write_b128 v165, v[144:147] offset:32256
	v_mfma_f32_16x16x32_bf16 v[18:21], v[224:227], v[232:235], v[18:21]
	v_mfma_f32_16x16x32_bf16 v[22:25], v[224:227], v[236:239], v[22:25]
	v_mfma_f32_16x16x32_bf16 v[2:5], v[224:227], v[240:243], v[2:5]
	v_mfma_f32_16x16x32_bf16 v[6:9], v[224:227], v[252:255], v[6:9]
	s_waitcnt lgkmcnt(4)
	v_mfma_f32_16x16x32_bf16 v[26:29], v[228:231], v[232:235], v[26:29]
	v_mfma_f32_16x16x32_bf16 v[30:33], v[228:231], v[236:239], v[30:33]
	v_mfma_f32_16x16x32_bf16 v[10:13], v[228:231], v[240:243], v[10:13]
	v_mfma_f32_16x16x32_bf16 v[14:17], v[228:231], v[252:255], v[14:17]
	s_waitcnt lgkmcnt(0)
	s_barrier
	s_setprio 0
	ds_read_b128 v[232:235], v245 offset:55296
	ds_read_b128 v[216:219], v244 offset:18432
	ds_read_b128 v[236:239], v245 offset:57600
	ds_read_b128 v[240:243], v245 offset:59904
	ds_read_b128 v[252:255], v245 offset:62208
	ds_read_b128 v[220:223], v244 offset:20736
	ds_read_b128 v[224:227], v244 offset:23040
	ds_read_b128 v[228:231], v244 offset:25344
	s_waitcnt lgkmcnt(6)
	v_mfma_f32_16x16x32_bf16 v[50:53], v[216:219], v[232:235], v[50:53]
	s_waitcnt lgkmcnt(5)
	v_mfma_f32_16x16x32_bf16 v[54:57], v[216:219], v[236:239], v[54:57]
	s_waitcnt lgkmcnt(4)
	v_mfma_f32_16x16x32_bf16 v[34:37], v[216:219], v[240:243], v[34:37]
	s_waitcnt lgkmcnt(3)
	v_mfma_f32_16x16x32_bf16 v[38:41], v[216:219], v[252:255], v[38:41]
	ds_read_b128 v[216:219], v244 offset:18496
	s_waitcnt lgkmcnt(3)
	v_mfma_f32_16x16x32_bf16 v[58:61], v[220:223], v[232:235], v[58:61]
	v_mfma_f32_16x16x32_bf16 v[62:65], v[220:223], v[236:239], v[62:65]
	v_mfma_f32_16x16x32_bf16 v[42:45], v[220:223], v[240:243], v[42:45]
	v_mfma_f32_16x16x32_bf16 v[46:49], v[220:223], v[252:255], v[46:49]
	ds_read_b128 v[220:223], v244 offset:20800
	s_waitcnt lgkmcnt(3)
	v_mfma_f32_16x16x32_bf16 v[18:21], v[224:227], v[232:235], v[18:21]
	v_mfma_f32_16x16x32_bf16 v[22:25], v[224:227], v[236:239], v[22:25]
	v_mfma_f32_16x16x32_bf16 v[2:5], v[224:227], v[240:243], v[2:5]
	v_mfma_f32_16x16x32_bf16 v[6:9], v[224:227], v[252:255], v[6:9]
	ds_read_b128 v[224:227], v244 offset:23104
	s_waitcnt lgkmcnt(3)
	v_mfma_f32_16x16x32_bf16 v[26:29], v[228:231], v[232:235], v[26:29]
	ds_read_b128 v[232:235], v245 offset:55360
	v_mfma_f32_16x16x32_bf16 v[30:33], v[228:231], v[236:239], v[30:33]
	ds_read_b128 v[236:239], v245 offset:57664
	v_mfma_f32_16x16x32_bf16 v[10:13], v[228:231], v[240:243], v[10:13]
	ds_read_b128 v[240:243], v245 offset:59968
	v_mfma_f32_16x16x32_bf16 v[14:17], v[228:231], v[252:255], v[14:17]
	ds_read_b128 v[252:255], v245 offset:62272
	ds_read_b128 v[228:231], v244 offset:25408
	s_waitcnt lgkmcnt(4)
	v_mfma_f32_16x16x32_bf16 v[50:53], v[216:219], v[232:235], v[50:53]
	s_waitcnt lgkmcnt(3)
	v_mfma_f32_16x16x32_bf16 v[54:57], v[216:219], v[236:239], v[54:57]
	s_waitcnt lgkmcnt(2)
	v_mfma_f32_16x16x32_bf16 v[34:37], v[216:219], v[240:243], v[34:37]
	s_waitcnt lgkmcnt(1)
	v_mfma_f32_16x16x32_bf16 v[38:41], v[216:219], v[252:255], v[38:41]
	v_mfma_f32_16x16x32_bf16 v[58:61], v[220:223], v[232:235], v[58:61]
	v_mfma_f32_16x16x32_bf16 v[62:65], v[220:223], v[236:239], v[62:65]
	v_mfma_f32_16x16x32_bf16 v[42:45], v[220:223], v[240:243], v[42:45]
	v_mfma_f32_16x16x32_bf16 v[46:49], v[220:223], v[252:255], v[46:49]
	v_mfma_f32_16x16x32_bf16 v[18:21], v[224:227], v[232:235], v[18:21]
	v_mfma_f32_16x16x32_bf16 v[22:25], v[224:227], v[236:239], v[22:25]
	v_mfma_f32_16x16x32_bf16 v[2:5], v[224:227], v[240:243], v[2:5]
	v_mfma_f32_16x16x32_bf16 v[6:9], v[224:227], v[252:255], v[6:9]
	s_waitcnt lgkmcnt(0)
	v_mfma_f32_16x16x32_bf16 v[26:29], v[228:231], v[232:235], v[26:29]
	v_mfma_f32_16x16x32_bf16 v[30:33], v[228:231], v[236:239], v[30:33]
	v_mfma_f32_16x16x32_bf16 v[10:13], v[228:231], v[240:243], v[10:13]
	v_mfma_f32_16x16x32_bf16 v[14:17], v[228:231], v[252:255], v[14:17]
	s_waitcnt lgkmcnt(0)
	s_barrier
	s_nop 7
	v_permlane16_swap_b32_e32 v50, v54
	v_permlane16_swap_b32_e32 v51, v55
	v_permlane16_swap_b32_e32 v52, v56
	v_permlane16_swap_b32_e32 v53, v57
	v_permlane16_swap_b32_e32 v58, v62
	v_permlane16_swap_b32_e32 v59, v63
	v_permlane16_swap_b32_e32 v60, v64
	v_permlane16_swap_b32_e32 v61, v65
	v_permlane16_swap_b32_e32 v34, v38
	v_permlane16_swap_b32_e32 v35, v39
	v_permlane16_swap_b32_e32 v36, v40
	v_permlane16_swap_b32_e32 v37, v41
	v_permlane16_swap_b32_e32 v42, v46
	v_permlane16_swap_b32_e32 v43, v47
	v_permlane16_swap_b32_e32 v44, v48
	v_permlane16_swap_b32_e32 v45, v49
	v_permlane16_swap_b32_e32 v18, v22
	v_permlane16_swap_b32_e32 v19, v23
	v_permlane16_swap_b32_e32 v20, v24
	v_permlane16_swap_b32_e32 v21, v25
	v_permlane16_swap_b32_e32 v26, v30
	v_permlane16_swap_b32_e32 v27, v31
	v_permlane16_swap_b32_e32 v28, v32
	v_permlane16_swap_b32_e32 v29, v33
	v_permlane16_swap_b32_e32 v2, v6
	v_permlane16_swap_b32_e32 v3, v7
	v_permlane16_swap_b32_e32 v4, v8
	v_permlane16_swap_b32_e32 v5, v9
	v_permlane16_swap_b32_e32 v10, v14
	v_permlane16_swap_b32_e32 v11, v15
	v_permlane16_swap_b32_e32 v12, v16
	v_permlane16_swap_b32_e32 v13, v17
	v_permlane32_swap_b32_e32 v50, v54
	v_permlane32_swap_b32_e32 v51, v55
	v_permlane32_swap_b32_e32 v52, v56
	v_permlane32_swap_b32_e32 v53, v57
	v_permlane32_swap_b32_e32 v58, v62
	v_permlane32_swap_b32_e32 v59, v63
	v_permlane32_swap_b32_e32 v60, v64
	v_permlane32_swap_b32_e32 v61, v65
	v_permlane32_swap_b32_e32 v34, v38
	v_permlane32_swap_b32_e32 v35, v39
	v_permlane32_swap_b32_e32 v36, v40
	v_permlane32_swap_b32_e32 v37, v41
	v_permlane32_swap_b32_e32 v42, v46
	v_permlane32_swap_b32_e32 v43, v47
	v_permlane32_swap_b32_e32 v44, v48
	v_permlane32_swap_b32_e32 v45, v49
	v_permlane32_swap_b32_e32 v18, v22
	v_permlane32_swap_b32_e32 v19, v23
	v_permlane32_swap_b32_e32 v20, v24
	v_permlane32_swap_b32_e32 v21, v25
	v_permlane32_swap_b32_e32 v26, v30
	v_permlane32_swap_b32_e32 v27, v31
	v_permlane32_swap_b32_e32 v28, v32
	v_permlane32_swap_b32_e32 v29, v33
	v_permlane32_swap_b32_e32 v2, v6
	v_permlane32_swap_b32_e32 v3, v7
	v_permlane32_swap_b32_e32 v4, v8
	v_permlane32_swap_b32_e32 v5, v9
	v_permlane32_swap_b32_e32 v10, v14
	v_permlane32_swap_b32_e32 v11, v15
	v_permlane32_swap_b32_e32 v12, v16
	v_permlane32_swap_b32_e32 v13, v17
